# K-loops: wave priority inverted (load segments at prio 1, MFMA segments at prio 0) on top of the v68 stack
# speedup vs baseline: 1.0071x; 1.0071x over previous
; #define PG8_STAGE(bufoff, gbase, voff) do { _Pragma("unroll") for (int _i = 0; _i < 2; ++_i) \
;         __builtin_amdgcn_global_load_lds((const unsigned*)((const char*)(gbase) + (voff)[_i]), (PG8_LAS unsigned*)(lds + (bufoff) + ldsw + _i * 8192), 16, 0, 0); } while (0)
; #define PG8_LDA(dst, b, h) do { _Pragma("unroll") for (int m = 0; m < 4; ++m) _Pragma("unroll") for (int k = 0; k < 2; ++k) dst[m][k] = *(const PG8_LAS bf16x8*)(lds + PG8_SA(b, h) + aoff + m * 2048 + k * 1024); } while (0)
; #define PG8_LDB(dst, b, h) do { _Pragma("unroll") for (int n = 0; n < 2; ++n) _Pragma("unroll") for (int k = 0; k < 2; ++k) dst[n][k] = *(const PG8_LAS bf16x8*)(lds + PG8_SB(b, h) + boff + n * 2048 + k * 1024); } while (0)
; #define PG8_MMA(ai, bj, At, Bt) do { __builtin_amdgcn_s_setprio(1); _Pragma("unroll") for (int m = 0; m < 4; ++m) _Pragma("unroll") for (int n = 0; n < 2; ++n) _Pragma("unroll") for (int k = 0; k < 2; ++k) \
;         acc[ai][bj][m][n] = __builtin_amdgcn_mfma_f32_16x16x32_bf16(Bt[n][k], At[m][k], acc[ai][bj][m][n], 0, 0, 0); __builtin_amdgcn_s_setprio(0); } while (0)
; #define PG8_WAIT_V(n) asm volatile("s_waitcnt vmcnt(" #n ")" ::: "memory")
; #define PG8_WAIT_L(n) asm volatile("s_waitcnt lgkmcnt(" #n ")" ::: "memory")
; template <class Epi, class Sched, bool ALIGN_EPI = false, bool SP2 = false>
; __device__ __forceinline__ void gemm_phase(PG8_LAS unsigned char* lds, const Gemm g, const Sched& S, const Epi& E) {
;     ...
;             const bool last = (t == nt - 2);
;             const char* a1 = cA + (size_t)(t + 1) * kstep;
;             const char* a2 = last ? nA : cA + (size_t)(t + 2) * kstep; const char* b2 = last ? nB : cB + (size_t)(t + 2) * kstep;
;             const char* a3 = a2 + kstep; const char* b3 = b2 + kstep;
;             if (last && has_next) S.a_ready(nxt);
;             if constexpr (SP2) {
;             PG8_LDB(B0, 0, 0); PG8_LDB(B1, 0, 1); PG8_SCHED; PG8_LDA(At, 0, 0); PG8_STAGE(PG8_SA(1, 1), a1 + hstep, voffA);
;             PG8_WAIT_V(8); PG8_WAIT_L(0); PG8_BAR; PG8_MMA(0, 0, At, B0); PG8_MMA(0, 1, At, B1); PG8_BAR; PG8_SCHED;
;             PG8_LDA(At, 0, 1); PG8_STAGE(PG8_SB(0, 0), b2, voffB); PG8_STAGE(PG8_SB(0, 1), b2 + hstep, voffB); PG8_STAGE(PG8_SA(0, 0), a2, voffA);
;             PG8_WAIT_V(8); PG8_WAIT_L(0); PG8_BAR; PG8_MMA(1, 0, At, B0); PG8_MMA(1, 1, At, B1); PG8_BAR; PG8_SCHED;
.LBB0_304:
	v_add_u32_e32 v166, s54, v169
	v_add_u32_e32 v168, s55, v169
	ds_read_b128 v[162:165], v166
	ds_read_b128 v[182:185], v166 offset:1024
	ds_read_b128 v[186:189], v166 offset:2048
	ds_read_b128 v[190:193], v166 offset:3072
	ds_read_b128 v[194:197], v168
	ds_read_b128 v[198:201], v168 offset:1024
	ds_read_b128 v[202:205], v168 offset:2048
	ds_read_b128 v[206:209], v168 offset:3072
	s_cmp_eq_u32 s53, s10
	v_lshl_add_u64 v[172:173], v[160:161], 0, s[22:23]
	s_cselect_b64 vcc, -1, 0
	s_add_i32 s10, s10, 2
	v_cndmask_b32_e32 v173, v173, v153, vcc
	v_cndmask_b32_e32 v172, v172, v152, vcc
	v_cndmask_b32_e32 v245, v159, v155, vcc
	v_cndmask_b32_e32 v244, v158, v154, vcc
	s_mov_b32 m0, s56
	v_lshl_add_u64 v[246:247], v[160:161], 0, v[148:149]
	ds_read_b128 v[210:213], v179
	ds_read_b128 v[216:219], v179 offset:1024
	ds_read_b128 v[220:223], v179 offset:2048
	ds_read_b128 v[224:227], v179 offset:3072
	ds_read_b128 v[228:231], v179 offset:4096
	ds_read_b128 v[232:235], v179 offset:5120
	ds_read_b128 v[236:239], v179 offset:6144
	ds_read_b128 v[240:243], v179 offset:7168
	global_load_lds_dwordx4 v[246:247], off
	s_mov_b32 m0, s57
	v_lshl_add_u64 v[246:247], v[160:161], 0, v[146:147]
	global_load_lds_dwordx4 v[246:247], off
	s_waitcnt vmcnt(8) lgkmcnt(0)
	s_setprio 0
	s_barrier
	v_mfma_f32_16x16x32_bf16 v[124:127], v[162:165], v[210:213], v[124:127]
	v_mfma_f32_16x16x32_bf16 v[116:119], v[186:189], v[210:213], v[116:119]
	v_mfma_f32_16x16x32_bf16 v[108:111], v[162:165], v[220:223], v[108:111]
	v_mfma_f32_16x16x32_bf16 v[100:103], v[186:189], v[220:223], v[100:103]
	v_mfma_f32_16x16x32_bf16 v[92:95], v[162:165], v[228:231], v[92:95]
	v_mfma_f32_16x16x32_bf16 v[84:87], v[186:189], v[228:231], v[84:87]
	v_mfma_f32_16x16x32_bf16 v[76:79], v[162:165], v[236:239], v[76:79]
	v_mfma_f32_16x16x32_bf16 v[68:71], v[186:189], v[236:239], v[68:71]
	v_mfma_f32_16x16x32_bf16 v[124:127], v[182:185], v[216:219], v[124:127]
	v_mfma_f32_16x16x32_bf16 v[116:119], v[190:193], v[216:219], v[116:119]
	v_mfma_f32_16x16x32_bf16 v[108:111], v[182:185], v[224:227], v[108:111]
	v_mfma_f32_16x16x32_bf16 v[100:103], v[190:193], v[224:227], v[100:103]
	v_mfma_f32_16x16x32_bf16 v[92:95], v[182:185], v[232:235], v[92:95]
	v_mfma_f32_16x16x32_bf16 v[84:87], v[190:193], v[232:235], v[84:87]
	v_mfma_f32_16x16x32_bf16 v[76:79], v[182:185], v[240:243], v[76:79]
	v_mfma_f32_16x16x32_bf16 v[68:71], v[190:193], v[240:243], v[68:71]
	v_mfma_f32_16x16x32_bf16 v[120:123], v[194:197], v[210:213], v[120:123]
	v_mfma_f32_16x16x32_bf16 v[112:115], v[202:205], v[210:213], v[112:115]
	v_mfma_f32_16x16x32_bf16 v[104:107], v[194:197], v[220:223], v[104:107]
	v_mfma_f32_16x16x32_bf16 v[96:99], v[202:205], v[220:223], v[96:99]
	v_mfma_f32_16x16x32_bf16 v[88:91], v[194:197], v[228:231], v[88:91]
	v_mfma_f32_16x16x32_bf16 v[80:83], v[202:205], v[228:231], v[80:83]
	v_mfma_f32_16x16x32_bf16 v[72:75], v[194:197], v[236:239], v[72:75]
	v_mfma_f32_16x16x32_bf16 v[64:67], v[202:205], v[236:239], v[64:67]
	v_mfma_f32_16x16x32_bf16 v[120:123], v[198:201], v[216:219], v[120:123]
	v_mfma_f32_16x16x32_bf16 v[112:115], v[206:209], v[216:219], v[112:115]
	v_mfma_f32_16x16x32_bf16 v[104:107], v[198:201], v[224:227], v[104:107]
	v_mfma_f32_16x16x32_bf16 v[96:99], v[206:209], v[224:227], v[96:99]
	v_mfma_f32_16x16x32_bf16 v[88:91], v[198:201], v[232:235], v[88:91]
	v_mfma_f32_16x16x32_bf16 v[80:83], v[206:209], v[232:235], v[80:83]
	v_mfma_f32_16x16x32_bf16 v[72:75], v[198:201], v[240:243], v[72:75]
	v_mfma_f32_16x16x32_bf16 v[64:67], v[206:209], v[240:243], v[64:67]
	s_setprio 1
	s_barrier
	s_mov_b32 m0, s60
	v_lshl_add_u64 v[246:247], v[244:245], 0, v[138:139]
	ds_read_b128 v[210:213], v179 offset:16384
	ds_read_b128 v[216:219], v179 offset:17408
	ds_read_b128 v[220:223], v179 offset:18432
	ds_read_b128 v[224:227], v179 offset:19456
	ds_read_b128 v[228:231], v179 offset:20480
	ds_read_b128 v[232:235], v179 offset:21504
	ds_read_b128 v[236:239], v179 offset:22528
	ds_read_b128 v[240:243], v179 offset:23552
	global_load_lds_dwordx4 v[246:247], off
	v_lshl_add_u64 v[248:249], v[244:245], 0, v[134:135]
	s_mov_b32 m0, s61
	v_lshl_add_u64 v[244:245], v[244:245], 0, s[14:15]
	global_load_lds_dwordx4 v[248:249], off
	v_lshl_add_u64 v[250:251], v[244:245], 0, v[138:139]
	s_mov_b32 m0, s62
	v_lshl_add_u64 v[244:245], v[244:245], 0, v[134:135]
	global_load_lds_dwordx4 v[250:251], off
	s_add_i32 m0, s62, 0x2000
	v_lshl_add_u64 v[252:253], v[172:173], 0, v[140:141]
	global_load_lds_dwordx4 v[244:245], off
	s_mov_b32 m0, s46
	v_lshl_add_u64 v[214:215], v[172:173], 0, v[136:137]
	global_load_lds_dwordx4 v[252:253], off
	s_mov_b32 m0, s47
	s_nop 0
	global_load_lds_dwordx4 v[214:215], off
	s_waitcnt vmcnt(8) lgkmcnt(0)
	s_setprio 0
	s_barrier
; #define PG8_STAGE(bufoff, gbase, voff) do { _Pragma("unroll") for (int _i = 0; _i < 2; ++_i) \
;         __builtin_amdgcn_global_load_lds((const unsigned*)((const char*)(gbase) + (voff)[_i]), (PG8_LAS unsigned*)(lds + (bufoff) + ldsw + _i * 8192), 16, 0, 0); } while (0)
; #define PG8_LDA(dst, b, h) do { _Pragma("unroll") for (int m = 0; m < 4; ++m) _Pragma("unroll") for (int k = 0; k < 2; ++k) dst[m][k] = *(const PG8_LAS bf16x8*)(lds + PG8_SA(b, h) + aoff + m * 2048 + k * 1024); } while (0)
; #define PG8_LDB(dst, b, h) do { _Pragma("unroll") for (int n = 0; n < 2; ++n) _Pragma("unroll") for (int k = 0; k < 2; ++k) dst[n][k] = *(const PG8_LAS bf16x8*)(lds + PG8_SB(b, h) + boff + n * 2048 + k * 1024); } while (0)
; #define PG8_MMA(ai, bj, At, Bt) do { __builtin_amdgcn_s_setprio(1); _Pragma("unroll") for (int m = 0; m < 4; ++m) _Pragma("unroll") for (int n = 0; n < 2; ++n) _Pragma("unroll") for (int k = 0; k < 2; ++k) \
;         acc[ai][bj][m][n] = __builtin_amdgcn_mfma_f32_16x16x32_bf16(Bt[n][k], At[m][k], acc[ai][bj][m][n], 0, 0, 0); __builtin_amdgcn_s_setprio(0); } while (0)
; #define PG8_WAIT_V(n) asm volatile("s_waitcnt vmcnt(" #n ")" ::: "memory")
; #define PG8_WAIT_L(n) asm volatile("s_waitcnt lgkmcnt(" #n ")" ::: "memory")
; #define PG8_BAR __builtin_amdgcn_s_barrier()
; #define PG8_SCHED __builtin_amdgcn_sched_barrier(0)
; template <class Epi, class Sched, bool ALIGN_EPI = false, bool SP2 = false>
; __device__ __forceinline__ void gemm_phase(PG8_LAS unsigned char* lds, const Gemm g, const Sched& S, const Epi& E) {
;     ...
;             PG8_WAIT_V(8); PG8_WAIT_L(0); PG8_BAR; PG8_MMA(1, 0, At, B0); PG8_MMA(1, 1, At, B1); PG8_BAR; PG8_SCHED;
;             PG8_LDB(B0, 1, 0); PG8_LDB(B1, 1, 1); PG8_SCHED; PG8_LDA(At, 1, 0); PG8_STAGE(PG8_SA(0, 1), a2 + hstep, voffA);
;             PG8_WAIT_V(8); PG8_WAIT_L(0); PG8_BAR; PG8_MMA(0, 0, At, B0); PG8_MMA(0, 1, At, B1); PG8_BAR; PG8_SCHED;
	v_mfma_f32_16x16x32_bf16 v[60:63], v[162:165], v[210:213], v[60:63]
	v_mfma_f32_16x16x32_bf16 v[52:55], v[186:189], v[210:213], v[52:55]
	v_mfma_f32_16x16x32_bf16 v[44:47], v[162:165], v[220:223], v[44:47]
	v_mfma_f32_16x16x32_bf16 v[36:39], v[186:189], v[220:223], v[36:39]
	v_mfma_f32_16x16x32_bf16 v[28:31], v[162:165], v[228:231], v[28:31]
	v_mfma_f32_16x16x32_bf16 v[20:23], v[186:189], v[228:231], v[20:23]
	v_mfma_f32_16x16x32_bf16 v[12:15], v[162:165], v[236:239], v[12:15]
	v_mfma_f32_16x16x32_bf16 v[4:7], v[186:189], v[236:239], v[4:7]
	v_mfma_f32_16x16x32_bf16 v[60:63], v[182:185], v[216:219], v[60:63]
	v_mfma_f32_16x16x32_bf16 v[52:55], v[190:193], v[216:219], v[52:55]
	v_mfma_f32_16x16x32_bf16 v[44:47], v[182:185], v[224:227], v[44:47]
	v_mfma_f32_16x16x32_bf16 v[36:39], v[190:193], v[224:227], v[36:39]
	v_mfma_f32_16x16x32_bf16 v[28:31], v[182:185], v[232:235], v[28:31]
	v_mfma_f32_16x16x32_bf16 v[20:23], v[190:193], v[232:235], v[20:23]
	v_mfma_f32_16x16x32_bf16 v[12:15], v[182:185], v[240:243], v[12:15]
	v_mfma_f32_16x16x32_bf16 v[4:7], v[190:193], v[240:243], v[4:7]
	v_mfma_f32_16x16x32_bf16 v[56:59], v[194:197], v[210:213], v[56:59]
	v_mfma_f32_16x16x32_bf16 v[48:51], v[202:205], v[210:213], v[48:51]
	v_mfma_f32_16x16x32_bf16 v[40:43], v[194:197], v[220:223], v[40:43]
	v_mfma_f32_16x16x32_bf16 v[32:35], v[202:205], v[220:223], v[32:35]
	v_mfma_f32_16x16x32_bf16 v[24:27], v[194:197], v[228:231], v[24:27]
	v_mfma_f32_16x16x32_bf16 v[16:19], v[202:205], v[228:231], v[16:19]
	v_mfma_f32_16x16x32_bf16 v[8:11], v[194:197], v[236:239], v[8:11]
	v_mfma_f32_16x16x32_bf16 v[0:3], v[202:205], v[236:239], v[0:3]
	v_mfma_f32_16x16x32_bf16 v[56:59], v[198:201], v[216:219], v[56:59]
	v_mfma_f32_16x16x32_bf16 v[48:51], v[206:209], v[216:219], v[48:51]
	v_mfma_f32_16x16x32_bf16 v[40:43], v[198:201], v[224:227], v[40:43]
	v_mfma_f32_16x16x32_bf16 v[32:35], v[206:209], v[224:227], v[32:35]
	v_mfma_f32_16x16x32_bf16 v[24:27], v[198:201], v[232:235], v[24:27]
	v_mfma_f32_16x16x32_bf16 v[16:19], v[206:209], v[232:235], v[16:19]
	v_mfma_f32_16x16x32_bf16 v[8:11], v[198:201], v[240:243], v[8:11]
	v_mfma_f32_16x16x32_bf16 v[0:3], v[206:209], v[240:243], v[0:3]
	s_setprio 1
	s_barrier
	s_add_i32 s11, 0, 0x18000
	v_add_u32_e32 v166, s11, v169
	s_add_i32 s13, 0, 0x1c000
	ds_read_b128 v[162:165], v166
	ds_read_b128 v[182:185], v166 offset:1024
	ds_read_b128 v[186:189], v166 offset:2048
	ds_read_b128 v[190:193], v166 offset:3072
	v_add_u32_e32 v166, s13, v169
	ds_read_b128 v[194:197], v166
	ds_read_b128 v[198:201], v166 offset:1024
	ds_read_b128 v[202:205], v166 offset:2048
	ds_read_b128 v[206:209], v166 offset:3072
	v_lshl_add_u64 v[172:173], v[172:173], 0, s[14:15]
	s_mov_b32 m0, s48
	v_lshl_add_u64 v[170:171], v[172:173], 0, v[140:141]
	ds_read_b128 v[210:213], v179 offset:32768
	ds_read_b128 v[216:219], v179 offset:33792
	ds_read_b128 v[220:223], v179 offset:34816
	ds_read_b128 v[224:227], v179 offset:35840
	ds_read_b128 v[228:231], v179 offset:36864
	ds_read_b128 v[232:235], v179 offset:37888
	ds_read_b128 v[236:239], v179 offset:38912
	ds_read_b128 v[240:243], v179 offset:39936
	global_load_lds_dwordx4 v[170:171], off
	s_mov_b32 m0, s49
	v_lshl_add_u64 v[170:171], v[172:173], 0, v[136:137]
	global_load_lds_dwordx4 v[170:171], off
	s_waitcnt vmcnt(8) lgkmcnt(0)
	s_setprio 0
	s_barrier
; #define PG8_STAGE(bufoff, gbase, voff) do { _Pragma("unroll") for (int _i = 0; _i < 2; ++_i) \
;         __builtin_amdgcn_global_load_lds((const unsigned*)((const char*)(gbase) + (voff)[_i]), (PG8_LAS unsigned*)(lds + (bufoff) + ldsw + _i * 8192), 16, 0, 0); } while (0)
; #define PG8_LDA(dst, b, h) do { _Pragma("unroll") for (int m = 0; m < 4; ++m) _Pragma("unroll") for (int k = 0; k < 2; ++k) dst[m][k] = *(const PG8_LAS bf16x8*)(lds + PG8_SA(b, h) + aoff + m * 2048 + k * 1024); } while (0)
; #define PG8_MMA(ai, bj, At, Bt) do { __builtin_amdgcn_s_setprio(1); _Pragma("unroll") for (int m = 0; m < 4; ++m) _Pragma("unroll") for (int n = 0; n < 2; ++n) _Pragma("unroll") for (int k = 0; k < 2; ++k) \
;         acc[ai][bj][m][n] = __builtin_amdgcn_mfma_f32_16x16x32_bf16(Bt[n][k], At[m][k], acc[ai][bj][m][n], 0, 0, 0); __builtin_amdgcn_s_setprio(0); } while (0)
; #define PG8_WAIT_V(n) asm volatile("s_waitcnt vmcnt(" #n ")" ::: "memory")
; #define PG8_WAIT_L(n) asm volatile("s_waitcnt lgkmcnt(" #n ")" ::: "memory")
; #define PG8_BAR __builtin_amdgcn_s_barrier()
; #define PG8_SCHED __builtin_amdgcn_sched_barrier(0)
; template <class Epi, class Sched, bool ALIGN_EPI = false, bool SP2 = false>
; __device__ __forceinline__ void gemm_phase(PG8_LAS unsigned char* lds, const Gemm g, const Sched& S, const Epi& E) {
;     ...
;             PG8_WAIT_V(8); PG8_WAIT_L(0); PG8_BAR; PG8_MMA(0, 0, At, B0); PG8_MMA(0, 1, At, B1); PG8_BAR; PG8_SCHED;
;             PG8_LDA(At, 1, 1); PG8_STAGE(PG8_SB(1, 0), b3, voffB); PG8_STAGE(PG8_SB(1, 1), b3 + hstep, voffB); PG8_STAGE(PG8_SA(1, 0), a3, voffA);
;             PG8_WAIT_V(8); PG8_WAIT_L(0); PG8_BAR; PG8_MMA(1, 0, At, B0); PG8_MMA(1, 1, At, B1); PG8_BAR; PG8_SCHED;
	v_mfma_f32_16x16x32_bf16 v[124:127], v[162:165], v[210:213], v[124:127]
	v_mfma_f32_16x16x32_bf16 v[116:119], v[186:189], v[210:213], v[116:119]
	v_mfma_f32_16x16x32_bf16 v[108:111], v[162:165], v[220:223], v[108:111]
	v_mfma_f32_16x16x32_bf16 v[100:103], v[186:189], v[220:223], v[100:103]
	v_mfma_f32_16x16x32_bf16 v[92:95], v[162:165], v[228:231], v[92:95]
	v_mfma_f32_16x16x32_bf16 v[84:87], v[186:189], v[228:231], v[84:87]
	v_mfma_f32_16x16x32_bf16 v[76:79], v[162:165], v[236:239], v[76:79]
	v_mfma_f32_16x16x32_bf16 v[68:71], v[186:189], v[236:239], v[68:71]
	v_mfma_f32_16x16x32_bf16 v[124:127], v[182:185], v[216:219], v[124:127]
	v_mfma_f32_16x16x32_bf16 v[116:119], v[190:193], v[216:219], v[116:119]
	v_mfma_f32_16x16x32_bf16 v[108:111], v[182:185], v[224:227], v[108:111]
	v_mfma_f32_16x16x32_bf16 v[100:103], v[190:193], v[224:227], v[100:103]
	v_mfma_f32_16x16x32_bf16 v[92:95], v[182:185], v[232:235], v[92:95]
	v_mfma_f32_16x16x32_bf16 v[84:87], v[190:193], v[232:235], v[84:87]
	v_mfma_f32_16x16x32_bf16 v[76:79], v[182:185], v[240:243], v[76:79]
	v_mfma_f32_16x16x32_bf16 v[68:71], v[190:193], v[240:243], v[68:71]
	v_mfma_f32_16x16x32_bf16 v[120:123], v[194:197], v[210:213], v[120:123]
	v_mfma_f32_16x16x32_bf16 v[112:115], v[202:205], v[210:213], v[112:115]
	v_mfma_f32_16x16x32_bf16 v[104:107], v[194:197], v[220:223], v[104:107]
	v_mfma_f32_16x16x32_bf16 v[96:99], v[202:205], v[220:223], v[96:99]
	v_mfma_f32_16x16x32_bf16 v[88:91], v[194:197], v[228:231], v[88:91]
	v_mfma_f32_16x16x32_bf16 v[80:83], v[202:205], v[228:231], v[80:83]
	v_mfma_f32_16x16x32_bf16 v[72:75], v[194:197], v[236:239], v[72:75]
	v_mfma_f32_16x16x32_bf16 v[64:67], v[202:205], v[236:239], v[64:67]
	v_mfma_f32_16x16x32_bf16 v[120:123], v[198:201], v[216:219], v[120:123]
	v_mfma_f32_16x16x32_bf16 v[112:115], v[206:209], v[216:219], v[112:115]
	v_mfma_f32_16x16x32_bf16 v[104:107], v[198:201], v[224:227], v[104:107]
	v_mfma_f32_16x16x32_bf16 v[96:99], v[206:209], v[224:227], v[96:99]
	v_mfma_f32_16x16x32_bf16 v[88:91], v[198:201], v[232:235], v[88:91]
	v_mfma_f32_16x16x32_bf16 v[80:83], v[206:209], v[232:235], v[80:83]
	v_mfma_f32_16x16x32_bf16 v[72:75], v[198:201], v[240:243], v[72:75]
	v_mfma_f32_16x16x32_bf16 v[64:67], v[206:209], v[240:243], v[64:67]
	s_setprio 1
	s_barrier
	s_add_i32 s11, s11, s29
	s_add_i32 m0, s11, 0xffffff80
	ds_read_b128 v[210:213], v179 offset:49152
	ds_read_b128 v[216:219], v179 offset:50176
	ds_read_b128 v[220:223], v179 offset:51200
	ds_read_b128 v[224:227], v179 offset:52224
	global_load_lds_dwordx4 v[246:247], off offset:128
	s_add_i32 m0, s11, 0x1f80
	s_add_i32 s11, s13, s29
	global_load_lds_dwordx4 v[248:249], off offset:128
	s_add_i32 m0, s11, 0xffffff80
	ds_read_b128 v[240:243], v179 offset:56320
	global_load_lds_dwordx4 v[250:251], off offset:128
	s_add_i32 m0, s11, 0x1f80
	ds_read_b128 v[236:239], v179 offset:55296
	global_load_lds_dwordx4 v[244:245], off offset:128
	s_add_i32 m0, s50, 0xffffff80
	ds_read_b128 v[232:235], v179 offset:54272
	global_load_lds_dwordx4 v[252:253], off offset:128
	s_add_i32 m0, s51, 0xffffff80
	ds_read_b128 v[228:231], v179 offset:53248
	global_load_lds_dwordx4 v[214:215], off offset:128
	s_waitcnt vmcnt(8) lgkmcnt(0)
	s_setprio 0
	s_barrier
	v_mfma_f32_16x16x32_bf16 v[60:63], v[162:165], v[210:213], v[60:63]
	v_mfma_f32_16x16x32_bf16 v[52:55], v[186:189], v[210:213], v[52:55]
	v_mfma_f32_16x16x32_bf16 v[44:47], v[162:165], v[220:223], v[44:47]
	v_mfma_f32_16x16x32_bf16 v[36:39], v[186:189], v[220:223], v[36:39]
	v_mfma_f32_16x16x32_bf16 v[28:31], v[162:165], v[228:231], v[28:31]
	v_mfma_f32_16x16x32_bf16 v[20:23], v[186:189], v[228:231], v[20:23]
	v_mfma_f32_16x16x32_bf16 v[12:15], v[162:165], v[236:239], v[12:15]
	v_mfma_f32_16x16x32_bf16 v[4:7], v[186:189], v[236:239], v[4:7]
	v_mfma_f32_16x16x32_bf16 v[60:63], v[182:185], v[216:219], v[60:63]
	v_mfma_f32_16x16x32_bf16 v[52:55], v[190:193], v[216:219], v[52:55]
	v_mfma_f32_16x16x32_bf16 v[44:47], v[182:185], v[224:227], v[44:47]
	v_mfma_f32_16x16x32_bf16 v[36:39], v[190:193], v[224:227], v[36:39]
	v_mfma_f32_16x16x32_bf16 v[28:31], v[182:185], v[232:235], v[28:31]
	v_mfma_f32_16x16x32_bf16 v[20:23], v[190:193], v[232:235], v[20:23]
	v_mfma_f32_16x16x32_bf16 v[12:15], v[182:185], v[240:243], v[12:15]
	v_mfma_f32_16x16x32_bf16 v[4:7], v[190:193], v[240:243], v[4:7]
	v_mfma_f32_16x16x32_bf16 v[56:59], v[194:197], v[210:213], v[56:59]
	v_mfma_f32_16x16x32_bf16 v[48:51], v[202:205], v[210:213], v[48:51]
	v_mfma_f32_16x16x32_bf16 v[40:43], v[194:197], v[220:223], v[40:43]
	v_mfma_f32_16x16x32_bf16 v[32:35], v[202:205], v[220:223], v[32:35]
	v_mfma_f32_16x16x32_bf16 v[24:27], v[194:197], v[228:231], v[24:27]
	v_mfma_f32_16x16x32_bf16 v[16:19], v[202:205], v[228:231], v[16:19]
	v_mfma_f32_16x16x32_bf16 v[8:11], v[194:197], v[236:239], v[8:11]
	v_mfma_f32_16x16x32_bf16 v[0:3], v[202:205], v[236:239], v[0:3]
	v_mfma_f32_16x16x32_bf16 v[56:59], v[198:201], v[216:219], v[56:59]
	v_mfma_f32_16x16x32_bf16 v[48:51], v[206:209], v[216:219], v[48:51]
	v_mfma_f32_16x16x32_bf16 v[40:43], v[198:201], v[224:227], v[40:43]
	v_mfma_f32_16x16x32_bf16 v[32:35], v[206:209], v[224:227], v[32:35]
	v_mfma_f32_16x16x32_bf16 v[24:27], v[198:201], v[232:235], v[24:27]
	v_mfma_f32_16x16x32_bf16 v[16:19], v[206:209], v[232:235], v[16:19]
	v_mfma_f32_16x16x32_bf16 v[8:11], v[198:201], v[240:243], v[8:11]
	v_mfma_f32_16x16x32_bf16 v[0:3], v[206:209], v[240:243], v[0:3]
	s_setprio 1
	s_barrier
	v_lshl_add_u64 v[158:159], v[158:159], 0, s[26:27]
	s_cmp_ge_i32 s10, s52
	v_lshl_add_u64 v[160:161], v[160:161], 0, s[26:27]
	s_cbranch_scc0 .LBB0_304
	s_setprio 0

; #define PG8_STAGE(bufoff, gbase, voff) do { _Pragma("unroll") for (int _i = 0; _i < 2; ++_i) \
;         __builtin_amdgcn_global_load_lds((const unsigned*)((const char*)(gbase) + (voff)[_i]), (PG8_LAS unsigned*)(lds + (bufoff) + ldsw + _i * 8192), 16, 0, 0); } while (0)
; #define PG8_LDA(dst, b, h) do { _Pragma("unroll") for (int m = 0; m < 4; ++m) _Pragma("unroll") for (int k = 0; k < 2; ++k) dst[m][k] = *(const PG8_LAS bf16x8*)(lds + PG8_SA(b, h) + aoff + m * 2048 + k * 1024); } while (0)
; #define PG8_LDB(dst, b, h) do { _Pragma("unroll") for (int n = 0; n < 2; ++n) _Pragma("unroll") for (int k = 0; k < 2; ++k) dst[n][k] = *(const PG8_LAS bf16x8*)(lds + PG8_SB(b, h) + boff + n * 2048 + k * 1024); } while (0)
; #define PG8_MMA(ai, bj, At, Bt) do { __builtin_amdgcn_s_setprio(1); _Pragma("unroll") for (int m = 0; m < 4; ++m) _Pragma("unroll") for (int n = 0; n < 2; ++n) _Pragma("unroll") for (int k = 0; k < 2; ++k) \
;         acc[ai][bj][m][n] = __builtin_amdgcn_mfma_f32_16x16x32_bf16(Bt[n][k], At[m][k], acc[ai][bj][m][n], 0, 0, 0); __builtin_amdgcn_s_setprio(0); } while (0)
; #define PG8_WAIT_V(n) asm volatile("s_waitcnt vmcnt(" #n ")" ::: "memory")
; #define PG8_WAIT_L(n) asm volatile("s_waitcnt lgkmcnt(" #n ")" ::: "memory")
; template <class Epi, class Sched, bool ALIGN_EPI = false, bool SP2 = false>
; __device__ __forceinline__ void gemm_phase(PG8_LAS unsigned char* lds, const Gemm g, const Sched& S, const Epi& E) {
;     ...
;             const bool last = (t == nt - 2);
;             const char* a1 = cA + (size_t)(t + 1) * kstep;
;             const char* a2 = last ? nA : cA + (size_t)(t + 2) * kstep; const char* b2 = last ? nB : cB + (size_t)(t + 2) * kstep;
;             const char* a3 = a2 + kstep; const char* b3 = b2 + kstep;
;             if (last && has_next) S.a_ready(nxt);
;             if constexpr (SP2) {
;             PG8_LDB(B0, 0, 0); PG8_LDB(B1, 0, 1); PG8_SCHED; PG8_LDA(At, 0, 0); PG8_STAGE(PG8_SA(1, 1), a1 + hstep, voffA);
;             PG8_WAIT_V(8); PG8_WAIT_L(0); PG8_BAR; PG8_MMA(0, 0, At, B0); PG8_MMA(0, 1, At, B1); PG8_BAR; PG8_SCHED;
;             PG8_LDA(At, 0, 1); PG8_STAGE(PG8_SB(0, 0), b2, voffB); PG8_STAGE(PG8_SB(0, 1), b2 + hstep, voffB); PG8_STAGE(PG8_SA(0, 0), a2, voffA);
;             PG8_WAIT_V(8); PG8_WAIT_L(0); PG8_BAR; PG8_MMA(1, 0, At, B0); PG8_MMA(1, 1, At, B1); PG8_BAR; PG8_SCHED;
.LBB0_371:
	v_add_u32_e32 v148, s54, v201
	v_add_u32_e32 v190, s55, v201
	ds_read_b128 v[136:139], v148
	ds_read_b128 v[140:143], v148 offset:1024
	ds_read_b128 v[144:147], v148 offset:2048
	ds_read_b128 v[148:151], v148 offset:3072
	ds_read_b128 v[152:155], v190
	ds_read_b128 v[182:185], v190 offset:1024
	ds_read_b128 v[186:189], v190 offset:2048
	ds_read_b128 v[190:193], v190 offset:3072
	s_cmp_eq_u32 s48, s12
	v_lshl_add_u64 v[194:195], v[134:135], 0, s[22:23]
	s_cselect_b64 vcc, -1, 0
	s_add_i32 s12, s12, 2
	v_cndmask_b32_e32 v199, v195, v179, vcc
	v_cndmask_b32_e32 v198, v194, v178, vcc
	v_cndmask_b32_e32 v215, v133, v181, vcc
	v_cndmask_b32_e32 v214, v132, v180, vcc
	s_mov_b32 m0, s56
	v_lshl_add_u64 v[236:237], v[134:135], 0, v[174:175]
	ds_read_b128 v[194:197], v203
	ds_read_b128 v[206:209], v203 offset:1024
	ds_read_b128 v[210:213], v203 offset:2048
	ds_read_b128 v[216:219], v203 offset:3072
	ds_read_b128 v[220:223], v203 offset:4096
	ds_read_b128 v[224:227], v203 offset:5120
	ds_read_b128 v[228:231], v203 offset:6144
	ds_read_b128 v[232:235], v203 offset:7168
	global_load_lds_dwordx4 v[236:237], off
	s_mov_b32 m0, s57
	v_lshl_add_u64 v[236:237], v[134:135], 0, v[172:173]
	global_load_lds_dwordx4 v[236:237], off
	s_waitcnt vmcnt(8) lgkmcnt(0)
	s_setprio 0
	s_barrier
	v_mfma_f32_16x16x32_bf16 v[124:127], v[136:139], v[194:197], v[124:127]
	v_mfma_f32_16x16x32_bf16 v[128:131], v[144:147], v[194:197], v[128:131]
	v_mfma_f32_16x16x32_bf16 v[112:115], v[136:139], v[210:213], v[112:115]
	v_mfma_f32_16x16x32_bf16 v[108:111], v[144:147], v[210:213], v[108:111]
	v_mfma_f32_16x16x32_bf16 v[96:99], v[136:139], v[220:223], v[96:99]
	v_mfma_f32_16x16x32_bf16 v[92:95], v[144:147], v[220:223], v[92:95]
	v_mfma_f32_16x16x32_bf16 v[80:83], v[136:139], v[228:231], v[80:83]
	v_mfma_f32_16x16x32_bf16 v[76:79], v[144:147], v[228:231], v[76:79]
	v_mfma_f32_16x16x32_bf16 v[124:127], v[140:143], v[206:209], v[124:127]
	v_mfma_f32_16x16x32_bf16 v[128:131], v[148:151], v[206:209], v[128:131]
	v_mfma_f32_16x16x32_bf16 v[112:115], v[140:143], v[216:219], v[112:115]
	v_mfma_f32_16x16x32_bf16 v[108:111], v[148:151], v[216:219], v[108:111]
	v_mfma_f32_16x16x32_bf16 v[96:99], v[140:143], v[224:227], v[96:99]
	v_mfma_f32_16x16x32_bf16 v[92:95], v[148:151], v[224:227], v[92:95]
	v_mfma_f32_16x16x32_bf16 v[80:83], v[140:143], v[232:235], v[80:83]
	v_mfma_f32_16x16x32_bf16 v[76:79], v[148:151], v[232:235], v[76:79]
	v_mfma_f32_16x16x32_bf16 v[120:123], v[152:155], v[194:197], v[120:123]
	v_mfma_f32_16x16x32_bf16 v[116:119], v[186:189], v[194:197], v[116:119]
	v_mfma_f32_16x16x32_bf16 v[104:107], v[152:155], v[210:213], v[104:107]
	v_mfma_f32_16x16x32_bf16 v[100:103], v[186:189], v[210:213], v[100:103]
	v_mfma_f32_16x16x32_bf16 v[88:91], v[152:155], v[220:223], v[88:91]
	v_mfma_f32_16x16x32_bf16 v[84:87], v[186:189], v[220:223], v[84:87]
	v_mfma_f32_16x16x32_bf16 v[72:75], v[152:155], v[228:231], v[72:75]
	v_mfma_f32_16x16x32_bf16 v[68:71], v[186:189], v[228:231], v[68:71]
	v_mfma_f32_16x16x32_bf16 v[120:123], v[182:185], v[206:209], v[120:123]
	v_mfma_f32_16x16x32_bf16 v[116:119], v[190:193], v[206:209], v[116:119]
	v_mfma_f32_16x16x32_bf16 v[104:107], v[182:185], v[216:219], v[104:107]
	v_mfma_f32_16x16x32_bf16 v[100:103], v[190:193], v[216:219], v[100:103]
	v_mfma_f32_16x16x32_bf16 v[88:91], v[182:185], v[224:227], v[88:91]
	v_mfma_f32_16x16x32_bf16 v[84:87], v[190:193], v[224:227], v[84:87]
	v_mfma_f32_16x16x32_bf16 v[72:75], v[182:185], v[232:235], v[72:75]
	v_mfma_f32_16x16x32_bf16 v[68:71], v[190:193], v[232:235], v[68:71]
	s_setprio 1
	s_barrier
	s_mov_b32 m0, s58
	v_lshl_add_u64 v[236:237], v[214:215], 0, v[166:167]
	ds_read_b128 v[194:197], v203 offset:16384
	ds_read_b128 v[206:209], v203 offset:17408
	ds_read_b128 v[210:213], v203 offset:18432
	ds_read_b128 v[216:219], v203 offset:19456
	ds_read_b128 v[220:223], v203 offset:20480
	ds_read_b128 v[224:227], v203 offset:21504
	ds_read_b128 v[228:231], v203 offset:22528
	ds_read_b128 v[232:235], v203 offset:23552
	global_load_lds_dwordx4 v[236:237], off
	v_lshl_add_u64 v[238:239], v[214:215], 0, v[170:171]
	s_mov_b32 m0, s59
	v_lshl_add_u64 v[214:215], v[214:215], 0, s[14:15]
	s_add_i32 s13, s55, s30
	global_load_lds_dwordx4 v[238:239], off
	v_lshl_add_u64 v[240:241], v[214:215], 0, v[166:167]
	s_mov_b32 m0, s13
	v_lshl_add_u64 v[214:215], v[214:215], 0, v[170:171]
	global_load_lds_dwordx4 v[240:241], off
	s_add_i32 m0, s13, 0x2000
	v_lshl_add_u64 v[242:243], v[198:199], 0, v[164:165]
	global_load_lds_dwordx4 v[214:215], off
	s_mov_b32 m0, s31
	v_lshl_add_u64 v[244:245], v[198:199], 0, v[168:169]
	global_load_lds_dwordx4 v[242:243], off
	s_mov_b32 m0, s34
	s_nop 0
	global_load_lds_dwordx4 v[244:245], off
	s_waitcnt vmcnt(8) lgkmcnt(0)
	s_setprio 0
	s_barrier
; #define PG8_STAGE(bufoff, gbase, voff) do { _Pragma("unroll") for (int _i = 0; _i < 2; ++_i) \
;         __builtin_amdgcn_global_load_lds((const unsigned*)((const char*)(gbase) + (voff)[_i]), (PG8_LAS unsigned*)(lds + (bufoff) + ldsw + _i * 8192), 16, 0, 0); } while (0)
; #define PG8_LDA(dst, b, h) do { _Pragma("unroll") for (int m = 0; m < 4; ++m) _Pragma("unroll") for (int k = 0; k < 2; ++k) dst[m][k] = *(const PG8_LAS bf16x8*)(lds + PG8_SA(b, h) + aoff + m * 2048 + k * 1024); } while (0)
; #define PG8_LDB(dst, b, h) do { _Pragma("unroll") for (int n = 0; n < 2; ++n) _Pragma("unroll") for (int k = 0; k < 2; ++k) dst[n][k] = *(const PG8_LAS bf16x8*)(lds + PG8_SB(b, h) + boff + n * 2048 + k * 1024); } while (0)
; #define PG8_MMA(ai, bj, At, Bt) do { __builtin_amdgcn_s_setprio(1); _Pragma("unroll") for (int m = 0; m < 4; ++m) _Pragma("unroll") for (int n = 0; n < 2; ++n) _Pragma("unroll") for (int k = 0; k < 2; ++k) \
;         acc[ai][bj][m][n] = __builtin_amdgcn_mfma_f32_16x16x32_bf16(Bt[n][k], At[m][k], acc[ai][bj][m][n], 0, 0, 0); __builtin_amdgcn_s_setprio(0); } while (0)
; #define PG8_WAIT_V(n) asm volatile("s_waitcnt vmcnt(" #n ")" ::: "memory")
; #define PG8_WAIT_L(n) asm volatile("s_waitcnt lgkmcnt(" #n ")" ::: "memory")
; #define PG8_BAR __builtin_amdgcn_s_barrier()
; #define PG8_SCHED __builtin_amdgcn_sched_barrier(0)
; template <class Epi, class Sched, bool ALIGN_EPI = false, bool SP2 = false>
; __device__ __forceinline__ void gemm_phase(PG8_LAS unsigned char* lds, const Gemm g, const Sched& S, const Epi& E) {
;     ...
;             PG8_WAIT_V(8); PG8_WAIT_L(0); PG8_BAR; PG8_MMA(1, 0, At, B0); PG8_MMA(1, 1, At, B1); PG8_BAR; PG8_SCHED;
;             PG8_LDB(B0, 1, 0); PG8_LDB(B1, 1, 1); PG8_SCHED; PG8_LDA(At, 1, 0); PG8_STAGE(PG8_SA(0, 1), a2 + hstep, voffA);
;             PG8_WAIT_V(8); PG8_WAIT_L(0); PG8_BAR; PG8_MMA(0, 0, At, B0); PG8_MMA(0, 1, At, B1); PG8_BAR; PG8_SCHED;
	v_mfma_f32_16x16x32_bf16 v[64:67], v[136:139], v[194:197], v[64:67]
	v_mfma_f32_16x16x32_bf16 v[60:63], v[144:147], v[194:197], v[60:63]
	v_mfma_f32_16x16x32_bf16 v[48:51], v[136:139], v[210:213], v[48:51]
	v_mfma_f32_16x16x32_bf16 v[44:47], v[144:147], v[210:213], v[44:47]
	v_mfma_f32_16x16x32_bf16 v[32:35], v[136:139], v[220:223], v[32:35]
	v_mfma_f32_16x16x32_bf16 v[28:31], v[144:147], v[220:223], v[28:31]
	v_mfma_f32_16x16x32_bf16 v[16:19], v[136:139], v[228:231], v[16:19]
	v_mfma_f32_16x16x32_bf16 v[12:15], v[144:147], v[228:231], v[12:15]
	v_mfma_f32_16x16x32_bf16 v[64:67], v[140:143], v[206:209], v[64:67]
	v_mfma_f32_16x16x32_bf16 v[60:63], v[148:151], v[206:209], v[60:63]
	v_mfma_f32_16x16x32_bf16 v[48:51], v[140:143], v[216:219], v[48:51]
	v_mfma_f32_16x16x32_bf16 v[44:47], v[148:151], v[216:219], v[44:47]
	v_mfma_f32_16x16x32_bf16 v[32:35], v[140:143], v[224:227], v[32:35]
	v_mfma_f32_16x16x32_bf16 v[28:31], v[148:151], v[224:227], v[28:31]
	v_mfma_f32_16x16x32_bf16 v[16:19], v[140:143], v[232:235], v[16:19]
	v_mfma_f32_16x16x32_bf16 v[12:15], v[148:151], v[232:235], v[12:15]
	v_mfma_f32_16x16x32_bf16 v[56:59], v[152:155], v[194:197], v[56:59]
	v_mfma_f32_16x16x32_bf16 v[52:55], v[186:189], v[194:197], v[52:55]
	v_mfma_f32_16x16x32_bf16 v[40:43], v[152:155], v[210:213], v[40:43]
	v_mfma_f32_16x16x32_bf16 v[36:39], v[186:189], v[210:213], v[36:39]
	v_mfma_f32_16x16x32_bf16 v[24:27], v[152:155], v[220:223], v[24:27]
	v_mfma_f32_16x16x32_bf16 v[20:23], v[186:189], v[220:223], v[20:23]
	v_mfma_f32_16x16x32_bf16 v[8:11], v[152:155], v[228:231], v[8:11]
	v_mfma_f32_16x16x32_bf16 v[4:7], v[186:189], v[228:231], v[4:7]
	v_mfma_f32_16x16x32_bf16 v[56:59], v[182:185], v[206:209], v[56:59]
	v_mfma_f32_16x16x32_bf16 v[52:55], v[190:193], v[206:209], v[52:55]
	v_mfma_f32_16x16x32_bf16 v[40:43], v[182:185], v[216:219], v[40:43]
	v_mfma_f32_16x16x32_bf16 v[36:39], v[190:193], v[216:219], v[36:39]
	v_mfma_f32_16x16x32_bf16 v[24:27], v[182:185], v[224:227], v[24:27]
	v_mfma_f32_16x16x32_bf16 v[20:23], v[190:193], v[224:227], v[20:23]
	v_mfma_f32_16x16x32_bf16 v[8:11], v[182:185], v[232:235], v[8:11]
	v_mfma_f32_16x16x32_bf16 v[4:7], v[190:193], v[232:235], v[4:7]
	s_setprio 1
	s_barrier
	s_add_i32 s13, 0, 0x18000
	s_add_i32 s29, 0, 0x1c000
	v_add_u32_e32 v148, s13, v201
	v_add_u32_e32 v190, s29, v201
	ds_read_b128 v[136:139], v148
	ds_read_b128 v[140:143], v148 offset:1024
	ds_read_b128 v[144:147], v148 offset:2048
	ds_read_b128 v[148:151], v148 offset:3072
	ds_read_b128 v[152:155], v190
	ds_read_b128 v[182:185], v190 offset:1024
	ds_read_b128 v[186:189], v190 offset:2048
	ds_read_b128 v[190:193], v190 offset:3072
	v_lshl_add_u64 v[198:199], v[198:199], 0, s[14:15]
	s_mov_b32 m0, s35
	v_lshl_add_u64 v[246:247], v[198:199], 0, v[164:165]
	ds_read_b128 v[194:197], v203 offset:32768
	ds_read_b128 v[206:209], v203 offset:33792
	ds_read_b128 v[210:213], v203 offset:34816
	ds_read_b128 v[216:219], v203 offset:35840
	ds_read_b128 v[220:223], v203 offset:36864
	ds_read_b128 v[224:227], v203 offset:37888
	ds_read_b128 v[228:231], v203 offset:38912
	ds_read_b128 v[232:235], v203 offset:39936
	global_load_lds_dwordx4 v[246:247], off
	s_mov_b32 m0, s36
	v_lshl_add_u64 v[198:199], v[198:199], 0, v[168:169]
	global_load_lds_dwordx4 v[198:199], off
	s_waitcnt vmcnt(8) lgkmcnt(0)
	s_setprio 0
	s_barrier
; #define PG8_STAGE(bufoff, gbase, voff) do { _Pragma("unroll") for (int _i = 0; _i < 2; ++_i) \
;         __builtin_amdgcn_global_load_lds((const unsigned*)((const char*)(gbase) + (voff)[_i]), (PG8_LAS unsigned*)(lds + (bufoff) + ldsw + _i * 8192), 16, 0, 0); } while (0)
; #define PG8_LDA(dst, b, h) do { _Pragma("unroll") for (int m = 0; m < 4; ++m) _Pragma("unroll") for (int k = 0; k < 2; ++k) dst[m][k] = *(const PG8_LAS bf16x8*)(lds + PG8_SA(b, h) + aoff + m * 2048 + k * 1024); } while (0)
; #define PG8_MMA(ai, bj, At, Bt) do { __builtin_amdgcn_s_setprio(1); _Pragma("unroll") for (int m = 0; m < 4; ++m) _Pragma("unroll") for (int n = 0; n < 2; ++n) _Pragma("unroll") for (int k = 0; k < 2; ++k) \
;         acc[ai][bj][m][n] = __builtin_amdgcn_mfma_f32_16x16x32_bf16(Bt[n][k], At[m][k], acc[ai][bj][m][n], 0, 0, 0); __builtin_amdgcn_s_setprio(0); } while (0)
; #define PG8_WAIT_V(n) asm volatile("s_waitcnt vmcnt(" #n ")" ::: "memory")
; #define PG8_WAIT_L(n) asm volatile("s_waitcnt lgkmcnt(" #n ")" ::: "memory")
; #define PG8_BAR __builtin_amdgcn_s_barrier()
; #define PG8_SCHED __builtin_amdgcn_sched_barrier(0)
; template <class Epi, class Sched, bool ALIGN_EPI = false, bool SP2 = false>
; __device__ __forceinline__ void gemm_phase(PG8_LAS unsigned char* lds, const Gemm g, const Sched& S, const Epi& E) {
;     ...
;             PG8_WAIT_V(8); PG8_WAIT_L(0); PG8_BAR; PG8_MMA(0, 0, At, B0); PG8_MMA(0, 1, At, B1); PG8_BAR; PG8_SCHED;
;             PG8_LDA(At, 1, 1); PG8_STAGE(PG8_SB(1, 0), b3, voffB); PG8_STAGE(PG8_SB(1, 1), b3 + hstep, voffB); PG8_STAGE(PG8_SA(1, 0), a3, voffA);
;             PG8_WAIT_V(8); PG8_WAIT_L(0); PG8_BAR; PG8_MMA(1, 0, At, B0); PG8_MMA(1, 1, At, B1); PG8_BAR; PG8_SCHED;
	v_mfma_f32_16x16x32_bf16 v[124:127], v[136:139], v[194:197], v[124:127]
	v_mfma_f32_16x16x32_bf16 v[128:131], v[144:147], v[194:197], v[128:131]
	v_mfma_f32_16x16x32_bf16 v[112:115], v[136:139], v[210:213], v[112:115]
	v_mfma_f32_16x16x32_bf16 v[108:111], v[144:147], v[210:213], v[108:111]
	v_mfma_f32_16x16x32_bf16 v[96:99], v[136:139], v[220:223], v[96:99]
	v_mfma_f32_16x16x32_bf16 v[92:95], v[144:147], v[220:223], v[92:95]
	v_mfma_f32_16x16x32_bf16 v[80:83], v[136:139], v[228:231], v[80:83]
	v_mfma_f32_16x16x32_bf16 v[76:79], v[144:147], v[228:231], v[76:79]
	v_mfma_f32_16x16x32_bf16 v[124:127], v[140:143], v[206:209], v[124:127]
	v_mfma_f32_16x16x32_bf16 v[128:131], v[148:151], v[206:209], v[128:131]
	v_mfma_f32_16x16x32_bf16 v[112:115], v[140:143], v[216:219], v[112:115]
	v_mfma_f32_16x16x32_bf16 v[108:111], v[148:151], v[216:219], v[108:111]
	v_mfma_f32_16x16x32_bf16 v[96:99], v[140:143], v[224:227], v[96:99]
	v_mfma_f32_16x16x32_bf16 v[92:95], v[148:151], v[224:227], v[92:95]
	v_mfma_f32_16x16x32_bf16 v[80:83], v[140:143], v[232:235], v[80:83]
	v_mfma_f32_16x16x32_bf16 v[76:79], v[148:151], v[232:235], v[76:79]
	v_mfma_f32_16x16x32_bf16 v[120:123], v[152:155], v[194:197], v[120:123]
	v_mfma_f32_16x16x32_bf16 v[116:119], v[186:189], v[194:197], v[116:119]
	v_mfma_f32_16x16x32_bf16 v[104:107], v[152:155], v[210:213], v[104:107]
	v_mfma_f32_16x16x32_bf16 v[100:103], v[186:189], v[210:213], v[100:103]
	v_mfma_f32_16x16x32_bf16 v[88:91], v[152:155], v[220:223], v[88:91]
	v_mfma_f32_16x16x32_bf16 v[84:87], v[186:189], v[220:223], v[84:87]
	v_mfma_f32_16x16x32_bf16 v[72:75], v[152:155], v[228:231], v[72:75]
	v_mfma_f32_16x16x32_bf16 v[68:71], v[186:189], v[228:231], v[68:71]
	v_mfma_f32_16x16x32_bf16 v[120:123], v[182:185], v[206:209], v[120:123]
	v_mfma_f32_16x16x32_bf16 v[116:119], v[190:193], v[206:209], v[116:119]
	v_mfma_f32_16x16x32_bf16 v[104:107], v[182:185], v[216:219], v[104:107]
	v_mfma_f32_16x16x32_bf16 v[100:103], v[190:193], v[216:219], v[100:103]
	v_mfma_f32_16x16x32_bf16 v[88:91], v[182:185], v[224:227], v[88:91]
	v_mfma_f32_16x16x32_bf16 v[84:87], v[190:193], v[224:227], v[84:87]
	v_mfma_f32_16x16x32_bf16 v[72:75], v[182:185], v[232:235], v[72:75]
	v_mfma_f32_16x16x32_bf16 v[68:71], v[190:193], v[232:235], v[68:71]
	s_setprio 1
	s_barrier
	s_add_i32 s13, s13, s30
	s_add_i32 m0, s13, 0xffffff80
	ds_read_b128 v[194:197], v203 offset:49152
	ds_read_b128 v[206:209], v203 offset:50176
	ds_read_b128 v[210:213], v203 offset:51200
	ds_read_b128 v[216:219], v203 offset:52224
	global_load_lds_dwordx4 v[236:237], off offset:128
	s_add_i32 m0, s13, 0x1f80
	s_add_i32 s13, s29, s30
	global_load_lds_dwordx4 v[238:239], off offset:128
	s_add_i32 m0, s13, 0xffffff80
	ds_read_b128 v[232:235], v203 offset:56320
	global_load_lds_dwordx4 v[240:241], off offset:128
	s_add_i32 m0, s13, 0x1f80
	ds_read_b128 v[228:231], v203 offset:55296
	global_load_lds_dwordx4 v[214:215], off offset:128
	s_add_i32 m0, s37, 0xffffff80
	ds_read_b128 v[224:227], v203 offset:54272
	global_load_lds_dwordx4 v[242:243], off offset:128
	s_add_i32 m0, s41, 0xffffff80
	ds_read_b128 v[220:223], v203 offset:53248
	global_load_lds_dwordx4 v[244:245], off offset:128
	s_waitcnt vmcnt(8) lgkmcnt(0)
	s_setprio 0
	s_barrier
	v_mfma_f32_16x16x32_bf16 v[64:67], v[136:139], v[194:197], v[64:67]
	v_mfma_f32_16x16x32_bf16 v[60:63], v[144:147], v[194:197], v[60:63]
	v_mfma_f32_16x16x32_bf16 v[48:51], v[136:139], v[210:213], v[48:51]
	v_mfma_f32_16x16x32_bf16 v[44:47], v[144:147], v[210:213], v[44:47]
	v_mfma_f32_16x16x32_bf16 v[32:35], v[136:139], v[220:223], v[32:35]
	v_mfma_f32_16x16x32_bf16 v[28:31], v[144:147], v[220:223], v[28:31]
	v_mfma_f32_16x16x32_bf16 v[16:19], v[136:139], v[228:231], v[16:19]
	v_mfma_f32_16x16x32_bf16 v[12:15], v[144:147], v[228:231], v[12:15]
	v_mfma_f32_16x16x32_bf16 v[64:67], v[140:143], v[206:209], v[64:67]
	v_mfma_f32_16x16x32_bf16 v[60:63], v[148:151], v[206:209], v[60:63]
	v_mfma_f32_16x16x32_bf16 v[48:51], v[140:143], v[216:219], v[48:51]
	v_mfma_f32_16x16x32_bf16 v[44:47], v[148:151], v[216:219], v[44:47]
	v_mfma_f32_16x16x32_bf16 v[32:35], v[140:143], v[224:227], v[32:35]
	v_mfma_f32_16x16x32_bf16 v[28:31], v[148:151], v[224:227], v[28:31]
	v_mfma_f32_16x16x32_bf16 v[16:19], v[140:143], v[232:235], v[16:19]
	v_mfma_f32_16x16x32_bf16 v[12:15], v[148:151], v[232:235], v[12:15]
	v_mfma_f32_16x16x32_bf16 v[56:59], v[152:155], v[194:197], v[56:59]
	v_mfma_f32_16x16x32_bf16 v[52:55], v[186:189], v[194:197], v[52:55]
	v_mfma_f32_16x16x32_bf16 v[40:43], v[152:155], v[210:213], v[40:43]
	v_mfma_f32_16x16x32_bf16 v[36:39], v[186:189], v[210:213], v[36:39]
	v_mfma_f32_16x16x32_bf16 v[24:27], v[152:155], v[220:223], v[24:27]
	v_mfma_f32_16x16x32_bf16 v[20:23], v[186:189], v[220:223], v[20:23]
	v_mfma_f32_16x16x32_bf16 v[8:11], v[152:155], v[228:231], v[8:11]
	v_mfma_f32_16x16x32_bf16 v[4:7], v[186:189], v[228:231], v[4:7]
	v_mfma_f32_16x16x32_bf16 v[56:59], v[182:185], v[206:209], v[56:59]
	v_mfma_f32_16x16x32_bf16 v[52:55], v[190:193], v[206:209], v[52:55]
	v_mfma_f32_16x16x32_bf16 v[40:43], v[182:185], v[216:219], v[40:43]
	v_mfma_f32_16x16x32_bf16 v[36:39], v[190:193], v[216:219], v[36:39]
	v_mfma_f32_16x16x32_bf16 v[24:27], v[182:185], v[224:227], v[24:27]
	v_mfma_f32_16x16x32_bf16 v[20:23], v[190:193], v[224:227], v[20:23]
	v_mfma_f32_16x16x32_bf16 v[8:11], v[182:185], v[232:235], v[8:11]
	v_mfma_f32_16x16x32_bf16 v[4:7], v[190:193], v[232:235], v[4:7]
	s_setprio 1
	s_barrier
	v_lshl_add_u64 v[132:133], v[132:133], 0, s[26:27]
	s_cmp_ge_i32 s12, s47
	v_lshl_add_u64 v[134:135], v[134:135], 0, s[26:27]
	s_cbranch_scc0 .LBB0_371
	s_setprio 0

; #define PG8_STAGE(bufoff, gbase, voff) do { _Pragma("unroll") for (int _i = 0; _i < 2; ++_i) \
;         __builtin_amdgcn_global_load_lds((const unsigned*)((const char*)(gbase) + (voff)[_i]), (PG8_LAS unsigned*)(lds + (bufoff) + ldsw + _i * 8192), 16, 0, 0); } while (0)
; #define PG8_LDA(dst, b, h) do { _Pragma("unroll") for (int m = 0; m < 4; ++m) _Pragma("unroll") for (int k = 0; k < 2; ++k) dst[m][k] = *(const PG8_LAS bf16x8*)(lds + PG8_SA(b, h) + aoff + m * 2048 + k * 1024); } while (0)
; #define PG8_LDB(dst, b, h) do { _Pragma("unroll") for (int n = 0; n < 2; ++n) _Pragma("unroll") for (int k = 0; k < 2; ++k) dst[n][k] = *(const PG8_LAS bf16x8*)(lds + PG8_SB(b, h) + boff + n * 2048 + k * 1024); } while (0)
; #define PG8_MMA(ai, bj, At, Bt) do { __builtin_amdgcn_s_setprio(1); _Pragma("unroll") for (int m = 0; m < 4; ++m) _Pragma("unroll") for (int n = 0; n < 2; ++n) _Pragma("unroll") for (int k = 0; k < 2; ++k) \
;         acc[ai][bj][m][n] = __builtin_amdgcn_mfma_f32_16x16x32_bf16(Bt[n][k], At[m][k], acc[ai][bj][m][n], 0, 0, 0); __builtin_amdgcn_s_setprio(0); } while (0)
; #define PG8_BAR __builtin_amdgcn_s_barrier()
; template <class Epi, class Sched, bool ALIGN_EPI = false, bool SP2 = false>
; __device__ __forceinline__ void gemm_phase(PG8_LAS unsigned char* lds, const Gemm g, const Sched& S, const Epi& E) {
;     ...
;             const bool last = (t == nt - 2);
;             const char* a1 = cA + (size_t)(t + 1) * kstep;
;             const char* a2 = last ? nA : cA + (size_t)(t + 2) * kstep; const char* b2 = last ? nB : cB + (size_t)(t + 2) * kstep;
;             const char* a3 = a2 + kstep; const char* b3 = b2 + kstep;
;             if (last && has_next) S.a_ready(nxt);
;             if constexpr (SP2) {
;             PG8_LDB(B0, 0, 0); PG8_LDB(B1, 0, 1); PG8_SCHED; PG8_LDA(At, 0, 0); PG8_STAGE(PG8_SA(1, 1), a1 + hstep, voffA);
;             PG8_WAIT_V(8); PG8_WAIT_L(0); PG8_BAR; PG8_MMA(0, 0, At, B0); PG8_MMA(0, 1, At, B1); PG8_BAR; PG8_SCHED;
;             PG8_LDA(At, 0, 1); PG8_STAGE(PG8_SB(0, 0), b2, voffB); PG8_STAGE(PG8_SB(0, 1), b2 + hstep, voffB); PG8_STAGE(PG8_SA(0, 0), a2, voffA);
;             PG8_WAIT_V(8); PG8_WAIT_L(0); PG8_BAR; PG8_MMA(1, 0, At, B0); PG8_MMA(1, 1, At, B1); PG8_BAR; PG8_SCHED;
;             PG8_LDB(B0, 1, 0); PG8_LDB(B1, 1, 1); PG8_SCHED; PG8_LDA(At, 1, 0); PG8_STAGE(PG8_SA(0, 1), a2 + hstep, voffA);
.LBB0_454:
	v_add_u32_e32 v165, s69, v171
	v_add_u32_e32 v167, s70, v171
	ds_read_b128 v[132:135], v165
	ds_read_b128 v[136:139], v165 offset:1024
	ds_read_b128 v[176:179], v165 offset:2048
	ds_read_b128 v[180:183], v165 offset:3072
	ds_read_b128 v[184:187], v167
	ds_read_b128 v[188:191], v167 offset:1024
	ds_read_b128 v[192:195], v167 offset:2048
	ds_read_b128 v[196:199], v167 offset:3072
	s_cmp_eq_u32 s62, s12
	v_lshl_add_u64 v[200:201], v[130:131], 0, s[24:25]
	s_cselect_b64 vcc, -1, 0
	s_add_i32 s12, s12, 2
	v_cndmask_b32_e32 v209, v201, v173, vcc
	v_cndmask_b32_e32 v208, v200, v172, vcc
	v_cndmask_b32_e32 v213, v129, v175, vcc
	v_cndmask_b32_e32 v212, v128, v174, vcc
	v_lshl_add_u64 v[214:215], v[130:131], 0, v[160:161]
	s_add_i32 m0, s41, 0xc000
	ds_read_b128 v[200:203], v216
	ds_read_b128 v[204:207], v216 offset:1024
	ds_read_b128 v[218:221], v216 offset:2048
	ds_read_b128 v[222:225], v216 offset:3072
	ds_read_b128 v[226:229], v216 offset:4096
	ds_read_b128 v[230:233], v216 offset:5120
	ds_read_b128 v[234:237], v216 offset:6144
	ds_read_b128 v[238:241], v216 offset:7168
	global_load_lds_dwordx4 v[214:215], off
	s_add_i32 m0, s41, 0xe000
	v_lshl_add_u64 v[214:215], v[130:131], 0, v[158:159]
	global_load_lds_dwordx4 v[214:215], off
	s_waitcnt vmcnt(8) lgkmcnt(0)
	s_setprio 0
	s_barrier
	v_mfma_f32_16x16x32_bf16 v[124:127], v[132:135], v[200:203], v[124:127]
	v_mfma_f32_16x16x32_bf16 v[120:123], v[176:179], v[200:203], v[120:123]
	v_mfma_f32_16x16x32_bf16 v[108:111], v[132:135], v[218:221], v[108:111]
	v_mfma_f32_16x16x32_bf16 v[104:107], v[176:179], v[218:221], v[104:107]
	v_mfma_f32_16x16x32_bf16 v[92:95], v[132:135], v[226:229], v[92:95]
	v_mfma_f32_16x16x32_bf16 v[88:91], v[176:179], v[226:229], v[88:91]
	v_mfma_f32_16x16x32_bf16 v[76:79], v[132:135], v[234:237], v[76:79]
	v_mfma_f32_16x16x32_bf16 v[72:75], v[176:179], v[234:237], v[72:75]
	v_mfma_f32_16x16x32_bf16 v[124:127], v[136:139], v[204:207], v[124:127]
	v_mfma_f32_16x16x32_bf16 v[120:123], v[180:183], v[204:207], v[120:123]
	v_mfma_f32_16x16x32_bf16 v[108:111], v[136:139], v[222:225], v[108:111]
	v_mfma_f32_16x16x32_bf16 v[104:107], v[180:183], v[222:225], v[104:107]
	v_mfma_f32_16x16x32_bf16 v[92:95], v[136:139], v[230:233], v[92:95]
	v_mfma_f32_16x16x32_bf16 v[88:91], v[180:183], v[230:233], v[88:91]
	v_mfma_f32_16x16x32_bf16 v[76:79], v[136:139], v[238:241], v[76:79]
	v_mfma_f32_16x16x32_bf16 v[72:75], v[180:183], v[238:241], v[72:75]
	s_cmp_gt_u32 s75, 3
	s_cbranch_scc1 .Lie_skipk0
	v_mfma_f32_16x16x32_bf16 v[116:119], v[184:187], v[200:203], v[116:119]
	v_mfma_f32_16x16x32_bf16 v[112:115], v[192:195], v[200:203], v[112:115]
	v_mfma_f32_16x16x32_bf16 v[100:103], v[184:187], v[218:221], v[100:103]
	v_mfma_f32_16x16x32_bf16 v[96:99], v[192:195], v[218:221], v[96:99]
	v_mfma_f32_16x16x32_bf16 v[84:87], v[184:187], v[226:229], v[84:87]
	v_mfma_f32_16x16x32_bf16 v[80:83], v[192:195], v[226:229], v[80:83]
	v_mfma_f32_16x16x32_bf16 v[68:71], v[184:187], v[234:237], v[68:71]
	v_mfma_f32_16x16x32_bf16 v[64:67], v[192:195], v[234:237], v[64:67]
	v_mfma_f32_16x16x32_bf16 v[116:119], v[188:191], v[204:207], v[116:119]
	v_mfma_f32_16x16x32_bf16 v[112:115], v[196:199], v[204:207], v[112:115]
	v_mfma_f32_16x16x32_bf16 v[100:103], v[188:191], v[222:225], v[100:103]
	v_mfma_f32_16x16x32_bf16 v[96:99], v[196:199], v[222:225], v[96:99]
	v_mfma_f32_16x16x32_bf16 v[84:87], v[188:191], v[230:233], v[84:87]
	v_mfma_f32_16x16x32_bf16 v[80:83], v[196:199], v[230:233], v[80:83]
	v_mfma_f32_16x16x32_bf16 v[68:71], v[188:191], v[238:241], v[68:71]
	v_mfma_f32_16x16x32_bf16 v[64:67], v[196:199], v[238:241], v[64:67]
.Lie_skipk0:
	s_setprio 1
	s_barrier
	s_add_i32 s13, s69, s37
	v_lshl_add_u64 v[214:215], v[212:213], 0, v[146:147]
	s_mov_b32 m0, s13
	ds_read_b128 v[200:203], v216 offset:16384
	ds_read_b128 v[204:207], v216 offset:17408
	ds_read_b128 v[218:221], v216 offset:18432
	ds_read_b128 v[222:225], v216 offset:19456
	ds_read_b128 v[226:229], v216 offset:20480
	ds_read_b128 v[230:233], v216 offset:21504
	ds_read_b128 v[234:237], v216 offset:22528
	ds_read_b128 v[238:241], v216 offset:23552
	global_load_lds_dwordx4 v[214:215], off
	v_lshl_add_u64 v[242:243], v[212:213], 0, v[150:151]
	s_add_i32 m0, s13, 0x2000
	v_lshl_add_u64 v[212:213], v[212:213], 0, s[16:17]
	s_add_i32 s13, s70, s37
	global_load_lds_dwordx4 v[242:243], off
	v_lshl_add_u64 v[244:245], v[212:213], 0, v[146:147]
	s_mov_b32 m0, s13
	v_lshl_add_u64 v[212:213], v[212:213], 0, v[150:151]
	global_load_lds_dwordx4 v[244:245], off
	s_add_i32 m0, s13, 0x2000
	v_lshl_add_u64 v[246:247], v[208:209], 0, v[144:145]
	global_load_lds_dwordx4 v[212:213], off
	s_mov_b32 m0, s41
	v_lshl_add_u64 v[248:249], v[208:209], 0, v[148:149]
	global_load_lds_dwordx4 v[246:247], off
	s_mov_b32 m0, s50
	s_nop 0
	global_load_lds_dwordx4 v[248:249], off
	s_waitcnt vmcnt(8) lgkmcnt(0)
	s_setprio 0
	s_barrier
	v_mfma_f32_16x16x32_bf16 v[60:63], v[132:135], v[200:203], v[60:63]
	v_mfma_f32_16x16x32_bf16 v[56:59], v[176:179], v[200:203], v[56:59]
	v_mfma_f32_16x16x32_bf16 v[44:47], v[132:135], v[218:221], v[44:47]
	v_mfma_f32_16x16x32_bf16 v[40:43], v[176:179], v[218:221], v[40:43]
	v_mfma_f32_16x16x32_bf16 v[28:31], v[132:135], v[226:229], v[28:31]
	v_mfma_f32_16x16x32_bf16 v[24:27], v[176:179], v[226:229], v[24:27]
	v_mfma_f32_16x16x32_bf16 v[12:15], v[132:135], v[234:237], v[12:15]
	v_mfma_f32_16x16x32_bf16 v[8:11], v[176:179], v[234:237], v[8:11]
	v_mfma_f32_16x16x32_bf16 v[60:63], v[136:139], v[204:207], v[60:63]
	v_mfma_f32_16x16x32_bf16 v[56:59], v[180:183], v[204:207], v[56:59]
	v_mfma_f32_16x16x32_bf16 v[44:47], v[136:139], v[222:225], v[44:47]
	v_mfma_f32_16x16x32_bf16 v[40:43], v[180:183], v[222:225], v[40:43]
	v_mfma_f32_16x16x32_bf16 v[28:31], v[136:139], v[230:233], v[28:31]
	v_mfma_f32_16x16x32_bf16 v[24:27], v[180:183], v[230:233], v[24:27]
	v_mfma_f32_16x16x32_bf16 v[12:15], v[136:139], v[238:241], v[12:15]
	v_mfma_f32_16x16x32_bf16 v[8:11], v[180:183], v[238:241], v[8:11]
	s_cmp_gt_u32 s75, 3
	s_cbranch_scc1 .Lie_skipk1
; #define PG8_STAGE(bufoff, gbase, voff) do { _Pragma("unroll") for (int _i = 0; _i < 2; ++_i) \
;         __builtin_amdgcn_global_load_lds((const unsigned*)((const char*)(gbase) + (voff)[_i]), (PG8_LAS unsigned*)(lds + (bufoff) + ldsw + _i * 8192), 16, 0, 0); } while (0)
; #define PG8_LDA(dst, b, h) do { _Pragma("unroll") for (int m = 0; m < 4; ++m) _Pragma("unroll") for (int k = 0; k < 2; ++k) dst[m][k] = *(const PG8_LAS bf16x8*)(lds + PG8_SA(b, h) + aoff + m * 2048 + k * 1024); } while (0)
; #define PG8_LDB(dst, b, h) do { _Pragma("unroll") for (int n = 0; n < 2; ++n) _Pragma("unroll") for (int k = 0; k < 2; ++k) dst[n][k] = *(const PG8_LAS bf16x8*)(lds + PG8_SB(b, h) + boff + n * 2048 + k * 1024); } while (0)
; #define PG8_MMA(ai, bj, At, Bt) do { __builtin_amdgcn_s_setprio(1); _Pragma("unroll") for (int m = 0; m < 4; ++m) _Pragma("unroll") for (int n = 0; n < 2; ++n) _Pragma("unroll") for (int k = 0; k < 2; ++k) \
;         acc[ai][bj][m][n] = __builtin_amdgcn_mfma_f32_16x16x32_bf16(Bt[n][k], At[m][k], acc[ai][bj][m][n], 0, 0, 0); __builtin_amdgcn_s_setprio(0); } while (0)
; #define PG8_WAIT_V(n) asm volatile("s_waitcnt vmcnt(" #n ")" ::: "memory")
; #define PG8_WAIT_L(n) asm volatile("s_waitcnt lgkmcnt(" #n ")" ::: "memory")
; #define PG8_BAR __builtin_amdgcn_s_barrier()
; #define PG8_SCHED __builtin_amdgcn_sched_barrier(0)
; template <class Epi, class Sched, bool ALIGN_EPI = false, bool SP2 = false>
; __device__ __forceinline__ void gemm_phase(PG8_LAS unsigned char* lds, const Gemm g, const Sched& S, const Epi& E) {
;     ...
;             PG8_LDB(B0, 1, 0); PG8_LDB(B1, 1, 1); PG8_SCHED; PG8_LDA(At, 1, 0); PG8_STAGE(PG8_SA(0, 1), a2 + hstep, voffA);
;             PG8_WAIT_V(8); PG8_WAIT_L(0); PG8_BAR; PG8_MMA(0, 0, At, B0); PG8_MMA(0, 1, At, B1); PG8_BAR; PG8_SCHED;
;             PG8_LDA(At, 1, 1); PG8_STAGE(PG8_SB(1, 0), b3, voffB); PG8_STAGE(PG8_SB(1, 1), b3 + hstep, voffB); PG8_STAGE(PG8_SA(1, 0), a3, voffA);
	v_mfma_f32_16x16x32_bf16 v[52:55], v[184:187], v[200:203], v[52:55]
	v_mfma_f32_16x16x32_bf16 v[48:51], v[192:195], v[200:203], v[48:51]
	v_mfma_f32_16x16x32_bf16 v[36:39], v[184:187], v[218:221], v[36:39]
	v_mfma_f32_16x16x32_bf16 v[32:35], v[192:195], v[218:221], v[32:35]
	v_mfma_f32_16x16x32_bf16 v[20:23], v[184:187], v[226:229], v[20:23]
	v_mfma_f32_16x16x32_bf16 v[16:19], v[192:195], v[226:229], v[16:19]
	v_mfma_f32_16x16x32_bf16 v[4:7], v[184:187], v[234:237], v[4:7]
	v_mfma_f32_16x16x32_bf16 v[0:3], v[192:195], v[234:237], v[0:3]
	v_mfma_f32_16x16x32_bf16 v[52:55], v[188:191], v[204:207], v[52:55]
	v_mfma_f32_16x16x32_bf16 v[48:51], v[196:199], v[204:207], v[48:51]
	v_mfma_f32_16x16x32_bf16 v[36:39], v[188:191], v[222:225], v[36:39]
	v_mfma_f32_16x16x32_bf16 v[32:35], v[196:199], v[222:225], v[32:35]
	v_mfma_f32_16x16x32_bf16 v[20:23], v[188:191], v[230:233], v[20:23]
	v_mfma_f32_16x16x32_bf16 v[16:19], v[196:199], v[230:233], v[16:19]
	v_mfma_f32_16x16x32_bf16 v[4:7], v[188:191], v[238:241], v[4:7]
	v_mfma_f32_16x16x32_bf16 v[0:3], v[196:199], v[238:241], v[0:3]
.Lie_skipk1:
	s_setprio 1
	s_barrier
	s_add_i32 s13, 0, 0x18000
	v_add_u32_e32 v165, s13, v171
	s_add_i32 s15, 0, 0x1c000
	ds_read_b128 v[132:135], v165
	ds_read_b128 v[136:139], v165 offset:1024
	ds_read_b128 v[176:179], v165 offset:2048
	ds_read_b128 v[180:183], v165 offset:3072
	v_add_u32_e32 v165, s15, v171
	ds_read_b128 v[184:187], v165
	ds_read_b128 v[188:191], v165 offset:1024
	ds_read_b128 v[192:195], v165 offset:2048
	ds_read_b128 v[196:199], v165 offset:3072
	v_lshl_add_u64 v[208:209], v[208:209], 0, s[16:17]
	s_mov_b32 m0, s52
	v_lshl_add_u64 v[250:251], v[208:209], 0, v[144:145]
	ds_read_b128 v[200:203], v216 offset:32768
	ds_read_b128 v[204:207], v216 offset:33792
	ds_read_b128 v[218:221], v216 offset:34816
	ds_read_b128 v[222:225], v216 offset:35840
	ds_read_b128 v[226:229], v216 offset:36864
	ds_read_b128 v[230:233], v216 offset:37888
	ds_read_b128 v[234:237], v216 offset:38912
	ds_read_b128 v[238:241], v216 offset:39936
	global_load_lds_dwordx4 v[250:251], off
	s_mov_b32 m0, s53
	v_lshl_add_u64 v[208:209], v[208:209], 0, v[148:149]
	global_load_lds_dwordx4 v[208:209], off
	s_waitcnt vmcnt(8) lgkmcnt(0)
	s_setprio 0
	s_barrier
	v_mfma_f32_16x16x32_bf16 v[124:127], v[132:135], v[200:203], v[124:127]
	v_mfma_f32_16x16x32_bf16 v[120:123], v[176:179], v[200:203], v[120:123]
	v_mfma_f32_16x16x32_bf16 v[108:111], v[132:135], v[218:221], v[108:111]
	v_mfma_f32_16x16x32_bf16 v[104:107], v[176:179], v[218:221], v[104:107]
	v_mfma_f32_16x16x32_bf16 v[92:95], v[132:135], v[226:229], v[92:95]
	v_mfma_f32_16x16x32_bf16 v[88:91], v[176:179], v[226:229], v[88:91]
	v_mfma_f32_16x16x32_bf16 v[76:79], v[132:135], v[234:237], v[76:79]
	v_mfma_f32_16x16x32_bf16 v[72:75], v[176:179], v[234:237], v[72:75]
	v_mfma_f32_16x16x32_bf16 v[124:127], v[136:139], v[204:207], v[124:127]
	v_mfma_f32_16x16x32_bf16 v[120:123], v[180:183], v[204:207], v[120:123]
	v_mfma_f32_16x16x32_bf16 v[108:111], v[136:139], v[222:225], v[108:111]
	v_mfma_f32_16x16x32_bf16 v[104:107], v[180:183], v[222:225], v[104:107]
	v_mfma_f32_16x16x32_bf16 v[92:95], v[136:139], v[230:233], v[92:95]
	v_mfma_f32_16x16x32_bf16 v[88:91], v[180:183], v[230:233], v[88:91]
	v_mfma_f32_16x16x32_bf16 v[76:79], v[136:139], v[238:241], v[76:79]
	v_mfma_f32_16x16x32_bf16 v[72:75], v[180:183], v[238:241], v[72:75]
	s_cmp_gt_u32 s75, 3
	s_cbranch_scc1 .Lie_skipk2
	v_mfma_f32_16x16x32_bf16 v[116:119], v[184:187], v[200:203], v[116:119]
	v_mfma_f32_16x16x32_bf16 v[112:115], v[192:195], v[200:203], v[112:115]
	v_mfma_f32_16x16x32_bf16 v[100:103], v[184:187], v[218:221], v[100:103]
	v_mfma_f32_16x16x32_bf16 v[96:99], v[192:195], v[218:221], v[96:99]
	v_mfma_f32_16x16x32_bf16 v[84:87], v[184:187], v[226:229], v[84:87]
	v_mfma_f32_16x16x32_bf16 v[80:83], v[192:195], v[226:229], v[80:83]
	v_mfma_f32_16x16x32_bf16 v[68:71], v[184:187], v[234:237], v[68:71]
	v_mfma_f32_16x16x32_bf16 v[64:67], v[192:195], v[234:237], v[64:67]
	v_mfma_f32_16x16x32_bf16 v[116:119], v[188:191], v[204:207], v[116:119]
	v_mfma_f32_16x16x32_bf16 v[112:115], v[196:199], v[204:207], v[112:115]
	v_mfma_f32_16x16x32_bf16 v[100:103], v[188:191], v[222:225], v[100:103]
	v_mfma_f32_16x16x32_bf16 v[96:99], v[196:199], v[222:225], v[96:99]
	v_mfma_f32_16x16x32_bf16 v[84:87], v[188:191], v[230:233], v[84:87]
	v_mfma_f32_16x16x32_bf16 v[80:83], v[196:199], v[230:233], v[80:83]
	v_mfma_f32_16x16x32_bf16 v[68:71], v[188:191], v[238:241], v[68:71]
	v_mfma_f32_16x16x32_bf16 v[64:67], v[196:199], v[238:241], v[64:67]
; #define PG8_STAGE(bufoff, gbase, voff) do { _Pragma("unroll") for (int _i = 0; _i < 2; ++_i) \
;         __builtin_amdgcn_global_load_lds((const unsigned*)((const char*)(gbase) + (voff)[_i]), (PG8_LAS unsigned*)(lds + (bufoff) + ldsw + _i * 8192), 16, 0, 0); } while (0)
; #define PG8_LDA(dst, b, h) do { _Pragma("unroll") for (int m = 0; m < 4; ++m) _Pragma("unroll") for (int k = 0; k < 2; ++k) dst[m][k] = *(const PG8_LAS bf16x8*)(lds + PG8_SA(b, h) + aoff + m * 2048 + k * 1024); } while (0)
; #define PG8_MMA(ai, bj, At, Bt) do { __builtin_amdgcn_s_setprio(1); _Pragma("unroll") for (int m = 0; m < 4; ++m) _Pragma("unroll") for (int n = 0; n < 2; ++n) _Pragma("unroll") for (int k = 0; k < 2; ++k) \
;         acc[ai][bj][m][n] = __builtin_amdgcn_mfma_f32_16x16x32_bf16(Bt[n][k], At[m][k], acc[ai][bj][m][n], 0, 0, 0); __builtin_amdgcn_s_setprio(0); } while (0)
; #define PG8_WAIT_V(n) asm volatile("s_waitcnt vmcnt(" #n ")" ::: "memory")
; #define PG8_WAIT_L(n) asm volatile("s_waitcnt lgkmcnt(" #n ")" ::: "memory")
; #define PG8_BAR __builtin_amdgcn_s_barrier()
; #define PG8_SCHED __builtin_amdgcn_sched_barrier(0)
; template <class Epi, class Sched, bool ALIGN_EPI = false, bool SP2 = false>
; __device__ __forceinline__ void gemm_phase(PG8_LAS unsigned char* lds, const Gemm g, const Sched& S, const Epi& E) {
;     ...
;             PG8_LDA(At, 1, 1); PG8_STAGE(PG8_SB(1, 0), b3, voffB); PG8_STAGE(PG8_SB(1, 1), b3 + hstep, voffB); PG8_STAGE(PG8_SA(1, 0), a3, voffA);
;             PG8_WAIT_V(8); PG8_WAIT_L(0); PG8_BAR; PG8_MMA(1, 0, At, B0); PG8_MMA(1, 1, At, B1); PG8_BAR; PG8_SCHED;
.Lie_skipk2:
	s_setprio 1
	s_barrier
	s_add_i32 s13, s13, s37
	s_add_i32 m0, s13, 0xffffff80
	ds_read_b128 v[200:203], v216 offset:49152
	ds_read_b128 v[204:207], v216 offset:50176
	ds_read_b128 v[218:221], v216 offset:51200
	ds_read_b128 v[222:225], v216 offset:52224
	global_load_lds_dwordx4 v[214:215], off offset:128
	s_add_i32 m0, s13, 0x1f80
	s_add_i32 s13, s15, s37
	global_load_lds_dwordx4 v[242:243], off offset:128
	s_add_i32 m0, s13, 0xffffff80
	ds_read_b128 v[238:241], v216 offset:56320
	global_load_lds_dwordx4 v[244:245], off offset:128
	s_add_i32 m0, s13, 0x1f80
	ds_read_b128 v[234:237], v216 offset:55296
	global_load_lds_dwordx4 v[212:213], off offset:128
	s_add_i32 m0, s56, 0xffffff80
	ds_read_b128 v[230:233], v216 offset:54272
	global_load_lds_dwordx4 v[246:247], off offset:128
	s_add_i32 m0, s57, 0xffffff80
	ds_read_b128 v[226:229], v216 offset:53248
	global_load_lds_dwordx4 v[248:249], off offset:128
	s_waitcnt vmcnt(8) lgkmcnt(0)
	s_setprio 0
	s_barrier
	v_mfma_f32_16x16x32_bf16 v[60:63], v[132:135], v[200:203], v[60:63]
	v_mfma_f32_16x16x32_bf16 v[56:59], v[176:179], v[200:203], v[56:59]
	v_mfma_f32_16x16x32_bf16 v[44:47], v[132:135], v[218:221], v[44:47]
	v_mfma_f32_16x16x32_bf16 v[40:43], v[176:179], v[218:221], v[40:43]
	v_mfma_f32_16x16x32_bf16 v[28:31], v[132:135], v[226:229], v[28:31]
	v_mfma_f32_16x16x32_bf16 v[24:27], v[176:179], v[226:229], v[24:27]
	v_mfma_f32_16x16x32_bf16 v[12:15], v[132:135], v[234:237], v[12:15]
	v_mfma_f32_16x16x32_bf16 v[8:11], v[176:179], v[234:237], v[8:11]
	v_mfma_f32_16x16x32_bf16 v[60:63], v[136:139], v[204:207], v[60:63]
	v_mfma_f32_16x16x32_bf16 v[56:59], v[180:183], v[204:207], v[56:59]
	v_mfma_f32_16x16x32_bf16 v[44:47], v[136:139], v[222:225], v[44:47]
	v_mfma_f32_16x16x32_bf16 v[40:43], v[180:183], v[222:225], v[40:43]
	v_mfma_f32_16x16x32_bf16 v[28:31], v[136:139], v[230:233], v[28:31]
	v_mfma_f32_16x16x32_bf16 v[24:27], v[180:183], v[230:233], v[24:27]
	v_mfma_f32_16x16x32_bf16 v[12:15], v[136:139], v[238:241], v[12:15]
	v_mfma_f32_16x16x32_bf16 v[8:11], v[180:183], v[238:241], v[8:11]
	s_cmp_gt_u32 s75, 3
	s_cbranch_scc1 .Lie_skipk3
	v_mfma_f32_16x16x32_bf16 v[52:55], v[184:187], v[200:203], v[52:55]
	v_mfma_f32_16x16x32_bf16 v[48:51], v[192:195], v[200:203], v[48:51]
	v_mfma_f32_16x16x32_bf16 v[36:39], v[184:187], v[218:221], v[36:39]
	v_mfma_f32_16x16x32_bf16 v[32:35], v[192:195], v[218:221], v[32:35]
	v_mfma_f32_16x16x32_bf16 v[20:23], v[184:187], v[226:229], v[20:23]
	v_mfma_f32_16x16x32_bf16 v[16:19], v[192:195], v[226:229], v[16:19]
	v_mfma_f32_16x16x32_bf16 v[4:7], v[184:187], v[234:237], v[4:7]
	v_mfma_f32_16x16x32_bf16 v[0:3], v[192:195], v[234:237], v[0:3]
	v_mfma_f32_16x16x32_bf16 v[52:55], v[188:191], v[204:207], v[52:55]
	v_mfma_f32_16x16x32_bf16 v[48:51], v[196:199], v[204:207], v[48:51]
	v_mfma_f32_16x16x32_bf16 v[36:39], v[188:191], v[222:225], v[36:39]
	v_mfma_f32_16x16x32_bf16 v[32:35], v[196:199], v[222:225], v[32:35]
	v_mfma_f32_16x16x32_bf16 v[20:23], v[188:191], v[230:233], v[20:23]
	v_mfma_f32_16x16x32_bf16 v[16:19], v[196:199], v[230:233], v[16:19]
	v_mfma_f32_16x16x32_bf16 v[4:7], v[188:191], v[238:241], v[4:7]
	v_mfma_f32_16x16x32_bf16 v[0:3], v[196:199], v[238:241], v[0:3]
.Lie_skipk3:
	s_setprio 1
	s_barrier
	v_lshl_add_u64 v[128:129], v[128:129], 0, s[34:35]
	s_cmp_ge_i32 s12, s58
	v_lshl_add_u64 v[130:131], v[130:131], 0, s[34:35]
	s_cbranch_scc0 .LBB0_454
	s_setprio 0

; #define PG8_STAGE(bufoff, gbase, voff) do { _Pragma("unroll") for (int _i = 0; _i < 2; ++_i) \
;         __builtin_amdgcn_global_load_lds((const unsigned*)((const char*)(gbase) + (voff)[_i]), (PG8_LAS unsigned*)(lds + (bufoff) + ldsw + _i * 8192), 16, 0, 0); } while (0)
; #define PG8_LDA(dst, b, h) do { _Pragma("unroll") for (int m = 0; m < 4; ++m) _Pragma("unroll") for (int k = 0; k < 2; ++k) dst[m][k] = *(const PG8_LAS bf16x8*)(lds + PG8_SA(b, h) + aoff + m * 2048 + k * 1024); } while (0)
; #define PG8_LDB(dst, b, h) do { _Pragma("unroll") for (int n = 0; n < 2; ++n) _Pragma("unroll") for (int k = 0; k < 2; ++k) dst[n][k] = *(const PG8_LAS bf16x8*)(lds + PG8_SB(b, h) + boff + n * 2048 + k * 1024); } while (0)
; #define PG8_MMA(ai, bj, At, Bt) do { __builtin_amdgcn_s_setprio(1); _Pragma("unroll") for (int m = 0; m < 4; ++m) _Pragma("unroll") for (int n = 0; n < 2; ++n) _Pragma("unroll") for (int k = 0; k < 2; ++k) \
;         acc[ai][bj][m][n] = __builtin_amdgcn_mfma_f32_16x16x32_bf16(Bt[n][k], At[m][k], acc[ai][bj][m][n], 0, 0, 0); __builtin_amdgcn_s_setprio(0); } while (0)
; #define PG8_WAIT_V(n) asm volatile("s_waitcnt vmcnt(" #n ")" ::: "memory")
; #define PG8_WAIT_L(n) asm volatile("s_waitcnt lgkmcnt(" #n ")" ::: "memory")
; #define PG8_BAR __builtin_amdgcn_s_barrier()
; #define PG8_SCHED __builtin_amdgcn_sched_barrier(0)
; template <class Epi, class Sched, bool ALIGN_EPI = false, bool SP2 = false>
; __device__ __forceinline__ void gemm_phase(PG8_LAS unsigned char* lds, const Gemm g, const Sched& S, const Epi& E) {
;     ...
;             const bool last = (t == nt - 2);
;             const char* a1 = cA + (size_t)(t + 1) * kstep;
;             const char* a2 = last ? nA : cA + (size_t)(t + 2) * kstep; const char* b2 = last ? nB : cB + (size_t)(t + 2) * kstep;
;             const char* a3 = a2 + kstep; const char* b3 = b2 + kstep;
;             if (last && has_next) S.a_ready(nxt);
;             if constexpr (SP2) {
;             PG8_LDB(B0, 0, 0); PG8_LDB(B1, 0, 1); PG8_SCHED; PG8_LDA(At, 0, 0); PG8_STAGE(PG8_SA(1, 1), a1 + hstep, voffA);
;             PG8_WAIT_V(8); PG8_WAIT_L(0); PG8_BAR; PG8_MMA(0, 0, At, B0); PG8_MMA(0, 1, At, B1); PG8_BAR; PG8_SCHED;
;             PG8_LDA(At, 0, 1); PG8_STAGE(PG8_SB(0, 0), b2, voffB); PG8_STAGE(PG8_SB(0, 1), b2 + hstep, voffB); PG8_STAGE(PG8_SA(0, 0), a2, voffA);
.LBB0_635:
	v_add_u32_e32 v144, s64, v209
	v_add_u32_e32 v194, s65, v209
	ds_read_b128 v[92:95], v144
	ds_read_b128 v[128:131], v144 offset:1024
	ds_read_b128 v[132:135], v144 offset:2048
	ds_read_b128 v[144:147], v144 offset:3072
	ds_read_b128 v[148:151], v194
	ds_read_b128 v[152:155], v194 offset:1024
	ds_read_b128 v[190:193], v194 offset:2048
	ds_read_b128 v[194:197], v194 offset:3072
	s_cmp_eq_u32 s58, s10
	v_lshl_add_u64 v[198:199], v[90:91], 0, s[24:25]
	s_cselect_b64 vcc, -1, 0
	s_add_i32 s10, s10, 2
	v_cndmask_b32_e32 v207, v199, v187, vcc
	v_cndmask_b32_e32 v206, v198, v186, vcc
	v_cndmask_b32_e32 v215, v89, v189, vcc
	v_cndmask_b32_e32 v214, v88, v188, vcc
	v_lshl_add_u64 v[238:239], v[90:91], 0, v[180:181]
	s_add_i32 m0, s41, 0xc000
	ds_read_b128 v[198:201], v216
	ds_read_b128 v[202:205], v216 offset:1024
	ds_read_b128 v[210:213], v216 offset:2048
	ds_read_b128 v[218:221], v216 offset:3072
	ds_read_b128 v[222:225], v216 offset:4096
	ds_read_b128 v[226:229], v216 offset:5120
	ds_read_b128 v[230:233], v216 offset:6144
	ds_read_b128 v[234:237], v216 offset:7168
	global_load_lds_dwordx4 v[238:239], off
	s_add_i32 m0, s41, 0xe000
	v_lshl_add_u64 v[238:239], v[90:91], 0, v[178:179]
	global_load_lds_dwordx4 v[238:239], off
	s_waitcnt vmcnt(8) lgkmcnt(0)
	s_setprio 0
	s_barrier
	v_mfma_f32_16x16x32_bf16 v[140:143], v[92:95], v[198:201], v[140:143]
	v_mfma_f32_16x16x32_bf16 v[136:139], v[132:135], v[198:201], v[136:139]
	v_mfma_f32_16x16x32_bf16 v[116:119], v[92:95], v[210:213], v[116:119]
	v_mfma_f32_16x16x32_bf16 v[112:115], v[132:135], v[210:213], v[112:115]
	v_mfma_f32_16x16x32_bf16 v[100:103], v[92:95], v[222:225], v[100:103]
	v_mfma_f32_16x16x32_bf16 v[96:99], v[132:135], v[222:225], v[96:99]
	v_mfma_f32_16x16x32_bf16 v[76:79], v[92:95], v[230:233], v[76:79]
	v_mfma_f32_16x16x32_bf16 v[72:75], v[132:135], v[230:233], v[72:75]
	v_mfma_f32_16x16x32_bf16 v[140:143], v[128:131], v[202:205], v[140:143]
	v_mfma_f32_16x16x32_bf16 v[136:139], v[144:147], v[202:205], v[136:139]
	v_mfma_f32_16x16x32_bf16 v[116:119], v[128:131], v[218:221], v[116:119]
	v_mfma_f32_16x16x32_bf16 v[112:115], v[144:147], v[218:221], v[112:115]
	v_mfma_f32_16x16x32_bf16 v[100:103], v[128:131], v[226:229], v[100:103]
	v_mfma_f32_16x16x32_bf16 v[96:99], v[144:147], v[226:229], v[96:99]
	v_mfma_f32_16x16x32_bf16 v[76:79], v[128:131], v[234:237], v[76:79]
	v_mfma_f32_16x16x32_bf16 v[72:75], v[144:147], v[234:237], v[72:75]
	v_mfma_f32_16x16x32_bf16 v[124:127], v[148:151], v[198:201], v[124:127]
	v_mfma_f32_16x16x32_bf16 v[120:123], v[190:193], v[198:201], v[120:123]
	v_mfma_f32_16x16x32_bf16 v[108:111], v[148:151], v[210:213], v[108:111]
	v_mfma_f32_16x16x32_bf16 v[104:107], v[190:193], v[210:213], v[104:107]
	v_mfma_f32_16x16x32_bf16 v[84:87], v[148:151], v[222:225], v[84:87]
	v_mfma_f32_16x16x32_bf16 v[80:83], v[190:193], v[222:225], v[80:83]
	v_mfma_f32_16x16x32_bf16 v[68:71], v[148:151], v[230:233], v[68:71]
	v_mfma_f32_16x16x32_bf16 v[64:67], v[190:193], v[230:233], v[64:67]
	v_mfma_f32_16x16x32_bf16 v[124:127], v[152:155], v[202:205], v[124:127]
	v_mfma_f32_16x16x32_bf16 v[120:123], v[194:197], v[202:205], v[120:123]
	v_mfma_f32_16x16x32_bf16 v[108:111], v[152:155], v[218:221], v[108:111]
	v_mfma_f32_16x16x32_bf16 v[104:107], v[194:197], v[218:221], v[104:107]
	v_mfma_f32_16x16x32_bf16 v[84:87], v[152:155], v[226:229], v[84:87]
	v_mfma_f32_16x16x32_bf16 v[80:83], v[194:197], v[226:229], v[80:83]
	v_mfma_f32_16x16x32_bf16 v[68:71], v[152:155], v[234:237], v[68:71]
	v_mfma_f32_16x16x32_bf16 v[64:67], v[194:197], v[234:237], v[64:67]
	s_setprio 1
	s_barrier
	s_add_i32 s11, s64, s35
	v_lshl_add_u64 v[238:239], v[214:215], 0, v[168:169]
	s_mov_b32 m0, s11
	ds_read_b128 v[198:201], v216 offset:16384
	ds_read_b128 v[202:205], v216 offset:17408
	ds_read_b128 v[210:213], v216 offset:18432
	ds_read_b128 v[218:221], v216 offset:19456
	ds_read_b128 v[222:225], v216 offset:20480
	ds_read_b128 v[226:229], v216 offset:21504
	ds_read_b128 v[230:233], v216 offset:22528
	ds_read_b128 v[234:237], v216 offset:23552
	global_load_lds_dwordx4 v[238:239], off
	v_lshl_add_u64 v[240:241], v[214:215], 0, v[172:173]
	s_add_i32 m0, s11, 0x2000
	v_lshl_add_u64 v[214:215], v[214:215], 0, s[18:19]
	s_add_i32 s11, s65, s35
	global_load_lds_dwordx4 v[240:241], off
	v_lshl_add_u64 v[242:243], v[214:215], 0, v[168:169]
	s_mov_b32 m0, s11
	v_lshl_add_u64 v[214:215], v[214:215], 0, v[172:173]
	global_load_lds_dwordx4 v[242:243], off
	s_add_i32 m0, s11, 0x2000
	v_lshl_add_u64 v[244:245], v[206:207], 0, v[166:167]
	global_load_lds_dwordx4 v[214:215], off
	s_mov_b32 m0, s41
	v_lshl_add_u64 v[246:247], v[206:207], 0, v[170:171]
	global_load_lds_dwordx4 v[244:245], off
	s_mov_b32 m0, s50
	s_nop 0
	global_load_lds_dwordx4 v[246:247], off
	s_waitcnt vmcnt(8) lgkmcnt(0)
	s_setprio 0
	s_barrier
; #define PG8_STAGE(bufoff, gbase, voff) do { _Pragma("unroll") for (int _i = 0; _i < 2; ++_i) \
;         __builtin_amdgcn_global_load_lds((const unsigned*)((const char*)(gbase) + (voff)[_i]), (PG8_LAS unsigned*)(lds + (bufoff) + ldsw + _i * 8192), 16, 0, 0); } while (0)
; #define PG8_LDA(dst, b, h) do { _Pragma("unroll") for (int m = 0; m < 4; ++m) _Pragma("unroll") for (int k = 0; k < 2; ++k) dst[m][k] = *(const PG8_LAS bf16x8*)(lds + PG8_SA(b, h) + aoff + m * 2048 + k * 1024); } while (0)
; #define PG8_LDB(dst, b, h) do { _Pragma("unroll") for (int n = 0; n < 2; ++n) _Pragma("unroll") for (int k = 0; k < 2; ++k) dst[n][k] = *(const PG8_LAS bf16x8*)(lds + PG8_SB(b, h) + boff + n * 2048 + k * 1024); } while (0)
; #define PG8_MMA(ai, bj, At, Bt) do { __builtin_amdgcn_s_setprio(1); _Pragma("unroll") for (int m = 0; m < 4; ++m) _Pragma("unroll") for (int n = 0; n < 2; ++n) _Pragma("unroll") for (int k = 0; k < 2; ++k) \
;         acc[ai][bj][m][n] = __builtin_amdgcn_mfma_f32_16x16x32_bf16(Bt[n][k], At[m][k], acc[ai][bj][m][n], 0, 0, 0); __builtin_amdgcn_s_setprio(0); } while (0)
; #define PG8_WAIT_V(n) asm volatile("s_waitcnt vmcnt(" #n ")" ::: "memory")
; #define PG8_WAIT_L(n) asm volatile("s_waitcnt lgkmcnt(" #n ")" ::: "memory")
; #define PG8_BAR __builtin_amdgcn_s_barrier()
; #define PG8_SCHED __builtin_amdgcn_sched_barrier(0)
; template <class Epi, class Sched, bool ALIGN_EPI = false, bool SP2 = false>
; __device__ __forceinline__ void gemm_phase(PG8_LAS unsigned char* lds, const Gemm g, const Sched& S, const Epi& E) {
;     ...
;             PG8_WAIT_V(8); PG8_WAIT_L(0); PG8_BAR; PG8_MMA(1, 0, At, B0); PG8_MMA(1, 1, At, B1); PG8_BAR; PG8_SCHED;
;             PG8_LDB(B0, 1, 0); PG8_LDB(B1, 1, 1); PG8_SCHED; PG8_LDA(At, 1, 0); PG8_STAGE(PG8_SA(0, 1), a2 + hstep, voffA);
	v_mfma_f32_16x16x32_bf16 v[60:63], v[92:95], v[198:201], v[60:63]
	v_mfma_f32_16x16x32_bf16 v[56:59], v[132:135], v[198:201], v[56:59]
	v_mfma_f32_16x16x32_bf16 v[44:47], v[92:95], v[210:213], v[44:47]
	v_mfma_f32_16x16x32_bf16 v[40:43], v[132:135], v[210:213], v[40:43]
	v_mfma_f32_16x16x32_bf16 v[28:31], v[92:95], v[222:225], v[28:31]
	v_mfma_f32_16x16x32_bf16 v[24:27], v[132:135], v[222:225], v[24:27]
	v_mfma_f32_16x16x32_bf16 v[12:15], v[92:95], v[230:233], v[12:15]
	v_mfma_f32_16x16x32_bf16 v[8:11], v[132:135], v[230:233], v[8:11]
	v_mfma_f32_16x16x32_bf16 v[60:63], v[128:131], v[202:205], v[60:63]
	v_mfma_f32_16x16x32_bf16 v[56:59], v[144:147], v[202:205], v[56:59]
	v_mfma_f32_16x16x32_bf16 v[44:47], v[128:131], v[218:221], v[44:47]
	v_mfma_f32_16x16x32_bf16 v[40:43], v[144:147], v[218:221], v[40:43]
	v_mfma_f32_16x16x32_bf16 v[28:31], v[128:131], v[226:229], v[28:31]
	v_mfma_f32_16x16x32_bf16 v[24:27], v[144:147], v[226:229], v[24:27]
	v_mfma_f32_16x16x32_bf16 v[12:15], v[128:131], v[234:237], v[12:15]
	v_mfma_f32_16x16x32_bf16 v[8:11], v[144:147], v[234:237], v[8:11]
	v_mfma_f32_16x16x32_bf16 v[52:55], v[148:151], v[198:201], v[52:55]
	v_mfma_f32_16x16x32_bf16 v[48:51], v[190:193], v[198:201], v[48:51]
	v_mfma_f32_16x16x32_bf16 v[36:39], v[148:151], v[210:213], v[36:39]
	v_mfma_f32_16x16x32_bf16 v[32:35], v[190:193], v[210:213], v[32:35]
	v_mfma_f32_16x16x32_bf16 v[20:23], v[148:151], v[222:225], v[20:23]
	v_mfma_f32_16x16x32_bf16 v[16:19], v[190:193], v[222:225], v[16:19]
	v_mfma_f32_16x16x32_bf16 v[4:7], v[148:151], v[230:233], v[4:7]
	v_mfma_f32_16x16x32_bf16 v[0:3], v[190:193], v[230:233], v[0:3]
	v_mfma_f32_16x16x32_bf16 v[52:55], v[152:155], v[202:205], v[52:55]
	v_mfma_f32_16x16x32_bf16 v[48:51], v[194:197], v[202:205], v[48:51]
	v_mfma_f32_16x16x32_bf16 v[36:39], v[152:155], v[218:221], v[36:39]
	v_mfma_f32_16x16x32_bf16 v[32:35], v[194:197], v[218:221], v[32:35]
	v_mfma_f32_16x16x32_bf16 v[20:23], v[152:155], v[226:229], v[20:23]
	v_mfma_f32_16x16x32_bf16 v[16:19], v[194:197], v[226:229], v[16:19]
	v_mfma_f32_16x16x32_bf16 v[4:7], v[152:155], v[234:237], v[4:7]
	v_mfma_f32_16x16x32_bf16 v[0:3], v[194:197], v[234:237], v[0:3]
	s_setprio 1
	s_barrier
	s_add_i32 s11, 0, 0x18000
	s_add_i32 s14, 0, 0x1c000
	v_add_u32_e32 v144, s11, v209
	v_add_u32_e32 v194, s14, v209
	ds_read_b128 v[92:95], v144
	ds_read_b128 v[128:131], v144 offset:1024
	ds_read_b128 v[132:135], v144 offset:2048
	ds_read_b128 v[144:147], v144 offset:3072
	ds_read_b128 v[148:151], v194
	ds_read_b128 v[152:155], v194 offset:1024
	ds_read_b128 v[190:193], v194 offset:2048
	ds_read_b128 v[194:197], v194 offset:3072
	v_lshl_add_u64 v[206:207], v[206:207], 0, s[18:19]
	s_mov_b32 m0, s51
	v_lshl_add_u64 v[248:249], v[206:207], 0, v[166:167]
	ds_read_b128 v[198:201], v216 offset:32768
	ds_read_b128 v[202:205], v216 offset:33792
	ds_read_b128 v[210:213], v216 offset:34816
	ds_read_b128 v[218:221], v216 offset:35840
	ds_read_b128 v[222:225], v216 offset:36864
	ds_read_b128 v[226:229], v216 offset:37888
	ds_read_b128 v[230:233], v216 offset:38912
	ds_read_b128 v[234:237], v216 offset:39936
	global_load_lds_dwordx4 v[248:249], off
	s_mov_b32 m0, s52
	v_lshl_add_u64 v[206:207], v[206:207], 0, v[170:171]
	global_load_lds_dwordx4 v[206:207], off
	s_waitcnt vmcnt(8) lgkmcnt(0)
	s_setprio 0
	s_barrier
; #define PG8_STAGE(bufoff, gbase, voff) do { _Pragma("unroll") for (int _i = 0; _i < 2; ++_i) \
;         __builtin_amdgcn_global_load_lds((const unsigned*)((const char*)(gbase) + (voff)[_i]), (PG8_LAS unsigned*)(lds + (bufoff) + ldsw + _i * 8192), 16, 0, 0); } while (0)
; #define PG8_LDA(dst, b, h) do { _Pragma("unroll") for (int m = 0; m < 4; ++m) _Pragma("unroll") for (int k = 0; k < 2; ++k) dst[m][k] = *(const PG8_LAS bf16x8*)(lds + PG8_SA(b, h) + aoff + m * 2048 + k * 1024); } while (0)
; #define PG8_MMA(ai, bj, At, Bt) do { __builtin_amdgcn_s_setprio(1); _Pragma("unroll") for (int m = 0; m < 4; ++m) _Pragma("unroll") for (int n = 0; n < 2; ++n) _Pragma("unroll") for (int k = 0; k < 2; ++k) \
;         acc[ai][bj][m][n] = __builtin_amdgcn_mfma_f32_16x16x32_bf16(Bt[n][k], At[m][k], acc[ai][bj][m][n], 0, 0, 0); __builtin_amdgcn_s_setprio(0); } while (0)
; #define PG8_WAIT_V(n) asm volatile("s_waitcnt vmcnt(" #n ")" ::: "memory")
; #define PG8_WAIT_L(n) asm volatile("s_waitcnt lgkmcnt(" #n ")" ::: "memory")
; #define PG8_BAR __builtin_amdgcn_s_barrier()
; #define PG8_SCHED __builtin_amdgcn_sched_barrier(0)
; template <class Epi, class Sched, bool ALIGN_EPI = false, bool SP2 = false>
; __device__ __forceinline__ void gemm_phase(PG8_LAS unsigned char* lds, const Gemm g, const Sched& S, const Epi& E) {
;     ...
;             PG8_WAIT_V(8); PG8_WAIT_L(0); PG8_BAR; PG8_MMA(0, 0, At, B0); PG8_MMA(0, 1, At, B1); PG8_BAR; PG8_SCHED;
;             PG8_LDA(At, 1, 1); PG8_STAGE(PG8_SB(1, 0), b3, voffB); PG8_STAGE(PG8_SB(1, 1), b3 + hstep, voffB); PG8_STAGE(PG8_SA(1, 0), a3, voffA);
;             PG8_WAIT_V(8); PG8_WAIT_L(0); PG8_BAR; PG8_MMA(1, 0, At, B0); PG8_MMA(1, 1, At, B1); PG8_BAR; PG8_SCHED;
	v_mfma_f32_16x16x32_bf16 v[140:143], v[92:95], v[198:201], v[140:143]
	v_mfma_f32_16x16x32_bf16 v[136:139], v[132:135], v[198:201], v[136:139]
	v_mfma_f32_16x16x32_bf16 v[116:119], v[92:95], v[210:213], v[116:119]
	v_mfma_f32_16x16x32_bf16 v[112:115], v[132:135], v[210:213], v[112:115]
	v_mfma_f32_16x16x32_bf16 v[100:103], v[92:95], v[222:225], v[100:103]
	v_mfma_f32_16x16x32_bf16 v[96:99], v[132:135], v[222:225], v[96:99]
	v_mfma_f32_16x16x32_bf16 v[76:79], v[92:95], v[230:233], v[76:79]
	v_mfma_f32_16x16x32_bf16 v[72:75], v[132:135], v[230:233], v[72:75]
	v_mfma_f32_16x16x32_bf16 v[140:143], v[128:131], v[202:205], v[140:143]
	v_mfma_f32_16x16x32_bf16 v[136:139], v[144:147], v[202:205], v[136:139]
	v_mfma_f32_16x16x32_bf16 v[116:119], v[128:131], v[218:221], v[116:119]
	v_mfma_f32_16x16x32_bf16 v[112:115], v[144:147], v[218:221], v[112:115]
	v_mfma_f32_16x16x32_bf16 v[100:103], v[128:131], v[226:229], v[100:103]
	v_mfma_f32_16x16x32_bf16 v[96:99], v[144:147], v[226:229], v[96:99]
	v_mfma_f32_16x16x32_bf16 v[76:79], v[128:131], v[234:237], v[76:79]
	v_mfma_f32_16x16x32_bf16 v[72:75], v[144:147], v[234:237], v[72:75]
	v_mfma_f32_16x16x32_bf16 v[124:127], v[148:151], v[198:201], v[124:127]
	v_mfma_f32_16x16x32_bf16 v[120:123], v[190:193], v[198:201], v[120:123]
	v_mfma_f32_16x16x32_bf16 v[108:111], v[148:151], v[210:213], v[108:111]
	v_mfma_f32_16x16x32_bf16 v[104:107], v[190:193], v[210:213], v[104:107]
	v_mfma_f32_16x16x32_bf16 v[84:87], v[148:151], v[222:225], v[84:87]
	v_mfma_f32_16x16x32_bf16 v[80:83], v[190:193], v[222:225], v[80:83]
	v_mfma_f32_16x16x32_bf16 v[68:71], v[148:151], v[230:233], v[68:71]
	v_mfma_f32_16x16x32_bf16 v[64:67], v[190:193], v[230:233], v[64:67]
	v_mfma_f32_16x16x32_bf16 v[124:127], v[152:155], v[202:205], v[124:127]
	v_mfma_f32_16x16x32_bf16 v[120:123], v[194:197], v[202:205], v[120:123]
	v_mfma_f32_16x16x32_bf16 v[108:111], v[152:155], v[218:221], v[108:111]
	v_mfma_f32_16x16x32_bf16 v[104:107], v[194:197], v[218:221], v[104:107]
	v_mfma_f32_16x16x32_bf16 v[84:87], v[152:155], v[226:229], v[84:87]
	v_mfma_f32_16x16x32_bf16 v[80:83], v[194:197], v[226:229], v[80:83]
	v_mfma_f32_16x16x32_bf16 v[68:71], v[152:155], v[234:237], v[68:71]
	v_mfma_f32_16x16x32_bf16 v[64:67], v[194:197], v[234:237], v[64:67]
	s_setprio 1
	s_barrier
	s_add_i32 s11, s11, s35
	s_add_i32 m0, s11, 0xffffff80
	ds_read_b128 v[198:201], v216 offset:49152
	ds_read_b128 v[202:205], v216 offset:50176
	ds_read_b128 v[210:213], v216 offset:51200
	ds_read_b128 v[218:221], v216 offset:52224
	global_load_lds_dwordx4 v[238:239], off offset:128
	s_add_i32 m0, s11, 0x1f80
	s_add_i32 s11, s14, s35
	global_load_lds_dwordx4 v[240:241], off offset:128
	s_add_i32 m0, s11, 0xffffff80
	ds_read_b128 v[234:237], v216 offset:56320
	global_load_lds_dwordx4 v[242:243], off offset:128
	s_add_i32 m0, s11, 0x1f80
	ds_read_b128 v[230:233], v216 offset:55296
	global_load_lds_dwordx4 v[214:215], off offset:128
	s_add_i32 m0, s54, 0xffffff80
	ds_read_b128 v[226:229], v216 offset:54272
	global_load_lds_dwordx4 v[244:245], off offset:128
	s_add_i32 m0, s55, 0xffffff80
	ds_read_b128 v[222:225], v216 offset:53248
	global_load_lds_dwordx4 v[246:247], off offset:128
	s_waitcnt vmcnt(8) lgkmcnt(0)
	s_setprio 0
	s_barrier
	v_mfma_f32_16x16x32_bf16 v[60:63], v[92:95], v[198:201], v[60:63]
	v_mfma_f32_16x16x32_bf16 v[56:59], v[132:135], v[198:201], v[56:59]
	v_mfma_f32_16x16x32_bf16 v[44:47], v[92:95], v[210:213], v[44:47]
	v_mfma_f32_16x16x32_bf16 v[40:43], v[132:135], v[210:213], v[40:43]
	v_mfma_f32_16x16x32_bf16 v[28:31], v[92:95], v[222:225], v[28:31]
	v_mfma_f32_16x16x32_bf16 v[24:27], v[132:135], v[222:225], v[24:27]
	v_mfma_f32_16x16x32_bf16 v[12:15], v[92:95], v[230:233], v[12:15]
	v_mfma_f32_16x16x32_bf16 v[8:11], v[132:135], v[230:233], v[8:11]
	v_mfma_f32_16x16x32_bf16 v[60:63], v[128:131], v[202:205], v[60:63]
	v_mfma_f32_16x16x32_bf16 v[56:59], v[144:147], v[202:205], v[56:59]
	v_mfma_f32_16x16x32_bf16 v[44:47], v[128:131], v[218:221], v[44:47]
	v_mfma_f32_16x16x32_bf16 v[40:43], v[144:147], v[218:221], v[40:43]
	v_mfma_f32_16x16x32_bf16 v[28:31], v[128:131], v[226:229], v[28:31]
	v_mfma_f32_16x16x32_bf16 v[24:27], v[144:147], v[226:229], v[24:27]
	v_mfma_f32_16x16x32_bf16 v[12:15], v[128:131], v[234:237], v[12:15]
	v_mfma_f32_16x16x32_bf16 v[8:11], v[144:147], v[234:237], v[8:11]
	v_mfma_f32_16x16x32_bf16 v[52:55], v[148:151], v[198:201], v[52:55]
	v_mfma_f32_16x16x32_bf16 v[48:51], v[190:193], v[198:201], v[48:51]
	v_mfma_f32_16x16x32_bf16 v[36:39], v[148:151], v[210:213], v[36:39]
	v_mfma_f32_16x16x32_bf16 v[32:35], v[190:193], v[210:213], v[32:35]
	v_mfma_f32_16x16x32_bf16 v[20:23], v[148:151], v[222:225], v[20:23]
	v_mfma_f32_16x16x32_bf16 v[16:19], v[190:193], v[222:225], v[16:19]
	v_mfma_f32_16x16x32_bf16 v[4:7], v[148:151], v[230:233], v[4:7]
	v_mfma_f32_16x16x32_bf16 v[0:3], v[190:193], v[230:233], v[0:3]
	v_mfma_f32_16x16x32_bf16 v[52:55], v[152:155], v[202:205], v[52:55]
	v_mfma_f32_16x16x32_bf16 v[48:51], v[194:197], v[202:205], v[48:51]
	v_mfma_f32_16x16x32_bf16 v[36:39], v[152:155], v[218:221], v[36:39]
	v_mfma_f32_16x16x32_bf16 v[32:35], v[194:197], v[218:221], v[32:35]
	v_mfma_f32_16x16x32_bf16 v[20:23], v[152:155], v[226:229], v[20:23]
	v_mfma_f32_16x16x32_bf16 v[16:19], v[194:197], v[226:229], v[16:19]
	v_mfma_f32_16x16x32_bf16 v[4:7], v[152:155], v[234:237], v[4:7]
	v_mfma_f32_16x16x32_bf16 v[0:3], v[194:197], v[234:237], v[0:3]
	s_setprio 1
	s_barrier
	v_lshl_add_u64 v[88:89], v[88:89], 0, s[30:31]
	s_cmp_ge_i32 s10, s57
	v_lshl_add_u64 v[90:91], v[90:91], 0, s[30:31]
	s_cbranch_scc0 .LBB0_635
	s_setprio 0

; #define PG8_STAGE(bufoff, gbase, voff) do { _Pragma("unroll") for (int _i = 0; _i < 2; ++_i) \
;         __builtin_amdgcn_global_load_lds((const unsigned*)((const char*)(gbase) + (voff)[_i]), (PG8_LAS unsigned*)(lds + (bufoff) + ldsw + _i * 8192), 16, 0, 0); } while (0)
; #define PG8_LDA(dst, b, h) do { _Pragma("unroll") for (int m = 0; m < 4; ++m) _Pragma("unroll") for (int k = 0; k < 2; ++k) dst[m][k] = *(const PG8_LAS bf16x8*)(lds + PG8_SA(b, h) + aoff + m * 2048 + k * 1024); } while (0)
; #define PG8_LDB(dst, b, h) do { _Pragma("unroll") for (int n = 0; n < 2; ++n) _Pragma("unroll") for (int k = 0; k < 2; ++k) dst[n][k] = *(const PG8_LAS bf16x8*)(lds + PG8_SB(b, h) + boff + n * 2048 + k * 1024); } while (0)
; #define PG8_MMA(ai, bj, At, Bt) do { __builtin_amdgcn_s_setprio(1); _Pragma("unroll") for (int m = 0; m < 4; ++m) _Pragma("unroll") for (int n = 0; n < 2; ++n) _Pragma("unroll") for (int k = 0; k < 2; ++k) \
;         acc[ai][bj][m][n] = __builtin_amdgcn_mfma_f32_16x16x32_bf16(Bt[n][k], At[m][k], acc[ai][bj][m][n], 0, 0, 0); __builtin_amdgcn_s_setprio(0); } while (0)
; #define PG8_WAIT_V(n) asm volatile("s_waitcnt vmcnt(" #n ")" ::: "memory")
; #define PG8_WAIT_L(n) asm volatile("s_waitcnt lgkmcnt(" #n ")" ::: "memory")
; #define PG8_BAR __builtin_amdgcn_s_barrier()
; #define PG8_SCHED __builtin_amdgcn_sched_barrier(0)
; template <class Epi, class Sched, bool ALIGN_EPI = false, bool SP2 = false>
; __device__ __forceinline__ void gemm_phase(PG8_LAS unsigned char* lds, const Gemm g, const Sched& S, const Epi& E) {
;     ...
;             const bool last = (t == nt - 2);
;             const char* a1 = cA + (size_t)(t + 1) * kstep;
;             const char* a2 = last ? nA : cA + (size_t)(t + 2) * kstep; const char* b2 = last ? nB : cB + (size_t)(t + 2) * kstep;
;             const char* a3 = a2 + kstep; const char* b3 = b2 + kstep;
;             if (last && has_next) S.a_ready(nxt);
;             if constexpr (SP2) {
;             PG8_LDB(B0, 0, 0); PG8_LDB(B1, 0, 1); PG8_SCHED; PG8_LDA(At, 0, 0); PG8_STAGE(PG8_SA(1, 1), a1 + hstep, voffA);
;             PG8_WAIT_V(8); PG8_WAIT_L(0); PG8_BAR; PG8_MMA(0, 0, At, B0); PG8_MMA(0, 1, At, B1); PG8_BAR; PG8_SCHED;
;             PG8_LDA(At, 0, 1); PG8_STAGE(PG8_SB(0, 0), b2, voffB); PG8_STAGE(PG8_SB(0, 1), b2 + hstep, voffB); PG8_STAGE(PG8_SA(0, 0), a2, voffA);
.LBB0_722:
	v_add_u32_e32 v144, s59, v183
	v_add_u32_e32 v170, s60, v183
	ds_read_b128 v[116:119], v144
	ds_read_b128 v[136:139], v144 offset:1024
	ds_read_b128 v[140:143], v144 offset:2048
	ds_read_b128 v[144:147], v144 offset:3072
	ds_read_b128 v[148:151], v170
	ds_read_b128 v[188:191], v170 offset:1024
	ds_read_b128 v[192:195], v170 offset:2048
	ds_read_b128 v[198:201], v170 offset:3072
	s_cmp_eq_u32 s53, s8
	v_lshl_add_u64 v[204:205], v[114:115], 0, s[18:19]
	s_cselect_b64 vcc, -1, 0
	s_add_i32 s8, s8, 2
	v_cndmask_b32_e32 v213, v205, v185, vcc
	v_cndmask_b32_e32 v212, v204, v184, vcc
	v_cndmask_b32_e32 v215, v113, v187, vcc
	v_cndmask_b32_e32 v214, v112, v186, vcc
	v_lshl_add_u64 v[240:241], v[114:115], 0, v[178:179]
	s_add_i32 m0, s34, 0xc000
	ds_read_b128 v[204:207], v202
	ds_read_b128 v[208:211], v202 offset:1024
	ds_read_b128 v[216:219], v202 offset:2048
	ds_read_b128 v[220:223], v202 offset:3072
	ds_read_b128 v[224:227], v202 offset:4096
	ds_read_b128 v[228:231], v202 offset:5120
	ds_read_b128 v[232:235], v202 offset:6144
	ds_read_b128 v[236:239], v202 offset:7168
	global_load_lds_dwordx4 v[240:241], off
	s_add_i32 m0, s34, 0xe000
	v_lshl_add_u64 v[240:241], v[114:115], 0, v[176:177]
	global_load_lds_dwordx4 v[240:241], off
	s_waitcnt vmcnt(8) lgkmcnt(0)
	s_setprio 0
	s_barrier
	v_mfma_f32_16x16x32_bf16 v[132:135], v[116:119], v[204:207], v[132:135]
	v_mfma_f32_16x16x32_bf16 v[128:131], v[140:143], v[204:207], v[128:131]
	v_mfma_f32_16x16x32_bf16 v[108:111], v[116:119], v[216:219], v[108:111]
	v_mfma_f32_16x16x32_bf16 v[104:107], v[140:143], v[216:219], v[104:107]
	v_mfma_f32_16x16x32_bf16 v[92:95], v[116:119], v[224:227], v[92:95]
	v_mfma_f32_16x16x32_bf16 v[88:91], v[140:143], v[224:227], v[88:91]
	v_mfma_f32_16x16x32_bf16 v[76:79], v[116:119], v[232:235], v[76:79]
	v_mfma_f32_16x16x32_bf16 v[72:75], v[140:143], v[232:235], v[72:75]
	v_mfma_f32_16x16x32_bf16 v[132:135], v[136:139], v[208:211], v[132:135]
	v_mfma_f32_16x16x32_bf16 v[128:131], v[144:147], v[208:211], v[128:131]
	v_mfma_f32_16x16x32_bf16 v[108:111], v[136:139], v[220:223], v[108:111]
	v_mfma_f32_16x16x32_bf16 v[104:107], v[144:147], v[220:223], v[104:107]
	v_mfma_f32_16x16x32_bf16 v[92:95], v[136:139], v[228:231], v[92:95]
	v_mfma_f32_16x16x32_bf16 v[88:91], v[144:147], v[228:231], v[88:91]
	v_mfma_f32_16x16x32_bf16 v[76:79], v[136:139], v[236:239], v[76:79]
	v_mfma_f32_16x16x32_bf16 v[72:75], v[144:147], v[236:239], v[72:75]
	v_mfma_f32_16x16x32_bf16 v[124:127], v[148:151], v[204:207], v[124:127]
	v_mfma_f32_16x16x32_bf16 v[120:123], v[192:195], v[204:207], v[120:123]
	v_mfma_f32_16x16x32_bf16 v[100:103], v[148:151], v[216:219], v[100:103]
	v_mfma_f32_16x16x32_bf16 v[96:99], v[192:195], v[216:219], v[96:99]
	v_mfma_f32_16x16x32_bf16 v[84:87], v[148:151], v[224:227], v[84:87]
	v_mfma_f32_16x16x32_bf16 v[80:83], v[192:195], v[224:227], v[80:83]
	v_mfma_f32_16x16x32_bf16 v[68:71], v[148:151], v[232:235], v[68:71]
	v_mfma_f32_16x16x32_bf16 v[64:67], v[192:195], v[232:235], v[64:67]
	v_mfma_f32_16x16x32_bf16 v[124:127], v[188:191], v[208:211], v[124:127]
	v_mfma_f32_16x16x32_bf16 v[120:123], v[198:201], v[208:211], v[120:123]
	v_mfma_f32_16x16x32_bf16 v[100:103], v[188:191], v[220:223], v[100:103]
	v_mfma_f32_16x16x32_bf16 v[96:99], v[198:201], v[220:223], v[96:99]
	v_mfma_f32_16x16x32_bf16 v[84:87], v[188:191], v[228:231], v[84:87]
	v_mfma_f32_16x16x32_bf16 v[80:83], v[198:201], v[228:231], v[80:83]
	v_mfma_f32_16x16x32_bf16 v[68:71], v[188:191], v[236:239], v[68:71]
	v_mfma_f32_16x16x32_bf16 v[64:67], v[198:201], v[236:239], v[64:67]
	s_setprio 1
	s_barrier
	s_add_i32 s9, s59, s29
	v_lshl_add_u64 v[240:241], v[214:215], 0, v[164:165]
	s_mov_b32 m0, s9
	ds_read_b128 v[204:207], v202 offset:16384
	ds_read_b128 v[208:211], v202 offset:17408
	ds_read_b128 v[216:219], v202 offset:18432
	ds_read_b128 v[220:223], v202 offset:19456
	ds_read_b128 v[224:227], v202 offset:20480
	ds_read_b128 v[228:231], v202 offset:21504
	ds_read_b128 v[232:235], v202 offset:22528
	ds_read_b128 v[236:239], v202 offset:23552
	global_load_lds_dwordx4 v[240:241], off
	v_lshl_add_u64 v[242:243], v[214:215], 0, v[168:169]
	s_add_i32 m0, s9, 0x2000
	v_lshl_add_u64 v[214:215], v[214:215], 0, s[12:13]
	s_add_i32 s9, s60, s29
	global_load_lds_dwordx4 v[242:243], off
	v_lshl_add_u64 v[244:245], v[214:215], 0, v[164:165]
	s_mov_b32 m0, s9
	v_lshl_add_u64 v[214:215], v[214:215], 0, v[168:169]
	global_load_lds_dwordx4 v[244:245], off
	s_add_i32 m0, s9, 0x2000
	v_lshl_add_u64 v[246:247], v[212:213], 0, v[162:163]
	global_load_lds_dwordx4 v[214:215], off
	s_mov_b32 m0, s34
	v_lshl_add_u64 v[248:249], v[212:213], 0, v[166:167]
	global_load_lds_dwordx4 v[246:247], off
	s_mov_b32 m0, s36
	s_nop 0
	global_load_lds_dwordx4 v[248:249], off
	s_waitcnt vmcnt(8) lgkmcnt(0)
	s_setprio 0
	s_barrier
; #define PG8_STAGE(bufoff, gbase, voff) do { _Pragma("unroll") for (int _i = 0; _i < 2; ++_i) \
;         __builtin_amdgcn_global_load_lds((const unsigned*)((const char*)(gbase) + (voff)[_i]), (PG8_LAS unsigned*)(lds + (bufoff) + ldsw + _i * 8192), 16, 0, 0); } while (0)
; #define PG8_LDA(dst, b, h) do { _Pragma("unroll") for (int m = 0; m < 4; ++m) _Pragma("unroll") for (int k = 0; k < 2; ++k) dst[m][k] = *(const PG8_LAS bf16x8*)(lds + PG8_SA(b, h) + aoff + m * 2048 + k * 1024); } while (0)
; #define PG8_LDB(dst, b, h) do { _Pragma("unroll") for (int n = 0; n < 2; ++n) _Pragma("unroll") for (int k = 0; k < 2; ++k) dst[n][k] = *(const PG8_LAS bf16x8*)(lds + PG8_SB(b, h) + boff + n * 2048 + k * 1024); } while (0)
; #define PG8_MMA(ai, bj, At, Bt) do { __builtin_amdgcn_s_setprio(1); _Pragma("unroll") for (int m = 0; m < 4; ++m) _Pragma("unroll") for (int n = 0; n < 2; ++n) _Pragma("unroll") for (int k = 0; k < 2; ++k) \
;         acc[ai][bj][m][n] = __builtin_amdgcn_mfma_f32_16x16x32_bf16(Bt[n][k], At[m][k], acc[ai][bj][m][n], 0, 0, 0); __builtin_amdgcn_s_setprio(0); } while (0)
; #define PG8_WAIT_V(n) asm volatile("s_waitcnt vmcnt(" #n ")" ::: "memory")
; #define PG8_WAIT_L(n) asm volatile("s_waitcnt lgkmcnt(" #n ")" ::: "memory")
; #define PG8_BAR __builtin_amdgcn_s_barrier()
; #define PG8_SCHED __builtin_amdgcn_sched_barrier(0)
; template <class Epi, class Sched, bool ALIGN_EPI = false, bool SP2 = false>
; __device__ __forceinline__ void gemm_phase(PG8_LAS unsigned char* lds, const Gemm g, const Sched& S, const Epi& E) {
;     ...
;             PG8_WAIT_V(8); PG8_WAIT_L(0); PG8_BAR; PG8_MMA(1, 0, At, B0); PG8_MMA(1, 1, At, B1); PG8_BAR; PG8_SCHED;
;             PG8_LDB(B0, 1, 0); PG8_LDB(B1, 1, 1); PG8_SCHED; PG8_LDA(At, 1, 0); PG8_STAGE(PG8_SA(0, 1), a2 + hstep, voffA);
	v_mfma_f32_16x16x32_bf16 v[60:63], v[116:119], v[204:207], v[60:63]
	v_mfma_f32_16x16x32_bf16 v[56:59], v[140:143], v[204:207], v[56:59]
	v_mfma_f32_16x16x32_bf16 v[44:47], v[116:119], v[216:219], v[44:47]
	v_mfma_f32_16x16x32_bf16 v[40:43], v[140:143], v[216:219], v[40:43]
	v_mfma_f32_16x16x32_bf16 v[28:31], v[116:119], v[224:227], v[28:31]
	v_mfma_f32_16x16x32_bf16 v[24:27], v[140:143], v[224:227], v[24:27]
	v_mfma_f32_16x16x32_bf16 v[12:15], v[116:119], v[232:235], v[12:15]
	v_mfma_f32_16x16x32_bf16 v[8:11], v[140:143], v[232:235], v[8:11]
	v_mfma_f32_16x16x32_bf16 v[60:63], v[136:139], v[208:211], v[60:63]
	v_mfma_f32_16x16x32_bf16 v[56:59], v[144:147], v[208:211], v[56:59]
	v_mfma_f32_16x16x32_bf16 v[44:47], v[136:139], v[220:223], v[44:47]
	v_mfma_f32_16x16x32_bf16 v[40:43], v[144:147], v[220:223], v[40:43]
	v_mfma_f32_16x16x32_bf16 v[28:31], v[136:139], v[228:231], v[28:31]
	v_mfma_f32_16x16x32_bf16 v[24:27], v[144:147], v[228:231], v[24:27]
	v_mfma_f32_16x16x32_bf16 v[12:15], v[136:139], v[236:239], v[12:15]
	v_mfma_f32_16x16x32_bf16 v[8:11], v[144:147], v[236:239], v[8:11]
	v_mfma_f32_16x16x32_bf16 v[52:55], v[148:151], v[204:207], v[52:55]
	v_mfma_f32_16x16x32_bf16 v[48:51], v[192:195], v[204:207], v[48:51]
	v_mfma_f32_16x16x32_bf16 v[36:39], v[148:151], v[216:219], v[36:39]
	v_mfma_f32_16x16x32_bf16 v[32:35], v[192:195], v[216:219], v[32:35]
	v_mfma_f32_16x16x32_bf16 v[20:23], v[148:151], v[224:227], v[20:23]
	v_mfma_f32_16x16x32_bf16 v[16:19], v[192:195], v[224:227], v[16:19]
	v_mfma_f32_16x16x32_bf16 v[4:7], v[148:151], v[232:235], v[4:7]
	v_mfma_f32_16x16x32_bf16 v[0:3], v[192:195], v[232:235], v[0:3]
	v_mfma_f32_16x16x32_bf16 v[52:55], v[188:191], v[208:211], v[52:55]
	v_mfma_f32_16x16x32_bf16 v[48:51], v[198:201], v[208:211], v[48:51]
	v_mfma_f32_16x16x32_bf16 v[36:39], v[188:191], v[220:223], v[36:39]
	v_mfma_f32_16x16x32_bf16 v[32:35], v[198:201], v[220:223], v[32:35]
	v_mfma_f32_16x16x32_bf16 v[20:23], v[188:191], v[228:231], v[20:23]
	v_mfma_f32_16x16x32_bf16 v[16:19], v[198:201], v[228:231], v[16:19]
	v_mfma_f32_16x16x32_bf16 v[4:7], v[188:191], v[236:239], v[4:7]
	v_mfma_f32_16x16x32_bf16 v[0:3], v[198:201], v[236:239], v[0:3]
	s_setprio 1
	s_barrier
	s_add_i32 s9, 0, 0x18000
	s_add_i32 s10, 0, 0x1c000
	v_add_u32_e32 v144, s9, v183
	v_add_u32_e32 v170, s10, v183
	ds_read_b128 v[116:119], v144
	ds_read_b128 v[136:139], v144 offset:1024
	ds_read_b128 v[140:143], v144 offset:2048
	ds_read_b128 v[144:147], v144 offset:3072
	ds_read_b128 v[148:151], v170
	ds_read_b128 v[188:191], v170 offset:1024
	ds_read_b128 v[192:195], v170 offset:2048
	ds_read_b128 v[198:201], v170 offset:3072
	v_lshl_add_u64 v[212:213], v[212:213], 0, s[12:13]
	s_mov_b32 m0, s37
	v_lshl_add_u64 v[250:251], v[212:213], 0, v[162:163]
	ds_read_b128 v[204:207], v202 offset:32768
	ds_read_b128 v[208:211], v202 offset:33792
	ds_read_b128 v[216:219], v202 offset:34816
	ds_read_b128 v[220:223], v202 offset:35840
	ds_read_b128 v[224:227], v202 offset:36864
	ds_read_b128 v[228:231], v202 offset:37888
	ds_read_b128 v[232:235], v202 offset:38912
	ds_read_b128 v[236:239], v202 offset:39936
	global_load_lds_dwordx4 v[250:251], off
	s_mov_b32 m0, s41
	v_lshl_add_u64 v[212:213], v[212:213], 0, v[166:167]
	global_load_lds_dwordx4 v[212:213], off
	s_waitcnt vmcnt(8) lgkmcnt(0)
	s_setprio 0
	s_barrier
; #define PG8_STAGE(bufoff, gbase, voff) do { _Pragma("unroll") for (int _i = 0; _i < 2; ++_i) \
;         __builtin_amdgcn_global_load_lds((const unsigned*)((const char*)(gbase) + (voff)[_i]), (PG8_LAS unsigned*)(lds + (bufoff) + ldsw + _i * 8192), 16, 0, 0); } while (0)
; #define PG8_LDA(dst, b, h) do { _Pragma("unroll") for (int m = 0; m < 4; ++m) _Pragma("unroll") for (int k = 0; k < 2; ++k) dst[m][k] = *(const PG8_LAS bf16x8*)(lds + PG8_SA(b, h) + aoff + m * 2048 + k * 1024); } while (0)
; #define PG8_MMA(ai, bj, At, Bt) do { __builtin_amdgcn_s_setprio(1); _Pragma("unroll") for (int m = 0; m < 4; ++m) _Pragma("unroll") for (int n = 0; n < 2; ++n) _Pragma("unroll") for (int k = 0; k < 2; ++k) \
;         acc[ai][bj][m][n] = __builtin_amdgcn_mfma_f32_16x16x32_bf16(Bt[n][k], At[m][k], acc[ai][bj][m][n], 0, 0, 0); __builtin_amdgcn_s_setprio(0); } while (0)
; #define PG8_WAIT_V(n) asm volatile("s_waitcnt vmcnt(" #n ")" ::: "memory")
; #define PG8_WAIT_L(n) asm volatile("s_waitcnt lgkmcnt(" #n ")" ::: "memory")
; #define PG8_BAR __builtin_amdgcn_s_barrier()
; #define PG8_SCHED __builtin_amdgcn_sched_barrier(0)
; template <class Epi, class Sched, bool ALIGN_EPI = false, bool SP2 = false>
; __device__ __forceinline__ void gemm_phase(PG8_LAS unsigned char* lds, const Gemm g, const Sched& S, const Epi& E) {
;     ...
;             PG8_WAIT_V(8); PG8_WAIT_L(0); PG8_BAR; PG8_MMA(0, 0, At, B0); PG8_MMA(0, 1, At, B1); PG8_BAR; PG8_SCHED;
;             PG8_LDA(At, 1, 1); PG8_STAGE(PG8_SB(1, 0), b3, voffB); PG8_STAGE(PG8_SB(1, 1), b3 + hstep, voffB); PG8_STAGE(PG8_SA(1, 0), a3, voffA);
;             PG8_WAIT_V(8); PG8_WAIT_L(0); PG8_BAR; PG8_MMA(1, 0, At, B0); PG8_MMA(1, 1, At, B1); PG8_BAR; PG8_SCHED;
	v_mfma_f32_16x16x32_bf16 v[132:135], v[116:119], v[204:207], v[132:135]
	v_mfma_f32_16x16x32_bf16 v[128:131], v[140:143], v[204:207], v[128:131]
	v_mfma_f32_16x16x32_bf16 v[108:111], v[116:119], v[216:219], v[108:111]
	v_mfma_f32_16x16x32_bf16 v[104:107], v[140:143], v[216:219], v[104:107]
	v_mfma_f32_16x16x32_bf16 v[92:95], v[116:119], v[224:227], v[92:95]
	v_mfma_f32_16x16x32_bf16 v[88:91], v[140:143], v[224:227], v[88:91]
	v_mfma_f32_16x16x32_bf16 v[76:79], v[116:119], v[232:235], v[76:79]
	v_mfma_f32_16x16x32_bf16 v[72:75], v[140:143], v[232:235], v[72:75]
	v_mfma_f32_16x16x32_bf16 v[132:135], v[136:139], v[208:211], v[132:135]
	v_mfma_f32_16x16x32_bf16 v[128:131], v[144:147], v[208:211], v[128:131]
	v_mfma_f32_16x16x32_bf16 v[108:111], v[136:139], v[220:223], v[108:111]
	v_mfma_f32_16x16x32_bf16 v[104:107], v[144:147], v[220:223], v[104:107]
	v_mfma_f32_16x16x32_bf16 v[92:95], v[136:139], v[228:231], v[92:95]
	v_mfma_f32_16x16x32_bf16 v[88:91], v[144:147], v[228:231], v[88:91]
	v_mfma_f32_16x16x32_bf16 v[76:79], v[136:139], v[236:239], v[76:79]
	v_mfma_f32_16x16x32_bf16 v[72:75], v[144:147], v[236:239], v[72:75]
	v_mfma_f32_16x16x32_bf16 v[124:127], v[148:151], v[204:207], v[124:127]
	v_mfma_f32_16x16x32_bf16 v[120:123], v[192:195], v[204:207], v[120:123]
	v_mfma_f32_16x16x32_bf16 v[100:103], v[148:151], v[216:219], v[100:103]
	v_mfma_f32_16x16x32_bf16 v[96:99], v[192:195], v[216:219], v[96:99]
	v_mfma_f32_16x16x32_bf16 v[84:87], v[148:151], v[224:227], v[84:87]
	v_mfma_f32_16x16x32_bf16 v[80:83], v[192:195], v[224:227], v[80:83]
	v_mfma_f32_16x16x32_bf16 v[68:71], v[148:151], v[232:235], v[68:71]
	v_mfma_f32_16x16x32_bf16 v[64:67], v[192:195], v[232:235], v[64:67]
	v_mfma_f32_16x16x32_bf16 v[124:127], v[188:191], v[208:211], v[124:127]
	v_mfma_f32_16x16x32_bf16 v[120:123], v[198:201], v[208:211], v[120:123]
	v_mfma_f32_16x16x32_bf16 v[100:103], v[188:191], v[220:223], v[100:103]
	v_mfma_f32_16x16x32_bf16 v[96:99], v[198:201], v[220:223], v[96:99]
	v_mfma_f32_16x16x32_bf16 v[84:87], v[188:191], v[228:231], v[84:87]
	v_mfma_f32_16x16x32_bf16 v[80:83], v[198:201], v[228:231], v[80:83]
	v_mfma_f32_16x16x32_bf16 v[68:71], v[188:191], v[236:239], v[68:71]
	v_mfma_f32_16x16x32_bf16 v[64:67], v[198:201], v[236:239], v[64:67]
	s_setprio 1
	s_barrier
	s_add_i32 s9, s9, s29
	s_add_i32 m0, s9, 0xffffff80
	ds_read_b128 v[204:207], v202 offset:49152
	ds_read_b128 v[208:211], v202 offset:50176
	ds_read_b128 v[216:219], v202 offset:51200
	ds_read_b128 v[220:223], v202 offset:52224
	global_load_lds_dwordx4 v[240:241], off offset:128
	s_add_i32 m0, s9, 0x1f80
	s_add_i32 s9, s10, s29
	global_load_lds_dwordx4 v[242:243], off offset:128
	s_add_i32 m0, s9, 0xffffff80
	ds_read_b128 v[236:239], v202 offset:56320
	global_load_lds_dwordx4 v[244:245], off offset:128
	s_add_i32 m0, s9, 0x1f80
	ds_read_b128 v[232:235], v202 offset:55296
	global_load_lds_dwordx4 v[214:215], off offset:128
	s_add_i32 m0, s49, 0xffffff80
	ds_read_b128 v[228:231], v202 offset:54272
	global_load_lds_dwordx4 v[246:247], off offset:128
	s_add_i32 m0, s50, 0xffffff80
	ds_read_b128 v[224:227], v202 offset:53248
	global_load_lds_dwordx4 v[248:249], off offset:128
	s_waitcnt vmcnt(8) lgkmcnt(0)
	s_setprio 0
	s_barrier
	v_mfma_f32_16x16x32_bf16 v[60:63], v[116:119], v[204:207], v[60:63]
	v_mfma_f32_16x16x32_bf16 v[56:59], v[140:143], v[204:207], v[56:59]
	v_mfma_f32_16x16x32_bf16 v[44:47], v[116:119], v[216:219], v[44:47]
	v_mfma_f32_16x16x32_bf16 v[40:43], v[140:143], v[216:219], v[40:43]
	v_mfma_f32_16x16x32_bf16 v[28:31], v[116:119], v[224:227], v[28:31]
	v_mfma_f32_16x16x32_bf16 v[24:27], v[140:143], v[224:227], v[24:27]
	v_mfma_f32_16x16x32_bf16 v[12:15], v[116:119], v[232:235], v[12:15]
	v_mfma_f32_16x16x32_bf16 v[8:11], v[140:143], v[232:235], v[8:11]
	v_mfma_f32_16x16x32_bf16 v[60:63], v[136:139], v[208:211], v[60:63]
	v_mfma_f32_16x16x32_bf16 v[56:59], v[144:147], v[208:211], v[56:59]
	v_mfma_f32_16x16x32_bf16 v[44:47], v[136:139], v[220:223], v[44:47]
	v_mfma_f32_16x16x32_bf16 v[40:43], v[144:147], v[220:223], v[40:43]
	v_mfma_f32_16x16x32_bf16 v[28:31], v[136:139], v[228:231], v[28:31]
	v_mfma_f32_16x16x32_bf16 v[24:27], v[144:147], v[228:231], v[24:27]
	v_mfma_f32_16x16x32_bf16 v[12:15], v[136:139], v[236:239], v[12:15]
	v_mfma_f32_16x16x32_bf16 v[8:11], v[144:147], v[236:239], v[8:11]
	v_mfma_f32_16x16x32_bf16 v[52:55], v[148:151], v[204:207], v[52:55]
	v_mfma_f32_16x16x32_bf16 v[48:51], v[192:195], v[204:207], v[48:51]
	v_mfma_f32_16x16x32_bf16 v[36:39], v[148:151], v[216:219], v[36:39]
	v_mfma_f32_16x16x32_bf16 v[32:35], v[192:195], v[216:219], v[32:35]
	v_mfma_f32_16x16x32_bf16 v[20:23], v[148:151], v[224:227], v[20:23]
	v_mfma_f32_16x16x32_bf16 v[16:19], v[192:195], v[224:227], v[16:19]
	v_mfma_f32_16x16x32_bf16 v[4:7], v[148:151], v[232:235], v[4:7]
	v_mfma_f32_16x16x32_bf16 v[0:3], v[192:195], v[232:235], v[0:3]
	v_mfma_f32_16x16x32_bf16 v[52:55], v[188:191], v[208:211], v[52:55]
	v_mfma_f32_16x16x32_bf16 v[48:51], v[198:201], v[208:211], v[48:51]
	v_mfma_f32_16x16x32_bf16 v[36:39], v[188:191], v[220:223], v[36:39]
	v_mfma_f32_16x16x32_bf16 v[32:35], v[198:201], v[220:223], v[32:35]
	v_mfma_f32_16x16x32_bf16 v[20:23], v[188:191], v[228:231], v[20:23]
	v_mfma_f32_16x16x32_bf16 v[16:19], v[198:201], v[228:231], v[16:19]
	v_mfma_f32_16x16x32_bf16 v[4:7], v[188:191], v[236:239], v[4:7]
	v_mfma_f32_16x16x32_bf16 v[0:3], v[198:201], v[236:239], v[0:3]
	s_setprio 1
	s_barrier
	v_lshl_add_u64 v[112:113], v[112:113], 0, s[26:27]
	s_cmp_ge_i32 s8, s51
	v_lshl_add_u64 v[114:115], v[114:115], 0, s[26:27]
	s_cbranch_scc0 .LBB0_722
	s_setprio 0

; #define PG8_STAGE(bufoff, gbase, voff) do { _Pragma("unroll") for (int _i = 0; _i < 2; ++_i) \
;         __builtin_amdgcn_global_load_lds((const unsigned*)((const char*)(gbase) + (voff)[_i]), (PG8_LAS unsigned*)(lds + (bufoff) + ldsw + _i * 8192), 16, 0, 0); } while (0)
; #define PG8_LDA(dst, b, h) do { _Pragma("unroll") for (int m = 0; m < 4; ++m) _Pragma("unroll") for (int k = 0; k < 2; ++k) dst[m][k] = *(const PG8_LAS bf16x8*)(lds + PG8_SA(b, h) + aoff + m * 2048 + k * 1024); } while (0)
; #define PG8_LDB(dst, b, h) do { _Pragma("unroll") for (int n = 0; n < 2; ++n) _Pragma("unroll") for (int k = 0; k < 2; ++k) dst[n][k] = *(const PG8_LAS bf16x8*)(lds + PG8_SB(b, h) + boff + n * 2048 + k * 1024); } while (0)
; #define PG8_MMA(ai, bj, At, Bt) do { __builtin_amdgcn_s_setprio(1); _Pragma("unroll") for (int m = 0; m < 4; ++m) _Pragma("unroll") for (int n = 0; n < 2; ++n) _Pragma("unroll") for (int k = 0; k < 2; ++k) \
;         acc[ai][bj][m][n] = __builtin_amdgcn_mfma_f32_16x16x32_bf16(Bt[n][k], At[m][k], acc[ai][bj][m][n], 0, 0, 0); __builtin_amdgcn_s_setprio(0); } while (0)
; #define PG8_WAIT_V(n) asm volatile("s_waitcnt vmcnt(" #n ")" ::: "memory")
; #define PG8_WAIT_L(n) asm volatile("s_waitcnt lgkmcnt(" #n ")" ::: "memory")
; #define PG8_BAR __builtin_amdgcn_s_barrier()
; #define PG8_SCHED __builtin_amdgcn_sched_barrier(0)
; template <class Epi, class Sched, bool ALIGN_EPI = false, bool SP2 = false>
; __device__ __forceinline__ void gemm_phase(PG8_LAS unsigned char* lds, const Gemm g, const Sched& S, const Epi& E) {
;     ...
;             const bool last = (t == nt - 2);
;             const char* a1 = cA + (size_t)(t + 1) * kstep;
;             const char* a2 = last ? nA : cA + (size_t)(t + 2) * kstep; const char* b2 = last ? nB : cB + (size_t)(t + 2) * kstep;
;             const char* a3 = a2 + kstep; const char* b3 = b2 + kstep;
;             if (last && has_next) S.a_ready(nxt);
;             if constexpr (SP2) {
;             PG8_LDB(B0, 0, 0); PG8_LDB(B1, 0, 1); PG8_SCHED; PG8_LDA(At, 0, 0); PG8_STAGE(PG8_SA(1, 1), a1 + hstep, voffA);
;             PG8_WAIT_V(8); PG8_WAIT_L(0); PG8_BAR; PG8_MMA(0, 0, At, B0); PG8_MMA(0, 1, At, B1); PG8_BAR; PG8_SCHED;
;             PG8_LDA(At, 0, 1); PG8_STAGE(PG8_SB(0, 0), b2, voffB); PG8_STAGE(PG8_SB(0, 1), b2 + hstep, voffB); PG8_STAGE(PG8_SA(0, 0), a2, voffA);
.LBB0_940:
	v_add_u32_e32 v188, s55, v199
	ds_read_b128 v[132:135], v201
	ds_read_b128 v[136:139], v201 offset:1024
	ds_read_b128 v[140:143], v201 offset:2048
	ds_read_b128 v[144:147], v201 offset:3072
	ds_read_b128 v[148:151], v188
	ds_read_b128 v[180:183], v188 offset:1024
	ds_read_b128 v[184:187], v188 offset:2048
	ds_read_b128 v[188:191], v188 offset:3072
	s_cmp_eq_u32 s48, s12
	v_lshl_add_u64 v[192:193], v[130:131], 0, s[22:23]
	s_cselect_b64 vcc, -1, 0
	s_add_i32 s12, s12, 2
	v_cndmask_b32_e32 v197, v193, v177, vcc
	v_cndmask_b32_e32 v196, v192, v176, vcc
	v_cndmask_b32_e32 v213, v129, v179, vcc
	v_cndmask_b32_e32 v212, v128, v178, vcc
	s_mov_b32 m0, s56
	v_lshl_add_u64 v[214:215], v[130:131], 0, v[172:173]
	ds_read_b128 v[192:195], v202
	ds_read_b128 v[204:207], v202 offset:1024
	ds_read_b128 v[208:211], v202 offset:2048
	ds_read_b128 v[216:219], v202 offset:3072
	ds_read_b128 v[220:223], v202 offset:4096
	ds_read_b128 v[224:227], v202 offset:5120
	ds_read_b128 v[228:231], v202 offset:6144
	ds_read_b128 v[232:235], v202 offset:7168
	global_load_lds_dwordx4 v[214:215], off
	s_mov_b32 m0, s57
	v_lshl_add_u64 v[214:215], v[130:131], 0, v[170:171]
	global_load_lds_dwordx4 v[214:215], off
	s_waitcnt vmcnt(8) lgkmcnt(0)
	s_setprio 0
	s_barrier
	v_mfma_f32_16x16x32_bf16 v[120:123], v[132:135], v[192:195], v[120:123]
	v_mfma_f32_16x16x32_bf16 v[124:127], v[140:143], v[192:195], v[124:127]
	v_mfma_f32_16x16x32_bf16 v[108:111], v[132:135], v[208:211], v[108:111]
	v_mfma_f32_16x16x32_bf16 v[104:107], v[140:143], v[208:211], v[104:107]
	v_mfma_f32_16x16x32_bf16 v[92:95], v[132:135], v[220:223], v[92:95]
	v_mfma_f32_16x16x32_bf16 v[88:91], v[140:143], v[220:223], v[88:91]
	v_mfma_f32_16x16x32_bf16 v[76:79], v[132:135], v[228:231], v[76:79]
	v_mfma_f32_16x16x32_bf16 v[72:75], v[140:143], v[228:231], v[72:75]
	v_mfma_f32_16x16x32_bf16 v[120:123], v[136:139], v[204:207], v[120:123]
	v_mfma_f32_16x16x32_bf16 v[124:127], v[144:147], v[204:207], v[124:127]
	v_mfma_f32_16x16x32_bf16 v[108:111], v[136:139], v[216:219], v[108:111]
	v_mfma_f32_16x16x32_bf16 v[104:107], v[144:147], v[216:219], v[104:107]
	v_mfma_f32_16x16x32_bf16 v[92:95], v[136:139], v[224:227], v[92:95]
	v_mfma_f32_16x16x32_bf16 v[88:91], v[144:147], v[224:227], v[88:91]
	v_mfma_f32_16x16x32_bf16 v[76:79], v[136:139], v[232:235], v[76:79]
	v_mfma_f32_16x16x32_bf16 v[72:75], v[144:147], v[232:235], v[72:75]
	v_mfma_f32_16x16x32_bf16 v[116:119], v[148:151], v[192:195], v[116:119]
	v_mfma_f32_16x16x32_bf16 v[112:115], v[184:187], v[192:195], v[112:115]
	v_mfma_f32_16x16x32_bf16 v[100:103], v[148:151], v[208:211], v[100:103]
	v_mfma_f32_16x16x32_bf16 v[96:99], v[184:187], v[208:211], v[96:99]
	v_mfma_f32_16x16x32_bf16 v[84:87], v[148:151], v[220:223], v[84:87]
	v_mfma_f32_16x16x32_bf16 v[80:83], v[184:187], v[220:223], v[80:83]
	v_mfma_f32_16x16x32_bf16 v[68:71], v[148:151], v[228:231], v[68:71]
	v_mfma_f32_16x16x32_bf16 v[64:67], v[184:187], v[228:231], v[64:67]
	v_mfma_f32_16x16x32_bf16 v[116:119], v[180:183], v[204:207], v[116:119]
	v_mfma_f32_16x16x32_bf16 v[112:115], v[188:191], v[204:207], v[112:115]
	v_mfma_f32_16x16x32_bf16 v[100:103], v[180:183], v[216:219], v[100:103]
	v_mfma_f32_16x16x32_bf16 v[96:99], v[188:191], v[216:219], v[96:99]
	v_mfma_f32_16x16x32_bf16 v[84:87], v[180:183], v[224:227], v[84:87]
	v_mfma_f32_16x16x32_bf16 v[80:83], v[188:191], v[224:227], v[80:83]
	v_mfma_f32_16x16x32_bf16 v[68:71], v[180:183], v[232:235], v[68:71]
	v_mfma_f32_16x16x32_bf16 v[64:67], v[188:191], v[232:235], v[64:67]
	s_setprio 1
	s_barrier
	s_mov_b32 m0, s58
	v_lshl_add_u64 v[214:215], v[212:213], 0, v[164:165]
	ds_read_b128 v[192:195], v202 offset:16384
	ds_read_b128 v[204:207], v202 offset:17408
	ds_read_b128 v[208:211], v202 offset:18432
	ds_read_b128 v[216:219], v202 offset:19456
	ds_read_b128 v[220:223], v202 offset:20480
	ds_read_b128 v[224:227], v202 offset:21504
	ds_read_b128 v[228:231], v202 offset:22528
	ds_read_b128 v[232:235], v202 offset:23552
	global_load_lds_dwordx4 v[214:215], off
	v_lshl_add_u64 v[236:237], v[212:213], 0, v[168:169]
	s_mov_b32 m0, s59
	v_lshl_add_u64 v[212:213], v[212:213], 0, s[14:15]
	s_add_i32 s13, s55, s30
	global_load_lds_dwordx4 v[236:237], off
	v_lshl_add_u64 v[238:239], v[212:213], 0, v[164:165]
	s_mov_b32 m0, s13
	v_lshl_add_u64 v[212:213], v[212:213], 0, v[168:169]
	global_load_lds_dwordx4 v[238:239], off
	s_add_i32 m0, s13, 0x2000
	v_lshl_add_u64 v[240:241], v[196:197], 0, v[162:163]
	global_load_lds_dwordx4 v[212:213], off
	s_mov_b32 m0, s31
	v_lshl_add_u64 v[242:243], v[196:197], 0, v[166:167]
	global_load_lds_dwordx4 v[240:241], off
	s_mov_b32 m0, s34
	s_nop 0
	global_load_lds_dwordx4 v[242:243], off
	s_waitcnt vmcnt(8) lgkmcnt(0)
	s_setprio 0
	s_barrier
; #define PG8_STAGE(bufoff, gbase, voff) do { _Pragma("unroll") for (int _i = 0; _i < 2; ++_i) \
;         __builtin_amdgcn_global_load_lds((const unsigned*)((const char*)(gbase) + (voff)[_i]), (PG8_LAS unsigned*)(lds + (bufoff) + ldsw + _i * 8192), 16, 0, 0); } while (0)
; #define PG8_LDA(dst, b, h) do { _Pragma("unroll") for (int m = 0; m < 4; ++m) _Pragma("unroll") for (int k = 0; k < 2; ++k) dst[m][k] = *(const PG8_LAS bf16x8*)(lds + PG8_SA(b, h) + aoff + m * 2048 + k * 1024); } while (0)
; #define PG8_LDB(dst, b, h) do { _Pragma("unroll") for (int n = 0; n < 2; ++n) _Pragma("unroll") for (int k = 0; k < 2; ++k) dst[n][k] = *(const PG8_LAS bf16x8*)(lds + PG8_SB(b, h) + boff + n * 2048 + k * 1024); } while (0)
; #define PG8_MMA(ai, bj, At, Bt) do { __builtin_amdgcn_s_setprio(1); _Pragma("unroll") for (int m = 0; m < 4; ++m) _Pragma("unroll") for (int n = 0; n < 2; ++n) _Pragma("unroll") for (int k = 0; k < 2; ++k) \
;         acc[ai][bj][m][n] = __builtin_amdgcn_mfma_f32_16x16x32_bf16(Bt[n][k], At[m][k], acc[ai][bj][m][n], 0, 0, 0); __builtin_amdgcn_s_setprio(0); } while (0)
; #define PG8_WAIT_V(n) asm volatile("s_waitcnt vmcnt(" #n ")" ::: "memory")
; #define PG8_WAIT_L(n) asm volatile("s_waitcnt lgkmcnt(" #n ")" ::: "memory")
; #define PG8_BAR __builtin_amdgcn_s_barrier()
; #define PG8_SCHED __builtin_amdgcn_sched_barrier(0)
; template <class Epi, class Sched, bool ALIGN_EPI = false, bool SP2 = false>
; __device__ __forceinline__ void gemm_phase(PG8_LAS unsigned char* lds, const Gemm g, const Sched& S, const Epi& E) {
;     ...
;             PG8_WAIT_V(8); PG8_WAIT_L(0); PG8_BAR; PG8_MMA(1, 0, At, B0); PG8_MMA(1, 1, At, B1); PG8_BAR; PG8_SCHED;
;             PG8_LDB(B0, 1, 0); PG8_LDB(B1, 1, 1); PG8_SCHED; PG8_LDA(At, 1, 0); PG8_STAGE(PG8_SA(0, 1), a2 + hstep, voffA);
	v_mfma_f32_16x16x32_bf16 v[60:63], v[132:135], v[192:195], v[60:63]
	v_mfma_f32_16x16x32_bf16 v[56:59], v[140:143], v[192:195], v[56:59]
	v_mfma_f32_16x16x32_bf16 v[44:47], v[132:135], v[208:211], v[44:47]
	v_mfma_f32_16x16x32_bf16 v[40:43], v[140:143], v[208:211], v[40:43]
	v_mfma_f32_16x16x32_bf16 v[28:31], v[132:135], v[220:223], v[28:31]
	v_mfma_f32_16x16x32_bf16 v[24:27], v[140:143], v[220:223], v[24:27]
	v_mfma_f32_16x16x32_bf16 v[12:15], v[132:135], v[228:231], v[12:15]
	v_mfma_f32_16x16x32_bf16 v[8:11], v[140:143], v[228:231], v[8:11]
	v_mfma_f32_16x16x32_bf16 v[60:63], v[136:139], v[204:207], v[60:63]
	v_mfma_f32_16x16x32_bf16 v[56:59], v[144:147], v[204:207], v[56:59]
	v_mfma_f32_16x16x32_bf16 v[44:47], v[136:139], v[216:219], v[44:47]
	v_mfma_f32_16x16x32_bf16 v[40:43], v[144:147], v[216:219], v[40:43]
	v_mfma_f32_16x16x32_bf16 v[28:31], v[136:139], v[224:227], v[28:31]
	v_mfma_f32_16x16x32_bf16 v[24:27], v[144:147], v[224:227], v[24:27]
	v_mfma_f32_16x16x32_bf16 v[12:15], v[136:139], v[232:235], v[12:15]
	v_mfma_f32_16x16x32_bf16 v[8:11], v[144:147], v[232:235], v[8:11]
	v_mfma_f32_16x16x32_bf16 v[52:55], v[148:151], v[192:195], v[52:55]
	v_mfma_f32_16x16x32_bf16 v[48:51], v[184:187], v[192:195], v[48:51]
	v_mfma_f32_16x16x32_bf16 v[36:39], v[148:151], v[208:211], v[36:39]
	v_mfma_f32_16x16x32_bf16 v[32:35], v[184:187], v[208:211], v[32:35]
	v_mfma_f32_16x16x32_bf16 v[20:23], v[148:151], v[220:223], v[20:23]
	v_mfma_f32_16x16x32_bf16 v[16:19], v[184:187], v[220:223], v[16:19]
	v_mfma_f32_16x16x32_bf16 v[4:7], v[148:151], v[228:231], v[4:7]
	v_mfma_f32_16x16x32_bf16 v[0:3], v[184:187], v[228:231], v[0:3]
	v_mfma_f32_16x16x32_bf16 v[52:55], v[180:183], v[204:207], v[52:55]
	v_mfma_f32_16x16x32_bf16 v[48:51], v[188:191], v[204:207], v[48:51]
	v_mfma_f32_16x16x32_bf16 v[36:39], v[180:183], v[216:219], v[36:39]
	v_mfma_f32_16x16x32_bf16 v[32:35], v[188:191], v[216:219], v[32:35]
	v_mfma_f32_16x16x32_bf16 v[20:23], v[180:183], v[224:227], v[20:23]
	v_mfma_f32_16x16x32_bf16 v[16:19], v[188:191], v[224:227], v[16:19]
	v_mfma_f32_16x16x32_bf16 v[4:7], v[180:183], v[232:235], v[4:7]
	v_mfma_f32_16x16x32_bf16 v[0:3], v[188:191], v[232:235], v[0:3]
	s_setprio 1
	s_barrier
	s_add_i32 s13, 0, 0x18000
	s_add_i32 s29, 0, 0x1c000
	v_add_u32_e32 v144, s13, v199
	v_add_u32_e32 v188, s29, v199
	ds_read_b128 v[132:135], v144
	ds_read_b128 v[136:139], v144 offset:1024
	ds_read_b128 v[140:143], v144 offset:2048
	ds_read_b128 v[144:147], v144 offset:3072
	ds_read_b128 v[148:151], v188
	ds_read_b128 v[180:183], v188 offset:1024
	ds_read_b128 v[184:187], v188 offset:2048
	ds_read_b128 v[188:191], v188 offset:3072
	v_lshl_add_u64 v[196:197], v[196:197], 0, s[14:15]
	s_mov_b32 m0, s35
	v_lshl_add_u64 v[244:245], v[196:197], 0, v[162:163]
	ds_read_b128 v[192:195], v202 offset:32768
	ds_read_b128 v[204:207], v202 offset:33792
	ds_read_b128 v[208:211], v202 offset:34816
	ds_read_b128 v[216:219], v202 offset:35840
	ds_read_b128 v[220:223], v202 offset:36864
	ds_read_b128 v[224:227], v202 offset:37888
	ds_read_b128 v[228:231], v202 offset:38912
	ds_read_b128 v[232:235], v202 offset:39936
	global_load_lds_dwordx4 v[244:245], off
	s_mov_b32 m0, s36
	v_lshl_add_u64 v[196:197], v[196:197], 0, v[166:167]
	global_load_lds_dwordx4 v[196:197], off
	s_waitcnt vmcnt(8) lgkmcnt(0)
	s_setprio 0
	s_barrier
; #define PG8_STAGE(bufoff, gbase, voff) do { _Pragma("unroll") for (int _i = 0; _i < 2; ++_i) \
;         __builtin_amdgcn_global_load_lds((const unsigned*)((const char*)(gbase) + (voff)[_i]), (PG8_LAS unsigned*)(lds + (bufoff) + ldsw + _i * 8192), 16, 0, 0); } while (0)
; #define PG8_LDA(dst, b, h) do { _Pragma("unroll") for (int m = 0; m < 4; ++m) _Pragma("unroll") for (int k = 0; k < 2; ++k) dst[m][k] = *(const PG8_LAS bf16x8*)(lds + PG8_SA(b, h) + aoff + m * 2048 + k * 1024); } while (0)
; #define PG8_MMA(ai, bj, At, Bt) do { __builtin_amdgcn_s_setprio(1); _Pragma("unroll") for (int m = 0; m < 4; ++m) _Pragma("unroll") for (int n = 0; n < 2; ++n) _Pragma("unroll") for (int k = 0; k < 2; ++k) \
;         acc[ai][bj][m][n] = __builtin_amdgcn_mfma_f32_16x16x32_bf16(Bt[n][k], At[m][k], acc[ai][bj][m][n], 0, 0, 0); __builtin_amdgcn_s_setprio(0); } while (0)
; #define PG8_WAIT_V(n) asm volatile("s_waitcnt vmcnt(" #n ")" ::: "memory")
; #define PG8_WAIT_L(n) asm volatile("s_waitcnt lgkmcnt(" #n ")" ::: "memory")
; #define PG8_BAR __builtin_amdgcn_s_barrier()
; #define PG8_SCHED __builtin_amdgcn_sched_barrier(0)
; template <class Epi, class Sched, bool ALIGN_EPI = false, bool SP2 = false>
; __device__ __forceinline__ void gemm_phase(PG8_LAS unsigned char* lds, const Gemm g, const Sched& S, const Epi& E) {
;     ...
;             PG8_WAIT_V(8); PG8_WAIT_L(0); PG8_BAR; PG8_MMA(0, 0, At, B0); PG8_MMA(0, 1, At, B1); PG8_BAR; PG8_SCHED;
;             PG8_LDA(At, 1, 1); PG8_STAGE(PG8_SB(1, 0), b3, voffB); PG8_STAGE(PG8_SB(1, 1), b3 + hstep, voffB); PG8_STAGE(PG8_SA(1, 0), a3, voffA);
;             PG8_WAIT_V(8); PG8_WAIT_L(0); PG8_BAR; PG8_MMA(1, 0, At, B0); PG8_MMA(1, 1, At, B1); PG8_BAR; PG8_SCHED;
	v_mfma_f32_16x16x32_bf16 v[120:123], v[132:135], v[192:195], v[120:123]
	v_mfma_f32_16x16x32_bf16 v[124:127], v[140:143], v[192:195], v[124:127]
	v_mfma_f32_16x16x32_bf16 v[108:111], v[132:135], v[208:211], v[108:111]
	v_mfma_f32_16x16x32_bf16 v[104:107], v[140:143], v[208:211], v[104:107]
	v_mfma_f32_16x16x32_bf16 v[92:95], v[132:135], v[220:223], v[92:95]
	v_mfma_f32_16x16x32_bf16 v[88:91], v[140:143], v[220:223], v[88:91]
	v_mfma_f32_16x16x32_bf16 v[76:79], v[132:135], v[228:231], v[76:79]
	v_mfma_f32_16x16x32_bf16 v[72:75], v[140:143], v[228:231], v[72:75]
	v_mfma_f32_16x16x32_bf16 v[120:123], v[136:139], v[204:207], v[120:123]
	v_mfma_f32_16x16x32_bf16 v[124:127], v[144:147], v[204:207], v[124:127]
	v_mfma_f32_16x16x32_bf16 v[108:111], v[136:139], v[216:219], v[108:111]
	v_mfma_f32_16x16x32_bf16 v[104:107], v[144:147], v[216:219], v[104:107]
	v_mfma_f32_16x16x32_bf16 v[92:95], v[136:139], v[224:227], v[92:95]
	v_mfma_f32_16x16x32_bf16 v[88:91], v[144:147], v[224:227], v[88:91]
	v_mfma_f32_16x16x32_bf16 v[76:79], v[136:139], v[232:235], v[76:79]
	v_mfma_f32_16x16x32_bf16 v[72:75], v[144:147], v[232:235], v[72:75]
	v_mfma_f32_16x16x32_bf16 v[116:119], v[148:151], v[192:195], v[116:119]
	v_mfma_f32_16x16x32_bf16 v[112:115], v[184:187], v[192:195], v[112:115]
	v_mfma_f32_16x16x32_bf16 v[100:103], v[148:151], v[208:211], v[100:103]
	v_mfma_f32_16x16x32_bf16 v[96:99], v[184:187], v[208:211], v[96:99]
	v_mfma_f32_16x16x32_bf16 v[84:87], v[148:151], v[220:223], v[84:87]
	v_mfma_f32_16x16x32_bf16 v[80:83], v[184:187], v[220:223], v[80:83]
	v_mfma_f32_16x16x32_bf16 v[68:71], v[148:151], v[228:231], v[68:71]
	v_mfma_f32_16x16x32_bf16 v[64:67], v[184:187], v[228:231], v[64:67]
	v_mfma_f32_16x16x32_bf16 v[116:119], v[180:183], v[204:207], v[116:119]
	v_mfma_f32_16x16x32_bf16 v[112:115], v[188:191], v[204:207], v[112:115]
	v_mfma_f32_16x16x32_bf16 v[100:103], v[180:183], v[216:219], v[100:103]
	v_mfma_f32_16x16x32_bf16 v[96:99], v[188:191], v[216:219], v[96:99]
	v_mfma_f32_16x16x32_bf16 v[84:87], v[180:183], v[224:227], v[84:87]
	v_mfma_f32_16x16x32_bf16 v[80:83], v[188:191], v[224:227], v[80:83]
	v_mfma_f32_16x16x32_bf16 v[68:71], v[180:183], v[232:235], v[68:71]
	v_mfma_f32_16x16x32_bf16 v[64:67], v[188:191], v[232:235], v[64:67]
	s_setprio 1
	s_barrier
	s_add_i32 s13, s13, s30
	s_add_i32 m0, s13, 0xffffff80
	ds_read_b128 v[192:195], v202 offset:49152
	ds_read_b128 v[204:207], v202 offset:50176
	ds_read_b128 v[208:211], v202 offset:51200
	ds_read_b128 v[216:219], v202 offset:52224
	global_load_lds_dwordx4 v[214:215], off offset:128
	s_add_i32 m0, s13, 0x1f80
	s_add_i32 s13, s29, s30
	global_load_lds_dwordx4 v[236:237], off offset:128
	s_add_i32 m0, s13, 0xffffff80
	ds_read_b128 v[232:235], v202 offset:56320
	global_load_lds_dwordx4 v[238:239], off offset:128
	s_add_i32 m0, s13, 0x1f80
	ds_read_b128 v[228:231], v202 offset:55296
	global_load_lds_dwordx4 v[212:213], off offset:128
	s_add_i32 m0, s37, 0xffffff80
	ds_read_b128 v[224:227], v202 offset:54272
	global_load_lds_dwordx4 v[240:241], off offset:128
	s_add_i32 m0, s41, 0xffffff80
	ds_read_b128 v[220:223], v202 offset:53248
	global_load_lds_dwordx4 v[242:243], off offset:128
	s_waitcnt vmcnt(8) lgkmcnt(0)
	s_setprio 0
	s_barrier
	v_mfma_f32_16x16x32_bf16 v[60:63], v[132:135], v[192:195], v[60:63]
	v_mfma_f32_16x16x32_bf16 v[56:59], v[140:143], v[192:195], v[56:59]
	v_mfma_f32_16x16x32_bf16 v[44:47], v[132:135], v[208:211], v[44:47]
	v_mfma_f32_16x16x32_bf16 v[40:43], v[140:143], v[208:211], v[40:43]
	v_mfma_f32_16x16x32_bf16 v[28:31], v[132:135], v[220:223], v[28:31]
	v_mfma_f32_16x16x32_bf16 v[24:27], v[140:143], v[220:223], v[24:27]
	v_mfma_f32_16x16x32_bf16 v[12:15], v[132:135], v[228:231], v[12:15]
	v_mfma_f32_16x16x32_bf16 v[8:11], v[140:143], v[228:231], v[8:11]
	v_mfma_f32_16x16x32_bf16 v[60:63], v[136:139], v[204:207], v[60:63]
	v_mfma_f32_16x16x32_bf16 v[56:59], v[144:147], v[204:207], v[56:59]
	v_mfma_f32_16x16x32_bf16 v[44:47], v[136:139], v[216:219], v[44:47]
	v_mfma_f32_16x16x32_bf16 v[40:43], v[144:147], v[216:219], v[40:43]
	v_mfma_f32_16x16x32_bf16 v[28:31], v[136:139], v[224:227], v[28:31]
	v_mfma_f32_16x16x32_bf16 v[24:27], v[144:147], v[224:227], v[24:27]
	v_mfma_f32_16x16x32_bf16 v[12:15], v[136:139], v[232:235], v[12:15]
	v_mfma_f32_16x16x32_bf16 v[8:11], v[144:147], v[232:235], v[8:11]
	v_mfma_f32_16x16x32_bf16 v[52:55], v[148:151], v[192:195], v[52:55]
	v_mfma_f32_16x16x32_bf16 v[48:51], v[184:187], v[192:195], v[48:51]
	v_mfma_f32_16x16x32_bf16 v[36:39], v[148:151], v[208:211], v[36:39]
	v_mfma_f32_16x16x32_bf16 v[32:35], v[184:187], v[208:211], v[32:35]
	v_mfma_f32_16x16x32_bf16 v[20:23], v[148:151], v[220:223], v[20:23]
	v_mfma_f32_16x16x32_bf16 v[16:19], v[184:187], v[220:223], v[16:19]
	v_mfma_f32_16x16x32_bf16 v[4:7], v[148:151], v[228:231], v[4:7]
	v_mfma_f32_16x16x32_bf16 v[0:3], v[184:187], v[228:231], v[0:3]
	v_mfma_f32_16x16x32_bf16 v[52:55], v[180:183], v[204:207], v[52:55]
	v_mfma_f32_16x16x32_bf16 v[48:51], v[188:191], v[204:207], v[48:51]
	v_mfma_f32_16x16x32_bf16 v[36:39], v[180:183], v[216:219], v[36:39]
	v_mfma_f32_16x16x32_bf16 v[32:35], v[188:191], v[216:219], v[32:35]
	v_mfma_f32_16x16x32_bf16 v[20:23], v[180:183], v[224:227], v[20:23]
	v_mfma_f32_16x16x32_bf16 v[16:19], v[188:191], v[224:227], v[16:19]
	v_mfma_f32_16x16x32_bf16 v[4:7], v[180:183], v[232:235], v[4:7]
	v_mfma_f32_16x16x32_bf16 v[0:3], v[188:191], v[232:235], v[0:3]
	s_setprio 1
	s_barrier
	v_lshl_add_u64 v[128:129], v[128:129], 0, s[26:27]
	s_cmp_ge_i32 s12, s47
	v_lshl_add_u64 v[130:131], v[130:131], 0, s[26:27]
	s_cbranch_scc0 .LBB0_940
	s_setprio 0

; #define PG8_STAGE(bufoff, gbase, voff) do { _Pragma("unroll") for (int _i = 0; _i < 2; ++_i) \
;         __builtin_amdgcn_global_load_lds((const unsigned*)((const char*)(gbase) + (voff)[_i]), (PG8_LAS unsigned*)(lds + (bufoff) + ldsw + _i * 8192), 16, 0, 0); } while (0)
; #define PG8_LDA(dst, b, h) do { _Pragma("unroll") for (int m = 0; m < 4; ++m) _Pragma("unroll") for (int k = 0; k < 2; ++k) dst[m][k] = *(const PG8_LAS bf16x8*)(lds + PG8_SA(b, h) + aoff + m * 2048 + k * 1024); } while (0)
; #define PG8_LDB(dst, b, h) do { _Pragma("unroll") for (int n = 0; n < 2; ++n) _Pragma("unroll") for (int k = 0; k < 2; ++k) dst[n][k] = *(const PG8_LAS bf16x8*)(lds + PG8_SB(b, h) + boff + n * 2048 + k * 1024); } while (0)
; #define PG8_MMA(ai, bj, At, Bt) do { __builtin_amdgcn_s_setprio(1); _Pragma("unroll") for (int m = 0; m < 4; ++m) _Pragma("unroll") for (int n = 0; n < 2; ++n) _Pragma("unroll") for (int k = 0; k < 2; ++k) \
;         acc[ai][bj][m][n] = __builtin_amdgcn_mfma_f32_16x16x32_bf16(Bt[n][k], At[m][k], acc[ai][bj][m][n], 0, 0, 0); __builtin_amdgcn_s_setprio(0); } while (0)
; #define PG8_WAIT_V(n) asm volatile("s_waitcnt vmcnt(" #n ")" ::: "memory")
; #define PG8_WAIT_L(n) asm volatile("s_waitcnt lgkmcnt(" #n ")" ::: "memory")
; #define PG8_BAR __builtin_amdgcn_s_barrier()
; #define PG8_SCHED __builtin_amdgcn_sched_barrier(0)
; template <class Epi, class Sched, bool ALIGN_EPI = false, bool SP2 = false>
; __device__ __forceinline__ void gemm_phase(PG8_LAS unsigned char* lds, const Gemm g, const Sched& S, const Epi& E) {
;     ...
;             const bool last = (t == nt - 2);
;             const char* a1 = cA + (size_t)(t + 1) * kstep;
;             const char* a2 = last ? nA : cA + (size_t)(t + 2) * kstep; const char* b2 = last ? nB : cB + (size_t)(t + 2) * kstep;
;             const char* a3 = a2 + kstep; const char* b3 = b2 + kstep;
;             if (last && has_next) S.a_ready(nxt);
;             if constexpr (SP2) {
;             PG8_LDB(B0, 0, 0); PG8_LDB(B1, 0, 1); PG8_SCHED; PG8_LDA(At, 0, 0); PG8_STAGE(PG8_SA(1, 1), a1 + hstep, voffA);
;             PG8_WAIT_V(8); PG8_WAIT_L(0); PG8_BAR; PG8_MMA(0, 0, At, B0); PG8_MMA(0, 1, At, B1); PG8_BAR; PG8_SCHED;
;             PG8_LDA(At, 0, 1); PG8_STAGE(PG8_SB(0, 0), b2, voffB); PG8_STAGE(PG8_SB(0, 1), b2 + hstep, voffB); PG8_STAGE(PG8_SA(0, 0), a2, voffA);
.LBB0_1021:
	v_add_u32_e32 v166, s55, v169
	v_add_u32_e32 v168, s56, v169
	ds_read_b128 v[162:165], v166
	ds_read_b128 v[182:185], v166 offset:1024
	ds_read_b128 v[186:189], v166 offset:2048
	ds_read_b128 v[190:193], v166 offset:3072
	ds_read_b128 v[194:197], v168
	ds_read_b128 v[198:201], v168 offset:1024
	ds_read_b128 v[202:205], v168 offset:2048
	ds_read_b128 v[206:209], v168 offset:3072
	s_cmp_eq_u32 s54, s10
	v_lshl_add_u64 v[172:173], v[160:161], 0, s[22:23]
	s_cselect_b64 vcc, -1, 0
	s_add_i32 s10, s10, 2
	v_cndmask_b32_e32 v173, v173, v153, vcc
	v_cndmask_b32_e32 v172, v172, v152, vcc
	v_cndmask_b32_e32 v215, v159, v155, vcc
	v_cndmask_b32_e32 v214, v158, v154, vcc
	s_mov_b32 m0, s57
	v_lshl_add_u64 v[244:245], v[160:161], 0, v[148:149]
	ds_read_b128 v[210:213], v179
	ds_read_b128 v[216:219], v179 offset:1024
	ds_read_b128 v[220:223], v179 offset:2048
	ds_read_b128 v[224:227], v179 offset:3072
	ds_read_b128 v[228:231], v179 offset:4096
	ds_read_b128 v[232:235], v179 offset:5120
	ds_read_b128 v[236:239], v179 offset:6144
	ds_read_b128 v[240:243], v179 offset:7168
	global_load_lds_dwordx4 v[244:245], off
	s_mov_b32 m0, s58
	v_lshl_add_u64 v[244:245], v[160:161], 0, v[146:147]
	global_load_lds_dwordx4 v[244:245], off
	s_waitcnt vmcnt(8) lgkmcnt(0)
	s_setprio 0
	s_barrier
	v_mfma_f32_16x16x32_bf16 v[124:127], v[162:165], v[210:213], v[124:127]
	v_mfma_f32_16x16x32_bf16 v[116:119], v[186:189], v[210:213], v[116:119]
	v_mfma_f32_16x16x32_bf16 v[108:111], v[162:165], v[220:223], v[108:111]
	v_mfma_f32_16x16x32_bf16 v[100:103], v[186:189], v[220:223], v[100:103]
	v_mfma_f32_16x16x32_bf16 v[92:95], v[162:165], v[228:231], v[92:95]
	v_mfma_f32_16x16x32_bf16 v[84:87], v[186:189], v[228:231], v[84:87]
	v_mfma_f32_16x16x32_bf16 v[76:79], v[162:165], v[236:239], v[76:79]
	v_mfma_f32_16x16x32_bf16 v[68:71], v[186:189], v[236:239], v[68:71]
	v_mfma_f32_16x16x32_bf16 v[124:127], v[182:185], v[216:219], v[124:127]
	v_mfma_f32_16x16x32_bf16 v[116:119], v[190:193], v[216:219], v[116:119]
	v_mfma_f32_16x16x32_bf16 v[108:111], v[182:185], v[224:227], v[108:111]
	v_mfma_f32_16x16x32_bf16 v[100:103], v[190:193], v[224:227], v[100:103]
	v_mfma_f32_16x16x32_bf16 v[92:95], v[182:185], v[232:235], v[92:95]
	v_mfma_f32_16x16x32_bf16 v[84:87], v[190:193], v[232:235], v[84:87]
	v_mfma_f32_16x16x32_bf16 v[76:79], v[182:185], v[240:243], v[76:79]
	v_mfma_f32_16x16x32_bf16 v[68:71], v[190:193], v[240:243], v[68:71]
	v_mfma_f32_16x16x32_bf16 v[120:123], v[194:197], v[210:213], v[120:123]
	v_mfma_f32_16x16x32_bf16 v[112:115], v[202:205], v[210:213], v[112:115]
	v_mfma_f32_16x16x32_bf16 v[104:107], v[194:197], v[220:223], v[104:107]
	v_mfma_f32_16x16x32_bf16 v[96:99], v[202:205], v[220:223], v[96:99]
	v_mfma_f32_16x16x32_bf16 v[88:91], v[194:197], v[228:231], v[88:91]
	v_mfma_f32_16x16x32_bf16 v[80:83], v[202:205], v[228:231], v[80:83]
	v_mfma_f32_16x16x32_bf16 v[72:75], v[194:197], v[236:239], v[72:75]
	v_mfma_f32_16x16x32_bf16 v[64:67], v[202:205], v[236:239], v[64:67]
	v_mfma_f32_16x16x32_bf16 v[120:123], v[198:201], v[216:219], v[120:123]
	v_mfma_f32_16x16x32_bf16 v[112:115], v[206:209], v[216:219], v[112:115]
	v_mfma_f32_16x16x32_bf16 v[104:107], v[198:201], v[224:227], v[104:107]
	v_mfma_f32_16x16x32_bf16 v[96:99], v[206:209], v[224:227], v[96:99]
	v_mfma_f32_16x16x32_bf16 v[88:91], v[198:201], v[232:235], v[88:91]
	v_mfma_f32_16x16x32_bf16 v[80:83], v[206:209], v[232:235], v[80:83]
	v_mfma_f32_16x16x32_bf16 v[72:75], v[198:201], v[240:243], v[72:75]
	v_mfma_f32_16x16x32_bf16 v[64:67], v[206:209], v[240:243], v[64:67]
	s_setprio 1
	s_barrier
	s_mov_b32 m0, s61
	v_lshl_add_u64 v[244:245], v[214:215], 0, v[138:139]
	ds_read_b128 v[210:213], v179 offset:16384
	ds_read_b128 v[216:219], v179 offset:17408
	ds_read_b128 v[220:223], v179 offset:18432
	ds_read_b128 v[224:227], v179 offset:19456
	ds_read_b128 v[228:231], v179 offset:20480
	ds_read_b128 v[232:235], v179 offset:21504
	ds_read_b128 v[236:239], v179 offset:22528
	ds_read_b128 v[240:243], v179 offset:23552
	global_load_lds_dwordx4 v[244:245], off
	v_lshl_add_u64 v[246:247], v[214:215], 0, v[134:135]
	s_mov_b32 m0, s62
	v_lshl_add_u64 v[214:215], v[214:215], 0, s[14:15]
	global_load_lds_dwordx4 v[246:247], off
	v_lshl_add_u64 v[248:249], v[214:215], 0, v[138:139]
	s_mov_b32 m0, s63
	v_lshl_add_u64 v[214:215], v[214:215], 0, v[134:135]
	global_load_lds_dwordx4 v[248:249], off
	s_add_i32 m0, s63, 0x2000
	v_lshl_add_u64 v[250:251], v[172:173], 0, v[140:141]
	global_load_lds_dwordx4 v[214:215], off
	s_mov_b32 m0, s46
	v_lshl_add_u64 v[252:253], v[172:173], 0, v[136:137]
	global_load_lds_dwordx4 v[250:251], off
	s_mov_b32 m0, s47
	s_nop 0
	global_load_lds_dwordx4 v[252:253], off
	s_waitcnt vmcnt(8) lgkmcnt(0)
	s_setprio 0
	s_barrier
; #define PG8_STAGE(bufoff, gbase, voff) do { _Pragma("unroll") for (int _i = 0; _i < 2; ++_i) \
;         __builtin_amdgcn_global_load_lds((const unsigned*)((const char*)(gbase) + (voff)[_i]), (PG8_LAS unsigned*)(lds + (bufoff) + ldsw + _i * 8192), 16, 0, 0); } while (0)
; #define PG8_LDA(dst, b, h) do { _Pragma("unroll") for (int m = 0; m < 4; ++m) _Pragma("unroll") for (int k = 0; k < 2; ++k) dst[m][k] = *(const PG8_LAS bf16x8*)(lds + PG8_SA(b, h) + aoff + m * 2048 + k * 1024); } while (0)
; #define PG8_LDB(dst, b, h) do { _Pragma("unroll") for (int n = 0; n < 2; ++n) _Pragma("unroll") for (int k = 0; k < 2; ++k) dst[n][k] = *(const PG8_LAS bf16x8*)(lds + PG8_SB(b, h) + boff + n * 2048 + k * 1024); } while (0)
; #define PG8_MMA(ai, bj, At, Bt) do { __builtin_amdgcn_s_setprio(1); _Pragma("unroll") for (int m = 0; m < 4; ++m) _Pragma("unroll") for (int n = 0; n < 2; ++n) _Pragma("unroll") for (int k = 0; k < 2; ++k) \
;         acc[ai][bj][m][n] = __builtin_amdgcn_mfma_f32_16x16x32_bf16(Bt[n][k], At[m][k], acc[ai][bj][m][n], 0, 0, 0); __builtin_amdgcn_s_setprio(0); } while (0)
; #define PG8_WAIT_V(n) asm volatile("s_waitcnt vmcnt(" #n ")" ::: "memory")
; #define PG8_WAIT_L(n) asm volatile("s_waitcnt lgkmcnt(" #n ")" ::: "memory")
; #define PG8_BAR __builtin_amdgcn_s_barrier()
; #define PG8_SCHED __builtin_amdgcn_sched_barrier(0)
; template <class Epi, class Sched, bool ALIGN_EPI = false, bool SP2 = false>
; __device__ __forceinline__ void gemm_phase(PG8_LAS unsigned char* lds, const Gemm g, const Sched& S, const Epi& E) {
;     ...
;             PG8_WAIT_V(8); PG8_WAIT_L(0); PG8_BAR; PG8_MMA(1, 0, At, B0); PG8_MMA(1, 1, At, B1); PG8_BAR; PG8_SCHED;
;             PG8_LDB(B0, 1, 0); PG8_LDB(B1, 1, 1); PG8_SCHED; PG8_LDA(At, 1, 0); PG8_STAGE(PG8_SA(0, 1), a2 + hstep, voffA);
	v_mfma_f32_16x16x32_bf16 v[60:63], v[162:165], v[210:213], v[60:63]
	v_mfma_f32_16x16x32_bf16 v[52:55], v[186:189], v[210:213], v[52:55]
	v_mfma_f32_16x16x32_bf16 v[44:47], v[162:165], v[220:223], v[44:47]
	v_mfma_f32_16x16x32_bf16 v[36:39], v[186:189], v[220:223], v[36:39]
	v_mfma_f32_16x16x32_bf16 v[28:31], v[162:165], v[228:231], v[28:31]
	v_mfma_f32_16x16x32_bf16 v[20:23], v[186:189], v[228:231], v[20:23]
	v_mfma_f32_16x16x32_bf16 v[12:15], v[162:165], v[236:239], v[12:15]
	v_mfma_f32_16x16x32_bf16 v[4:7], v[186:189], v[236:239], v[4:7]
	v_mfma_f32_16x16x32_bf16 v[60:63], v[182:185], v[216:219], v[60:63]
	v_mfma_f32_16x16x32_bf16 v[52:55], v[190:193], v[216:219], v[52:55]
	v_mfma_f32_16x16x32_bf16 v[44:47], v[182:185], v[224:227], v[44:47]
	v_mfma_f32_16x16x32_bf16 v[36:39], v[190:193], v[224:227], v[36:39]
	v_mfma_f32_16x16x32_bf16 v[28:31], v[182:185], v[232:235], v[28:31]
	v_mfma_f32_16x16x32_bf16 v[20:23], v[190:193], v[232:235], v[20:23]
	v_mfma_f32_16x16x32_bf16 v[12:15], v[182:185], v[240:243], v[12:15]
	v_mfma_f32_16x16x32_bf16 v[4:7], v[190:193], v[240:243], v[4:7]
	v_mfma_f32_16x16x32_bf16 v[56:59], v[194:197], v[210:213], v[56:59]
	v_mfma_f32_16x16x32_bf16 v[48:51], v[202:205], v[210:213], v[48:51]
	v_mfma_f32_16x16x32_bf16 v[40:43], v[194:197], v[220:223], v[40:43]
	v_mfma_f32_16x16x32_bf16 v[32:35], v[202:205], v[220:223], v[32:35]
	v_mfma_f32_16x16x32_bf16 v[24:27], v[194:197], v[228:231], v[24:27]
	v_mfma_f32_16x16x32_bf16 v[16:19], v[202:205], v[228:231], v[16:19]
	v_mfma_f32_16x16x32_bf16 v[8:11], v[194:197], v[236:239], v[8:11]
	v_mfma_f32_16x16x32_bf16 v[0:3], v[202:205], v[236:239], v[0:3]
	v_mfma_f32_16x16x32_bf16 v[56:59], v[198:201], v[216:219], v[56:59]
	v_mfma_f32_16x16x32_bf16 v[48:51], v[206:209], v[216:219], v[48:51]
	v_mfma_f32_16x16x32_bf16 v[40:43], v[198:201], v[224:227], v[40:43]
	v_mfma_f32_16x16x32_bf16 v[32:35], v[206:209], v[224:227], v[32:35]
	v_mfma_f32_16x16x32_bf16 v[24:27], v[198:201], v[232:235], v[24:27]
	v_mfma_f32_16x16x32_bf16 v[16:19], v[206:209], v[232:235], v[16:19]
	v_mfma_f32_16x16x32_bf16 v[8:11], v[198:201], v[240:243], v[8:11]
	v_mfma_f32_16x16x32_bf16 v[0:3], v[206:209], v[240:243], v[0:3]
	s_setprio 1
	s_barrier
	s_add_i32 s11, 0, 0x18000
	v_add_u32_e32 v166, s11, v169
	s_add_i32 s13, 0, 0x1c000
	ds_read_b128 v[162:165], v166
	ds_read_b128 v[182:185], v166 offset:1024
	ds_read_b128 v[186:189], v166 offset:2048
	ds_read_b128 v[190:193], v166 offset:3072
	v_add_u32_e32 v166, s13, v169
	ds_read_b128 v[194:197], v166
	ds_read_b128 v[198:201], v166 offset:1024
	ds_read_b128 v[202:205], v166 offset:2048
	ds_read_b128 v[206:209], v166 offset:3072
	v_lshl_add_u64 v[172:173], v[172:173], 0, s[14:15]
	s_mov_b32 m0, s48
	v_lshl_add_u64 v[170:171], v[172:173], 0, v[140:141]
	ds_read_b128 v[210:213], v179 offset:32768
	ds_read_b128 v[216:219], v179 offset:33792
	ds_read_b128 v[220:223], v179 offset:34816
	ds_read_b128 v[224:227], v179 offset:35840
	ds_read_b128 v[228:231], v179 offset:36864
	ds_read_b128 v[232:235], v179 offset:37888
	ds_read_b128 v[236:239], v179 offset:38912
	ds_read_b128 v[240:243], v179 offset:39936
	global_load_lds_dwordx4 v[170:171], off
	s_mov_b32 m0, s49
	v_lshl_add_u64 v[170:171], v[172:173], 0, v[136:137]
	global_load_lds_dwordx4 v[170:171], off
	s_waitcnt vmcnt(8) lgkmcnt(0)
	s_setprio 0
	s_barrier
; #define PG8_STAGE(bufoff, gbase, voff) do { _Pragma("unroll") for (int _i = 0; _i < 2; ++_i) \
;         __builtin_amdgcn_global_load_lds((const unsigned*)((const char*)(gbase) + (voff)[_i]), (PG8_LAS unsigned*)(lds + (bufoff) + ldsw + _i * 8192), 16, 0, 0); } while (0)
; #define PG8_LDA(dst, b, h) do { _Pragma("unroll") for (int m = 0; m < 4; ++m) _Pragma("unroll") for (int k = 0; k < 2; ++k) dst[m][k] = *(const PG8_LAS bf16x8*)(lds + PG8_SA(b, h) + aoff + m * 2048 + k * 1024); } while (0)
; #define PG8_MMA(ai, bj, At, Bt) do { __builtin_amdgcn_s_setprio(1); _Pragma("unroll") for (int m = 0; m < 4; ++m) _Pragma("unroll") for (int n = 0; n < 2; ++n) _Pragma("unroll") for (int k = 0; k < 2; ++k) \
;         acc[ai][bj][m][n] = __builtin_amdgcn_mfma_f32_16x16x32_bf16(Bt[n][k], At[m][k], acc[ai][bj][m][n], 0, 0, 0); __builtin_amdgcn_s_setprio(0); } while (0)
; #define PG8_WAIT_V(n) asm volatile("s_waitcnt vmcnt(" #n ")" ::: "memory")
; #define PG8_WAIT_L(n) asm volatile("s_waitcnt lgkmcnt(" #n ")" ::: "memory")
; #define PG8_BAR __builtin_amdgcn_s_barrier()
; #define PG8_SCHED __builtin_amdgcn_sched_barrier(0)
; template <class Epi, class Sched, bool ALIGN_EPI = false, bool SP2 = false>
; __device__ __forceinline__ void gemm_phase(PG8_LAS unsigned char* lds, const Gemm g, const Sched& S, const Epi& E) {
;     ...
;             PG8_WAIT_V(8); PG8_WAIT_L(0); PG8_BAR; PG8_MMA(0, 0, At, B0); PG8_MMA(0, 1, At, B1); PG8_BAR; PG8_SCHED;
;             PG8_LDA(At, 1, 1); PG8_STAGE(PG8_SB(1, 0), b3, voffB); PG8_STAGE(PG8_SB(1, 1), b3 + hstep, voffB); PG8_STAGE(PG8_SA(1, 0), a3, voffA);
;             PG8_WAIT_V(8); PG8_WAIT_L(0); PG8_BAR; PG8_MMA(1, 0, At, B0); PG8_MMA(1, 1, At, B1); PG8_BAR; PG8_SCHED;
	v_mfma_f32_16x16x32_bf16 v[124:127], v[162:165], v[210:213], v[124:127]
	v_mfma_f32_16x16x32_bf16 v[116:119], v[186:189], v[210:213], v[116:119]
	v_mfma_f32_16x16x32_bf16 v[108:111], v[162:165], v[220:223], v[108:111]
	v_mfma_f32_16x16x32_bf16 v[100:103], v[186:189], v[220:223], v[100:103]
	v_mfma_f32_16x16x32_bf16 v[92:95], v[162:165], v[228:231], v[92:95]
	v_mfma_f32_16x16x32_bf16 v[84:87], v[186:189], v[228:231], v[84:87]
	v_mfma_f32_16x16x32_bf16 v[76:79], v[162:165], v[236:239], v[76:79]
	v_mfma_f32_16x16x32_bf16 v[68:71], v[186:189], v[236:239], v[68:71]
	v_mfma_f32_16x16x32_bf16 v[124:127], v[182:185], v[216:219], v[124:127]
	v_mfma_f32_16x16x32_bf16 v[116:119], v[190:193], v[216:219], v[116:119]
	v_mfma_f32_16x16x32_bf16 v[108:111], v[182:185], v[224:227], v[108:111]
	v_mfma_f32_16x16x32_bf16 v[100:103], v[190:193], v[224:227], v[100:103]
	v_mfma_f32_16x16x32_bf16 v[92:95], v[182:185], v[232:235], v[92:95]
	v_mfma_f32_16x16x32_bf16 v[84:87], v[190:193], v[232:235], v[84:87]
	v_mfma_f32_16x16x32_bf16 v[76:79], v[182:185], v[240:243], v[76:79]
	v_mfma_f32_16x16x32_bf16 v[68:71], v[190:193], v[240:243], v[68:71]
	v_mfma_f32_16x16x32_bf16 v[120:123], v[194:197], v[210:213], v[120:123]
	v_mfma_f32_16x16x32_bf16 v[112:115], v[202:205], v[210:213], v[112:115]
	v_mfma_f32_16x16x32_bf16 v[104:107], v[194:197], v[220:223], v[104:107]
	v_mfma_f32_16x16x32_bf16 v[96:99], v[202:205], v[220:223], v[96:99]
	v_mfma_f32_16x16x32_bf16 v[88:91], v[194:197], v[228:231], v[88:91]
	v_mfma_f32_16x16x32_bf16 v[80:83], v[202:205], v[228:231], v[80:83]
	v_mfma_f32_16x16x32_bf16 v[72:75], v[194:197], v[236:239], v[72:75]
	v_mfma_f32_16x16x32_bf16 v[64:67], v[202:205], v[236:239], v[64:67]
	v_mfma_f32_16x16x32_bf16 v[120:123], v[198:201], v[216:219], v[120:123]
	v_mfma_f32_16x16x32_bf16 v[112:115], v[206:209], v[216:219], v[112:115]
	v_mfma_f32_16x16x32_bf16 v[104:107], v[198:201], v[224:227], v[104:107]
	v_mfma_f32_16x16x32_bf16 v[96:99], v[206:209], v[224:227], v[96:99]
	v_mfma_f32_16x16x32_bf16 v[88:91], v[198:201], v[232:235], v[88:91]
	v_mfma_f32_16x16x32_bf16 v[80:83], v[206:209], v[232:235], v[80:83]
	v_mfma_f32_16x16x32_bf16 v[72:75], v[198:201], v[240:243], v[72:75]
	v_mfma_f32_16x16x32_bf16 v[64:67], v[206:209], v[240:243], v[64:67]
	s_setprio 1
	s_barrier
	s_add_i32 s11, s11, s29
	s_add_i32 m0, s11, 0xffffff80
	ds_read_b128 v[210:213], v179 offset:49152
	ds_read_b128 v[216:219], v179 offset:50176
	ds_read_b128 v[220:223], v179 offset:51200
	ds_read_b128 v[224:227], v179 offset:52224
	global_load_lds_dwordx4 v[244:245], off offset:128
	s_add_i32 m0, s11, 0x1f80
	s_add_i32 s11, s13, s29
	global_load_lds_dwordx4 v[246:247], off offset:128
	s_add_i32 m0, s11, 0xffffff80
	ds_read_b128 v[240:243], v179 offset:56320
	global_load_lds_dwordx4 v[248:249], off offset:128
	s_add_i32 m0, s11, 0x1f80
	ds_read_b128 v[236:239], v179 offset:55296
	global_load_lds_dwordx4 v[214:215], off offset:128
	s_add_i32 m0, s50, 0xffffff80
	ds_read_b128 v[232:235], v179 offset:54272
	global_load_lds_dwordx4 v[250:251], off offset:128
	s_add_i32 m0, s51, 0xffffff80
	ds_read_b128 v[228:231], v179 offset:53248
	global_load_lds_dwordx4 v[252:253], off offset:128
	s_waitcnt vmcnt(8) lgkmcnt(0)
	s_setprio 0
	s_barrier
	v_mfma_f32_16x16x32_bf16 v[60:63], v[162:165], v[210:213], v[60:63]
	v_mfma_f32_16x16x32_bf16 v[52:55], v[186:189], v[210:213], v[52:55]
	v_mfma_f32_16x16x32_bf16 v[44:47], v[162:165], v[220:223], v[44:47]
	v_mfma_f32_16x16x32_bf16 v[36:39], v[186:189], v[220:223], v[36:39]
	v_mfma_f32_16x16x32_bf16 v[28:31], v[162:165], v[228:231], v[28:31]
	v_mfma_f32_16x16x32_bf16 v[20:23], v[186:189], v[228:231], v[20:23]
	v_mfma_f32_16x16x32_bf16 v[12:15], v[162:165], v[236:239], v[12:15]
	v_mfma_f32_16x16x32_bf16 v[4:7], v[186:189], v[236:239], v[4:7]
	v_mfma_f32_16x16x32_bf16 v[60:63], v[182:185], v[216:219], v[60:63]
	v_mfma_f32_16x16x32_bf16 v[52:55], v[190:193], v[216:219], v[52:55]
	v_mfma_f32_16x16x32_bf16 v[44:47], v[182:185], v[224:227], v[44:47]
	v_mfma_f32_16x16x32_bf16 v[36:39], v[190:193], v[224:227], v[36:39]
	v_mfma_f32_16x16x32_bf16 v[28:31], v[182:185], v[232:235], v[28:31]
	v_mfma_f32_16x16x32_bf16 v[20:23], v[190:193], v[232:235], v[20:23]
	v_mfma_f32_16x16x32_bf16 v[12:15], v[182:185], v[240:243], v[12:15]
	v_mfma_f32_16x16x32_bf16 v[4:7], v[190:193], v[240:243], v[4:7]
	v_mfma_f32_16x16x32_bf16 v[56:59], v[194:197], v[210:213], v[56:59]
	v_mfma_f32_16x16x32_bf16 v[48:51], v[202:205], v[210:213], v[48:51]
	v_mfma_f32_16x16x32_bf16 v[40:43], v[194:197], v[220:223], v[40:43]
	v_mfma_f32_16x16x32_bf16 v[32:35], v[202:205], v[220:223], v[32:35]
	v_mfma_f32_16x16x32_bf16 v[24:27], v[194:197], v[228:231], v[24:27]
	v_mfma_f32_16x16x32_bf16 v[16:19], v[202:205], v[228:231], v[16:19]
	v_mfma_f32_16x16x32_bf16 v[8:11], v[194:197], v[236:239], v[8:11]
	v_mfma_f32_16x16x32_bf16 v[0:3], v[202:205], v[236:239], v[0:3]
	v_mfma_f32_16x16x32_bf16 v[56:59], v[198:201], v[216:219], v[56:59]
	v_mfma_f32_16x16x32_bf16 v[48:51], v[206:209], v[216:219], v[48:51]
	v_mfma_f32_16x16x32_bf16 v[40:43], v[198:201], v[224:227], v[40:43]
	v_mfma_f32_16x16x32_bf16 v[32:35], v[206:209], v[224:227], v[32:35]
	v_mfma_f32_16x16x32_bf16 v[24:27], v[198:201], v[232:235], v[24:27]
	v_mfma_f32_16x16x32_bf16 v[16:19], v[206:209], v[232:235], v[16:19]
	v_mfma_f32_16x16x32_bf16 v[8:11], v[198:201], v[240:243], v[8:11]
	v_mfma_f32_16x16x32_bf16 v[0:3], v[206:209], v[240:243], v[0:3]
	s_setprio 1
	s_barrier
	v_lshl_add_u64 v[158:159], v[158:159], 0, s[26:27]
	s_cmp_ge_i32 s10, s52
	v_lshl_add_u64 v[160:161], v[160:161], 0, s[26:27]
	s_cbranch_scc0 .LBB0_1021
	s_setprio 0

; #define PG8_STAGE(bufoff, gbase, voff) do { _Pragma("unroll") for (int _i = 0; _i < 2; ++_i) \
;         __builtin_amdgcn_global_load_lds((const unsigned*)((const char*)(gbase) + (voff)[_i]), (PG8_LAS unsigned*)(lds + (bufoff) + ldsw + _i * 8192), 16, 0, 0); } while (0)
; #define PG8_LDA(dst, b, h) do { _Pragma("unroll") for (int m = 0; m < 4; ++m) _Pragma("unroll") for (int k = 0; k < 2; ++k) dst[m][k] = *(const PG8_LAS bf16x8*)(lds + PG8_SA(b, h) + aoff + m * 2048 + k * 1024); } while (0)
; #define PG8_LDB(dst, b, h) do { _Pragma("unroll") for (int n = 0; n < 2; ++n) _Pragma("unroll") for (int k = 0; k < 2; ++k) dst[n][k] = *(const PG8_LAS bf16x8*)(lds + PG8_SB(b, h) + boff + n * 2048 + k * 1024); } while (0)
; #define PG8_MMA(ai, bj, At, Bt) do { __builtin_amdgcn_s_setprio(1); _Pragma("unroll") for (int m = 0; m < 4; ++m) _Pragma("unroll") for (int n = 0; n < 2; ++n) _Pragma("unroll") for (int k = 0; k < 2; ++k) \
;         acc[ai][bj][m][n] = __builtin_amdgcn_mfma_f32_16x16x32_bf16(Bt[n][k], At[m][k], acc[ai][bj][m][n], 0, 0, 0); __builtin_amdgcn_s_setprio(0); } while (0)
; #define PG8_WAIT_V(n) asm volatile("s_waitcnt vmcnt(" #n ")" ::: "memory")
; #define PG8_WAIT_L(n) asm volatile("s_waitcnt lgkmcnt(" #n ")" ::: "memory")
; #define PG8_BAR __builtin_amdgcn_s_barrier()
; #define PG8_SCHED __builtin_amdgcn_sched_barrier(0)
; template <class Epi, class Sched, bool ALIGN_EPI = false, bool SP2 = false>
; __device__ __forceinline__ void gemm_phase(PG8_LAS unsigned char* lds, const Gemm g, const Sched& S, const Epi& E) {
;     ...
;             const bool last = (t == nt - 2);
;             const char* a1 = cA + (size_t)(t + 1) * kstep;
;             const char* a2 = last ? nA : cA + (size_t)(t + 2) * kstep; const char* b2 = last ? nB : cB + (size_t)(t + 2) * kstep;
;             const char* a3 = a2 + kstep; const char* b3 = b2 + kstep;
;             if (last && has_next) S.a_ready(nxt);
;             if constexpr (SP2) {
;             PG8_LDB(B0, 0, 0); PG8_LDB(B1, 0, 1); PG8_SCHED; PG8_LDA(At, 0, 0); PG8_STAGE(PG8_SA(1, 1), a1 + hstep, voffA);
;             PG8_WAIT_V(8); PG8_WAIT_L(0); PG8_BAR; PG8_MMA(0, 0, At, B0); PG8_MMA(0, 1, At, B1); PG8_BAR; PG8_SCHED;
;             PG8_LDA(At, 0, 1); PG8_STAGE(PG8_SB(0, 0), b2, voffB); PG8_STAGE(PG8_SB(0, 1), b2 + hstep, voffB); PG8_STAGE(PG8_SA(0, 0), a2, voffA);
.LBB0_1169:
	v_add_u32_e32 v192, s52, v161
	ds_read_b128 v[164:167], v162
	ds_read_b128 v[168:171], v162 offset:1024
	ds_read_b128 v[172:175], v162 offset:2048
	ds_read_b128 v[176:179], v162 offset:3072
	ds_read_b128 v[180:183], v192
	ds_read_b128 v[184:187], v192 offset:1024
	ds_read_b128 v[188:191], v192 offset:2048
	ds_read_b128 v[192:195], v192 offset:3072
	s_cmp_eq_u32 s51, s10
	v_lshl_add_u64 v[196:197], v[158:159], 0, s[24:25]
	s_cselect_b64 vcc, -1, 0
	s_add_i32 s10, s10, 2
	v_cndmask_b32_e32 v213, v197, v151, vcc
	v_cndmask_b32_e32 v212, v196, v150, vcc
	v_cndmask_b32_e32 v215, v155, v153, vcc
	v_cndmask_b32_e32 v214, v154, v152, vcc
	s_mov_b32 m0, s54
	v_lshl_add_u64 v[232:233], v[158:159], 0, v[146:147]
	ds_read_b128 v[196:199], v163
	ds_read_b128 v[200:203], v163 offset:1024
	ds_read_b128 v[204:207], v163 offset:2048
	ds_read_b128 v[208:211], v163 offset:3072
	ds_read_b128 v[216:219], v163 offset:4096
	ds_read_b128 v[220:223], v163 offset:5120
	ds_read_b128 v[224:227], v163 offset:6144
	ds_read_b128 v[228:231], v163 offset:7168
	global_load_lds_dwordx4 v[232:233], off
	s_mov_b32 m0, s55
	v_lshl_add_u64 v[232:233], v[158:159], 0, v[144:145]
	global_load_lds_dwordx4 v[232:233], off
	s_waitcnt vmcnt(8) lgkmcnt(0)
	s_setprio 0
	s_barrier
	v_mfma_f32_16x16x32_bf16 v[124:127], v[164:167], v[196:199], v[124:127]
	v_mfma_f32_16x16x32_bf16 v[120:123], v[172:175], v[196:199], v[120:123]
	v_mfma_f32_16x16x32_bf16 v[108:111], v[164:167], v[204:207], v[108:111]
	v_mfma_f32_16x16x32_bf16 v[104:107], v[172:175], v[204:207], v[104:107]
	v_mfma_f32_16x16x32_bf16 v[92:95], v[164:167], v[216:219], v[92:95]
	v_mfma_f32_16x16x32_bf16 v[88:91], v[172:175], v[216:219], v[88:91]
	v_mfma_f32_16x16x32_bf16 v[76:79], v[164:167], v[224:227], v[76:79]
	v_mfma_f32_16x16x32_bf16 v[72:75], v[172:175], v[224:227], v[72:75]
	v_mfma_f32_16x16x32_bf16 v[124:127], v[168:171], v[200:203], v[124:127]
	v_mfma_f32_16x16x32_bf16 v[120:123], v[176:179], v[200:203], v[120:123]
	v_mfma_f32_16x16x32_bf16 v[108:111], v[168:171], v[208:211], v[108:111]
	v_mfma_f32_16x16x32_bf16 v[104:107], v[176:179], v[208:211], v[104:107]
	v_mfma_f32_16x16x32_bf16 v[92:95], v[168:171], v[220:223], v[92:95]
	v_mfma_f32_16x16x32_bf16 v[88:91], v[176:179], v[220:223], v[88:91]
	v_mfma_f32_16x16x32_bf16 v[76:79], v[168:171], v[228:231], v[76:79]
	v_mfma_f32_16x16x32_bf16 v[72:75], v[176:179], v[228:231], v[72:75]
	v_mfma_f32_16x16x32_bf16 v[116:119], v[180:183], v[196:199], v[116:119]
	v_mfma_f32_16x16x32_bf16 v[112:115], v[188:191], v[196:199], v[112:115]
	v_mfma_f32_16x16x32_bf16 v[100:103], v[180:183], v[204:207], v[100:103]
	v_mfma_f32_16x16x32_bf16 v[96:99], v[188:191], v[204:207], v[96:99]
	v_mfma_f32_16x16x32_bf16 v[84:87], v[180:183], v[216:219], v[84:87]
	v_mfma_f32_16x16x32_bf16 v[80:83], v[188:191], v[216:219], v[80:83]
	v_mfma_f32_16x16x32_bf16 v[68:71], v[180:183], v[224:227], v[68:71]
	v_mfma_f32_16x16x32_bf16 v[64:67], v[188:191], v[224:227], v[64:67]
	v_mfma_f32_16x16x32_bf16 v[116:119], v[184:187], v[200:203], v[116:119]
	v_mfma_f32_16x16x32_bf16 v[112:115], v[192:195], v[200:203], v[112:115]
	v_mfma_f32_16x16x32_bf16 v[100:103], v[184:187], v[208:211], v[100:103]
	v_mfma_f32_16x16x32_bf16 v[96:99], v[192:195], v[208:211], v[96:99]
	v_mfma_f32_16x16x32_bf16 v[84:87], v[184:187], v[220:223], v[84:87]
	v_mfma_f32_16x16x32_bf16 v[80:83], v[192:195], v[220:223], v[80:83]
	v_mfma_f32_16x16x32_bf16 v[68:71], v[184:187], v[228:231], v[68:71]
	v_mfma_f32_16x16x32_bf16 v[64:67], v[192:195], v[228:231], v[64:67]
	s_setprio 1
	s_barrier
	s_mov_b32 m0, s56
	v_lshl_add_u64 v[232:233], v[214:215], 0, v[138:139]
	ds_read_b128 v[196:199], v163 offset:16384
	ds_read_b128 v[200:203], v163 offset:17408
	ds_read_b128 v[204:207], v163 offset:18432
	ds_read_b128 v[208:211], v163 offset:19456
	ds_read_b128 v[216:219], v163 offset:20480
	ds_read_b128 v[220:223], v163 offset:21504
	ds_read_b128 v[224:227], v163 offset:22528
	ds_read_b128 v[228:231], v163 offset:23552
	global_load_lds_dwordx4 v[232:233], off
	v_lshl_add_u64 v[234:235], v[214:215], 0, v[134:135]
	s_mov_b32 m0, s57
	v_lshl_add_u64 v[214:215], v[214:215], 0, s[14:15]
	global_load_lds_dwordx4 v[234:235], off
	v_lshl_add_u64 v[236:237], v[214:215], 0, v[138:139]
	s_mov_b32 m0, s58
	v_lshl_add_u64 v[214:215], v[214:215], 0, v[134:135]
	global_load_lds_dwordx4 v[236:237], off
	s_mov_b32 m0, s59
	v_lshl_add_u64 v[238:239], v[212:213], 0, v[140:141]
	global_load_lds_dwordx4 v[214:215], off
	s_mov_b32 m0, s37
	v_lshl_add_u64 v[240:241], v[212:213], 0, v[136:137]
	global_load_lds_dwordx4 v[238:239], off
	s_mov_b32 m0, s41
	s_nop 0
	global_load_lds_dwordx4 v[240:241], off
	s_waitcnt vmcnt(8) lgkmcnt(0)
	s_setprio 0
	s_barrier
; #define PG8_STAGE(bufoff, gbase, voff) do { _Pragma("unroll") for (int _i = 0; _i < 2; ++_i) \
;         __builtin_amdgcn_global_load_lds((const unsigned*)((const char*)(gbase) + (voff)[_i]), (PG8_LAS unsigned*)(lds + (bufoff) + ldsw + _i * 8192), 16, 0, 0); } while (0)
; #define PG8_LDA(dst, b, h) do { _Pragma("unroll") for (int m = 0; m < 4; ++m) _Pragma("unroll") for (int k = 0; k < 2; ++k) dst[m][k] = *(const PG8_LAS bf16x8*)(lds + PG8_SA(b, h) + aoff + m * 2048 + k * 1024); } while (0)
; #define PG8_LDB(dst, b, h) do { _Pragma("unroll") for (int n = 0; n < 2; ++n) _Pragma("unroll") for (int k = 0; k < 2; ++k) dst[n][k] = *(const PG8_LAS bf16x8*)(lds + PG8_SB(b, h) + boff + n * 2048 + k * 1024); } while (0)
; #define PG8_MMA(ai, bj, At, Bt) do { __builtin_amdgcn_s_setprio(1); _Pragma("unroll") for (int m = 0; m < 4; ++m) _Pragma("unroll") for (int n = 0; n < 2; ++n) _Pragma("unroll") for (int k = 0; k < 2; ++k) \
;         acc[ai][bj][m][n] = __builtin_amdgcn_mfma_f32_16x16x32_bf16(Bt[n][k], At[m][k], acc[ai][bj][m][n], 0, 0, 0); __builtin_amdgcn_s_setprio(0); } while (0)
; #define PG8_WAIT_V(n) asm volatile("s_waitcnt vmcnt(" #n ")" ::: "memory")
; #define PG8_WAIT_L(n) asm volatile("s_waitcnt lgkmcnt(" #n ")" ::: "memory")
; #define PG8_BAR __builtin_amdgcn_s_barrier()
; #define PG8_SCHED __builtin_amdgcn_sched_barrier(0)
; template <class Epi, class Sched, bool ALIGN_EPI = false, bool SP2 = false>
; __device__ __forceinline__ void gemm_phase(PG8_LAS unsigned char* lds, const Gemm g, const Sched& S, const Epi& E) {
;     ...
;             PG8_WAIT_V(8); PG8_WAIT_L(0); PG8_BAR; PG8_MMA(0, 0, At, B0); PG8_MMA(0, 1, At, B1); PG8_BAR; PG8_SCHED;
;             PG8_LDA(At, 0, 1); PG8_STAGE(PG8_SB(0, 0), b2, voffB); PG8_STAGE(PG8_SB(0, 1), b2 + hstep, voffB); PG8_STAGE(PG8_SA(0, 0), a2, voffA);
;             PG8_WAIT_V(8); PG8_WAIT_L(0); PG8_BAR; PG8_MMA(1, 0, At, B0); PG8_MMA(1, 1, At, B1); PG8_BAR; PG8_SCHED;
;             PG8_LDB(B0, 1, 0); PG8_LDB(B1, 1, 1); PG8_SCHED; PG8_LDA(At, 1, 0); PG8_STAGE(PG8_SA(0, 1), a2 + hstep, voffA);
;             PG8_WAIT_V(8); PG8_WAIT_L(0); PG8_BAR; PG8_MMA(0, 0, At, B0); PG8_MMA(0, 1, At, B1); PG8_BAR; PG8_SCHED;
	v_mfma_f32_16x16x32_bf16 v[60:63], v[164:167], v[196:199], v[60:63]
	v_mfma_f32_16x16x32_bf16 v[56:59], v[172:175], v[196:199], v[56:59]
	v_mfma_f32_16x16x32_bf16 v[44:47], v[164:167], v[204:207], v[44:47]
	v_mfma_f32_16x16x32_bf16 v[40:43], v[172:175], v[204:207], v[40:43]
	v_mfma_f32_16x16x32_bf16 v[28:31], v[164:167], v[216:219], v[28:31]
	v_mfma_f32_16x16x32_bf16 v[24:27], v[172:175], v[216:219], v[24:27]
	v_mfma_f32_16x16x32_bf16 v[12:15], v[164:167], v[224:227], v[12:15]
	v_mfma_f32_16x16x32_bf16 v[8:11], v[172:175], v[224:227], v[8:11]
	v_mfma_f32_16x16x32_bf16 v[60:63], v[168:171], v[200:203], v[60:63]
	v_mfma_f32_16x16x32_bf16 v[56:59], v[176:179], v[200:203], v[56:59]
	v_mfma_f32_16x16x32_bf16 v[44:47], v[168:171], v[208:211], v[44:47]
	v_mfma_f32_16x16x32_bf16 v[40:43], v[176:179], v[208:211], v[40:43]
	v_mfma_f32_16x16x32_bf16 v[28:31], v[168:171], v[220:223], v[28:31]
	v_mfma_f32_16x16x32_bf16 v[24:27], v[176:179], v[220:223], v[24:27]
	v_mfma_f32_16x16x32_bf16 v[12:15], v[168:171], v[228:231], v[12:15]
	v_mfma_f32_16x16x32_bf16 v[8:11], v[176:179], v[228:231], v[8:11]
	v_mfma_f32_16x16x32_bf16 v[52:55], v[180:183], v[196:199], v[52:55]
	v_mfma_f32_16x16x32_bf16 v[48:51], v[188:191], v[196:199], v[48:51]
	v_mfma_f32_16x16x32_bf16 v[36:39], v[180:183], v[204:207], v[36:39]
	v_mfma_f32_16x16x32_bf16 v[32:35], v[188:191], v[204:207], v[32:35]
	v_mfma_f32_16x16x32_bf16 v[20:23], v[180:183], v[216:219], v[20:23]
	v_mfma_f32_16x16x32_bf16 v[16:19], v[188:191], v[216:219], v[16:19]
	v_mfma_f32_16x16x32_bf16 v[4:7], v[180:183], v[224:227], v[4:7]
	v_mfma_f32_16x16x32_bf16 v[0:3], v[188:191], v[224:227], v[0:3]
	v_mfma_f32_16x16x32_bf16 v[52:55], v[184:187], v[200:203], v[52:55]
	v_mfma_f32_16x16x32_bf16 v[48:51], v[192:195], v[200:203], v[48:51]
	v_mfma_f32_16x16x32_bf16 v[36:39], v[184:187], v[208:211], v[36:39]
	v_mfma_f32_16x16x32_bf16 v[32:35], v[192:195], v[208:211], v[32:35]
	v_mfma_f32_16x16x32_bf16 v[20:23], v[184:187], v[220:223], v[20:23]
	v_mfma_f32_16x16x32_bf16 v[16:19], v[192:195], v[220:223], v[16:19]
	v_mfma_f32_16x16x32_bf16 v[4:7], v[184:187], v[228:231], v[4:7]
	v_mfma_f32_16x16x32_bf16 v[0:3], v[192:195], v[228:231], v[0:3]
	s_setprio 1
	s_barrier
	v_add_u32_e32 v176, s60, v161
	v_add_u32_e32 v192, s61, v161
	ds_read_b128 v[164:167], v176
	ds_read_b128 v[168:171], v176 offset:1024
	ds_read_b128 v[172:175], v176 offset:2048
	ds_read_b128 v[176:179], v176 offset:3072
	ds_read_b128 v[180:183], v192
	ds_read_b128 v[184:187], v192 offset:1024
	ds_read_b128 v[188:191], v192 offset:2048
	ds_read_b128 v[192:195], v192 offset:3072
	v_lshl_add_u64 v[212:213], v[212:213], 0, s[14:15]
	s_mov_b32 m0, s46
	v_lshl_add_u64 v[242:243], v[212:213], 0, v[140:141]
	ds_read_b128 v[196:199], v163 offset:32768
	ds_read_b128 v[200:203], v163 offset:33792
	ds_read_b128 v[204:207], v163 offset:34816
	ds_read_b128 v[208:211], v163 offset:35840
	ds_read_b128 v[216:219], v163 offset:36864
	ds_read_b128 v[220:223], v163 offset:37888
	ds_read_b128 v[224:227], v163 offset:38912
	ds_read_b128 v[228:231], v163 offset:39936
	global_load_lds_dwordx4 v[242:243], off
	s_mov_b32 m0, s47
	v_lshl_add_u64 v[212:213], v[212:213], 0, v[136:137]
	global_load_lds_dwordx4 v[212:213], off
	s_waitcnt vmcnt(8) lgkmcnt(0)
	s_setprio 0
	s_barrier
	v_mfma_f32_16x16x32_bf16 v[124:127], v[164:167], v[196:199], v[124:127]
	v_mfma_f32_16x16x32_bf16 v[120:123], v[172:175], v[196:199], v[120:123]
	v_mfma_f32_16x16x32_bf16 v[108:111], v[164:167], v[204:207], v[108:111]
	v_mfma_f32_16x16x32_bf16 v[104:107], v[172:175], v[204:207], v[104:107]
	v_mfma_f32_16x16x32_bf16 v[92:95], v[164:167], v[216:219], v[92:95]
	v_mfma_f32_16x16x32_bf16 v[88:91], v[172:175], v[216:219], v[88:91]
	v_mfma_f32_16x16x32_bf16 v[76:79], v[164:167], v[224:227], v[76:79]
	v_mfma_f32_16x16x32_bf16 v[72:75], v[172:175], v[224:227], v[72:75]
	v_mfma_f32_16x16x32_bf16 v[124:127], v[168:171], v[200:203], v[124:127]
	v_mfma_f32_16x16x32_bf16 v[120:123], v[176:179], v[200:203], v[120:123]
	v_mfma_f32_16x16x32_bf16 v[108:111], v[168:171], v[208:211], v[108:111]
	v_mfma_f32_16x16x32_bf16 v[104:107], v[176:179], v[208:211], v[104:107]
	v_mfma_f32_16x16x32_bf16 v[92:95], v[168:171], v[220:223], v[92:95]
	v_mfma_f32_16x16x32_bf16 v[88:91], v[176:179], v[220:223], v[88:91]
	v_mfma_f32_16x16x32_bf16 v[76:79], v[168:171], v[228:231], v[76:79]
	v_mfma_f32_16x16x32_bf16 v[72:75], v[176:179], v[228:231], v[72:75]
	v_mfma_f32_16x16x32_bf16 v[116:119], v[180:183], v[196:199], v[116:119]
	v_mfma_f32_16x16x32_bf16 v[112:115], v[188:191], v[196:199], v[112:115]
	v_mfma_f32_16x16x32_bf16 v[100:103], v[180:183], v[204:207], v[100:103]
	v_mfma_f32_16x16x32_bf16 v[96:99], v[188:191], v[204:207], v[96:99]
	v_mfma_f32_16x16x32_bf16 v[84:87], v[180:183], v[216:219], v[84:87]
	v_mfma_f32_16x16x32_bf16 v[80:83], v[188:191], v[216:219], v[80:83]
	v_mfma_f32_16x16x32_bf16 v[68:71], v[180:183], v[224:227], v[68:71]
	v_mfma_f32_16x16x32_bf16 v[64:67], v[188:191], v[224:227], v[64:67]
	v_mfma_f32_16x16x32_bf16 v[116:119], v[184:187], v[200:203], v[116:119]
	v_mfma_f32_16x16x32_bf16 v[112:115], v[192:195], v[200:203], v[112:115]
	v_mfma_f32_16x16x32_bf16 v[100:103], v[184:187], v[208:211], v[100:103]
	v_mfma_f32_16x16x32_bf16 v[96:99], v[192:195], v[208:211], v[96:99]
	v_mfma_f32_16x16x32_bf16 v[84:87], v[184:187], v[220:223], v[84:87]
	v_mfma_f32_16x16x32_bf16 v[80:83], v[192:195], v[220:223], v[80:83]
	v_mfma_f32_16x16x32_bf16 v[68:71], v[184:187], v[228:231], v[68:71]
	v_mfma_f32_16x16x32_bf16 v[64:67], v[192:195], v[228:231], v[64:67]
	s_setprio 1
	s_barrier
; #define PG8_STAGE(bufoff, gbase, voff) do { _Pragma("unroll") for (int _i = 0; _i < 2; ++_i) \
;         __builtin_amdgcn_global_load_lds((const unsigned*)((const char*)(gbase) + (voff)[_i]), (PG8_LAS unsigned*)(lds + (bufoff) + ldsw + _i * 8192), 16, 0, 0); } while (0)
; #define PG8_LDA(dst, b, h) do { _Pragma("unroll") for (int m = 0; m < 4; ++m) _Pragma("unroll") for (int k = 0; k < 2; ++k) dst[m][k] = *(const PG8_LAS bf16x8*)(lds + PG8_SA(b, h) + aoff + m * 2048 + k * 1024); } while (0)
; #define PG8_MMA(ai, bj, At, Bt) do { __builtin_amdgcn_s_setprio(1); _Pragma("unroll") for (int m = 0; m < 4; ++m) _Pragma("unroll") for (int n = 0; n < 2; ++n) _Pragma("unroll") for (int k = 0; k < 2; ++k) \
;         acc[ai][bj][m][n] = __builtin_amdgcn_mfma_f32_16x16x32_bf16(Bt[n][k], At[m][k], acc[ai][bj][m][n], 0, 0, 0); __builtin_amdgcn_s_setprio(0); } while (0)
; #define PG8_WAIT_V(n) asm volatile("s_waitcnt vmcnt(" #n ")" ::: "memory")
; #define PG8_WAIT_L(n) asm volatile("s_waitcnt lgkmcnt(" #n ")" ::: "memory")
; #define PG8_BAR __builtin_amdgcn_s_barrier()
; #define PG8_SCHED __builtin_amdgcn_sched_barrier(0)
; template <class Epi, class Sched, bool ALIGN_EPI = false, bool SP2 = false>
; __device__ __forceinline__ void gemm_phase(PG8_LAS unsigned char* lds, const Gemm g, const Sched& S, const Epi& E) {
;     ...
;             PG8_LDA(At, 1, 1); PG8_STAGE(PG8_SB(1, 0), b3, voffB); PG8_STAGE(PG8_SB(1, 1), b3 + hstep, voffB); PG8_STAGE(PG8_SA(1, 0), a3, voffA);
;             PG8_WAIT_V(8); PG8_WAIT_L(0); PG8_BAR; PG8_MMA(1, 0, At, B0); PG8_MMA(1, 1, At, B1); PG8_BAR; PG8_SCHED;
	s_add_i32 m0, s62, 0xffffff80
	ds_read_b128 v[196:199], v163 offset:49152
	ds_read_b128 v[200:203], v163 offset:50176
	ds_read_b128 v[204:207], v163 offset:51200
	global_load_lds_dwordx4 v[232:233], off offset:128
	s_add_i32 m0, s63, 0xffffff80
	ds_read_b128 v[228:231], v163 offset:56320
	global_load_lds_dwordx4 v[234:235], off offset:128
	s_add_i32 m0, s64, 0xffffff80
	ds_read_b128 v[224:227], v163 offset:55296
	global_load_lds_dwordx4 v[236:237], off offset:128
	s_add_i32 m0, s65, 0xffffff80
	ds_read_b128 v[220:223], v163 offset:54272
	global_load_lds_dwordx4 v[214:215], off offset:128
	s_add_i32 m0, s48, 0xffffff80
	ds_read_b128 v[216:219], v163 offset:53248
	global_load_lds_dwordx4 v[238:239], off offset:128
	s_add_i32 m0, s49, 0xffffff80
	ds_read_b128 v[208:211], v163 offset:52224
	global_load_lds_dwordx4 v[240:241], off offset:128
	s_waitcnt vmcnt(8) lgkmcnt(0)
	s_setprio 0
	s_barrier
	v_mfma_f32_16x16x32_bf16 v[60:63], v[164:167], v[196:199], v[60:63]
	v_mfma_f32_16x16x32_bf16 v[56:59], v[172:175], v[196:199], v[56:59]
	v_mfma_f32_16x16x32_bf16 v[44:47], v[164:167], v[204:207], v[44:47]
	v_mfma_f32_16x16x32_bf16 v[40:43], v[172:175], v[204:207], v[40:43]
	v_mfma_f32_16x16x32_bf16 v[28:31], v[164:167], v[216:219], v[28:31]
	v_mfma_f32_16x16x32_bf16 v[24:27], v[172:175], v[216:219], v[24:27]
	v_mfma_f32_16x16x32_bf16 v[12:15], v[164:167], v[224:227], v[12:15]
	v_mfma_f32_16x16x32_bf16 v[8:11], v[172:175], v[224:227], v[8:11]
	v_mfma_f32_16x16x32_bf16 v[60:63], v[168:171], v[200:203], v[60:63]
	v_mfma_f32_16x16x32_bf16 v[56:59], v[176:179], v[200:203], v[56:59]
	v_mfma_f32_16x16x32_bf16 v[44:47], v[168:171], v[208:211], v[44:47]
	v_mfma_f32_16x16x32_bf16 v[40:43], v[176:179], v[208:211], v[40:43]
	v_mfma_f32_16x16x32_bf16 v[28:31], v[168:171], v[220:223], v[28:31]
	v_mfma_f32_16x16x32_bf16 v[24:27], v[176:179], v[220:223], v[24:27]
	v_mfma_f32_16x16x32_bf16 v[12:15], v[168:171], v[228:231], v[12:15]
	v_mfma_f32_16x16x32_bf16 v[8:11], v[176:179], v[228:231], v[8:11]
	v_mfma_f32_16x16x32_bf16 v[52:55], v[180:183], v[196:199], v[52:55]
	v_mfma_f32_16x16x32_bf16 v[48:51], v[188:191], v[196:199], v[48:51]
	v_mfma_f32_16x16x32_bf16 v[36:39], v[180:183], v[204:207], v[36:39]
	v_mfma_f32_16x16x32_bf16 v[32:35], v[188:191], v[204:207], v[32:35]
	v_mfma_f32_16x16x32_bf16 v[20:23], v[180:183], v[216:219], v[20:23]
	v_mfma_f32_16x16x32_bf16 v[16:19], v[188:191], v[216:219], v[16:19]
	v_mfma_f32_16x16x32_bf16 v[4:7], v[180:183], v[224:227], v[4:7]
	v_mfma_f32_16x16x32_bf16 v[0:3], v[188:191], v[224:227], v[0:3]
	v_mfma_f32_16x16x32_bf16 v[52:55], v[184:187], v[200:203], v[52:55]
	v_mfma_f32_16x16x32_bf16 v[48:51], v[192:195], v[200:203], v[48:51]
	v_mfma_f32_16x16x32_bf16 v[36:39], v[184:187], v[208:211], v[36:39]
	v_mfma_f32_16x16x32_bf16 v[32:35], v[192:195], v[208:211], v[32:35]
	v_mfma_f32_16x16x32_bf16 v[20:23], v[184:187], v[220:223], v[20:23]
	v_mfma_f32_16x16x32_bf16 v[16:19], v[192:195], v[220:223], v[16:19]
	v_mfma_f32_16x16x32_bf16 v[4:7], v[184:187], v[228:231], v[4:7]
	v_mfma_f32_16x16x32_bf16 v[0:3], v[192:195], v[228:231], v[0:3]
	s_setprio 1
	s_barrier
	v_lshl_add_u64 v[154:155], v[154:155], 0, s[28:29]
	s_cmp_ge_i32 s10, s50
	v_lshl_add_u64 v[158:159], v[158:159], 0, s[28:29]
	s_cbranch_scc0 .LBB0_1169
	s_setprio 0

; #define PG8_STAGE(bufoff, gbase, voff) do { _Pragma("unroll") for (int _i = 0; _i < 2; ++_i) \
;         __builtin_amdgcn_global_load_lds((const unsigned*)((const char*)(gbase) + (voff)[_i]), (PG8_LAS unsigned*)(lds + (bufoff) + ldsw + _i * 8192), 16, 0, 0); } while (0)
; #define PG8_LDA(dst, b, h) do { _Pragma("unroll") for (int m = 0; m < 4; ++m) _Pragma("unroll") for (int k = 0; k < 2; ++k) dst[m][k] = *(const PG8_LAS bf16x8*)(lds + PG8_SA(b, h) + aoff + m * 2048 + k * 1024); } while (0)
; #define PG8_LDB(dst, b, h) do { _Pragma("unroll") for (int n = 0; n < 2; ++n) _Pragma("unroll") for (int k = 0; k < 2; ++k) dst[n][k] = *(const PG8_LAS bf16x8*)(lds + PG8_SB(b, h) + boff + n * 2048 + k * 1024); } while (0)
; #define PG8_MMA(ai, bj, At, Bt) do { __builtin_amdgcn_s_setprio(1); _Pragma("unroll") for (int m = 0; m < 4; ++m) _Pragma("unroll") for (int n = 0; n < 2; ++n) _Pragma("unroll") for (int k = 0; k < 2; ++k) \
;         acc[ai][bj][m][n] = __builtin_amdgcn_mfma_f32_16x16x32_bf16(Bt[n][k], At[m][k], acc[ai][bj][m][n], 0, 0, 0); __builtin_amdgcn_s_setprio(0); } while (0)
; #define PG8_WAIT_V(n) asm volatile("s_waitcnt vmcnt(" #n ")" ::: "memory")
; #define PG8_WAIT_L(n) asm volatile("s_waitcnt lgkmcnt(" #n ")" ::: "memory")
; #define PG8_BAR __builtin_amdgcn_s_barrier()
; #define PG8_SCHED __builtin_amdgcn_sched_barrier(0)
; template <class Epi, class Sched, bool ALIGN_EPI = false, bool SP2 = false>
; __device__ __forceinline__ void gemm_phase(PG8_LAS unsigned char* lds, const Gemm g, const Sched& S, const Epi& E) {
;     ...
;             const bool last = (t == nt - 2);
;             const char* a1 = cA + (size_t)(t + 1) * kstep;
;             const char* a2 = last ? nA : cA + (size_t)(t + 2) * kstep; const char* b2 = last ? nB : cB + (size_t)(t + 2) * kstep;
;             const char* a3 = a2 + kstep; const char* b3 = b2 + kstep;
;             if (last && has_next) S.a_ready(nxt);
;             if constexpr (SP2) {
;             PG8_LDB(B0, 0, 0); PG8_LDB(B1, 0, 1); PG8_SCHED; PG8_LDA(At, 0, 0); PG8_STAGE(PG8_SA(1, 1), a1 + hstep, voffA);
;             PG8_WAIT_V(8); PG8_WAIT_L(0); PG8_BAR; PG8_MMA(0, 0, At, B0); PG8_MMA(0, 1, At, B1); PG8_BAR; PG8_SCHED;
;             PG8_LDA(At, 0, 1); PG8_STAGE(PG8_SB(0, 0), b2, voffB); PG8_STAGE(PG8_SB(0, 1), b2 + hstep, voffB); PG8_STAGE(PG8_SA(0, 0), a2, voffA);
.LBB0_1192:
	v_add_u32_e32 v178, s56, v216
	v_add_u32_e32 v194, s57, v216
	ds_read_b128 v[138:141], v178
	ds_read_b128 v[142:145], v178 offset:1024
	ds_read_b128 v[146:149], v178 offset:2048
	ds_read_b128 v[178:181], v178 offset:3072
	ds_read_b128 v[182:185], v194
	ds_read_b128 v[186:189], v194 offset:1024
	ds_read_b128 v[190:193], v194 offset:2048
	ds_read_b128 v[194:197], v194 offset:3072
	s_cmp_eq_u32 s49, s10
	v_lshl_add_u64 v[198:199], v[136:137], 0, s[20:21]
	s_cselect_b64 vcc, -1, 0
	s_add_i32 s10, s10, 2
	v_cndmask_b32_e32 v215, v199, v175, vcc
	v_cndmask_b32_e32 v214, v198, v174, vcc
	v_cndmask_b32_e32 v237, v135, v177, vcc
	v_cndmask_b32_e32 v236, v134, v176, vcc
	v_lshl_add_u64 v[238:239], v[136:137], 0, v[168:169]
	s_add_i32 m0, s34, 0xc000
	ds_read_b128 v[198:201], v218
	ds_read_b128 v[202:205], v218 offset:1024
	ds_read_b128 v[206:209], v218 offset:2048
	ds_read_b128 v[210:213], v218 offset:3072
	ds_read_b128 v[220:223], v218 offset:4096
	ds_read_b128 v[224:227], v218 offset:5120
	ds_read_b128 v[228:231], v218 offset:6144
	ds_read_b128 v[232:235], v218 offset:7168
	global_load_lds_dwordx4 v[238:239], off
	s_add_i32 m0, s34, 0xe000
	v_lshl_add_u64 v[238:239], v[136:137], 0, v[166:167]
	global_load_lds_dwordx4 v[238:239], off
	s_waitcnt vmcnt(8) lgkmcnt(0)
	s_setprio 0
	s_barrier
	v_mfma_f32_16x16x32_bf16 v[130:133], v[138:141], v[198:201], v[130:133]
	v_mfma_f32_16x16x32_bf16 v[126:129], v[146:149], v[198:201], v[126:129]
	v_mfma_f32_16x16x32_bf16 v[114:117], v[138:141], v[206:209], v[114:117]
	v_mfma_f32_16x16x32_bf16 v[110:113], v[146:149], v[206:209], v[110:113]
	v_mfma_f32_16x16x32_bf16 v[98:101], v[138:141], v[220:223], v[98:101]
	v_mfma_f32_16x16x32_bf16 v[94:97], v[146:149], v[220:223], v[94:97]
	v_mfma_f32_16x16x32_bf16 v[82:85], v[138:141], v[228:231], v[82:85]
	v_mfma_f32_16x16x32_bf16 v[78:81], v[146:149], v[228:231], v[78:81]
	v_mfma_f32_16x16x32_bf16 v[130:133], v[142:145], v[202:205], v[130:133]
	v_mfma_f32_16x16x32_bf16 v[126:129], v[178:181], v[202:205], v[126:129]
	v_mfma_f32_16x16x32_bf16 v[114:117], v[142:145], v[210:213], v[114:117]
	v_mfma_f32_16x16x32_bf16 v[110:113], v[178:181], v[210:213], v[110:113]
	v_mfma_f32_16x16x32_bf16 v[98:101], v[142:145], v[224:227], v[98:101]
	v_mfma_f32_16x16x32_bf16 v[94:97], v[178:181], v[224:227], v[94:97]
	v_mfma_f32_16x16x32_bf16 v[82:85], v[142:145], v[232:235], v[82:85]
	v_mfma_f32_16x16x32_bf16 v[78:81], v[178:181], v[232:235], v[78:81]
	v_mfma_f32_16x16x32_bf16 v[122:125], v[182:185], v[198:201], v[122:125]
	v_mfma_f32_16x16x32_bf16 v[118:121], v[190:193], v[198:201], v[118:121]
	v_mfma_f32_16x16x32_bf16 v[106:109], v[182:185], v[206:209], v[106:109]
	v_mfma_f32_16x16x32_bf16 v[102:105], v[190:193], v[206:209], v[102:105]
	v_mfma_f32_16x16x32_bf16 v[90:93], v[182:185], v[220:223], v[90:93]
	v_mfma_f32_16x16x32_bf16 v[86:89], v[190:193], v[220:223], v[86:89]
	v_mfma_f32_16x16x32_bf16 v[74:77], v[182:185], v[228:231], v[74:77]
	v_mfma_f32_16x16x32_bf16 v[70:73], v[190:193], v[228:231], v[70:73]
	v_mfma_f32_16x16x32_bf16 v[122:125], v[186:189], v[202:205], v[122:125]
	v_mfma_f32_16x16x32_bf16 v[118:121], v[194:197], v[202:205], v[118:121]
	v_mfma_f32_16x16x32_bf16 v[106:109], v[186:189], v[210:213], v[106:109]
	v_mfma_f32_16x16x32_bf16 v[102:105], v[194:197], v[210:213], v[102:105]
	v_mfma_f32_16x16x32_bf16 v[90:93], v[186:189], v[224:227], v[90:93]
	v_mfma_f32_16x16x32_bf16 v[86:89], v[194:197], v[224:227], v[86:89]
	v_mfma_f32_16x16x32_bf16 v[74:77], v[186:189], v[232:235], v[74:77]
	v_mfma_f32_16x16x32_bf16 v[70:73], v[194:197], v[232:235], v[70:73]
	s_setprio 1
	s_barrier
	s_add_i32 s11, s56, s29
	v_lshl_add_u64 v[238:239], v[236:237], 0, v[158:159]
	s_mov_b32 m0, s11
	ds_read_b128 v[198:201], v218 offset:16384
	ds_read_b128 v[202:205], v218 offset:17408
	ds_read_b128 v[206:209], v218 offset:18432
	ds_read_b128 v[210:213], v218 offset:19456
	ds_read_b128 v[220:223], v218 offset:20480
	ds_read_b128 v[224:227], v218 offset:21504
	ds_read_b128 v[228:231], v218 offset:22528
	ds_read_b128 v[232:235], v218 offset:23552
	global_load_lds_dwordx4 v[238:239], off
	v_lshl_add_u64 v[240:241], v[236:237], 0, v[162:163]
	s_add_i32 m0, s11, 0x2000
	v_lshl_add_u64 v[236:237], v[236:237], 0, s[12:13]
	s_add_i32 s11, s57, s29
	global_load_lds_dwordx4 v[240:241], off
	v_lshl_add_u64 v[242:243], v[236:237], 0, v[158:159]
	s_mov_b32 m0, s11
	v_lshl_add_u64 v[236:237], v[236:237], 0, v[162:163]
	global_load_lds_dwordx4 v[242:243], off
	s_add_i32 m0, s11, 0x2000
	v_lshl_add_u64 v[244:245], v[214:215], 0, v[154:155]
	global_load_lds_dwordx4 v[236:237], off
	s_mov_b32 m0, s34
	v_lshl_add_u64 v[246:247], v[214:215], 0, v[160:161]
	global_load_lds_dwordx4 v[244:245], off
	s_mov_b32 m0, s35
	s_nop 0
	global_load_lds_dwordx4 v[246:247], off
	s_waitcnt vmcnt(8) lgkmcnt(0)
	s_setprio 0
	s_barrier
; #define PG8_STAGE(bufoff, gbase, voff) do { _Pragma("unroll") for (int _i = 0; _i < 2; ++_i) \
;         __builtin_amdgcn_global_load_lds((const unsigned*)((const char*)(gbase) + (voff)[_i]), (PG8_LAS unsigned*)(lds + (bufoff) + ldsw + _i * 8192), 16, 0, 0); } while (0)
; #define PG8_LDA(dst, b, h) do { _Pragma("unroll") for (int m = 0; m < 4; ++m) _Pragma("unroll") for (int k = 0; k < 2; ++k) dst[m][k] = *(const PG8_LAS bf16x8*)(lds + PG8_SA(b, h) + aoff + m * 2048 + k * 1024); } while (0)
; #define PG8_LDB(dst, b, h) do { _Pragma("unroll") for (int n = 0; n < 2; ++n) _Pragma("unroll") for (int k = 0; k < 2; ++k) dst[n][k] = *(const PG8_LAS bf16x8*)(lds + PG8_SB(b, h) + boff + n * 2048 + k * 1024); } while (0)
; #define PG8_MMA(ai, bj, At, Bt) do { __builtin_amdgcn_s_setprio(1); _Pragma("unroll") for (int m = 0; m < 4; ++m) _Pragma("unroll") for (int n = 0; n < 2; ++n) _Pragma("unroll") for (int k = 0; k < 2; ++k) \
;         acc[ai][bj][m][n] = __builtin_amdgcn_mfma_f32_16x16x32_bf16(Bt[n][k], At[m][k], acc[ai][bj][m][n], 0, 0, 0); __builtin_amdgcn_s_setprio(0); } while (0)
; #define PG8_WAIT_V(n) asm volatile("s_waitcnt vmcnt(" #n ")" ::: "memory")
; #define PG8_WAIT_L(n) asm volatile("s_waitcnt lgkmcnt(" #n ")" ::: "memory")
; #define PG8_BAR __builtin_amdgcn_s_barrier()
; #define PG8_SCHED __builtin_amdgcn_sched_barrier(0)
; template <class Epi, class Sched, bool ALIGN_EPI = false, bool SP2 = false>
; __device__ __forceinline__ void gemm_phase(PG8_LAS unsigned char* lds, const Gemm g, const Sched& S, const Epi& E) {
;     ...
;             PG8_WAIT_V(8); PG8_WAIT_L(0); PG8_BAR; PG8_MMA(1, 0, At, B0); PG8_MMA(1, 1, At, B1); PG8_BAR; PG8_SCHED;
;             PG8_LDB(B0, 1, 0); PG8_LDB(B1, 1, 1); PG8_SCHED; PG8_LDA(At, 1, 0); PG8_STAGE(PG8_SA(0, 1), a2 + hstep, voffA);
	v_mfma_f32_16x16x32_bf16 v[66:69], v[138:141], v[198:201], v[66:69]
	v_mfma_f32_16x16x32_bf16 v[62:65], v[146:149], v[198:201], v[62:65]
	v_mfma_f32_16x16x32_bf16 v[50:53], v[138:141], v[206:209], v[50:53]
	v_mfma_f32_16x16x32_bf16 v[46:49], v[146:149], v[206:209], v[46:49]
	v_mfma_f32_16x16x32_bf16 v[34:37], v[138:141], v[220:223], v[34:37]
	v_mfma_f32_16x16x32_bf16 v[30:33], v[146:149], v[220:223], v[30:33]
	v_mfma_f32_16x16x32_bf16 v[18:21], v[138:141], v[228:231], v[18:21]
	v_mfma_f32_16x16x32_bf16 v[14:17], v[146:149], v[228:231], v[14:17]
	v_mfma_f32_16x16x32_bf16 v[66:69], v[142:145], v[202:205], v[66:69]
	v_mfma_f32_16x16x32_bf16 v[62:65], v[178:181], v[202:205], v[62:65]
	v_mfma_f32_16x16x32_bf16 v[50:53], v[142:145], v[210:213], v[50:53]
	v_mfma_f32_16x16x32_bf16 v[46:49], v[178:181], v[210:213], v[46:49]
	v_mfma_f32_16x16x32_bf16 v[34:37], v[142:145], v[224:227], v[34:37]
	v_mfma_f32_16x16x32_bf16 v[30:33], v[178:181], v[224:227], v[30:33]
	v_mfma_f32_16x16x32_bf16 v[18:21], v[142:145], v[232:235], v[18:21]
	v_mfma_f32_16x16x32_bf16 v[14:17], v[178:181], v[232:235], v[14:17]
	v_mfma_f32_16x16x32_bf16 v[58:61], v[182:185], v[198:201], v[58:61]
	v_mfma_f32_16x16x32_bf16 v[54:57], v[190:193], v[198:201], v[54:57]
	v_mfma_f32_16x16x32_bf16 v[42:45], v[182:185], v[206:209], v[42:45]
	v_mfma_f32_16x16x32_bf16 v[38:41], v[190:193], v[206:209], v[38:41]
	v_mfma_f32_16x16x32_bf16 v[26:29], v[182:185], v[220:223], v[26:29]
	v_mfma_f32_16x16x32_bf16 v[22:25], v[190:193], v[220:223], v[22:25]
	v_mfma_f32_16x16x32_bf16 v[10:13], v[182:185], v[228:231], v[10:13]
	v_mfma_f32_16x16x32_bf16 v[6:9], v[190:193], v[228:231], v[6:9]
	v_mfma_f32_16x16x32_bf16 v[58:61], v[186:189], v[202:205], v[58:61]
	v_mfma_f32_16x16x32_bf16 v[54:57], v[194:197], v[202:205], v[54:57]
	v_mfma_f32_16x16x32_bf16 v[42:45], v[186:189], v[210:213], v[42:45]
	v_mfma_f32_16x16x32_bf16 v[38:41], v[194:197], v[210:213], v[38:41]
	v_mfma_f32_16x16x32_bf16 v[26:29], v[186:189], v[224:227], v[26:29]
	v_mfma_f32_16x16x32_bf16 v[22:25], v[194:197], v[224:227], v[22:25]
	v_mfma_f32_16x16x32_bf16 v[10:13], v[186:189], v[232:235], v[10:13]
	v_mfma_f32_16x16x32_bf16 v[6:9], v[194:197], v[232:235], v[6:9]
	s_setprio 1
	s_barrier
	s_add_i32 s11, 0, 0x18000
	s_add_i32 s31, 0, 0x1c000
	v_add_u32_e32 v178, s11, v216
	v_add_u32_e32 v194, s31, v216
	ds_read_b128 v[138:141], v178
	ds_read_b128 v[142:145], v178 offset:1024
	ds_read_b128 v[146:149], v178 offset:2048
	ds_read_b128 v[178:181], v178 offset:3072
	ds_read_b128 v[182:185], v194
	ds_read_b128 v[186:189], v194 offset:1024
	ds_read_b128 v[190:193], v194 offset:2048
	ds_read_b128 v[194:197], v194 offset:3072
	v_lshl_add_u64 v[214:215], v[214:215], 0, s[12:13]
	s_mov_b32 m0, s36
	v_lshl_add_u64 v[248:249], v[214:215], 0, v[154:155]
	ds_read_b128 v[198:201], v218 offset:32768
	ds_read_b128 v[202:205], v218 offset:33792
	ds_read_b128 v[206:209], v218 offset:34816
	ds_read_b128 v[210:213], v218 offset:35840
	ds_read_b128 v[220:223], v218 offset:36864
	ds_read_b128 v[224:227], v218 offset:37888
	ds_read_b128 v[228:231], v218 offset:38912
	ds_read_b128 v[232:235], v218 offset:39936
	global_load_lds_dwordx4 v[248:249], off
	s_mov_b32 m0, s37
	v_lshl_add_u64 v[214:215], v[214:215], 0, v[160:161]
	global_load_lds_dwordx4 v[214:215], off
	s_waitcnt vmcnt(8) lgkmcnt(0)
	s_setprio 0
	s_barrier
; #define PG8_STAGE(bufoff, gbase, voff) do { _Pragma("unroll") for (int _i = 0; _i < 2; ++_i) \
;         __builtin_amdgcn_global_load_lds((const unsigned*)((const char*)(gbase) + (voff)[_i]), (PG8_LAS unsigned*)(lds + (bufoff) + ldsw + _i * 8192), 16, 0, 0); } while (0)
; #define PG8_LDA(dst, b, h) do { _Pragma("unroll") for (int m = 0; m < 4; ++m) _Pragma("unroll") for (int k = 0; k < 2; ++k) dst[m][k] = *(const PG8_LAS bf16x8*)(lds + PG8_SA(b, h) + aoff + m * 2048 + k * 1024); } while (0)
; #define PG8_MMA(ai, bj, At, Bt) do { __builtin_amdgcn_s_setprio(1); _Pragma("unroll") for (int m = 0; m < 4; ++m) _Pragma("unroll") for (int n = 0; n < 2; ++n) _Pragma("unroll") for (int k = 0; k < 2; ++k) \
;         acc[ai][bj][m][n] = __builtin_amdgcn_mfma_f32_16x16x32_bf16(Bt[n][k], At[m][k], acc[ai][bj][m][n], 0, 0, 0); __builtin_amdgcn_s_setprio(0); } while (0)
; #define PG8_WAIT_V(n) asm volatile("s_waitcnt vmcnt(" #n ")" ::: "memory")
; #define PG8_WAIT_L(n) asm volatile("s_waitcnt lgkmcnt(" #n ")" ::: "memory")
; #define PG8_BAR __builtin_amdgcn_s_barrier()
; #define PG8_SCHED __builtin_amdgcn_sched_barrier(0)
; template <class Epi, class Sched, bool ALIGN_EPI = false, bool SP2 = false>
; __device__ __forceinline__ void gemm_phase(PG8_LAS unsigned char* lds, const Gemm g, const Sched& S, const Epi& E) {
;     ...
;             PG8_WAIT_V(8); PG8_WAIT_L(0); PG8_BAR; PG8_MMA(0, 0, At, B0); PG8_MMA(0, 1, At, B1); PG8_BAR; PG8_SCHED;
;             PG8_LDA(At, 1, 1); PG8_STAGE(PG8_SB(1, 0), b3, voffB); PG8_STAGE(PG8_SB(1, 1), b3 + hstep, voffB); PG8_STAGE(PG8_SA(1, 0), a3, voffA);
;             PG8_WAIT_V(8); PG8_WAIT_L(0); PG8_BAR; PG8_MMA(1, 0, At, B0); PG8_MMA(1, 1, At, B1); PG8_BAR; PG8_SCHED;
	v_mfma_f32_16x16x32_bf16 v[130:133], v[138:141], v[198:201], v[130:133]
	v_mfma_f32_16x16x32_bf16 v[126:129], v[146:149], v[198:201], v[126:129]
	v_mfma_f32_16x16x32_bf16 v[114:117], v[138:141], v[206:209], v[114:117]
	v_mfma_f32_16x16x32_bf16 v[110:113], v[146:149], v[206:209], v[110:113]
	v_mfma_f32_16x16x32_bf16 v[98:101], v[138:141], v[220:223], v[98:101]
	v_mfma_f32_16x16x32_bf16 v[94:97], v[146:149], v[220:223], v[94:97]
	v_mfma_f32_16x16x32_bf16 v[82:85], v[138:141], v[228:231], v[82:85]
	v_mfma_f32_16x16x32_bf16 v[78:81], v[146:149], v[228:231], v[78:81]
	v_mfma_f32_16x16x32_bf16 v[130:133], v[142:145], v[202:205], v[130:133]
	v_mfma_f32_16x16x32_bf16 v[126:129], v[178:181], v[202:205], v[126:129]
	v_mfma_f32_16x16x32_bf16 v[114:117], v[142:145], v[210:213], v[114:117]
	v_mfma_f32_16x16x32_bf16 v[110:113], v[178:181], v[210:213], v[110:113]
	v_mfma_f32_16x16x32_bf16 v[98:101], v[142:145], v[224:227], v[98:101]
	v_mfma_f32_16x16x32_bf16 v[94:97], v[178:181], v[224:227], v[94:97]
	v_mfma_f32_16x16x32_bf16 v[82:85], v[142:145], v[232:235], v[82:85]
	v_mfma_f32_16x16x32_bf16 v[78:81], v[178:181], v[232:235], v[78:81]
	v_mfma_f32_16x16x32_bf16 v[122:125], v[182:185], v[198:201], v[122:125]
	v_mfma_f32_16x16x32_bf16 v[118:121], v[190:193], v[198:201], v[118:121]
	v_mfma_f32_16x16x32_bf16 v[106:109], v[182:185], v[206:209], v[106:109]
	v_mfma_f32_16x16x32_bf16 v[102:105], v[190:193], v[206:209], v[102:105]
	v_mfma_f32_16x16x32_bf16 v[90:93], v[182:185], v[220:223], v[90:93]
	v_mfma_f32_16x16x32_bf16 v[86:89], v[190:193], v[220:223], v[86:89]
	v_mfma_f32_16x16x32_bf16 v[74:77], v[182:185], v[228:231], v[74:77]
	v_mfma_f32_16x16x32_bf16 v[70:73], v[190:193], v[228:231], v[70:73]
	v_mfma_f32_16x16x32_bf16 v[122:125], v[186:189], v[202:205], v[122:125]
	v_mfma_f32_16x16x32_bf16 v[118:121], v[194:197], v[202:205], v[118:121]
	v_mfma_f32_16x16x32_bf16 v[106:109], v[186:189], v[210:213], v[106:109]
	v_mfma_f32_16x16x32_bf16 v[102:105], v[194:197], v[210:213], v[102:105]
	v_mfma_f32_16x16x32_bf16 v[90:93], v[186:189], v[224:227], v[90:93]
	v_mfma_f32_16x16x32_bf16 v[86:89], v[194:197], v[224:227], v[86:89]
	v_mfma_f32_16x16x32_bf16 v[74:77], v[186:189], v[232:235], v[74:77]
	v_mfma_f32_16x16x32_bf16 v[70:73], v[194:197], v[232:235], v[70:73]
	s_setprio 1
	s_barrier
	s_add_i32 s11, s11, s29
	s_add_i32 m0, s11, 0xffffff80
	ds_read_b128 v[198:201], v218 offset:49152
	ds_read_b128 v[202:205], v218 offset:50176
	ds_read_b128 v[206:209], v218 offset:51200
	ds_read_b128 v[210:213], v218 offset:52224
	global_load_lds_dwordx4 v[238:239], off offset:128
	s_add_i32 m0, s11, 0x1f80
	s_add_i32 s11, s31, s29
	global_load_lds_dwordx4 v[240:241], off offset:128
	s_add_i32 m0, s11, 0xffffff80
	ds_read_b128 v[232:235], v218 offset:56320
	global_load_lds_dwordx4 v[242:243], off offset:128
	s_add_i32 m0, s11, 0x1f80
	ds_read_b128 v[228:231], v218 offset:55296
	global_load_lds_dwordx4 v[236:237], off offset:128
	s_add_i32 m0, s41, 0xffffff80
	ds_read_b128 v[224:227], v218 offset:54272
	global_load_lds_dwordx4 v[244:245], off offset:128
	s_add_i32 m0, s46, 0xffffff80
	ds_read_b128 v[220:223], v218 offset:53248
	global_load_lds_dwordx4 v[246:247], off offset:128
	s_waitcnt vmcnt(8) lgkmcnt(0)
	s_setprio 0
	s_barrier
	v_mfma_f32_16x16x32_bf16 v[66:69], v[138:141], v[198:201], v[66:69]
	v_mfma_f32_16x16x32_bf16 v[62:65], v[146:149], v[198:201], v[62:65]
	v_mfma_f32_16x16x32_bf16 v[50:53], v[138:141], v[206:209], v[50:53]
	v_mfma_f32_16x16x32_bf16 v[46:49], v[146:149], v[206:209], v[46:49]
	v_mfma_f32_16x16x32_bf16 v[34:37], v[138:141], v[220:223], v[34:37]
	v_mfma_f32_16x16x32_bf16 v[30:33], v[146:149], v[220:223], v[30:33]
	v_mfma_f32_16x16x32_bf16 v[18:21], v[138:141], v[228:231], v[18:21]
	v_mfma_f32_16x16x32_bf16 v[14:17], v[146:149], v[228:231], v[14:17]
	v_mfma_f32_16x16x32_bf16 v[66:69], v[142:145], v[202:205], v[66:69]
	v_mfma_f32_16x16x32_bf16 v[62:65], v[178:181], v[202:205], v[62:65]
	v_mfma_f32_16x16x32_bf16 v[50:53], v[142:145], v[210:213], v[50:53]
	v_mfma_f32_16x16x32_bf16 v[46:49], v[178:181], v[210:213], v[46:49]
	v_mfma_f32_16x16x32_bf16 v[34:37], v[142:145], v[224:227], v[34:37]
	v_mfma_f32_16x16x32_bf16 v[30:33], v[178:181], v[224:227], v[30:33]
	v_mfma_f32_16x16x32_bf16 v[18:21], v[142:145], v[232:235], v[18:21]
	v_mfma_f32_16x16x32_bf16 v[14:17], v[178:181], v[232:235], v[14:17]
	v_mfma_f32_16x16x32_bf16 v[58:61], v[182:185], v[198:201], v[58:61]
	v_mfma_f32_16x16x32_bf16 v[54:57], v[190:193], v[198:201], v[54:57]
	v_mfma_f32_16x16x32_bf16 v[42:45], v[182:185], v[206:209], v[42:45]
	v_mfma_f32_16x16x32_bf16 v[38:41], v[190:193], v[206:209], v[38:41]
	v_mfma_f32_16x16x32_bf16 v[26:29], v[182:185], v[220:223], v[26:29]
	v_mfma_f32_16x16x32_bf16 v[22:25], v[190:193], v[220:223], v[22:25]
	v_mfma_f32_16x16x32_bf16 v[10:13], v[182:185], v[228:231], v[10:13]
	v_mfma_f32_16x16x32_bf16 v[6:9], v[190:193], v[228:231], v[6:9]
	v_mfma_f32_16x16x32_bf16 v[58:61], v[186:189], v[202:205], v[58:61]
	v_mfma_f32_16x16x32_bf16 v[54:57], v[194:197], v[202:205], v[54:57]
	v_mfma_f32_16x16x32_bf16 v[42:45], v[186:189], v[210:213], v[42:45]
	v_mfma_f32_16x16x32_bf16 v[38:41], v[194:197], v[210:213], v[38:41]
	v_mfma_f32_16x16x32_bf16 v[26:29], v[186:189], v[224:227], v[26:29]
	v_mfma_f32_16x16x32_bf16 v[22:25], v[194:197], v[224:227], v[22:25]
	v_mfma_f32_16x16x32_bf16 v[10:13], v[186:189], v[232:235], v[10:13]
	v_mfma_f32_16x16x32_bf16 v[6:9], v[194:197], v[232:235], v[6:9]
	s_setprio 1
	s_barrier
	v_lshl_add_u64 v[134:135], v[134:135], 0, s[26:27]
	s_cmp_ge_i32 s10, s48
	v_lshl_add_u64 v[136:137], v[136:137], 0, s[26:27]
	s_cbranch_scc0 .LBB0_1192
	s_setprio 0

; #define PG8_STAGE(bufoff, gbase, voff) do { _Pragma("unroll") for (int _i = 0; _i < 2; ++_i) \
;         __builtin_amdgcn_global_load_lds((const unsigned*)((const char*)(gbase) + (voff)[_i]), (PG8_LAS unsigned*)(lds + (bufoff) + ldsw + _i * 8192), 16, 0, 0); } while (0)
; #define PG8_LDA(dst, b, h) do { _Pragma("unroll") for (int m = 0; m < 4; ++m) _Pragma("unroll") for (int k = 0; k < 2; ++k) dst[m][k] = *(const PG8_LAS bf16x8*)(lds + PG8_SA(b, h) + aoff + m * 2048 + k * 1024); } while (0)
; #define PG8_LDB(dst, b, h) do { _Pragma("unroll") for (int n = 0; n < 2; ++n) _Pragma("unroll") for (int k = 0; k < 2; ++k) dst[n][k] = *(const PG8_LAS bf16x8*)(lds + PG8_SB(b, h) + boff + n * 2048 + k * 1024); } while (0)
; #define PG8_MMA(ai, bj, At, Bt) do { __builtin_amdgcn_s_setprio(1); _Pragma("unroll") for (int m = 0; m < 4; ++m) _Pragma("unroll") for (int n = 0; n < 2; ++n) _Pragma("unroll") for (int k = 0; k < 2; ++k) \
;         acc[ai][bj][m][n] = __builtin_amdgcn_mfma_f32_16x16x32_bf16(Bt[n][k], At[m][k], acc[ai][bj][m][n], 0, 0, 0); __builtin_amdgcn_s_setprio(0); } while (0)
; #define PG8_WAIT_V(n) asm volatile("s_waitcnt vmcnt(" #n ")" ::: "memory")
; #define PG8_WAIT_L(n) asm volatile("s_waitcnt lgkmcnt(" #n ")" ::: "memory")
; #define PG8_BAR __builtin_amdgcn_s_barrier()
; #define PG8_SCHED __builtin_amdgcn_sched_barrier(0)
; template <class Epi, class Sched, bool ALIGN_EPI = false, bool SP2 = false>
; __device__ __forceinline__ void gemm_phase(PG8_LAS unsigned char* lds, const Gemm g, const Sched& S, const Epi& E) {
;     ...
;             const bool last = (t == nt - 2);
;             const char* a1 = cA + (size_t)(t + 1) * kstep;
;             const char* a2 = last ? nA : cA + (size_t)(t + 2) * kstep; const char* b2 = last ? nB : cB + (size_t)(t + 2) * kstep;
;             const char* a3 = a2 + kstep; const char* b3 = b2 + kstep;
;             if (last && has_next) S.a_ready(nxt);
;             if constexpr (SP2) {
;             PG8_LDB(B0, 0, 0); PG8_LDB(B1, 0, 1); PG8_SCHED; PG8_LDA(At, 0, 0); PG8_STAGE(PG8_SA(1, 1), a1 + hstep, voffA);
;             PG8_WAIT_V(8); PG8_WAIT_L(0); PG8_BAR; PG8_MMA(0, 0, At, B0); PG8_MMA(0, 1, At, B1); PG8_BAR; PG8_SCHED;
;             PG8_LDA(At, 0, 1); PG8_STAGE(PG8_SB(0, 0), b2, voffB); PG8_STAGE(PG8_SB(0, 1), b2 + hstep, voffB); PG8_STAGE(PG8_SA(0, 0), a2, voffA);
.LBB0_1340:
	v_add_u32_e32 v148, s55, v201
	v_add_u32_e32 v190, s56, v201
	ds_read_b128 v[136:139], v148
	ds_read_b128 v[140:143], v148 offset:1024
	ds_read_b128 v[144:147], v148 offset:2048
	ds_read_b128 v[148:151], v148 offset:3072
	ds_read_b128 v[152:155], v190
	ds_read_b128 v[182:185], v190 offset:1024
	ds_read_b128 v[186:189], v190 offset:2048
	ds_read_b128 v[190:193], v190 offset:3072
	s_cmp_eq_u32 s48, s12
	v_lshl_add_u64 v[194:195], v[134:135], 0, s[22:23]
	s_cselect_b64 vcc, -1, 0
	s_add_i32 s12, s12, 2
	v_cndmask_b32_e32 v199, v195, v179, vcc
	v_cndmask_b32_e32 v198, v194, v178, vcc
	v_cndmask_b32_e32 v215, v133, v181, vcc
	v_cndmask_b32_e32 v214, v132, v180, vcc
	s_mov_b32 m0, s57
	v_lshl_add_u64 v[236:237], v[134:135], 0, v[174:175]
	ds_read_b128 v[194:197], v203
	ds_read_b128 v[206:209], v203 offset:1024
	ds_read_b128 v[210:213], v203 offset:2048
	ds_read_b128 v[216:219], v203 offset:3072
	ds_read_b128 v[220:223], v203 offset:4096
	ds_read_b128 v[224:227], v203 offset:5120
	ds_read_b128 v[228:231], v203 offset:6144
	ds_read_b128 v[232:235], v203 offset:7168
	global_load_lds_dwordx4 v[236:237], off
	s_mov_b32 m0, s58
	v_lshl_add_u64 v[236:237], v[134:135], 0, v[172:173]
	global_load_lds_dwordx4 v[236:237], off
	s_waitcnt vmcnt(8) lgkmcnt(0)
	s_setprio 0
	s_barrier
	v_mfma_f32_16x16x32_bf16 v[124:127], v[136:139], v[194:197], v[124:127]
	v_mfma_f32_16x16x32_bf16 v[128:131], v[144:147], v[194:197], v[128:131]
	v_mfma_f32_16x16x32_bf16 v[112:115], v[136:139], v[210:213], v[112:115]
	v_mfma_f32_16x16x32_bf16 v[108:111], v[144:147], v[210:213], v[108:111]
	v_mfma_f32_16x16x32_bf16 v[96:99], v[136:139], v[220:223], v[96:99]
	v_mfma_f32_16x16x32_bf16 v[92:95], v[144:147], v[220:223], v[92:95]
	v_mfma_f32_16x16x32_bf16 v[80:83], v[136:139], v[228:231], v[80:83]
	v_mfma_f32_16x16x32_bf16 v[76:79], v[144:147], v[228:231], v[76:79]
	v_mfma_f32_16x16x32_bf16 v[124:127], v[140:143], v[206:209], v[124:127]
	v_mfma_f32_16x16x32_bf16 v[128:131], v[148:151], v[206:209], v[128:131]
	v_mfma_f32_16x16x32_bf16 v[112:115], v[140:143], v[216:219], v[112:115]
	v_mfma_f32_16x16x32_bf16 v[108:111], v[148:151], v[216:219], v[108:111]
	v_mfma_f32_16x16x32_bf16 v[96:99], v[140:143], v[224:227], v[96:99]
	v_mfma_f32_16x16x32_bf16 v[92:95], v[148:151], v[224:227], v[92:95]
	v_mfma_f32_16x16x32_bf16 v[80:83], v[140:143], v[232:235], v[80:83]
	v_mfma_f32_16x16x32_bf16 v[76:79], v[148:151], v[232:235], v[76:79]
	v_mfma_f32_16x16x32_bf16 v[120:123], v[152:155], v[194:197], v[120:123]
	v_mfma_f32_16x16x32_bf16 v[116:119], v[186:189], v[194:197], v[116:119]
	v_mfma_f32_16x16x32_bf16 v[104:107], v[152:155], v[210:213], v[104:107]
	v_mfma_f32_16x16x32_bf16 v[100:103], v[186:189], v[210:213], v[100:103]
	v_mfma_f32_16x16x32_bf16 v[88:91], v[152:155], v[220:223], v[88:91]
	v_mfma_f32_16x16x32_bf16 v[84:87], v[186:189], v[220:223], v[84:87]
	v_mfma_f32_16x16x32_bf16 v[72:75], v[152:155], v[228:231], v[72:75]
	v_mfma_f32_16x16x32_bf16 v[68:71], v[186:189], v[228:231], v[68:71]
	v_mfma_f32_16x16x32_bf16 v[120:123], v[182:185], v[206:209], v[120:123]
	v_mfma_f32_16x16x32_bf16 v[116:119], v[190:193], v[206:209], v[116:119]
	v_mfma_f32_16x16x32_bf16 v[104:107], v[182:185], v[216:219], v[104:107]
	v_mfma_f32_16x16x32_bf16 v[100:103], v[190:193], v[216:219], v[100:103]
	v_mfma_f32_16x16x32_bf16 v[88:91], v[182:185], v[224:227], v[88:91]
	v_mfma_f32_16x16x32_bf16 v[84:87], v[190:193], v[224:227], v[84:87]
	v_mfma_f32_16x16x32_bf16 v[72:75], v[182:185], v[232:235], v[72:75]
	v_mfma_f32_16x16x32_bf16 v[68:71], v[190:193], v[232:235], v[68:71]
	s_setprio 1
	s_barrier
	s_mov_b32 m0, s59
	v_lshl_add_u64 v[236:237], v[214:215], 0, v[166:167]
	ds_read_b128 v[194:197], v203 offset:16384
	ds_read_b128 v[206:209], v203 offset:17408
	ds_read_b128 v[210:213], v203 offset:18432
	ds_read_b128 v[216:219], v203 offset:19456
	ds_read_b128 v[220:223], v203 offset:20480
	ds_read_b128 v[224:227], v203 offset:21504
	ds_read_b128 v[228:231], v203 offset:22528
	ds_read_b128 v[232:235], v203 offset:23552
	global_load_lds_dwordx4 v[236:237], off
	v_lshl_add_u64 v[238:239], v[214:215], 0, v[170:171]
	s_mov_b32 m0, s60
	v_lshl_add_u64 v[214:215], v[214:215], 0, s[14:15]
	s_add_i32 s13, s56, s30
	global_load_lds_dwordx4 v[238:239], off
	v_lshl_add_u64 v[240:241], v[214:215], 0, v[166:167]
	s_mov_b32 m0, s13
	v_lshl_add_u64 v[214:215], v[214:215], 0, v[170:171]
	global_load_lds_dwordx4 v[240:241], off
	s_add_i32 m0, s13, 0x2000
	v_lshl_add_u64 v[242:243], v[198:199], 0, v[164:165]
	global_load_lds_dwordx4 v[214:215], off
	s_mov_b32 m0, s31
	v_lshl_add_u64 v[244:245], v[198:199], 0, v[168:169]
	global_load_lds_dwordx4 v[242:243], off
	s_mov_b32 m0, s34
	s_nop 0
	global_load_lds_dwordx4 v[244:245], off
	s_waitcnt vmcnt(8) lgkmcnt(0)
	s_setprio 0
	s_barrier
; #define PG8_STAGE(bufoff, gbase, voff) do { _Pragma("unroll") for (int _i = 0; _i < 2; ++_i) \
;         __builtin_amdgcn_global_load_lds((const unsigned*)((const char*)(gbase) + (voff)[_i]), (PG8_LAS unsigned*)(lds + (bufoff) + ldsw + _i * 8192), 16, 0, 0); } while (0)
; #define PG8_LDA(dst, b, h) do { _Pragma("unroll") for (int m = 0; m < 4; ++m) _Pragma("unroll") for (int k = 0; k < 2; ++k) dst[m][k] = *(const PG8_LAS bf16x8*)(lds + PG8_SA(b, h) + aoff + m * 2048 + k * 1024); } while (0)
; #define PG8_LDB(dst, b, h) do { _Pragma("unroll") for (int n = 0; n < 2; ++n) _Pragma("unroll") for (int k = 0; k < 2; ++k) dst[n][k] = *(const PG8_LAS bf16x8*)(lds + PG8_SB(b, h) + boff + n * 2048 + k * 1024); } while (0)
; #define PG8_MMA(ai, bj, At, Bt) do { __builtin_amdgcn_s_setprio(1); _Pragma("unroll") for (int m = 0; m < 4; ++m) _Pragma("unroll") for (int n = 0; n < 2; ++n) _Pragma("unroll") for (int k = 0; k < 2; ++k) \
;         acc[ai][bj][m][n] = __builtin_amdgcn_mfma_f32_16x16x32_bf16(Bt[n][k], At[m][k], acc[ai][bj][m][n], 0, 0, 0); __builtin_amdgcn_s_setprio(0); } while (0)
; #define PG8_WAIT_V(n) asm volatile("s_waitcnt vmcnt(" #n ")" ::: "memory")
; #define PG8_WAIT_L(n) asm volatile("s_waitcnt lgkmcnt(" #n ")" ::: "memory")
; #define PG8_BAR __builtin_amdgcn_s_barrier()
; #define PG8_SCHED __builtin_amdgcn_sched_barrier(0)
; template <class Epi, class Sched, bool ALIGN_EPI = false, bool SP2 = false>
; __device__ __forceinline__ void gemm_phase(PG8_LAS unsigned char* lds, const Gemm g, const Sched& S, const Epi& E) {
;     ...
;             PG8_WAIT_V(8); PG8_WAIT_L(0); PG8_BAR; PG8_MMA(1, 0, At, B0); PG8_MMA(1, 1, At, B1); PG8_BAR; PG8_SCHED;
;             PG8_LDB(B0, 1, 0); PG8_LDB(B1, 1, 1); PG8_SCHED; PG8_LDA(At, 1, 0); PG8_STAGE(PG8_SA(0, 1), a2 + hstep, voffA);
	v_mfma_f32_16x16x32_bf16 v[64:67], v[136:139], v[194:197], v[64:67]
	v_mfma_f32_16x16x32_bf16 v[60:63], v[144:147], v[194:197], v[60:63]
	v_mfma_f32_16x16x32_bf16 v[48:51], v[136:139], v[210:213], v[48:51]
	v_mfma_f32_16x16x32_bf16 v[44:47], v[144:147], v[210:213], v[44:47]
	v_mfma_f32_16x16x32_bf16 v[32:35], v[136:139], v[220:223], v[32:35]
	v_mfma_f32_16x16x32_bf16 v[28:31], v[144:147], v[220:223], v[28:31]
	v_mfma_f32_16x16x32_bf16 v[16:19], v[136:139], v[228:231], v[16:19]
	v_mfma_f32_16x16x32_bf16 v[12:15], v[144:147], v[228:231], v[12:15]
	v_mfma_f32_16x16x32_bf16 v[64:67], v[140:143], v[206:209], v[64:67]
	v_mfma_f32_16x16x32_bf16 v[60:63], v[148:151], v[206:209], v[60:63]
	v_mfma_f32_16x16x32_bf16 v[48:51], v[140:143], v[216:219], v[48:51]
	v_mfma_f32_16x16x32_bf16 v[44:47], v[148:151], v[216:219], v[44:47]
	v_mfma_f32_16x16x32_bf16 v[32:35], v[140:143], v[224:227], v[32:35]
	v_mfma_f32_16x16x32_bf16 v[28:31], v[148:151], v[224:227], v[28:31]
	v_mfma_f32_16x16x32_bf16 v[16:19], v[140:143], v[232:235], v[16:19]
	v_mfma_f32_16x16x32_bf16 v[12:15], v[148:151], v[232:235], v[12:15]
	v_mfma_f32_16x16x32_bf16 v[56:59], v[152:155], v[194:197], v[56:59]
	v_mfma_f32_16x16x32_bf16 v[52:55], v[186:189], v[194:197], v[52:55]
	v_mfma_f32_16x16x32_bf16 v[40:43], v[152:155], v[210:213], v[40:43]
	v_mfma_f32_16x16x32_bf16 v[36:39], v[186:189], v[210:213], v[36:39]
	v_mfma_f32_16x16x32_bf16 v[24:27], v[152:155], v[220:223], v[24:27]
	v_mfma_f32_16x16x32_bf16 v[20:23], v[186:189], v[220:223], v[20:23]
	v_mfma_f32_16x16x32_bf16 v[8:11], v[152:155], v[228:231], v[8:11]
	v_mfma_f32_16x16x32_bf16 v[4:7], v[186:189], v[228:231], v[4:7]
	v_mfma_f32_16x16x32_bf16 v[56:59], v[182:185], v[206:209], v[56:59]
	v_mfma_f32_16x16x32_bf16 v[52:55], v[190:193], v[206:209], v[52:55]
	v_mfma_f32_16x16x32_bf16 v[40:43], v[182:185], v[216:219], v[40:43]
	v_mfma_f32_16x16x32_bf16 v[36:39], v[190:193], v[216:219], v[36:39]
	v_mfma_f32_16x16x32_bf16 v[24:27], v[182:185], v[224:227], v[24:27]
	v_mfma_f32_16x16x32_bf16 v[20:23], v[190:193], v[224:227], v[20:23]
	v_mfma_f32_16x16x32_bf16 v[8:11], v[182:185], v[232:235], v[8:11]
	v_mfma_f32_16x16x32_bf16 v[4:7], v[190:193], v[232:235], v[4:7]
	s_setprio 1
	s_barrier
	s_add_i32 s13, 0, 0x18000
	s_add_i32 s29, 0, 0x1c000
	v_add_u32_e32 v148, s13, v201
	v_add_u32_e32 v190, s29, v201
	ds_read_b128 v[136:139], v148
	ds_read_b128 v[140:143], v148 offset:1024
	ds_read_b128 v[144:147], v148 offset:2048
	ds_read_b128 v[148:151], v148 offset:3072
	ds_read_b128 v[152:155], v190
	ds_read_b128 v[182:185], v190 offset:1024
	ds_read_b128 v[186:189], v190 offset:2048
	ds_read_b128 v[190:193], v190 offset:3072
	v_lshl_add_u64 v[198:199], v[198:199], 0, s[14:15]
	s_mov_b32 m0, s35
	v_lshl_add_u64 v[246:247], v[198:199], 0, v[164:165]
	ds_read_b128 v[194:197], v203 offset:32768
	ds_read_b128 v[206:209], v203 offset:33792
	ds_read_b128 v[210:213], v203 offset:34816
	ds_read_b128 v[216:219], v203 offset:35840
	ds_read_b128 v[220:223], v203 offset:36864
	ds_read_b128 v[224:227], v203 offset:37888
	ds_read_b128 v[228:231], v203 offset:38912
	ds_read_b128 v[232:235], v203 offset:39936
	global_load_lds_dwordx4 v[246:247], off
	s_mov_b32 m0, s36
	v_lshl_add_u64 v[198:199], v[198:199], 0, v[168:169]
	global_load_lds_dwordx4 v[198:199], off
	s_waitcnt vmcnt(8) lgkmcnt(0)
	s_setprio 0
	s_barrier
; #define PG8_STAGE(bufoff, gbase, voff) do { _Pragma("unroll") for (int _i = 0; _i < 2; ++_i) \
;         __builtin_amdgcn_global_load_lds((const unsigned*)((const char*)(gbase) + (voff)[_i]), (PG8_LAS unsigned*)(lds + (bufoff) + ldsw + _i * 8192), 16, 0, 0); } while (0)
; #define PG8_LDA(dst, b, h) do { _Pragma("unroll") for (int m = 0; m < 4; ++m) _Pragma("unroll") for (int k = 0; k < 2; ++k) dst[m][k] = *(const PG8_LAS bf16x8*)(lds + PG8_SA(b, h) + aoff + m * 2048 + k * 1024); } while (0)
; #define PG8_MMA(ai, bj, At, Bt) do { __builtin_amdgcn_s_setprio(1); _Pragma("unroll") for (int m = 0; m < 4; ++m) _Pragma("unroll") for (int n = 0; n < 2; ++n) _Pragma("unroll") for (int k = 0; k < 2; ++k) \
;         acc[ai][bj][m][n] = __builtin_amdgcn_mfma_f32_16x16x32_bf16(Bt[n][k], At[m][k], acc[ai][bj][m][n], 0, 0, 0); __builtin_amdgcn_s_setprio(0); } while (0)
; #define PG8_WAIT_V(n) asm volatile("s_waitcnt vmcnt(" #n ")" ::: "memory")
; #define PG8_WAIT_L(n) asm volatile("s_waitcnt lgkmcnt(" #n ")" ::: "memory")
; #define PG8_BAR __builtin_amdgcn_s_barrier()
; #define PG8_SCHED __builtin_amdgcn_sched_barrier(0)
; template <class Epi, class Sched, bool ALIGN_EPI = false, bool SP2 = false>
; __device__ __forceinline__ void gemm_phase(PG8_LAS unsigned char* lds, const Gemm g, const Sched& S, const Epi& E) {
;     ...
;             PG8_WAIT_V(8); PG8_WAIT_L(0); PG8_BAR; PG8_MMA(0, 0, At, B0); PG8_MMA(0, 1, At, B1); PG8_BAR; PG8_SCHED;
;             PG8_LDA(At, 1, 1); PG8_STAGE(PG8_SB(1, 0), b3, voffB); PG8_STAGE(PG8_SB(1, 1), b3 + hstep, voffB); PG8_STAGE(PG8_SA(1, 0), a3, voffA);
;             PG8_WAIT_V(8); PG8_WAIT_L(0); PG8_BAR; PG8_MMA(1, 0, At, B0); PG8_MMA(1, 1, At, B1); PG8_BAR; PG8_SCHED;
	v_mfma_f32_16x16x32_bf16 v[124:127], v[136:139], v[194:197], v[124:127]
	v_mfma_f32_16x16x32_bf16 v[128:131], v[144:147], v[194:197], v[128:131]
	v_mfma_f32_16x16x32_bf16 v[112:115], v[136:139], v[210:213], v[112:115]
	v_mfma_f32_16x16x32_bf16 v[108:111], v[144:147], v[210:213], v[108:111]
	v_mfma_f32_16x16x32_bf16 v[96:99], v[136:139], v[220:223], v[96:99]
	v_mfma_f32_16x16x32_bf16 v[92:95], v[144:147], v[220:223], v[92:95]
	v_mfma_f32_16x16x32_bf16 v[80:83], v[136:139], v[228:231], v[80:83]
	v_mfma_f32_16x16x32_bf16 v[76:79], v[144:147], v[228:231], v[76:79]
	v_mfma_f32_16x16x32_bf16 v[124:127], v[140:143], v[206:209], v[124:127]
	v_mfma_f32_16x16x32_bf16 v[128:131], v[148:151], v[206:209], v[128:131]
	v_mfma_f32_16x16x32_bf16 v[112:115], v[140:143], v[216:219], v[112:115]
	v_mfma_f32_16x16x32_bf16 v[108:111], v[148:151], v[216:219], v[108:111]
	v_mfma_f32_16x16x32_bf16 v[96:99], v[140:143], v[224:227], v[96:99]
	v_mfma_f32_16x16x32_bf16 v[92:95], v[148:151], v[224:227], v[92:95]
	v_mfma_f32_16x16x32_bf16 v[80:83], v[140:143], v[232:235], v[80:83]
	v_mfma_f32_16x16x32_bf16 v[76:79], v[148:151], v[232:235], v[76:79]
	v_mfma_f32_16x16x32_bf16 v[120:123], v[152:155], v[194:197], v[120:123]
	v_mfma_f32_16x16x32_bf16 v[116:119], v[186:189], v[194:197], v[116:119]
	v_mfma_f32_16x16x32_bf16 v[104:107], v[152:155], v[210:213], v[104:107]
	v_mfma_f32_16x16x32_bf16 v[100:103], v[186:189], v[210:213], v[100:103]
	v_mfma_f32_16x16x32_bf16 v[88:91], v[152:155], v[220:223], v[88:91]
	v_mfma_f32_16x16x32_bf16 v[84:87], v[186:189], v[220:223], v[84:87]
	v_mfma_f32_16x16x32_bf16 v[72:75], v[152:155], v[228:231], v[72:75]
	v_mfma_f32_16x16x32_bf16 v[68:71], v[186:189], v[228:231], v[68:71]
	v_mfma_f32_16x16x32_bf16 v[120:123], v[182:185], v[206:209], v[120:123]
	v_mfma_f32_16x16x32_bf16 v[116:119], v[190:193], v[206:209], v[116:119]
	v_mfma_f32_16x16x32_bf16 v[104:107], v[182:185], v[216:219], v[104:107]
	v_mfma_f32_16x16x32_bf16 v[100:103], v[190:193], v[216:219], v[100:103]
	v_mfma_f32_16x16x32_bf16 v[88:91], v[182:185], v[224:227], v[88:91]
	v_mfma_f32_16x16x32_bf16 v[84:87], v[190:193], v[224:227], v[84:87]
	v_mfma_f32_16x16x32_bf16 v[72:75], v[182:185], v[232:235], v[72:75]
	v_mfma_f32_16x16x32_bf16 v[68:71], v[190:193], v[232:235], v[68:71]
	s_setprio 1
	s_barrier
	s_add_i32 s13, s13, s30
	s_add_i32 m0, s13, 0xffffff80
	ds_read_b128 v[194:197], v203 offset:49152
	ds_read_b128 v[206:209], v203 offset:50176
	ds_read_b128 v[210:213], v203 offset:51200
	ds_read_b128 v[216:219], v203 offset:52224
	global_load_lds_dwordx4 v[236:237], off offset:128
	s_add_i32 m0, s13, 0x1f80
	s_add_i32 s13, s29, s30
	global_load_lds_dwordx4 v[238:239], off offset:128
	s_add_i32 m0, s13, 0xffffff80
	ds_read_b128 v[232:235], v203 offset:56320
	global_load_lds_dwordx4 v[240:241], off offset:128
	s_add_i32 m0, s13, 0x1f80
	ds_read_b128 v[228:231], v203 offset:55296
	global_load_lds_dwordx4 v[214:215], off offset:128
	s_add_i32 m0, s37, 0xffffff80
	ds_read_b128 v[224:227], v203 offset:54272
	global_load_lds_dwordx4 v[242:243], off offset:128
	s_add_i32 m0, s41, 0xffffff80
	ds_read_b128 v[220:223], v203 offset:53248
	global_load_lds_dwordx4 v[244:245], off offset:128
	s_waitcnt vmcnt(8) lgkmcnt(0)
	s_setprio 0
	s_barrier
	v_mfma_f32_16x16x32_bf16 v[64:67], v[136:139], v[194:197], v[64:67]
	v_mfma_f32_16x16x32_bf16 v[60:63], v[144:147], v[194:197], v[60:63]
	v_mfma_f32_16x16x32_bf16 v[48:51], v[136:139], v[210:213], v[48:51]
	v_mfma_f32_16x16x32_bf16 v[44:47], v[144:147], v[210:213], v[44:47]
	v_mfma_f32_16x16x32_bf16 v[32:35], v[136:139], v[220:223], v[32:35]
	v_mfma_f32_16x16x32_bf16 v[28:31], v[144:147], v[220:223], v[28:31]
	v_mfma_f32_16x16x32_bf16 v[16:19], v[136:139], v[228:231], v[16:19]
	v_mfma_f32_16x16x32_bf16 v[12:15], v[144:147], v[228:231], v[12:15]
	v_mfma_f32_16x16x32_bf16 v[64:67], v[140:143], v[206:209], v[64:67]
	v_mfma_f32_16x16x32_bf16 v[60:63], v[148:151], v[206:209], v[60:63]
	v_mfma_f32_16x16x32_bf16 v[48:51], v[140:143], v[216:219], v[48:51]
	v_mfma_f32_16x16x32_bf16 v[44:47], v[148:151], v[216:219], v[44:47]
	v_mfma_f32_16x16x32_bf16 v[32:35], v[140:143], v[224:227], v[32:35]
	v_mfma_f32_16x16x32_bf16 v[28:31], v[148:151], v[224:227], v[28:31]
	v_mfma_f32_16x16x32_bf16 v[16:19], v[140:143], v[232:235], v[16:19]
	v_mfma_f32_16x16x32_bf16 v[12:15], v[148:151], v[232:235], v[12:15]
	v_mfma_f32_16x16x32_bf16 v[56:59], v[152:155], v[194:197], v[56:59]
	v_mfma_f32_16x16x32_bf16 v[52:55], v[186:189], v[194:197], v[52:55]
	v_mfma_f32_16x16x32_bf16 v[40:43], v[152:155], v[210:213], v[40:43]
	v_mfma_f32_16x16x32_bf16 v[36:39], v[186:189], v[210:213], v[36:39]
	v_mfma_f32_16x16x32_bf16 v[24:27], v[152:155], v[220:223], v[24:27]
	v_mfma_f32_16x16x32_bf16 v[20:23], v[186:189], v[220:223], v[20:23]
	v_mfma_f32_16x16x32_bf16 v[8:11], v[152:155], v[228:231], v[8:11]
	v_mfma_f32_16x16x32_bf16 v[4:7], v[186:189], v[228:231], v[4:7]
	v_mfma_f32_16x16x32_bf16 v[56:59], v[182:185], v[206:209], v[56:59]
	v_mfma_f32_16x16x32_bf16 v[52:55], v[190:193], v[206:209], v[52:55]
	v_mfma_f32_16x16x32_bf16 v[40:43], v[182:185], v[216:219], v[40:43]
	v_mfma_f32_16x16x32_bf16 v[36:39], v[190:193], v[216:219], v[36:39]
	v_mfma_f32_16x16x32_bf16 v[24:27], v[182:185], v[224:227], v[24:27]
	v_mfma_f32_16x16x32_bf16 v[20:23], v[190:193], v[224:227], v[20:23]
	v_mfma_f32_16x16x32_bf16 v[8:11], v[182:185], v[232:235], v[8:11]
	v_mfma_f32_16x16x32_bf16 v[4:7], v[190:193], v[232:235], v[4:7]
	s_setprio 1
	s_barrier
	v_lshl_add_u64 v[132:133], v[132:133], 0, s[26:27]
	s_cmp_ge_i32 s12, s47
	v_lshl_add_u64 v[134:135], v[134:135], 0, s[26:27]
	s_cbranch_scc0 .LBB0_1340
	s_setprio 0

; #define PG8_STAGE(bufoff, gbase, voff) do { _Pragma("unroll") for (int _i = 0; _i < 2; ++_i) \
;         __builtin_amdgcn_global_load_lds((const unsigned*)((const char*)(gbase) + (voff)[_i]), (PG8_LAS unsigned*)(lds + (bufoff) + ldsw + _i * 8192), 16, 0, 0); } while (0)
; #define PG8_LDA(dst, b, h) do { _Pragma("unroll") for (int m = 0; m < 4; ++m) _Pragma("unroll") for (int k = 0; k < 2; ++k) dst[m][k] = *(const PG8_LAS bf16x8*)(lds + PG8_SA(b, h) + aoff + m * 2048 + k * 1024); } while (0)
; #define PG8_LDB(dst, b, h) do { _Pragma("unroll") for (int n = 0; n < 2; ++n) _Pragma("unroll") for (int k = 0; k < 2; ++k) dst[n][k] = *(const PG8_LAS bf16x8*)(lds + PG8_SB(b, h) + boff + n * 2048 + k * 1024); } while (0)
; #define PG8_MMA(ai, bj, At, Bt) do { __builtin_amdgcn_s_setprio(1); _Pragma("unroll") for (int m = 0; m < 4; ++m) _Pragma("unroll") for (int n = 0; n < 2; ++n) _Pragma("unroll") for (int k = 0; k < 2; ++k) \
;         acc[ai][bj][m][n] = __builtin_amdgcn_mfma_f32_16x16x32_bf16(Bt[n][k], At[m][k], acc[ai][bj][m][n], 0, 0, 0); __builtin_amdgcn_s_setprio(0); } while (0)
; #define PG8_WAIT_V(n) asm volatile("s_waitcnt vmcnt(" #n ")" ::: "memory")
; #define PG8_WAIT_L(n) asm volatile("s_waitcnt lgkmcnt(" #n ")" ::: "memory")
; #define PG8_BAR __builtin_amdgcn_s_barrier()
; #define PG8_SCHED __builtin_amdgcn_sched_barrier(0)
; template <class Epi, class Sched, bool ALIGN_EPI = false, bool SP2 = false>
; __device__ __forceinline__ void gemm_phase(PG8_LAS unsigned char* lds, const Gemm g, const Sched& S, const Epi& E) {
;     ...
;             PG8_LDB(B0, 0, 0); PG8_LDB(B1, 0, 1); PG8_SCHED; PG8_LDA(At, 0, 0); PG8_STAGE(PG8_SA(1, 1), a1 + hstep, voffA);
;             PG8_WAIT_V(8); PG8_WAIT_L(0); PG8_BAR; PG8_MMA(0, 0, At, B0); PG8_MMA(0, 1, At, B1); PG8_BAR; PG8_SCHED;
;             PG8_LDA(At, 0, 1); PG8_STAGE(PG8_SB(0, 0), b2, voffB); PG8_STAGE(PG8_SB(0, 1), b2 + hstep, voffB); PG8_STAGE(PG8_SA(0, 0), a2, voffA);
;             PG8_WAIT_V(8); PG8_WAIT_L(0); PG8_BAR; PG8_MMA(1, 0, At, B0); PG8_MMA(1, 1, At, B1); PG8_BAR; PG8_SCHED;
.LBB0_1423:
	v_add_u32_e32 v152, s81, v169
	v_add_u32_e32 v165, s82, v169
	ds_read_b128 v[132:135], v152
	ds_read_b128 v[136:139], v152 offset:1024
	ds_read_b128 v[174:177], v152 offset:2048
	ds_read_b128 v[178:181], v152 offset:3072
	ds_read_b128 v[182:185], v165
	ds_read_b128 v[186:189], v165 offset:1024
	ds_read_b128 v[190:193], v165 offset:2048
	ds_read_b128 v[194:197], v165 offset:3072
	s_cmp_eq_u32 s74, s10
	v_lshl_add_u64 v[198:199], v[130:131], 0, s[26:27]
	s_cselect_b64 vcc, -1, 0
	s_add_i32 s10, s10, 2
	v_cndmask_b32_e32 v211, v199, v171, vcc
	v_cndmask_b32_e32 v210, v198, v170, vcc
	v_cndmask_b32_e32 v215, v129, v173, vcc
	v_cndmask_b32_e32 v214, v128, v172, vcc
	v_lshl_add_u64 v[240:241], v[130:131], 0, v[160:161]
	s_add_i32 m0, s47, 0xc000
	ds_read_b128 v[198:201], v213
	ds_read_b128 v[202:205], v213 offset:1024
	ds_read_b128 v[206:209], v213 offset:2048
	ds_read_b128 v[220:223], v213 offset:3072
	ds_read_b128 v[224:227], v213 offset:4096
	ds_read_b128 v[228:231], v213 offset:5120
	ds_read_b128 v[232:235], v213 offset:6144
	ds_read_b128 v[236:239], v213 offset:7168
	global_load_lds_dwordx4 v[240:241], off
	s_add_i32 m0, s47, 0xe000
	v_lshl_add_u64 v[240:241], v[130:131], 0, v[158:159]
	global_load_lds_dwordx4 v[240:241], off
	s_waitcnt vmcnt(8) lgkmcnt(0)
	s_setprio 0
	s_barrier
	v_mfma_f32_16x16x32_bf16 v[124:127], v[132:135], v[198:201], v[124:127]
	v_mfma_f32_16x16x32_bf16 v[120:123], v[174:177], v[198:201], v[120:123]
	v_mfma_f32_16x16x32_bf16 v[108:111], v[132:135], v[206:209], v[108:111]
	v_mfma_f32_16x16x32_bf16 v[104:107], v[174:177], v[206:209], v[104:107]
	v_mfma_f32_16x16x32_bf16 v[92:95], v[132:135], v[224:227], v[92:95]
	v_mfma_f32_16x16x32_bf16 v[88:91], v[174:177], v[224:227], v[88:91]
	v_mfma_f32_16x16x32_bf16 v[76:79], v[132:135], v[232:235], v[76:79]
	v_mfma_f32_16x16x32_bf16 v[72:75], v[174:177], v[232:235], v[72:75]
	v_mfma_f32_16x16x32_bf16 v[124:127], v[136:139], v[202:205], v[124:127]
	v_mfma_f32_16x16x32_bf16 v[120:123], v[178:181], v[202:205], v[120:123]
	v_mfma_f32_16x16x32_bf16 v[108:111], v[136:139], v[220:223], v[108:111]
	v_mfma_f32_16x16x32_bf16 v[104:107], v[178:181], v[220:223], v[104:107]
	v_mfma_f32_16x16x32_bf16 v[92:95], v[136:139], v[228:231], v[92:95]
	v_mfma_f32_16x16x32_bf16 v[88:91], v[178:181], v[228:231], v[88:91]
	v_mfma_f32_16x16x32_bf16 v[76:79], v[136:139], v[236:239], v[76:79]
	v_mfma_f32_16x16x32_bf16 v[72:75], v[178:181], v[236:239], v[72:75]
	s_cmp_eq_u32 s22, 12
	s_cbranch_scc1 .Lio_skipk0
	v_mfma_f32_16x16x32_bf16 v[116:119], v[182:185], v[198:201], v[116:119]
	v_mfma_f32_16x16x32_bf16 v[112:115], v[190:193], v[198:201], v[112:115]
	v_mfma_f32_16x16x32_bf16 v[100:103], v[182:185], v[206:209], v[100:103]
	v_mfma_f32_16x16x32_bf16 v[96:99], v[190:193], v[206:209], v[96:99]
	v_mfma_f32_16x16x32_bf16 v[84:87], v[182:185], v[224:227], v[84:87]
	v_mfma_f32_16x16x32_bf16 v[80:83], v[190:193], v[224:227], v[80:83]
	v_mfma_f32_16x16x32_bf16 v[68:71], v[182:185], v[232:235], v[68:71]
	v_mfma_f32_16x16x32_bf16 v[64:67], v[190:193], v[232:235], v[64:67]
	v_mfma_f32_16x16x32_bf16 v[116:119], v[186:189], v[202:205], v[116:119]
	v_mfma_f32_16x16x32_bf16 v[112:115], v[194:197], v[202:205], v[112:115]
	v_mfma_f32_16x16x32_bf16 v[100:103], v[186:189], v[220:223], v[100:103]
	v_mfma_f32_16x16x32_bf16 v[96:99], v[194:197], v[220:223], v[96:99]
	v_mfma_f32_16x16x32_bf16 v[84:87], v[186:189], v[228:231], v[84:87]
	v_mfma_f32_16x16x32_bf16 v[80:83], v[194:197], v[228:231], v[80:83]
	v_mfma_f32_16x16x32_bf16 v[68:71], v[186:189], v[236:239], v[68:71]
	v_mfma_f32_16x16x32_bf16 v[64:67], v[194:197], v[236:239], v[64:67]
.Lio_skipk0:
	s_setprio 1
	s_barrier
	s_add_i32 s11, s81, s41
	v_lshl_add_u64 v[240:241], v[214:215], 0, v[146:147]
	s_mov_b32 m0, s11
	ds_read_b128 v[198:201], v213 offset:16384
	ds_read_b128 v[202:205], v213 offset:17408
	ds_read_b128 v[206:209], v213 offset:18432
	ds_read_b128 v[220:223], v213 offset:19456
	ds_read_b128 v[224:227], v213 offset:20480
	ds_read_b128 v[228:231], v213 offset:21504
	ds_read_b128 v[232:235], v213 offset:22528
	ds_read_b128 v[236:239], v213 offset:23552
	global_load_lds_dwordx4 v[240:241], off
	v_lshl_add_u64 v[242:243], v[214:215], 0, v[150:151]
	s_add_i32 m0, s11, 0x2000
	v_lshl_add_u64 v[214:215], v[214:215], 0, s[18:19]
	s_add_i32 s11, s82, s41
	global_load_lds_dwordx4 v[242:243], off
	v_lshl_add_u64 v[244:245], v[214:215], 0, v[146:147]
	s_mov_b32 m0, s11
	v_lshl_add_u64 v[214:215], v[214:215], 0, v[150:151]
	global_load_lds_dwordx4 v[244:245], off
	s_add_i32 m0, s11, 0x2000
	v_lshl_add_u64 v[246:247], v[210:211], 0, v[144:145]
	global_load_lds_dwordx4 v[214:215], off
	s_mov_b32 m0, s47
	v_lshl_add_u64 v[248:249], v[210:211], 0, v[148:149]
	global_load_lds_dwordx4 v[246:247], off
	s_mov_b32 m0, s55
	s_nop 0
	global_load_lds_dwordx4 v[248:249], off
	s_waitcnt vmcnt(8) lgkmcnt(0)
	s_setprio 0
	s_barrier
	v_mfma_f32_16x16x32_bf16 v[60:63], v[132:135], v[198:201], v[60:63]
	v_mfma_f32_16x16x32_bf16 v[56:59], v[174:177], v[198:201], v[56:59]
	v_mfma_f32_16x16x32_bf16 v[44:47], v[132:135], v[206:209], v[44:47]
	v_mfma_f32_16x16x32_bf16 v[40:43], v[174:177], v[206:209], v[40:43]
	v_mfma_f32_16x16x32_bf16 v[28:31], v[132:135], v[224:227], v[28:31]
	v_mfma_f32_16x16x32_bf16 v[24:27], v[174:177], v[224:227], v[24:27]
	v_mfma_f32_16x16x32_bf16 v[12:15], v[132:135], v[232:235], v[12:15]
	v_mfma_f32_16x16x32_bf16 v[8:11], v[174:177], v[232:235], v[8:11]
	v_mfma_f32_16x16x32_bf16 v[60:63], v[136:139], v[202:205], v[60:63]
	v_mfma_f32_16x16x32_bf16 v[56:59], v[178:181], v[202:205], v[56:59]
	v_mfma_f32_16x16x32_bf16 v[44:47], v[136:139], v[220:223], v[44:47]
	v_mfma_f32_16x16x32_bf16 v[40:43], v[178:181], v[220:223], v[40:43]
	v_mfma_f32_16x16x32_bf16 v[28:31], v[136:139], v[228:231], v[28:31]
	v_mfma_f32_16x16x32_bf16 v[24:27], v[178:181], v[228:231], v[24:27]
	v_mfma_f32_16x16x32_bf16 v[12:15], v[136:139], v[236:239], v[12:15]
	v_mfma_f32_16x16x32_bf16 v[8:11], v[178:181], v[236:239], v[8:11]
	s_cmp_eq_u32 s22, 12
	s_cbranch_scc1 .Lio_skipk1
; #define PG8_STAGE(bufoff, gbase, voff) do { _Pragma("unroll") for (int _i = 0; _i < 2; ++_i) \
;         __builtin_amdgcn_global_load_lds((const unsigned*)((const char*)(gbase) + (voff)[_i]), (PG8_LAS unsigned*)(lds + (bufoff) + ldsw + _i * 8192), 16, 0, 0); } while (0)
; #define PG8_LDA(dst, b, h) do { _Pragma("unroll") for (int m = 0; m < 4; ++m) _Pragma("unroll") for (int k = 0; k < 2; ++k) dst[m][k] = *(const PG8_LAS bf16x8*)(lds + PG8_SA(b, h) + aoff + m * 2048 + k * 1024); } while (0)
; #define PG8_LDB(dst, b, h) do { _Pragma("unroll") for (int n = 0; n < 2; ++n) _Pragma("unroll") for (int k = 0; k < 2; ++k) dst[n][k] = *(const PG8_LAS bf16x8*)(lds + PG8_SB(b, h) + boff + n * 2048 + k * 1024); } while (0)
; #define PG8_MMA(ai, bj, At, Bt) do { __builtin_amdgcn_s_setprio(1); _Pragma("unroll") for (int m = 0; m < 4; ++m) _Pragma("unroll") for (int n = 0; n < 2; ++n) _Pragma("unroll") for (int k = 0; k < 2; ++k) \
;         acc[ai][bj][m][n] = __builtin_amdgcn_mfma_f32_16x16x32_bf16(Bt[n][k], At[m][k], acc[ai][bj][m][n], 0, 0, 0); __builtin_amdgcn_s_setprio(0); } while (0)
; #define PG8_WAIT_V(n) asm volatile("s_waitcnt vmcnt(" #n ")" ::: "memory")
; #define PG8_WAIT_L(n) asm volatile("s_waitcnt lgkmcnt(" #n ")" ::: "memory")
; #define PG8_BAR __builtin_amdgcn_s_barrier()
; #define PG8_SCHED __builtin_amdgcn_sched_barrier(0)
; template <class Epi, class Sched, bool ALIGN_EPI = false, bool SP2 = false>
; __device__ __forceinline__ void gemm_phase(PG8_LAS unsigned char* lds, const Gemm g, const Sched& S, const Epi& E) {
;     ...
;             PG8_WAIT_V(8); PG8_WAIT_L(0); PG8_BAR; PG8_MMA(1, 0, At, B0); PG8_MMA(1, 1, At, B1); PG8_BAR; PG8_SCHED;
;             PG8_LDB(B0, 1, 0); PG8_LDB(B1, 1, 1); PG8_SCHED; PG8_LDA(At, 1, 0); PG8_STAGE(PG8_SA(0, 1), a2 + hstep, voffA);
;             PG8_WAIT_V(8); PG8_WAIT_L(0); PG8_BAR; PG8_MMA(0, 0, At, B0); PG8_MMA(0, 1, At, B1); PG8_BAR; PG8_SCHED;
	v_mfma_f32_16x16x32_bf16 v[52:55], v[182:185], v[198:201], v[52:55]
	v_mfma_f32_16x16x32_bf16 v[48:51], v[190:193], v[198:201], v[48:51]
	v_mfma_f32_16x16x32_bf16 v[36:39], v[182:185], v[206:209], v[36:39]
	v_mfma_f32_16x16x32_bf16 v[32:35], v[190:193], v[206:209], v[32:35]
	v_mfma_f32_16x16x32_bf16 v[20:23], v[182:185], v[224:227], v[20:23]
	v_mfma_f32_16x16x32_bf16 v[16:19], v[190:193], v[224:227], v[16:19]
	v_mfma_f32_16x16x32_bf16 v[4:7], v[182:185], v[232:235], v[4:7]
	v_mfma_f32_16x16x32_bf16 v[0:3], v[190:193], v[232:235], v[0:3]
	v_mfma_f32_16x16x32_bf16 v[52:55], v[186:189], v[202:205], v[52:55]
	v_mfma_f32_16x16x32_bf16 v[48:51], v[194:197], v[202:205], v[48:51]
	v_mfma_f32_16x16x32_bf16 v[36:39], v[186:189], v[220:223], v[36:39]
	v_mfma_f32_16x16x32_bf16 v[32:35], v[194:197], v[220:223], v[32:35]
	v_mfma_f32_16x16x32_bf16 v[20:23], v[186:189], v[228:231], v[20:23]
	v_mfma_f32_16x16x32_bf16 v[16:19], v[194:197], v[228:231], v[16:19]
	v_mfma_f32_16x16x32_bf16 v[4:7], v[186:189], v[236:239], v[4:7]
	v_mfma_f32_16x16x32_bf16 v[0:3], v[194:197], v[236:239], v[0:3]
.Lio_skipk1:
	s_setprio 1
	s_barrier
	s_add_i32 s11, 0, 0x18000
	v_add_u32_e32 v152, s11, v169
	s_add_i32 s13, 0, 0x1c000
	ds_read_b128 v[132:135], v152
	ds_read_b128 v[136:139], v152 offset:1024
	ds_read_b128 v[174:177], v152 offset:2048
	ds_read_b128 v[178:181], v152 offset:3072
	v_add_u32_e32 v152, s13, v169
	ds_read_b128 v[182:185], v152
	ds_read_b128 v[186:189], v152 offset:1024
	ds_read_b128 v[190:193], v152 offset:2048
	ds_read_b128 v[194:197], v152 offset:3072
	v_lshl_add_u64 v[210:211], v[210:211], 0, s[18:19]
	s_mov_b32 m0, s57
	v_lshl_add_u64 v[250:251], v[210:211], 0, v[144:145]
	ds_read_b128 v[198:201], v213 offset:32768
	ds_read_b128 v[202:205], v213 offset:33792
	ds_read_b128 v[206:209], v213 offset:34816
	ds_read_b128 v[220:223], v213 offset:35840
	ds_read_b128 v[224:227], v213 offset:36864
	ds_read_b128 v[228:231], v213 offset:37888
	ds_read_b128 v[232:235], v213 offset:38912
	ds_read_b128 v[236:239], v213 offset:39936
	global_load_lds_dwordx4 v[250:251], off
	s_mov_b32 m0, s59
	v_lshl_add_u64 v[210:211], v[210:211], 0, v[148:149]
	global_load_lds_dwordx4 v[210:211], off
	s_waitcnt vmcnt(8) lgkmcnt(0)
	s_setprio 0
	s_barrier
	v_mfma_f32_16x16x32_bf16 v[124:127], v[132:135], v[198:201], v[124:127]
	v_mfma_f32_16x16x32_bf16 v[120:123], v[174:177], v[198:201], v[120:123]
	v_mfma_f32_16x16x32_bf16 v[108:111], v[132:135], v[206:209], v[108:111]
	v_mfma_f32_16x16x32_bf16 v[104:107], v[174:177], v[206:209], v[104:107]
	v_mfma_f32_16x16x32_bf16 v[92:95], v[132:135], v[224:227], v[92:95]
	v_mfma_f32_16x16x32_bf16 v[88:91], v[174:177], v[224:227], v[88:91]
	v_mfma_f32_16x16x32_bf16 v[76:79], v[132:135], v[232:235], v[76:79]
	v_mfma_f32_16x16x32_bf16 v[72:75], v[174:177], v[232:235], v[72:75]
	v_mfma_f32_16x16x32_bf16 v[124:127], v[136:139], v[202:205], v[124:127]
	v_mfma_f32_16x16x32_bf16 v[120:123], v[178:181], v[202:205], v[120:123]
	v_mfma_f32_16x16x32_bf16 v[108:111], v[136:139], v[220:223], v[108:111]
	v_mfma_f32_16x16x32_bf16 v[104:107], v[178:181], v[220:223], v[104:107]
	v_mfma_f32_16x16x32_bf16 v[92:95], v[136:139], v[228:231], v[92:95]
	v_mfma_f32_16x16x32_bf16 v[88:91], v[178:181], v[228:231], v[88:91]
	v_mfma_f32_16x16x32_bf16 v[76:79], v[136:139], v[236:239], v[76:79]
	v_mfma_f32_16x16x32_bf16 v[72:75], v[178:181], v[236:239], v[72:75]
	s_cmp_eq_u32 s22, 12
	s_cbranch_scc1 .Lio_skipk2
	v_mfma_f32_16x16x32_bf16 v[116:119], v[182:185], v[198:201], v[116:119]
	v_mfma_f32_16x16x32_bf16 v[112:115], v[190:193], v[198:201], v[112:115]
	v_mfma_f32_16x16x32_bf16 v[100:103], v[182:185], v[206:209], v[100:103]
	v_mfma_f32_16x16x32_bf16 v[96:99], v[190:193], v[206:209], v[96:99]
	v_mfma_f32_16x16x32_bf16 v[84:87], v[182:185], v[224:227], v[84:87]
	v_mfma_f32_16x16x32_bf16 v[80:83], v[190:193], v[224:227], v[80:83]
	v_mfma_f32_16x16x32_bf16 v[68:71], v[182:185], v[232:235], v[68:71]
	v_mfma_f32_16x16x32_bf16 v[64:67], v[190:193], v[232:235], v[64:67]
	v_mfma_f32_16x16x32_bf16 v[116:119], v[186:189], v[202:205], v[116:119]
	v_mfma_f32_16x16x32_bf16 v[112:115], v[194:197], v[202:205], v[112:115]
	v_mfma_f32_16x16x32_bf16 v[100:103], v[186:189], v[220:223], v[100:103]
	v_mfma_f32_16x16x32_bf16 v[96:99], v[194:197], v[220:223], v[96:99]
	v_mfma_f32_16x16x32_bf16 v[84:87], v[186:189], v[228:231], v[84:87]
	v_mfma_f32_16x16x32_bf16 v[80:83], v[194:197], v[228:231], v[80:83]
	v_mfma_f32_16x16x32_bf16 v[68:71], v[186:189], v[236:239], v[68:71]
	v_mfma_f32_16x16x32_bf16 v[64:67], v[194:197], v[236:239], v[64:67]
; #define PG8_STAGE(bufoff, gbase, voff) do { _Pragma("unroll") for (int _i = 0; _i < 2; ++_i) \
;         __builtin_amdgcn_global_load_lds((const unsigned*)((const char*)(gbase) + (voff)[_i]), (PG8_LAS unsigned*)(lds + (bufoff) + ldsw + _i * 8192), 16, 0, 0); } while (0)
; #define PG8_LDA(dst, b, h) do { _Pragma("unroll") for (int m = 0; m < 4; ++m) _Pragma("unroll") for (int k = 0; k < 2; ++k) dst[m][k] = *(const PG8_LAS bf16x8*)(lds + PG8_SA(b, h) + aoff + m * 2048 + k * 1024); } while (0)
; #define PG8_MMA(ai, bj, At, Bt) do { __builtin_amdgcn_s_setprio(1); _Pragma("unroll") for (int m = 0; m < 4; ++m) _Pragma("unroll") for (int n = 0; n < 2; ++n) _Pragma("unroll") for (int k = 0; k < 2; ++k) \
;         acc[ai][bj][m][n] = __builtin_amdgcn_mfma_f32_16x16x32_bf16(Bt[n][k], At[m][k], acc[ai][bj][m][n], 0, 0, 0); __builtin_amdgcn_s_setprio(0); } while (0)
; #define PG8_WAIT_V(n) asm volatile("s_waitcnt vmcnt(" #n ")" ::: "memory")
; #define PG8_WAIT_L(n) asm volatile("s_waitcnt lgkmcnt(" #n ")" ::: "memory")
; #define PG8_BAR __builtin_amdgcn_s_barrier()
; #define PG8_SCHED __builtin_amdgcn_sched_barrier(0)
; template <class Epi, class Sched, bool ALIGN_EPI = false, bool SP2 = false>
; __device__ __forceinline__ void gemm_phase(PG8_LAS unsigned char* lds, const Gemm g, const Sched& S, const Epi& E) {
;     ...
;             PG8_LDA(At, 1, 1); PG8_STAGE(PG8_SB(1, 0), b3, voffB); PG8_STAGE(PG8_SB(1, 1), b3 + hstep, voffB); PG8_STAGE(PG8_SA(1, 0), a3, voffA);
;             PG8_WAIT_V(8); PG8_WAIT_L(0); PG8_BAR; PG8_MMA(1, 0, At, B0); PG8_MMA(1, 1, At, B1); PG8_BAR; PG8_SCHED;
.Lio_skipk2:
	s_setprio 1
	s_barrier
	s_add_i32 s11, s11, s41
	s_add_i32 m0, s11, 0xffffff80
	ds_read_b128 v[198:201], v213 offset:49152
	ds_read_b128 v[202:205], v213 offset:50176
	ds_read_b128 v[206:209], v213 offset:51200
	ds_read_b128 v[220:223], v213 offset:52224
	global_load_lds_dwordx4 v[240:241], off offset:128
	s_add_i32 m0, s11, 0x1f80
	s_add_i32 s11, s13, s41
	global_load_lds_dwordx4 v[242:243], off offset:128
	s_add_i32 m0, s11, 0xffffff80
	ds_read_b128 v[236:239], v213 offset:56320
	global_load_lds_dwordx4 v[244:245], off offset:128
	s_add_i32 m0, s11, 0x1f80
	ds_read_b128 v[232:235], v213 offset:55296
	global_load_lds_dwordx4 v[214:215], off offset:128
	s_add_i32 m0, s69, 0xffffff80
	ds_read_b128 v[228:231], v213 offset:54272
	global_load_lds_dwordx4 v[246:247], off offset:128
	s_add_i32 m0, s70, 0xffffff80
	ds_read_b128 v[224:227], v213 offset:53248
	global_load_lds_dwordx4 v[248:249], off offset:128
	s_waitcnt vmcnt(8) lgkmcnt(0)
	s_setprio 0
	s_barrier
	v_mfma_f32_16x16x32_bf16 v[60:63], v[132:135], v[198:201], v[60:63]
	v_mfma_f32_16x16x32_bf16 v[56:59], v[174:177], v[198:201], v[56:59]
	v_mfma_f32_16x16x32_bf16 v[44:47], v[132:135], v[206:209], v[44:47]
	v_mfma_f32_16x16x32_bf16 v[40:43], v[174:177], v[206:209], v[40:43]
	v_mfma_f32_16x16x32_bf16 v[28:31], v[132:135], v[224:227], v[28:31]
	v_mfma_f32_16x16x32_bf16 v[24:27], v[174:177], v[224:227], v[24:27]
	v_mfma_f32_16x16x32_bf16 v[12:15], v[132:135], v[232:235], v[12:15]
	v_mfma_f32_16x16x32_bf16 v[8:11], v[174:177], v[232:235], v[8:11]
	v_mfma_f32_16x16x32_bf16 v[60:63], v[136:139], v[202:205], v[60:63]
	v_mfma_f32_16x16x32_bf16 v[56:59], v[178:181], v[202:205], v[56:59]
	v_mfma_f32_16x16x32_bf16 v[44:47], v[136:139], v[220:223], v[44:47]
	v_mfma_f32_16x16x32_bf16 v[40:43], v[178:181], v[220:223], v[40:43]
	v_mfma_f32_16x16x32_bf16 v[28:31], v[136:139], v[228:231], v[28:31]
	v_mfma_f32_16x16x32_bf16 v[24:27], v[178:181], v[228:231], v[24:27]
	v_mfma_f32_16x16x32_bf16 v[12:15], v[136:139], v[236:239], v[12:15]
	v_mfma_f32_16x16x32_bf16 v[8:11], v[178:181], v[236:239], v[8:11]
	s_cmp_eq_u32 s22, 12
	s_cbranch_scc1 .Lio_skipk3
	v_mfma_f32_16x16x32_bf16 v[52:55], v[182:185], v[198:201], v[52:55]
	v_mfma_f32_16x16x32_bf16 v[48:51], v[190:193], v[198:201], v[48:51]
	v_mfma_f32_16x16x32_bf16 v[36:39], v[182:185], v[206:209], v[36:39]
	v_mfma_f32_16x16x32_bf16 v[32:35], v[190:193], v[206:209], v[32:35]
	v_mfma_f32_16x16x32_bf16 v[20:23], v[182:185], v[224:227], v[20:23]
	v_mfma_f32_16x16x32_bf16 v[16:19], v[190:193], v[224:227], v[16:19]
	v_mfma_f32_16x16x32_bf16 v[4:7], v[182:185], v[232:235], v[4:7]
	v_mfma_f32_16x16x32_bf16 v[0:3], v[190:193], v[232:235], v[0:3]
	v_mfma_f32_16x16x32_bf16 v[52:55], v[186:189], v[202:205], v[52:55]
	v_mfma_f32_16x16x32_bf16 v[48:51], v[194:197], v[202:205], v[48:51]
	v_mfma_f32_16x16x32_bf16 v[36:39], v[186:189], v[220:223], v[36:39]
	v_mfma_f32_16x16x32_bf16 v[32:35], v[194:197], v[220:223], v[32:35]
	v_mfma_f32_16x16x32_bf16 v[20:23], v[186:189], v[228:231], v[20:23]
	v_mfma_f32_16x16x32_bf16 v[16:19], v[194:197], v[228:231], v[16:19]
	v_mfma_f32_16x16x32_bf16 v[4:7], v[186:189], v[236:239], v[4:7]
	v_mfma_f32_16x16x32_bf16 v[0:3], v[194:197], v[236:239], v[0:3]
.Lio_skipk3:
	s_setprio 1
	s_barrier
	v_lshl_add_u64 v[128:129], v[128:129], 0, s[36:37]
	s_cmp_ge_i32 s10, s67
	v_lshl_add_u64 v[130:131], v[130:131], 0, s[36:37]
	s_cbranch_scc0 .LBB0_1423
	s_setprio 0

; #define PG8_STAGE(bufoff, gbase, voff) do { _Pragma("unroll") for (int _i = 0; _i < 2; ++_i) \
;         __builtin_amdgcn_global_load_lds((const unsigned*)((const char*)(gbase) + (voff)[_i]), (PG8_LAS unsigned*)(lds + (bufoff) + ldsw + _i * 8192), 16, 0, 0); } while (0)
; #define PG8_LDA(dst, b, h) do { _Pragma("unroll") for (int m = 0; m < 4; ++m) _Pragma("unroll") for (int k = 0; k < 2; ++k) dst[m][k] = *(const PG8_LAS bf16x8*)(lds + PG8_SA(b, h) + aoff + m * 2048 + k * 1024); } while (0)
; #define PG8_LDB(dst, b, h) do { _Pragma("unroll") for (int n = 0; n < 2; ++n) _Pragma("unroll") for (int k = 0; k < 2; ++k) dst[n][k] = *(const PG8_LAS bf16x8*)(lds + PG8_SB(b, h) + boff + n * 2048 + k * 1024); } while (0)
; #define PG8_MMA(ai, bj, At, Bt) do { __builtin_amdgcn_s_setprio(1); _Pragma("unroll") for (int m = 0; m < 4; ++m) _Pragma("unroll") for (int n = 0; n < 2; ++n) _Pragma("unroll") for (int k = 0; k < 2; ++k) \
;         acc[ai][bj][m][n] = __builtin_amdgcn_mfma_f32_16x16x32_bf16(Bt[n][k], At[m][k], acc[ai][bj][m][n], 0, 0, 0); __builtin_amdgcn_s_setprio(0); } while (0)
; #define PG8_WAIT_V(n) asm volatile("s_waitcnt vmcnt(" #n ")" ::: "memory")
; #define PG8_WAIT_L(n) asm volatile("s_waitcnt lgkmcnt(" #n ")" ::: "memory")
; #define PG8_BAR __builtin_amdgcn_s_barrier()
; #define PG8_SCHED __builtin_amdgcn_sched_barrier(0)
; template <class Epi, class Sched, bool ALIGN_EPI = false, bool SP2 = false>
; __device__ __forceinline__ void gemm_phase(PG8_LAS unsigned char* lds, const Gemm g, const Sched& S, const Epi& E) {
;     ...
;             const bool last = (t == nt - 2);
;             const char* a1 = cA + (size_t)(t + 1) * kstep;
;             const char* a2 = last ? nA : cA + (size_t)(t + 2) * kstep; const char* b2 = last ? nB : cB + (size_t)(t + 2) * kstep;
;             const char* a3 = a2 + kstep; const char* b3 = b2 + kstep;
;             if (last && has_next) S.a_ready(nxt);
;             if constexpr (SP2) {
;             PG8_LDB(B0, 0, 0); PG8_LDB(B1, 0, 1); PG8_SCHED; PG8_LDA(At, 0, 0); PG8_STAGE(PG8_SA(1, 1), a1 + hstep, voffA);
;             PG8_WAIT_V(8); PG8_WAIT_L(0); PG8_BAR; PG8_MMA(0, 0, At, B0); PG8_MMA(0, 1, At, B1); PG8_BAR; PG8_SCHED;
;             PG8_LDA(At, 0, 1); PG8_STAGE(PG8_SB(0, 0), b2, voffB); PG8_STAGE(PG8_SB(0, 1), b2 + hstep, voffB); PG8_STAGE(PG8_SA(0, 0), a2, voffA);
.LBB0_1695:
	v_add_u32_e32 v188, s54, v199
	ds_read_b128 v[132:135], v201
	ds_read_b128 v[136:139], v201 offset:1024
	ds_read_b128 v[140:143], v201 offset:2048
	ds_read_b128 v[144:147], v201 offset:3072
	ds_read_b128 v[148:151], v188
	ds_read_b128 v[180:183], v188 offset:1024
	ds_read_b128 v[184:187], v188 offset:2048
	ds_read_b128 v[188:191], v188 offset:3072
	s_cmp_eq_u32 s48, s12
	v_lshl_add_u64 v[192:193], v[130:131], 0, s[22:23]
	s_cselect_b64 vcc, -1, 0
	s_add_i32 s12, s12, 2
	v_cndmask_b32_e32 v197, v193, v177, vcc
	v_cndmask_b32_e32 v196, v192, v176, vcc
	v_cndmask_b32_e32 v213, v129, v179, vcc
	v_cndmask_b32_e32 v212, v128, v178, vcc
	s_mov_b32 m0, s55
	v_lshl_add_u64 v[214:215], v[130:131], 0, v[172:173]
	ds_read_b128 v[192:195], v202
	ds_read_b128 v[204:207], v202 offset:1024
	ds_read_b128 v[208:211], v202 offset:2048
	ds_read_b128 v[216:219], v202 offset:3072
	ds_read_b128 v[220:223], v202 offset:4096
	ds_read_b128 v[224:227], v202 offset:5120
	ds_read_b128 v[228:231], v202 offset:6144
	ds_read_b128 v[232:235], v202 offset:7168
	global_load_lds_dwordx4 v[214:215], off
	s_mov_b32 m0, s56
	v_lshl_add_u64 v[214:215], v[130:131], 0, v[170:171]
	global_load_lds_dwordx4 v[214:215], off
	s_waitcnt vmcnt(8) lgkmcnt(0)
	s_setprio 0
	s_barrier
	v_mfma_f32_16x16x32_bf16 v[120:123], v[132:135], v[192:195], v[120:123]
	v_mfma_f32_16x16x32_bf16 v[124:127], v[140:143], v[192:195], v[124:127]
	v_mfma_f32_16x16x32_bf16 v[108:111], v[132:135], v[208:211], v[108:111]
	v_mfma_f32_16x16x32_bf16 v[104:107], v[140:143], v[208:211], v[104:107]
	v_mfma_f32_16x16x32_bf16 v[92:95], v[132:135], v[220:223], v[92:95]
	v_mfma_f32_16x16x32_bf16 v[88:91], v[140:143], v[220:223], v[88:91]
	v_mfma_f32_16x16x32_bf16 v[76:79], v[132:135], v[228:231], v[76:79]
	v_mfma_f32_16x16x32_bf16 v[72:75], v[140:143], v[228:231], v[72:75]
	v_mfma_f32_16x16x32_bf16 v[120:123], v[136:139], v[204:207], v[120:123]
	v_mfma_f32_16x16x32_bf16 v[124:127], v[144:147], v[204:207], v[124:127]
	v_mfma_f32_16x16x32_bf16 v[108:111], v[136:139], v[216:219], v[108:111]
	v_mfma_f32_16x16x32_bf16 v[104:107], v[144:147], v[216:219], v[104:107]
	v_mfma_f32_16x16x32_bf16 v[92:95], v[136:139], v[224:227], v[92:95]
	v_mfma_f32_16x16x32_bf16 v[88:91], v[144:147], v[224:227], v[88:91]
	v_mfma_f32_16x16x32_bf16 v[76:79], v[136:139], v[232:235], v[76:79]
	v_mfma_f32_16x16x32_bf16 v[72:75], v[144:147], v[232:235], v[72:75]
	v_mfma_f32_16x16x32_bf16 v[116:119], v[148:151], v[192:195], v[116:119]
	v_mfma_f32_16x16x32_bf16 v[112:115], v[184:187], v[192:195], v[112:115]
	v_mfma_f32_16x16x32_bf16 v[100:103], v[148:151], v[208:211], v[100:103]
	v_mfma_f32_16x16x32_bf16 v[96:99], v[184:187], v[208:211], v[96:99]
	v_mfma_f32_16x16x32_bf16 v[84:87], v[148:151], v[220:223], v[84:87]
	v_mfma_f32_16x16x32_bf16 v[80:83], v[184:187], v[220:223], v[80:83]
	v_mfma_f32_16x16x32_bf16 v[68:71], v[148:151], v[228:231], v[68:71]
	v_mfma_f32_16x16x32_bf16 v[64:67], v[184:187], v[228:231], v[64:67]
	v_mfma_f32_16x16x32_bf16 v[116:119], v[180:183], v[204:207], v[116:119]
	v_mfma_f32_16x16x32_bf16 v[112:115], v[188:191], v[204:207], v[112:115]
	v_mfma_f32_16x16x32_bf16 v[100:103], v[180:183], v[216:219], v[100:103]
	v_mfma_f32_16x16x32_bf16 v[96:99], v[188:191], v[216:219], v[96:99]
	v_mfma_f32_16x16x32_bf16 v[84:87], v[180:183], v[224:227], v[84:87]
	v_mfma_f32_16x16x32_bf16 v[80:83], v[188:191], v[224:227], v[80:83]
	v_mfma_f32_16x16x32_bf16 v[68:71], v[180:183], v[232:235], v[68:71]
	v_mfma_f32_16x16x32_bf16 v[64:67], v[188:191], v[232:235], v[64:67]
	s_setprio 1
	s_barrier
	s_mov_b32 m0, s57
	v_lshl_add_u64 v[214:215], v[212:213], 0, v[164:165]
	ds_read_b128 v[192:195], v202 offset:16384
	ds_read_b128 v[204:207], v202 offset:17408
	ds_read_b128 v[208:211], v202 offset:18432
	ds_read_b128 v[216:219], v202 offset:19456
	ds_read_b128 v[220:223], v202 offset:20480
	ds_read_b128 v[224:227], v202 offset:21504
	ds_read_b128 v[228:231], v202 offset:22528
	ds_read_b128 v[232:235], v202 offset:23552
	global_load_lds_dwordx4 v[214:215], off
	v_lshl_add_u64 v[236:237], v[212:213], 0, v[168:169]
	s_mov_b32 m0, s58
	v_lshl_add_u64 v[212:213], v[212:213], 0, s[14:15]
	s_add_i32 s13, s54, s30
	global_load_lds_dwordx4 v[236:237], off
	v_lshl_add_u64 v[238:239], v[212:213], 0, v[164:165]
	s_mov_b32 m0, s13
	v_lshl_add_u64 v[212:213], v[212:213], 0, v[168:169]
	global_load_lds_dwordx4 v[238:239], off
	s_add_i32 m0, s13, 0x2000
	v_lshl_add_u64 v[240:241], v[196:197], 0, v[162:163]
	global_load_lds_dwordx4 v[212:213], off
	s_mov_b32 m0, s31
	v_lshl_add_u64 v[242:243], v[196:197], 0, v[166:167]
	global_load_lds_dwordx4 v[240:241], off
	s_mov_b32 m0, s34
	s_nop 0
	global_load_lds_dwordx4 v[242:243], off
	s_waitcnt vmcnt(8) lgkmcnt(0)
	s_setprio 0
	s_barrier
; #define PG8_STAGE(bufoff, gbase, voff) do { _Pragma("unroll") for (int _i = 0; _i < 2; ++_i) \
;         __builtin_amdgcn_global_load_lds((const unsigned*)((const char*)(gbase) + (voff)[_i]), (PG8_LAS unsigned*)(lds + (bufoff) + ldsw + _i * 8192), 16, 0, 0); } while (0)
; #define PG8_LDA(dst, b, h) do { _Pragma("unroll") for (int m = 0; m < 4; ++m) _Pragma("unroll") for (int k = 0; k < 2; ++k) dst[m][k] = *(const PG8_LAS bf16x8*)(lds + PG8_SA(b, h) + aoff + m * 2048 + k * 1024); } while (0)
; #define PG8_LDB(dst, b, h) do { _Pragma("unroll") for (int n = 0; n < 2; ++n) _Pragma("unroll") for (int k = 0; k < 2; ++k) dst[n][k] = *(const PG8_LAS bf16x8*)(lds + PG8_SB(b, h) + boff + n * 2048 + k * 1024); } while (0)
; #define PG8_MMA(ai, bj, At, Bt) do { __builtin_amdgcn_s_setprio(1); _Pragma("unroll") for (int m = 0; m < 4; ++m) _Pragma("unroll") for (int n = 0; n < 2; ++n) _Pragma("unroll") for (int k = 0; k < 2; ++k) \
;         acc[ai][bj][m][n] = __builtin_amdgcn_mfma_f32_16x16x32_bf16(Bt[n][k], At[m][k], acc[ai][bj][m][n], 0, 0, 0); __builtin_amdgcn_s_setprio(0); } while (0)
; #define PG8_WAIT_V(n) asm volatile("s_waitcnt vmcnt(" #n ")" ::: "memory")
; #define PG8_WAIT_L(n) asm volatile("s_waitcnt lgkmcnt(" #n ")" ::: "memory")
; #define PG8_BAR __builtin_amdgcn_s_barrier()
; #define PG8_SCHED __builtin_amdgcn_sched_barrier(0)
; template <class Epi, class Sched, bool ALIGN_EPI = false, bool SP2 = false>
; __device__ __forceinline__ void gemm_phase(PG8_LAS unsigned char* lds, const Gemm g, const Sched& S, const Epi& E) {
;     ...
;             PG8_WAIT_V(8); PG8_WAIT_L(0); PG8_BAR; PG8_MMA(1, 0, At, B0); PG8_MMA(1, 1, At, B1); PG8_BAR; PG8_SCHED;
;             PG8_LDB(B0, 1, 0); PG8_LDB(B1, 1, 1); PG8_SCHED; PG8_LDA(At, 1, 0); PG8_STAGE(PG8_SA(0, 1), a2 + hstep, voffA);
	v_mfma_f32_16x16x32_bf16 v[60:63], v[132:135], v[192:195], v[60:63]
	v_mfma_f32_16x16x32_bf16 v[56:59], v[140:143], v[192:195], v[56:59]
	v_mfma_f32_16x16x32_bf16 v[44:47], v[132:135], v[208:211], v[44:47]
	v_mfma_f32_16x16x32_bf16 v[40:43], v[140:143], v[208:211], v[40:43]
	v_mfma_f32_16x16x32_bf16 v[28:31], v[132:135], v[220:223], v[28:31]
	v_mfma_f32_16x16x32_bf16 v[24:27], v[140:143], v[220:223], v[24:27]
	v_mfma_f32_16x16x32_bf16 v[12:15], v[132:135], v[228:231], v[12:15]
	v_mfma_f32_16x16x32_bf16 v[8:11], v[140:143], v[228:231], v[8:11]
	v_mfma_f32_16x16x32_bf16 v[60:63], v[136:139], v[204:207], v[60:63]
	v_mfma_f32_16x16x32_bf16 v[56:59], v[144:147], v[204:207], v[56:59]
	v_mfma_f32_16x16x32_bf16 v[44:47], v[136:139], v[216:219], v[44:47]
	v_mfma_f32_16x16x32_bf16 v[40:43], v[144:147], v[216:219], v[40:43]
	v_mfma_f32_16x16x32_bf16 v[28:31], v[136:139], v[224:227], v[28:31]
	v_mfma_f32_16x16x32_bf16 v[24:27], v[144:147], v[224:227], v[24:27]
	v_mfma_f32_16x16x32_bf16 v[12:15], v[136:139], v[232:235], v[12:15]
	v_mfma_f32_16x16x32_bf16 v[8:11], v[144:147], v[232:235], v[8:11]
	v_mfma_f32_16x16x32_bf16 v[52:55], v[148:151], v[192:195], v[52:55]
	v_mfma_f32_16x16x32_bf16 v[48:51], v[184:187], v[192:195], v[48:51]
	v_mfma_f32_16x16x32_bf16 v[36:39], v[148:151], v[208:211], v[36:39]
	v_mfma_f32_16x16x32_bf16 v[32:35], v[184:187], v[208:211], v[32:35]
	v_mfma_f32_16x16x32_bf16 v[20:23], v[148:151], v[220:223], v[20:23]
	v_mfma_f32_16x16x32_bf16 v[16:19], v[184:187], v[220:223], v[16:19]
	v_mfma_f32_16x16x32_bf16 v[4:7], v[148:151], v[228:231], v[4:7]
	v_mfma_f32_16x16x32_bf16 v[0:3], v[184:187], v[228:231], v[0:3]
	v_mfma_f32_16x16x32_bf16 v[52:55], v[180:183], v[204:207], v[52:55]
	v_mfma_f32_16x16x32_bf16 v[48:51], v[188:191], v[204:207], v[48:51]
	v_mfma_f32_16x16x32_bf16 v[36:39], v[180:183], v[216:219], v[36:39]
	v_mfma_f32_16x16x32_bf16 v[32:35], v[188:191], v[216:219], v[32:35]
	v_mfma_f32_16x16x32_bf16 v[20:23], v[180:183], v[224:227], v[20:23]
	v_mfma_f32_16x16x32_bf16 v[16:19], v[188:191], v[224:227], v[16:19]
	v_mfma_f32_16x16x32_bf16 v[4:7], v[180:183], v[232:235], v[4:7]
	v_mfma_f32_16x16x32_bf16 v[0:3], v[188:191], v[232:235], v[0:3]
	s_setprio 1
	s_barrier
	s_add_i32 s13, 0, 0x18000
	s_add_i32 s29, 0, 0x1c000
	v_add_u32_e32 v144, s13, v199
	v_add_u32_e32 v188, s29, v199
	ds_read_b128 v[132:135], v144
	ds_read_b128 v[136:139], v144 offset:1024
	ds_read_b128 v[140:143], v144 offset:2048
	ds_read_b128 v[144:147], v144 offset:3072
	ds_read_b128 v[148:151], v188
	ds_read_b128 v[180:183], v188 offset:1024
	ds_read_b128 v[184:187], v188 offset:2048
	ds_read_b128 v[188:191], v188 offset:3072
	v_lshl_add_u64 v[196:197], v[196:197], 0, s[14:15]
	s_mov_b32 m0, s35
	v_lshl_add_u64 v[244:245], v[196:197], 0, v[162:163]
	ds_read_b128 v[192:195], v202 offset:32768
	ds_read_b128 v[204:207], v202 offset:33792
	ds_read_b128 v[208:211], v202 offset:34816
	ds_read_b128 v[216:219], v202 offset:35840
	ds_read_b128 v[220:223], v202 offset:36864
	ds_read_b128 v[224:227], v202 offset:37888
	ds_read_b128 v[228:231], v202 offset:38912
	ds_read_b128 v[232:235], v202 offset:39936
	global_load_lds_dwordx4 v[244:245], off
	s_mov_b32 m0, s36
	v_lshl_add_u64 v[196:197], v[196:197], 0, v[166:167]
	global_load_lds_dwordx4 v[196:197], off
	s_waitcnt vmcnt(8) lgkmcnt(0)
	s_setprio 0
	s_barrier
; #define PG8_STAGE(bufoff, gbase, voff) do { _Pragma("unroll") for (int _i = 0; _i < 2; ++_i) \
;         __builtin_amdgcn_global_load_lds((const unsigned*)((const char*)(gbase) + (voff)[_i]), (PG8_LAS unsigned*)(lds + (bufoff) + ldsw + _i * 8192), 16, 0, 0); } while (0)
; #define PG8_LDA(dst, b, h) do { _Pragma("unroll") for (int m = 0; m < 4; ++m) _Pragma("unroll") for (int k = 0; k < 2; ++k) dst[m][k] = *(const PG8_LAS bf16x8*)(lds + PG8_SA(b, h) + aoff + m * 2048 + k * 1024); } while (0)
; #define PG8_MMA(ai, bj, At, Bt) do { __builtin_amdgcn_s_setprio(1); _Pragma("unroll") for (int m = 0; m < 4; ++m) _Pragma("unroll") for (int n = 0; n < 2; ++n) _Pragma("unroll") for (int k = 0; k < 2; ++k) \
;         acc[ai][bj][m][n] = __builtin_amdgcn_mfma_f32_16x16x32_bf16(Bt[n][k], At[m][k], acc[ai][bj][m][n], 0, 0, 0); __builtin_amdgcn_s_setprio(0); } while (0)
; #define PG8_WAIT_V(n) asm volatile("s_waitcnt vmcnt(" #n ")" ::: "memory")
; #define PG8_WAIT_L(n) asm volatile("s_waitcnt lgkmcnt(" #n ")" ::: "memory")
; #define PG8_BAR __builtin_amdgcn_s_barrier()
; #define PG8_SCHED __builtin_amdgcn_sched_barrier(0)
; template <class Epi, class Sched, bool ALIGN_EPI = false, bool SP2 = false>
; __device__ __forceinline__ void gemm_phase(PG8_LAS unsigned char* lds, const Gemm g, const Sched& S, const Epi& E) {
;     ...
;             PG8_WAIT_V(8); PG8_WAIT_L(0); PG8_BAR; PG8_MMA(0, 0, At, B0); PG8_MMA(0, 1, At, B1); PG8_BAR; PG8_SCHED;
;             PG8_LDA(At, 1, 1); PG8_STAGE(PG8_SB(1, 0), b3, voffB); PG8_STAGE(PG8_SB(1, 1), b3 + hstep, voffB); PG8_STAGE(PG8_SA(1, 0), a3, voffA);
;             PG8_WAIT_V(8); PG8_WAIT_L(0); PG8_BAR; PG8_MMA(1, 0, At, B0); PG8_MMA(1, 1, At, B1); PG8_BAR; PG8_SCHED;
	v_mfma_f32_16x16x32_bf16 v[120:123], v[132:135], v[192:195], v[120:123]
	v_mfma_f32_16x16x32_bf16 v[124:127], v[140:143], v[192:195], v[124:127]
	v_mfma_f32_16x16x32_bf16 v[108:111], v[132:135], v[208:211], v[108:111]
	v_mfma_f32_16x16x32_bf16 v[104:107], v[140:143], v[208:211], v[104:107]
	v_mfma_f32_16x16x32_bf16 v[92:95], v[132:135], v[220:223], v[92:95]
	v_mfma_f32_16x16x32_bf16 v[88:91], v[140:143], v[220:223], v[88:91]
	v_mfma_f32_16x16x32_bf16 v[76:79], v[132:135], v[228:231], v[76:79]
	v_mfma_f32_16x16x32_bf16 v[72:75], v[140:143], v[228:231], v[72:75]
	v_mfma_f32_16x16x32_bf16 v[120:123], v[136:139], v[204:207], v[120:123]
	v_mfma_f32_16x16x32_bf16 v[124:127], v[144:147], v[204:207], v[124:127]
	v_mfma_f32_16x16x32_bf16 v[108:111], v[136:139], v[216:219], v[108:111]
	v_mfma_f32_16x16x32_bf16 v[104:107], v[144:147], v[216:219], v[104:107]
	v_mfma_f32_16x16x32_bf16 v[92:95], v[136:139], v[224:227], v[92:95]
	v_mfma_f32_16x16x32_bf16 v[88:91], v[144:147], v[224:227], v[88:91]
	v_mfma_f32_16x16x32_bf16 v[76:79], v[136:139], v[232:235], v[76:79]
	v_mfma_f32_16x16x32_bf16 v[72:75], v[144:147], v[232:235], v[72:75]
	v_mfma_f32_16x16x32_bf16 v[116:119], v[148:151], v[192:195], v[116:119]
	v_mfma_f32_16x16x32_bf16 v[112:115], v[184:187], v[192:195], v[112:115]
	v_mfma_f32_16x16x32_bf16 v[100:103], v[148:151], v[208:211], v[100:103]
	v_mfma_f32_16x16x32_bf16 v[96:99], v[184:187], v[208:211], v[96:99]
	v_mfma_f32_16x16x32_bf16 v[84:87], v[148:151], v[220:223], v[84:87]
	v_mfma_f32_16x16x32_bf16 v[80:83], v[184:187], v[220:223], v[80:83]
	v_mfma_f32_16x16x32_bf16 v[68:71], v[148:151], v[228:231], v[68:71]
	v_mfma_f32_16x16x32_bf16 v[64:67], v[184:187], v[228:231], v[64:67]
	v_mfma_f32_16x16x32_bf16 v[116:119], v[180:183], v[204:207], v[116:119]
	v_mfma_f32_16x16x32_bf16 v[112:115], v[188:191], v[204:207], v[112:115]
	v_mfma_f32_16x16x32_bf16 v[100:103], v[180:183], v[216:219], v[100:103]
	v_mfma_f32_16x16x32_bf16 v[96:99], v[188:191], v[216:219], v[96:99]
	v_mfma_f32_16x16x32_bf16 v[84:87], v[180:183], v[224:227], v[84:87]
	v_mfma_f32_16x16x32_bf16 v[80:83], v[188:191], v[224:227], v[80:83]
	v_mfma_f32_16x16x32_bf16 v[68:71], v[180:183], v[232:235], v[68:71]
	v_mfma_f32_16x16x32_bf16 v[64:67], v[188:191], v[232:235], v[64:67]
	s_setprio 1
	s_barrier
	s_add_i32 s13, s13, s30
	s_add_i32 m0, s13, 0xffffff80
	ds_read_b128 v[192:195], v202 offset:49152
	ds_read_b128 v[204:207], v202 offset:50176
	ds_read_b128 v[208:211], v202 offset:51200
	ds_read_b128 v[216:219], v202 offset:52224
	global_load_lds_dwordx4 v[214:215], off offset:128
	s_add_i32 m0, s13, 0x1f80
	s_add_i32 s13, s29, s30
	global_load_lds_dwordx4 v[236:237], off offset:128
	s_add_i32 m0, s13, 0xffffff80
	ds_read_b128 v[232:235], v202 offset:56320
	global_load_lds_dwordx4 v[238:239], off offset:128
	s_add_i32 m0, s13, 0x1f80
	ds_read_b128 v[228:231], v202 offset:55296
	global_load_lds_dwordx4 v[212:213], off offset:128
	s_add_i32 m0, s37, 0xffffff80
	ds_read_b128 v[224:227], v202 offset:54272
	global_load_lds_dwordx4 v[240:241], off offset:128
	s_add_i32 m0, s41, 0xffffff80
	ds_read_b128 v[220:223], v202 offset:53248
	global_load_lds_dwordx4 v[242:243], off offset:128
	s_waitcnt vmcnt(8) lgkmcnt(0)
	s_setprio 0
	s_barrier
	v_mfma_f32_16x16x32_bf16 v[60:63], v[132:135], v[192:195], v[60:63]
	v_mfma_f32_16x16x32_bf16 v[56:59], v[140:143], v[192:195], v[56:59]
	v_mfma_f32_16x16x32_bf16 v[44:47], v[132:135], v[208:211], v[44:47]
	v_mfma_f32_16x16x32_bf16 v[40:43], v[140:143], v[208:211], v[40:43]
	v_mfma_f32_16x16x32_bf16 v[28:31], v[132:135], v[220:223], v[28:31]
	v_mfma_f32_16x16x32_bf16 v[24:27], v[140:143], v[220:223], v[24:27]
	v_mfma_f32_16x16x32_bf16 v[12:15], v[132:135], v[228:231], v[12:15]
	v_mfma_f32_16x16x32_bf16 v[8:11], v[140:143], v[228:231], v[8:11]
	v_mfma_f32_16x16x32_bf16 v[60:63], v[136:139], v[204:207], v[60:63]
	v_mfma_f32_16x16x32_bf16 v[56:59], v[144:147], v[204:207], v[56:59]
	v_mfma_f32_16x16x32_bf16 v[44:47], v[136:139], v[216:219], v[44:47]
	v_mfma_f32_16x16x32_bf16 v[40:43], v[144:147], v[216:219], v[40:43]
	v_mfma_f32_16x16x32_bf16 v[28:31], v[136:139], v[224:227], v[28:31]
	v_mfma_f32_16x16x32_bf16 v[24:27], v[144:147], v[224:227], v[24:27]
	v_mfma_f32_16x16x32_bf16 v[12:15], v[136:139], v[232:235], v[12:15]
	v_mfma_f32_16x16x32_bf16 v[8:11], v[144:147], v[232:235], v[8:11]
	v_mfma_f32_16x16x32_bf16 v[52:55], v[148:151], v[192:195], v[52:55]
	v_mfma_f32_16x16x32_bf16 v[48:51], v[184:187], v[192:195], v[48:51]
	v_mfma_f32_16x16x32_bf16 v[36:39], v[148:151], v[208:211], v[36:39]
	v_mfma_f32_16x16x32_bf16 v[32:35], v[184:187], v[208:211], v[32:35]
	v_mfma_f32_16x16x32_bf16 v[20:23], v[148:151], v[220:223], v[20:23]
	v_mfma_f32_16x16x32_bf16 v[16:19], v[184:187], v[220:223], v[16:19]
	v_mfma_f32_16x16x32_bf16 v[4:7], v[148:151], v[228:231], v[4:7]
	v_mfma_f32_16x16x32_bf16 v[0:3], v[184:187], v[228:231], v[0:3]
	v_mfma_f32_16x16x32_bf16 v[52:55], v[180:183], v[204:207], v[52:55]
	v_mfma_f32_16x16x32_bf16 v[48:51], v[188:191], v[204:207], v[48:51]
	v_mfma_f32_16x16x32_bf16 v[36:39], v[180:183], v[216:219], v[36:39]
	v_mfma_f32_16x16x32_bf16 v[32:35], v[188:191], v[216:219], v[32:35]
	v_mfma_f32_16x16x32_bf16 v[20:23], v[180:183], v[224:227], v[20:23]
	v_mfma_f32_16x16x32_bf16 v[16:19], v[188:191], v[224:227], v[16:19]
	v_mfma_f32_16x16x32_bf16 v[4:7], v[180:183], v[232:235], v[4:7]
	v_mfma_f32_16x16x32_bf16 v[0:3], v[188:191], v[232:235], v[0:3]
	s_setprio 1
	s_barrier
	v_lshl_add_u64 v[128:129], v[128:129], 0, s[26:27]
	s_cmp_ge_i32 s12, s47
	v_lshl_add_u64 v[130:131], v[130:131], 0, s[26:27]
	s_cbranch_scc0 .LBB0_1695
	s_setprio 0

; #define PG8_STAGE(bufoff, gbase, voff) do { _Pragma("unroll") for (int _i = 0; _i < 2; ++_i) \
;         __builtin_amdgcn_global_load_lds((const unsigned*)((const char*)(gbase) + (voff)[_i]), (PG8_LAS unsigned*)(lds + (bufoff) + ldsw + _i * 8192), 16, 0, 0); } while (0)
; #define PG8_LDA(dst, b, h) do { _Pragma("unroll") for (int m = 0; m < 4; ++m) _Pragma("unroll") for (int k = 0; k < 2; ++k) dst[m][k] = *(const PG8_LAS bf16x8*)(lds + PG8_SA(b, h) + aoff + m * 2048 + k * 1024); } while (0)
; #define PG8_LDB(dst, b, h) do { _Pragma("unroll") for (int n = 0; n < 2; ++n) _Pragma("unroll") for (int k = 0; k < 2; ++k) dst[n][k] = *(const PG8_LAS bf16x8*)(lds + PG8_SB(b, h) + boff + n * 2048 + k * 1024); } while (0)
; #define PG8_MMA(ai, bj, At, Bt) do { __builtin_amdgcn_s_setprio(1); _Pragma("unroll") for (int m = 0; m < 4; ++m) _Pragma("unroll") for (int n = 0; n < 2; ++n) _Pragma("unroll") for (int k = 0; k < 2; ++k) \
;         acc[ai][bj][m][n] = __builtin_amdgcn_mfma_f32_16x16x32_bf16(Bt[n][k], At[m][k], acc[ai][bj][m][n], 0, 0, 0); __builtin_amdgcn_s_setprio(0); } while (0)
; #define PG8_WAIT_V(n) asm volatile("s_waitcnt vmcnt(" #n ")" ::: "memory")
; #define PG8_WAIT_L(n) asm volatile("s_waitcnt lgkmcnt(" #n ")" ::: "memory")
; template <class Epi, class Sched, bool ALIGN_EPI = false, bool SP2 = false>
; __device__ __forceinline__ void gemm_phase(PG8_LAS unsigned char* lds, const Gemm g, const Sched& S, const Epi& E) {
;     ...
;             const bool last = (t == nt - 2);
;             const char* a1 = cA + (size_t)(t + 1) * kstep;
;             const char* a2 = last ? nA : cA + (size_t)(t + 2) * kstep; const char* b2 = last ? nB : cB + (size_t)(t + 2) * kstep;
;             const char* a3 = a2 + kstep; const char* b3 = b2 + kstep;
;             if (last && has_next) S.a_ready(nxt);
;             if constexpr (SP2) {
;             PG8_LDB(B0, 0, 0); PG8_LDB(B1, 0, 1); PG8_SCHED; PG8_LDA(At, 0, 0); PG8_STAGE(PG8_SA(1, 1), a1 + hstep, voffA);
;             PG8_WAIT_V(8); PG8_WAIT_L(0); PG8_BAR; PG8_MMA(0, 0, At, B0); PG8_MMA(0, 1, At, B1); PG8_BAR; PG8_SCHED;
;             PG8_LDA(At, 0, 1); PG8_STAGE(PG8_SB(0, 0), b2, voffB); PG8_STAGE(PG8_SB(0, 1), b2 + hstep, voffB); PG8_STAGE(PG8_SA(0, 0), a2, voffA);
;             PG8_WAIT_V(8); PG8_WAIT_L(0); PG8_BAR; PG8_MMA(1, 0, At, B0); PG8_MMA(1, 1, At, B1); PG8_BAR; PG8_SCHED;
.LBB0_1776:
	v_add_u32_e32 v166, s54, v169
	v_add_u32_e32 v168, s55, v169
	ds_read_b128 v[162:165], v166
	ds_read_b128 v[182:185], v166 offset:1024
	ds_read_b128 v[186:189], v166 offset:2048
	ds_read_b128 v[190:193], v166 offset:3072
	ds_read_b128 v[194:197], v168
	ds_read_b128 v[198:201], v168 offset:1024
	ds_read_b128 v[202:205], v168 offset:2048
	ds_read_b128 v[206:209], v168 offset:3072
	s_cmp_eq_u32 s53, s10
	v_lshl_add_u64 v[172:173], v[160:161], 0, s[22:23]
	s_cselect_b64 vcc, -1, 0
	s_add_i32 s10, s10, 2
	v_cndmask_b32_e32 v173, v173, v153, vcc
	v_cndmask_b32_e32 v172, v172, v152, vcc
	v_cndmask_b32_e32 v215, v159, v155, vcc
	v_cndmask_b32_e32 v214, v158, v154, vcc
	s_mov_b32 m0, s56
	v_lshl_add_u64 v[244:245], v[160:161], 0, v[148:149]
	ds_read_b128 v[210:213], v179
	ds_read_b128 v[216:219], v179 offset:1024
	ds_read_b128 v[220:223], v179 offset:2048
	ds_read_b128 v[224:227], v179 offset:3072
	ds_read_b128 v[228:231], v179 offset:4096
	ds_read_b128 v[232:235], v179 offset:5120
	ds_read_b128 v[236:239], v179 offset:6144
	ds_read_b128 v[240:243], v179 offset:7168
	global_load_lds_dwordx4 v[244:245], off
	s_mov_b32 m0, s57
	v_lshl_add_u64 v[244:245], v[160:161], 0, v[146:147]
	global_load_lds_dwordx4 v[244:245], off
	s_waitcnt vmcnt(8) lgkmcnt(0)
	s_setprio 0
	s_barrier
	v_mfma_f32_16x16x32_bf16 v[124:127], v[162:165], v[210:213], v[124:127]
	v_mfma_f32_16x16x32_bf16 v[116:119], v[186:189], v[210:213], v[116:119]
	v_mfma_f32_16x16x32_bf16 v[108:111], v[162:165], v[220:223], v[108:111]
	v_mfma_f32_16x16x32_bf16 v[100:103], v[186:189], v[220:223], v[100:103]
	v_mfma_f32_16x16x32_bf16 v[92:95], v[162:165], v[228:231], v[92:95]
	v_mfma_f32_16x16x32_bf16 v[84:87], v[186:189], v[228:231], v[84:87]
	v_mfma_f32_16x16x32_bf16 v[76:79], v[162:165], v[236:239], v[76:79]
	v_mfma_f32_16x16x32_bf16 v[68:71], v[186:189], v[236:239], v[68:71]
	v_mfma_f32_16x16x32_bf16 v[124:127], v[182:185], v[216:219], v[124:127]
	v_mfma_f32_16x16x32_bf16 v[116:119], v[190:193], v[216:219], v[116:119]
	v_mfma_f32_16x16x32_bf16 v[108:111], v[182:185], v[224:227], v[108:111]
	v_mfma_f32_16x16x32_bf16 v[100:103], v[190:193], v[224:227], v[100:103]
	v_mfma_f32_16x16x32_bf16 v[92:95], v[182:185], v[232:235], v[92:95]
	v_mfma_f32_16x16x32_bf16 v[84:87], v[190:193], v[232:235], v[84:87]
	v_mfma_f32_16x16x32_bf16 v[76:79], v[182:185], v[240:243], v[76:79]
	v_mfma_f32_16x16x32_bf16 v[68:71], v[190:193], v[240:243], v[68:71]
	v_mfma_f32_16x16x32_bf16 v[120:123], v[194:197], v[210:213], v[120:123]
	v_mfma_f32_16x16x32_bf16 v[112:115], v[202:205], v[210:213], v[112:115]
	v_mfma_f32_16x16x32_bf16 v[104:107], v[194:197], v[220:223], v[104:107]
	v_mfma_f32_16x16x32_bf16 v[96:99], v[202:205], v[220:223], v[96:99]
	v_mfma_f32_16x16x32_bf16 v[88:91], v[194:197], v[228:231], v[88:91]
	v_mfma_f32_16x16x32_bf16 v[80:83], v[202:205], v[228:231], v[80:83]
	v_mfma_f32_16x16x32_bf16 v[72:75], v[194:197], v[236:239], v[72:75]
	v_mfma_f32_16x16x32_bf16 v[64:67], v[202:205], v[236:239], v[64:67]
	v_mfma_f32_16x16x32_bf16 v[120:123], v[198:201], v[216:219], v[120:123]
	v_mfma_f32_16x16x32_bf16 v[112:115], v[206:209], v[216:219], v[112:115]
	v_mfma_f32_16x16x32_bf16 v[104:107], v[198:201], v[224:227], v[104:107]
	v_mfma_f32_16x16x32_bf16 v[96:99], v[206:209], v[224:227], v[96:99]
	v_mfma_f32_16x16x32_bf16 v[88:91], v[198:201], v[232:235], v[88:91]
	v_mfma_f32_16x16x32_bf16 v[80:83], v[206:209], v[232:235], v[80:83]
	v_mfma_f32_16x16x32_bf16 v[72:75], v[198:201], v[240:243], v[72:75]
	v_mfma_f32_16x16x32_bf16 v[64:67], v[206:209], v[240:243], v[64:67]
	s_setprio 1
	s_barrier
	s_mov_b32 m0, s60
	v_lshl_add_u64 v[244:245], v[214:215], 0, v[138:139]
	ds_read_b128 v[210:213], v179 offset:16384
	ds_read_b128 v[216:219], v179 offset:17408
	ds_read_b128 v[220:223], v179 offset:18432
	ds_read_b128 v[224:227], v179 offset:19456
	ds_read_b128 v[228:231], v179 offset:20480
	ds_read_b128 v[232:235], v179 offset:21504
	ds_read_b128 v[236:239], v179 offset:22528
	ds_read_b128 v[240:243], v179 offset:23552
	global_load_lds_dwordx4 v[244:245], off
	v_lshl_add_u64 v[246:247], v[214:215], 0, v[134:135]
	s_mov_b32 m0, s61
	v_lshl_add_u64 v[214:215], v[214:215], 0, s[14:15]
	global_load_lds_dwordx4 v[246:247], off
	v_lshl_add_u64 v[248:249], v[214:215], 0, v[138:139]
	s_mov_b32 m0, s62
	v_lshl_add_u64 v[214:215], v[214:215], 0, v[134:135]
	global_load_lds_dwordx4 v[248:249], off
	s_add_i32 m0, s62, 0x2000
	v_lshl_add_u64 v[250:251], v[172:173], 0, v[140:141]
	global_load_lds_dwordx4 v[214:215], off
	s_mov_b32 m0, s46
	v_lshl_add_u64 v[252:253], v[172:173], 0, v[136:137]
	global_load_lds_dwordx4 v[250:251], off
	s_mov_b32 m0, s47
	s_nop 0
	global_load_lds_dwordx4 v[252:253], off
	s_waitcnt vmcnt(8) lgkmcnt(0)
	s_setprio 0
	s_barrier
; #define PG8_STAGE(bufoff, gbase, voff) do { _Pragma("unroll") for (int _i = 0; _i < 2; ++_i) \
;         __builtin_amdgcn_global_load_lds((const unsigned*)((const char*)(gbase) + (voff)[_i]), (PG8_LAS unsigned*)(lds + (bufoff) + ldsw + _i * 8192), 16, 0, 0); } while (0)
; #define PG8_LDA(dst, b, h) do { _Pragma("unroll") for (int m = 0; m < 4; ++m) _Pragma("unroll") for (int k = 0; k < 2; ++k) dst[m][k] = *(const PG8_LAS bf16x8*)(lds + PG8_SA(b, h) + aoff + m * 2048 + k * 1024); } while (0)
; #define PG8_LDB(dst, b, h) do { _Pragma("unroll") for (int n = 0; n < 2; ++n) _Pragma("unroll") for (int k = 0; k < 2; ++k) dst[n][k] = *(const PG8_LAS bf16x8*)(lds + PG8_SB(b, h) + boff + n * 2048 + k * 1024); } while (0)
; #define PG8_MMA(ai, bj, At, Bt) do { __builtin_amdgcn_s_setprio(1); _Pragma("unroll") for (int m = 0; m < 4; ++m) _Pragma("unroll") for (int n = 0; n < 2; ++n) _Pragma("unroll") for (int k = 0; k < 2; ++k) \
;         acc[ai][bj][m][n] = __builtin_amdgcn_mfma_f32_16x16x32_bf16(Bt[n][k], At[m][k], acc[ai][bj][m][n], 0, 0, 0); __builtin_amdgcn_s_setprio(0); } while (0)
; #define PG8_WAIT_V(n) asm volatile("s_waitcnt vmcnt(" #n ")" ::: "memory")
; #define PG8_WAIT_L(n) asm volatile("s_waitcnt lgkmcnt(" #n ")" ::: "memory")
; #define PG8_BAR __builtin_amdgcn_s_barrier()
; #define PG8_SCHED __builtin_amdgcn_sched_barrier(0)
; template <class Epi, class Sched, bool ALIGN_EPI = false, bool SP2 = false>
; __device__ __forceinline__ void gemm_phase(PG8_LAS unsigned char* lds, const Gemm g, const Sched& S, const Epi& E) {
;     ...
;             PG8_WAIT_V(8); PG8_WAIT_L(0); PG8_BAR; PG8_MMA(1, 0, At, B0); PG8_MMA(1, 1, At, B1); PG8_BAR; PG8_SCHED;
;             PG8_LDB(B0, 1, 0); PG8_LDB(B1, 1, 1); PG8_SCHED; PG8_LDA(At, 1, 0); PG8_STAGE(PG8_SA(0, 1), a2 + hstep, voffA);
	v_mfma_f32_16x16x32_bf16 v[60:63], v[162:165], v[210:213], v[60:63]
	v_mfma_f32_16x16x32_bf16 v[52:55], v[186:189], v[210:213], v[52:55]
	v_mfma_f32_16x16x32_bf16 v[44:47], v[162:165], v[220:223], v[44:47]
	v_mfma_f32_16x16x32_bf16 v[36:39], v[186:189], v[220:223], v[36:39]
	v_mfma_f32_16x16x32_bf16 v[28:31], v[162:165], v[228:231], v[28:31]
	v_mfma_f32_16x16x32_bf16 v[20:23], v[186:189], v[228:231], v[20:23]
	v_mfma_f32_16x16x32_bf16 v[12:15], v[162:165], v[236:239], v[12:15]
	v_mfma_f32_16x16x32_bf16 v[4:7], v[186:189], v[236:239], v[4:7]
	v_mfma_f32_16x16x32_bf16 v[60:63], v[182:185], v[216:219], v[60:63]
	v_mfma_f32_16x16x32_bf16 v[52:55], v[190:193], v[216:219], v[52:55]
	v_mfma_f32_16x16x32_bf16 v[44:47], v[182:185], v[224:227], v[44:47]
	v_mfma_f32_16x16x32_bf16 v[36:39], v[190:193], v[224:227], v[36:39]
	v_mfma_f32_16x16x32_bf16 v[28:31], v[182:185], v[232:235], v[28:31]
	v_mfma_f32_16x16x32_bf16 v[20:23], v[190:193], v[232:235], v[20:23]
	v_mfma_f32_16x16x32_bf16 v[12:15], v[182:185], v[240:243], v[12:15]
	v_mfma_f32_16x16x32_bf16 v[4:7], v[190:193], v[240:243], v[4:7]
	v_mfma_f32_16x16x32_bf16 v[56:59], v[194:197], v[210:213], v[56:59]
	v_mfma_f32_16x16x32_bf16 v[48:51], v[202:205], v[210:213], v[48:51]
	v_mfma_f32_16x16x32_bf16 v[40:43], v[194:197], v[220:223], v[40:43]
	v_mfma_f32_16x16x32_bf16 v[32:35], v[202:205], v[220:223], v[32:35]
	v_mfma_f32_16x16x32_bf16 v[24:27], v[194:197], v[228:231], v[24:27]
	v_mfma_f32_16x16x32_bf16 v[16:19], v[202:205], v[228:231], v[16:19]
	v_mfma_f32_16x16x32_bf16 v[8:11], v[194:197], v[236:239], v[8:11]
	v_mfma_f32_16x16x32_bf16 v[0:3], v[202:205], v[236:239], v[0:3]
	v_mfma_f32_16x16x32_bf16 v[56:59], v[198:201], v[216:219], v[56:59]
	v_mfma_f32_16x16x32_bf16 v[48:51], v[206:209], v[216:219], v[48:51]
	v_mfma_f32_16x16x32_bf16 v[40:43], v[198:201], v[224:227], v[40:43]
	v_mfma_f32_16x16x32_bf16 v[32:35], v[206:209], v[224:227], v[32:35]
	v_mfma_f32_16x16x32_bf16 v[24:27], v[198:201], v[232:235], v[24:27]
	v_mfma_f32_16x16x32_bf16 v[16:19], v[206:209], v[232:235], v[16:19]
	v_mfma_f32_16x16x32_bf16 v[8:11], v[198:201], v[240:243], v[8:11]
	v_mfma_f32_16x16x32_bf16 v[0:3], v[206:209], v[240:243], v[0:3]
	s_setprio 1
	s_barrier
	s_add_i32 s11, 0, 0x18000
	v_add_u32_e32 v166, s11, v169
	s_add_i32 s13, 0, 0x1c000
	ds_read_b128 v[162:165], v166
	ds_read_b128 v[182:185], v166 offset:1024
	ds_read_b128 v[186:189], v166 offset:2048
	ds_read_b128 v[190:193], v166 offset:3072
	v_add_u32_e32 v166, s13, v169
	ds_read_b128 v[194:197], v166
	ds_read_b128 v[198:201], v166 offset:1024
	ds_read_b128 v[202:205], v166 offset:2048
	ds_read_b128 v[206:209], v166 offset:3072
	v_lshl_add_u64 v[172:173], v[172:173], 0, s[14:15]
	s_mov_b32 m0, s48
	v_lshl_add_u64 v[170:171], v[172:173], 0, v[140:141]
	ds_read_b128 v[210:213], v179 offset:32768
	ds_read_b128 v[216:219], v179 offset:33792
	ds_read_b128 v[220:223], v179 offset:34816
	ds_read_b128 v[224:227], v179 offset:35840
	ds_read_b128 v[228:231], v179 offset:36864
	ds_read_b128 v[232:235], v179 offset:37888
	ds_read_b128 v[236:239], v179 offset:38912
	ds_read_b128 v[240:243], v179 offset:39936
	global_load_lds_dwordx4 v[170:171], off
	s_mov_b32 m0, s49
	v_lshl_add_u64 v[170:171], v[172:173], 0, v[136:137]
	global_load_lds_dwordx4 v[170:171], off
	s_waitcnt vmcnt(8) lgkmcnt(0)
	s_setprio 0
	s_barrier
; #define PG8_STAGE(bufoff, gbase, voff) do { _Pragma("unroll") for (int _i = 0; _i < 2; ++_i) \
;         __builtin_amdgcn_global_load_lds((const unsigned*)((const char*)(gbase) + (voff)[_i]), (PG8_LAS unsigned*)(lds + (bufoff) + ldsw + _i * 8192), 16, 0, 0); } while (0)
; #define PG8_LDA(dst, b, h) do { _Pragma("unroll") for (int m = 0; m < 4; ++m) _Pragma("unroll") for (int k = 0; k < 2; ++k) dst[m][k] = *(const PG8_LAS bf16x8*)(lds + PG8_SA(b, h) + aoff + m * 2048 + k * 1024); } while (0)
; #define PG8_MMA(ai, bj, At, Bt) do { __builtin_amdgcn_s_setprio(1); _Pragma("unroll") for (int m = 0; m < 4; ++m) _Pragma("unroll") for (int n = 0; n < 2; ++n) _Pragma("unroll") for (int k = 0; k < 2; ++k) \
;         acc[ai][bj][m][n] = __builtin_amdgcn_mfma_f32_16x16x32_bf16(Bt[n][k], At[m][k], acc[ai][bj][m][n], 0, 0, 0); __builtin_amdgcn_s_setprio(0); } while (0)
; #define PG8_WAIT_V(n) asm volatile("s_waitcnt vmcnt(" #n ")" ::: "memory")
; #define PG8_WAIT_L(n) asm volatile("s_waitcnt lgkmcnt(" #n ")" ::: "memory")
; #define PG8_BAR __builtin_amdgcn_s_barrier()
; #define PG8_SCHED __builtin_amdgcn_sched_barrier(0)
; template <class Epi, class Sched, bool ALIGN_EPI = false, bool SP2 = false>
; __device__ __forceinline__ void gemm_phase(PG8_LAS unsigned char* lds, const Gemm g, const Sched& S, const Epi& E) {
;     ...
;             PG8_WAIT_V(8); PG8_WAIT_L(0); PG8_BAR; PG8_MMA(0, 0, At, B0); PG8_MMA(0, 1, At, B1); PG8_BAR; PG8_SCHED;
;             PG8_LDA(At, 1, 1); PG8_STAGE(PG8_SB(1, 0), b3, voffB); PG8_STAGE(PG8_SB(1, 1), b3 + hstep, voffB); PG8_STAGE(PG8_SA(1, 0), a3, voffA);
;             PG8_WAIT_V(8); PG8_WAIT_L(0); PG8_BAR; PG8_MMA(1, 0, At, B0); PG8_MMA(1, 1, At, B1); PG8_BAR; PG8_SCHED;
	v_mfma_f32_16x16x32_bf16 v[124:127], v[162:165], v[210:213], v[124:127]
	v_mfma_f32_16x16x32_bf16 v[116:119], v[186:189], v[210:213], v[116:119]
	v_mfma_f32_16x16x32_bf16 v[108:111], v[162:165], v[220:223], v[108:111]
	v_mfma_f32_16x16x32_bf16 v[100:103], v[186:189], v[220:223], v[100:103]
	v_mfma_f32_16x16x32_bf16 v[92:95], v[162:165], v[228:231], v[92:95]
	v_mfma_f32_16x16x32_bf16 v[84:87], v[186:189], v[228:231], v[84:87]
	v_mfma_f32_16x16x32_bf16 v[76:79], v[162:165], v[236:239], v[76:79]
	v_mfma_f32_16x16x32_bf16 v[68:71], v[186:189], v[236:239], v[68:71]
	v_mfma_f32_16x16x32_bf16 v[124:127], v[182:185], v[216:219], v[124:127]
	v_mfma_f32_16x16x32_bf16 v[116:119], v[190:193], v[216:219], v[116:119]
	v_mfma_f32_16x16x32_bf16 v[108:111], v[182:185], v[224:227], v[108:111]
	v_mfma_f32_16x16x32_bf16 v[100:103], v[190:193], v[224:227], v[100:103]
	v_mfma_f32_16x16x32_bf16 v[92:95], v[182:185], v[232:235], v[92:95]
	v_mfma_f32_16x16x32_bf16 v[84:87], v[190:193], v[232:235], v[84:87]
	v_mfma_f32_16x16x32_bf16 v[76:79], v[182:185], v[240:243], v[76:79]
	v_mfma_f32_16x16x32_bf16 v[68:71], v[190:193], v[240:243], v[68:71]
	v_mfma_f32_16x16x32_bf16 v[120:123], v[194:197], v[210:213], v[120:123]
	v_mfma_f32_16x16x32_bf16 v[112:115], v[202:205], v[210:213], v[112:115]
	v_mfma_f32_16x16x32_bf16 v[104:107], v[194:197], v[220:223], v[104:107]
	v_mfma_f32_16x16x32_bf16 v[96:99], v[202:205], v[220:223], v[96:99]
	v_mfma_f32_16x16x32_bf16 v[88:91], v[194:197], v[228:231], v[88:91]
	v_mfma_f32_16x16x32_bf16 v[80:83], v[202:205], v[228:231], v[80:83]
	v_mfma_f32_16x16x32_bf16 v[72:75], v[194:197], v[236:239], v[72:75]
	v_mfma_f32_16x16x32_bf16 v[64:67], v[202:205], v[236:239], v[64:67]
	v_mfma_f32_16x16x32_bf16 v[120:123], v[198:201], v[216:219], v[120:123]
	v_mfma_f32_16x16x32_bf16 v[112:115], v[206:209], v[216:219], v[112:115]
	v_mfma_f32_16x16x32_bf16 v[104:107], v[198:201], v[224:227], v[104:107]
	v_mfma_f32_16x16x32_bf16 v[96:99], v[206:209], v[224:227], v[96:99]
	v_mfma_f32_16x16x32_bf16 v[88:91], v[198:201], v[232:235], v[88:91]
	v_mfma_f32_16x16x32_bf16 v[80:83], v[206:209], v[232:235], v[80:83]
	v_mfma_f32_16x16x32_bf16 v[72:75], v[198:201], v[240:243], v[72:75]
	v_mfma_f32_16x16x32_bf16 v[64:67], v[206:209], v[240:243], v[64:67]
	s_setprio 1
	s_barrier
	s_add_i32 s11, s11, s29
	s_add_i32 m0, s11, 0xffffff80
	ds_read_b128 v[210:213], v179 offset:49152
	ds_read_b128 v[216:219], v179 offset:50176
	ds_read_b128 v[220:223], v179 offset:51200
	ds_read_b128 v[224:227], v179 offset:52224
	global_load_lds_dwordx4 v[244:245], off offset:128
	s_add_i32 m0, s11, 0x1f80
	s_add_i32 s11, s13, s29
	global_load_lds_dwordx4 v[246:247], off offset:128
	s_add_i32 m0, s11, 0xffffff80
	ds_read_b128 v[240:243], v179 offset:56320
	global_load_lds_dwordx4 v[248:249], off offset:128
	s_add_i32 m0, s11, 0x1f80
	ds_read_b128 v[236:239], v179 offset:55296
	global_load_lds_dwordx4 v[214:215], off offset:128
	s_add_i32 m0, s50, 0xffffff80
	ds_read_b128 v[232:235], v179 offset:54272
	global_load_lds_dwordx4 v[250:251], off offset:128
	s_add_i32 m0, s51, 0xffffff80
	ds_read_b128 v[228:231], v179 offset:53248
	global_load_lds_dwordx4 v[252:253], off offset:128
	s_waitcnt vmcnt(8) lgkmcnt(0)
	s_setprio 0
	s_barrier
	v_mfma_f32_16x16x32_bf16 v[60:63], v[162:165], v[210:213], v[60:63]
	v_mfma_f32_16x16x32_bf16 v[52:55], v[186:189], v[210:213], v[52:55]
	v_mfma_f32_16x16x32_bf16 v[44:47], v[162:165], v[220:223], v[44:47]
	v_mfma_f32_16x16x32_bf16 v[36:39], v[186:189], v[220:223], v[36:39]
	v_mfma_f32_16x16x32_bf16 v[28:31], v[162:165], v[228:231], v[28:31]
	v_mfma_f32_16x16x32_bf16 v[20:23], v[186:189], v[228:231], v[20:23]
	v_mfma_f32_16x16x32_bf16 v[12:15], v[162:165], v[236:239], v[12:15]
	v_mfma_f32_16x16x32_bf16 v[4:7], v[186:189], v[236:239], v[4:7]
	v_mfma_f32_16x16x32_bf16 v[60:63], v[182:185], v[216:219], v[60:63]
	v_mfma_f32_16x16x32_bf16 v[52:55], v[190:193], v[216:219], v[52:55]
	v_mfma_f32_16x16x32_bf16 v[44:47], v[182:185], v[224:227], v[44:47]
	v_mfma_f32_16x16x32_bf16 v[36:39], v[190:193], v[224:227], v[36:39]
	v_mfma_f32_16x16x32_bf16 v[28:31], v[182:185], v[232:235], v[28:31]
	v_mfma_f32_16x16x32_bf16 v[20:23], v[190:193], v[232:235], v[20:23]
	v_mfma_f32_16x16x32_bf16 v[12:15], v[182:185], v[240:243], v[12:15]
	v_mfma_f32_16x16x32_bf16 v[4:7], v[190:193], v[240:243], v[4:7]
	v_mfma_f32_16x16x32_bf16 v[56:59], v[194:197], v[210:213], v[56:59]
	v_mfma_f32_16x16x32_bf16 v[48:51], v[202:205], v[210:213], v[48:51]
	v_mfma_f32_16x16x32_bf16 v[40:43], v[194:197], v[220:223], v[40:43]
	v_mfma_f32_16x16x32_bf16 v[32:35], v[202:205], v[220:223], v[32:35]
	v_mfma_f32_16x16x32_bf16 v[24:27], v[194:197], v[228:231], v[24:27]
	v_mfma_f32_16x16x32_bf16 v[16:19], v[202:205], v[228:231], v[16:19]
	v_mfma_f32_16x16x32_bf16 v[8:11], v[194:197], v[236:239], v[8:11]
	v_mfma_f32_16x16x32_bf16 v[0:3], v[202:205], v[236:239], v[0:3]
	v_mfma_f32_16x16x32_bf16 v[56:59], v[198:201], v[216:219], v[56:59]
	v_mfma_f32_16x16x32_bf16 v[48:51], v[206:209], v[216:219], v[48:51]
	v_mfma_f32_16x16x32_bf16 v[40:43], v[198:201], v[224:227], v[40:43]
	v_mfma_f32_16x16x32_bf16 v[32:35], v[206:209], v[224:227], v[32:35]
	v_mfma_f32_16x16x32_bf16 v[24:27], v[198:201], v[232:235], v[24:27]
	v_mfma_f32_16x16x32_bf16 v[16:19], v[206:209], v[232:235], v[16:19]
	v_mfma_f32_16x16x32_bf16 v[8:11], v[198:201], v[240:243], v[8:11]
	v_mfma_f32_16x16x32_bf16 v[0:3], v[206:209], v[240:243], v[0:3]
	s_setprio 1
	s_barrier
	v_lshl_add_u64 v[158:159], v[158:159], 0, s[26:27]
	s_cmp_ge_i32 s10, s52
	v_lshl_add_u64 v[160:161], v[160:161], 0, s[26:27]
	s_cbranch_scc0 .LBB0_1776
	s_setprio 0

; #define PG8_STAGE(bufoff, gbase, voff) do { _Pragma("unroll") for (int _i = 0; _i < 2; ++_i) \
;         __builtin_amdgcn_global_load_lds((const unsigned*)((const char*)(gbase) + (voff)[_i]), (PG8_LAS unsigned*)(lds + (bufoff) + ldsw + _i * 8192), 16, 0, 0); } while (0)
; #define PG8_LDA(dst, b, h) do { _Pragma("unroll") for (int m = 0; m < 4; ++m) _Pragma("unroll") for (int k = 0; k < 2; ++k) dst[m][k] = *(const PG8_LAS bf16x8*)(lds + PG8_SA(b, h) + aoff + m * 2048 + k * 1024); } while (0)
; #define PG8_LDB(dst, b, h) do { _Pragma("unroll") for (int n = 0; n < 2; ++n) _Pragma("unroll") for (int k = 0; k < 2; ++k) dst[n][k] = *(const PG8_LAS bf16x8*)(lds + PG8_SB(b, h) + boff + n * 2048 + k * 1024); } while (0)
; #define PG8_MMA(ai, bj, At, Bt) do { __builtin_amdgcn_s_setprio(1); _Pragma("unroll") for (int m = 0; m < 4; ++m) _Pragma("unroll") for (int n = 0; n < 2; ++n) _Pragma("unroll") for (int k = 0; k < 2; ++k) \
;         acc[ai][bj][m][n] = __builtin_amdgcn_mfma_f32_16x16x32_bf16(Bt[n][k], At[m][k], acc[ai][bj][m][n], 0, 0, 0); __builtin_amdgcn_s_setprio(0); } while (0)
; #define PG8_WAIT_V(n) asm volatile("s_waitcnt vmcnt(" #n ")" ::: "memory")
; #define PG8_WAIT_L(n) asm volatile("s_waitcnt lgkmcnt(" #n ")" ::: "memory")
; template <class Epi, class Sched, bool ALIGN_EPI = false, bool SP2 = false>
; __device__ __forceinline__ void gemm_phase(PG8_LAS unsigned char* lds, const Gemm g, const Sched& S, const Epi& E) {
;     ...
;             const bool last = (t == nt - 2);
;             const char* a1 = cA + (size_t)(t + 1) * kstep;
;             const char* a2 = last ? nA : cA + (size_t)(t + 2) * kstep; const char* b2 = last ? nB : cB + (size_t)(t + 2) * kstep;
;             const char* a3 = a2 + kstep; const char* b3 = b2 + kstep;
;             if (last && has_next) S.a_ready(nxt);
;             if constexpr (SP2) {
;             PG8_LDB(B0, 0, 0); PG8_LDB(B1, 0, 1); PG8_SCHED; PG8_LDA(At, 0, 0); PG8_STAGE(PG8_SA(1, 1), a1 + hstep, voffA);
;             PG8_WAIT_V(8); PG8_WAIT_L(0); PG8_BAR; PG8_MMA(0, 0, At, B0); PG8_MMA(0, 1, At, B1); PG8_BAR; PG8_SCHED;
;             PG8_LDA(At, 0, 1); PG8_STAGE(PG8_SB(0, 0), b2, voffB); PG8_STAGE(PG8_SB(0, 1), b2 + hstep, voffB); PG8_STAGE(PG8_SA(0, 0), a2, voffA);
;             PG8_WAIT_V(8); PG8_WAIT_L(0); PG8_BAR; PG8_MMA(1, 0, At, B0); PG8_MMA(1, 1, At, B1); PG8_BAR; PG8_SCHED;
.LBB0_1924:
	v_add_u32_e32 v192, s50, v161
	ds_read_b128 v[164:167], v162
	ds_read_b128 v[168:171], v162 offset:1024
	ds_read_b128 v[172:175], v162 offset:2048
	ds_read_b128 v[176:179], v162 offset:3072
	ds_read_b128 v[180:183], v192
	ds_read_b128 v[184:187], v192 offset:1024
	ds_read_b128 v[188:191], v192 offset:2048
	ds_read_b128 v[192:195], v192 offset:3072
	s_cmp_eq_u32 s49, s10
	v_lshl_add_u64 v[196:197], v[158:159], 0, s[24:25]
	s_cselect_b64 vcc, -1, 0
	s_add_i32 s10, s10, 2
	v_cndmask_b32_e32 v213, v197, v151, vcc
	v_cndmask_b32_e32 v212, v196, v150, vcc
	v_cndmask_b32_e32 v215, v155, v153, vcc
	v_cndmask_b32_e32 v214, v154, v152, vcc
	s_mov_b32 m0, s51
	v_lshl_add_u64 v[232:233], v[158:159], 0, v[146:147]
	ds_read_b128 v[196:199], v163
	ds_read_b128 v[200:203], v163 offset:1024
	ds_read_b128 v[204:207], v163 offset:2048
	ds_read_b128 v[208:211], v163 offset:3072
	ds_read_b128 v[216:219], v163 offset:4096
	ds_read_b128 v[220:223], v163 offset:5120
	ds_read_b128 v[224:227], v163 offset:6144
	ds_read_b128 v[228:231], v163 offset:7168
	global_load_lds_dwordx4 v[232:233], off
	s_mov_b32 m0, s52
	v_lshl_add_u64 v[232:233], v[158:159], 0, v[144:145]
	global_load_lds_dwordx4 v[232:233], off
	s_waitcnt vmcnt(8) lgkmcnt(0)
	s_setprio 0
	s_barrier
	v_mfma_f32_16x16x32_bf16 v[124:127], v[164:167], v[196:199], v[124:127]
	v_mfma_f32_16x16x32_bf16 v[120:123], v[172:175], v[196:199], v[120:123]
	v_mfma_f32_16x16x32_bf16 v[108:111], v[164:167], v[204:207], v[108:111]
	v_mfma_f32_16x16x32_bf16 v[104:107], v[172:175], v[204:207], v[104:107]
	v_mfma_f32_16x16x32_bf16 v[92:95], v[164:167], v[216:219], v[92:95]
	v_mfma_f32_16x16x32_bf16 v[88:91], v[172:175], v[216:219], v[88:91]
	v_mfma_f32_16x16x32_bf16 v[76:79], v[164:167], v[224:227], v[76:79]
	v_mfma_f32_16x16x32_bf16 v[72:75], v[172:175], v[224:227], v[72:75]
	v_mfma_f32_16x16x32_bf16 v[124:127], v[168:171], v[200:203], v[124:127]
	v_mfma_f32_16x16x32_bf16 v[120:123], v[176:179], v[200:203], v[120:123]
	v_mfma_f32_16x16x32_bf16 v[108:111], v[168:171], v[208:211], v[108:111]
	v_mfma_f32_16x16x32_bf16 v[104:107], v[176:179], v[208:211], v[104:107]
	v_mfma_f32_16x16x32_bf16 v[92:95], v[168:171], v[220:223], v[92:95]
	v_mfma_f32_16x16x32_bf16 v[88:91], v[176:179], v[220:223], v[88:91]
	v_mfma_f32_16x16x32_bf16 v[76:79], v[168:171], v[228:231], v[76:79]
	v_mfma_f32_16x16x32_bf16 v[72:75], v[176:179], v[228:231], v[72:75]
	v_mfma_f32_16x16x32_bf16 v[116:119], v[180:183], v[196:199], v[116:119]
	v_mfma_f32_16x16x32_bf16 v[112:115], v[188:191], v[196:199], v[112:115]
	v_mfma_f32_16x16x32_bf16 v[100:103], v[180:183], v[204:207], v[100:103]
	v_mfma_f32_16x16x32_bf16 v[96:99], v[188:191], v[204:207], v[96:99]
	v_mfma_f32_16x16x32_bf16 v[84:87], v[180:183], v[216:219], v[84:87]
	v_mfma_f32_16x16x32_bf16 v[80:83], v[188:191], v[216:219], v[80:83]
	v_mfma_f32_16x16x32_bf16 v[68:71], v[180:183], v[224:227], v[68:71]
	v_mfma_f32_16x16x32_bf16 v[64:67], v[188:191], v[224:227], v[64:67]
	v_mfma_f32_16x16x32_bf16 v[116:119], v[184:187], v[200:203], v[116:119]
	v_mfma_f32_16x16x32_bf16 v[112:115], v[192:195], v[200:203], v[112:115]
	v_mfma_f32_16x16x32_bf16 v[100:103], v[184:187], v[208:211], v[100:103]
	v_mfma_f32_16x16x32_bf16 v[96:99], v[192:195], v[208:211], v[96:99]
	v_mfma_f32_16x16x32_bf16 v[84:87], v[184:187], v[220:223], v[84:87]
	v_mfma_f32_16x16x32_bf16 v[80:83], v[192:195], v[220:223], v[80:83]
	v_mfma_f32_16x16x32_bf16 v[68:71], v[184:187], v[228:231], v[68:71]
	v_mfma_f32_16x16x32_bf16 v[64:67], v[192:195], v[228:231], v[64:67]
	s_setprio 1
	s_barrier
	s_mov_b32 m0, s53
	v_lshl_add_u64 v[232:233], v[214:215], 0, v[138:139]
	ds_read_b128 v[196:199], v163 offset:16384
	ds_read_b128 v[200:203], v163 offset:17408
	ds_read_b128 v[204:207], v163 offset:18432
	ds_read_b128 v[208:211], v163 offset:19456
	ds_read_b128 v[216:219], v163 offset:20480
	ds_read_b128 v[220:223], v163 offset:21504
	ds_read_b128 v[224:227], v163 offset:22528
	ds_read_b128 v[228:231], v163 offset:23552
	global_load_lds_dwordx4 v[232:233], off
	v_lshl_add_u64 v[234:235], v[214:215], 0, v[134:135]
	s_mov_b32 m0, s54
	v_lshl_add_u64 v[214:215], v[214:215], 0, s[14:15]
	global_load_lds_dwordx4 v[234:235], off
	v_lshl_add_u64 v[236:237], v[214:215], 0, v[138:139]
	s_mov_b32 m0, s55
	v_lshl_add_u64 v[214:215], v[214:215], 0, v[134:135]
	global_load_lds_dwordx4 v[236:237], off
	s_mov_b32 m0, s56
	v_lshl_add_u64 v[238:239], v[212:213], 0, v[140:141]
	global_load_lds_dwordx4 v[214:215], off
	s_mov_b32 m0, s37
	v_lshl_add_u64 v[240:241], v[212:213], 0, v[136:137]
	global_load_lds_dwordx4 v[238:239], off
	s_mov_b32 m0, s41
	s_nop 0
	global_load_lds_dwordx4 v[240:241], off
	s_waitcnt vmcnt(8) lgkmcnt(0)
	s_setprio 0
	s_barrier
; #define PG8_STAGE(bufoff, gbase, voff) do { _Pragma("unroll") for (int _i = 0; _i < 2; ++_i) \
;         __builtin_amdgcn_global_load_lds((const unsigned*)((const char*)(gbase) + (voff)[_i]), (PG8_LAS unsigned*)(lds + (bufoff) + ldsw + _i * 8192), 16, 0, 0); } while (0)
; #define PG8_LDA(dst, b, h) do { _Pragma("unroll") for (int m = 0; m < 4; ++m) _Pragma("unroll") for (int k = 0; k < 2; ++k) dst[m][k] = *(const PG8_LAS bf16x8*)(lds + PG8_SA(b, h) + aoff + m * 2048 + k * 1024); } while (0)
; #define PG8_LDB(dst, b, h) do { _Pragma("unroll") for (int n = 0; n < 2; ++n) _Pragma("unroll") for (int k = 0; k < 2; ++k) dst[n][k] = *(const PG8_LAS bf16x8*)(lds + PG8_SB(b, h) + boff + n * 2048 + k * 1024); } while (0)
; #define PG8_MMA(ai, bj, At, Bt) do { __builtin_amdgcn_s_setprio(1); _Pragma("unroll") for (int m = 0; m < 4; ++m) _Pragma("unroll") for (int n = 0; n < 2; ++n) _Pragma("unroll") for (int k = 0; k < 2; ++k) \
;         acc[ai][bj][m][n] = __builtin_amdgcn_mfma_f32_16x16x32_bf16(Bt[n][k], At[m][k], acc[ai][bj][m][n], 0, 0, 0); __builtin_amdgcn_s_setprio(0); } while (0)
; #define PG8_WAIT_V(n) asm volatile("s_waitcnt vmcnt(" #n ")" ::: "memory")
; #define PG8_WAIT_L(n) asm volatile("s_waitcnt lgkmcnt(" #n ")" ::: "memory")
; #define PG8_BAR __builtin_amdgcn_s_barrier()
; #define PG8_SCHED __builtin_amdgcn_sched_barrier(0)
; template <class Epi, class Sched, bool ALIGN_EPI = false, bool SP2 = false>
; __device__ __forceinline__ void gemm_phase(PG8_LAS unsigned char* lds, const Gemm g, const Sched& S, const Epi& E) {
;     ...
;             PG8_WAIT_V(8); PG8_WAIT_L(0); PG8_BAR; PG8_MMA(1, 0, At, B0); PG8_MMA(1, 1, At, B1); PG8_BAR; PG8_SCHED;
;             PG8_LDB(B0, 1, 0); PG8_LDB(B1, 1, 1); PG8_SCHED; PG8_LDA(At, 1, 0); PG8_STAGE(PG8_SA(0, 1), a2 + hstep, voffA);
;             PG8_WAIT_V(8); PG8_WAIT_L(0); PG8_BAR; PG8_MMA(0, 0, At, B0); PG8_MMA(0, 1, At, B1); PG8_BAR; PG8_SCHED;
	v_mfma_f32_16x16x32_bf16 v[60:63], v[164:167], v[196:199], v[60:63]
	v_mfma_f32_16x16x32_bf16 v[56:59], v[172:175], v[196:199], v[56:59]
	v_mfma_f32_16x16x32_bf16 v[44:47], v[164:167], v[204:207], v[44:47]
	v_mfma_f32_16x16x32_bf16 v[40:43], v[172:175], v[204:207], v[40:43]
	v_mfma_f32_16x16x32_bf16 v[28:31], v[164:167], v[216:219], v[28:31]
	v_mfma_f32_16x16x32_bf16 v[24:27], v[172:175], v[216:219], v[24:27]
	v_mfma_f32_16x16x32_bf16 v[12:15], v[164:167], v[224:227], v[12:15]
	v_mfma_f32_16x16x32_bf16 v[8:11], v[172:175], v[224:227], v[8:11]
	v_mfma_f32_16x16x32_bf16 v[60:63], v[168:171], v[200:203], v[60:63]
	v_mfma_f32_16x16x32_bf16 v[56:59], v[176:179], v[200:203], v[56:59]
	v_mfma_f32_16x16x32_bf16 v[44:47], v[168:171], v[208:211], v[44:47]
	v_mfma_f32_16x16x32_bf16 v[40:43], v[176:179], v[208:211], v[40:43]
	v_mfma_f32_16x16x32_bf16 v[28:31], v[168:171], v[220:223], v[28:31]
	v_mfma_f32_16x16x32_bf16 v[24:27], v[176:179], v[220:223], v[24:27]
	v_mfma_f32_16x16x32_bf16 v[12:15], v[168:171], v[228:231], v[12:15]
	v_mfma_f32_16x16x32_bf16 v[8:11], v[176:179], v[228:231], v[8:11]
	v_mfma_f32_16x16x32_bf16 v[52:55], v[180:183], v[196:199], v[52:55]
	v_mfma_f32_16x16x32_bf16 v[48:51], v[188:191], v[196:199], v[48:51]
	v_mfma_f32_16x16x32_bf16 v[36:39], v[180:183], v[204:207], v[36:39]
	v_mfma_f32_16x16x32_bf16 v[32:35], v[188:191], v[204:207], v[32:35]
	v_mfma_f32_16x16x32_bf16 v[20:23], v[180:183], v[216:219], v[20:23]
	v_mfma_f32_16x16x32_bf16 v[16:19], v[188:191], v[216:219], v[16:19]
	v_mfma_f32_16x16x32_bf16 v[4:7], v[180:183], v[224:227], v[4:7]
	v_mfma_f32_16x16x32_bf16 v[0:3], v[188:191], v[224:227], v[0:3]
	v_mfma_f32_16x16x32_bf16 v[52:55], v[184:187], v[200:203], v[52:55]
	v_mfma_f32_16x16x32_bf16 v[48:51], v[192:195], v[200:203], v[48:51]
	v_mfma_f32_16x16x32_bf16 v[36:39], v[184:187], v[208:211], v[36:39]
	v_mfma_f32_16x16x32_bf16 v[32:35], v[192:195], v[208:211], v[32:35]
	v_mfma_f32_16x16x32_bf16 v[20:23], v[184:187], v[220:223], v[20:23]
	v_mfma_f32_16x16x32_bf16 v[16:19], v[192:195], v[220:223], v[16:19]
	v_mfma_f32_16x16x32_bf16 v[4:7], v[184:187], v[228:231], v[4:7]
	v_mfma_f32_16x16x32_bf16 v[0:3], v[192:195], v[228:231], v[0:3]
	s_setprio 1
	s_barrier
	v_add_u32_e32 v176, s57, v161
	v_add_u32_e32 v192, s58, v161
	ds_read_b128 v[164:167], v176
	ds_read_b128 v[168:171], v176 offset:1024
	ds_read_b128 v[172:175], v176 offset:2048
	ds_read_b128 v[176:179], v176 offset:3072
	ds_read_b128 v[180:183], v192
	ds_read_b128 v[184:187], v192 offset:1024
	ds_read_b128 v[188:191], v192 offset:2048
	ds_read_b128 v[192:195], v192 offset:3072
	v_lshl_add_u64 v[212:213], v[212:213], 0, s[14:15]
	s_mov_b32 m0, s44
	v_lshl_add_u64 v[242:243], v[212:213], 0, v[140:141]
	ds_read_b128 v[196:199], v163 offset:32768
	ds_read_b128 v[200:203], v163 offset:33792
	ds_read_b128 v[204:207], v163 offset:34816
	ds_read_b128 v[208:211], v163 offset:35840
	ds_read_b128 v[216:219], v163 offset:36864
	ds_read_b128 v[220:223], v163 offset:37888
	ds_read_b128 v[224:227], v163 offset:38912
	ds_read_b128 v[228:231], v163 offset:39936
	global_load_lds_dwordx4 v[242:243], off
	s_mov_b32 m0, s45
	v_lshl_add_u64 v[212:213], v[212:213], 0, v[136:137]
	global_load_lds_dwordx4 v[212:213], off
	s_waitcnt vmcnt(8) lgkmcnt(0)
	s_setprio 0
	s_barrier
	v_mfma_f32_16x16x32_bf16 v[124:127], v[164:167], v[196:199], v[124:127]
	v_mfma_f32_16x16x32_bf16 v[120:123], v[172:175], v[196:199], v[120:123]
	v_mfma_f32_16x16x32_bf16 v[108:111], v[164:167], v[204:207], v[108:111]
	v_mfma_f32_16x16x32_bf16 v[104:107], v[172:175], v[204:207], v[104:107]
	v_mfma_f32_16x16x32_bf16 v[92:95], v[164:167], v[216:219], v[92:95]
	v_mfma_f32_16x16x32_bf16 v[88:91], v[172:175], v[216:219], v[88:91]
	v_mfma_f32_16x16x32_bf16 v[76:79], v[164:167], v[224:227], v[76:79]
	v_mfma_f32_16x16x32_bf16 v[72:75], v[172:175], v[224:227], v[72:75]
	v_mfma_f32_16x16x32_bf16 v[124:127], v[168:171], v[200:203], v[124:127]
	v_mfma_f32_16x16x32_bf16 v[120:123], v[176:179], v[200:203], v[120:123]
	v_mfma_f32_16x16x32_bf16 v[108:111], v[168:171], v[208:211], v[108:111]
	v_mfma_f32_16x16x32_bf16 v[104:107], v[176:179], v[208:211], v[104:107]
	v_mfma_f32_16x16x32_bf16 v[92:95], v[168:171], v[220:223], v[92:95]
	v_mfma_f32_16x16x32_bf16 v[88:91], v[176:179], v[220:223], v[88:91]
	v_mfma_f32_16x16x32_bf16 v[76:79], v[168:171], v[228:231], v[76:79]
	v_mfma_f32_16x16x32_bf16 v[72:75], v[176:179], v[228:231], v[72:75]
	v_mfma_f32_16x16x32_bf16 v[116:119], v[180:183], v[196:199], v[116:119]
	v_mfma_f32_16x16x32_bf16 v[112:115], v[188:191], v[196:199], v[112:115]
	v_mfma_f32_16x16x32_bf16 v[100:103], v[180:183], v[204:207], v[100:103]
	v_mfma_f32_16x16x32_bf16 v[96:99], v[188:191], v[204:207], v[96:99]
	v_mfma_f32_16x16x32_bf16 v[84:87], v[180:183], v[216:219], v[84:87]
	v_mfma_f32_16x16x32_bf16 v[80:83], v[188:191], v[216:219], v[80:83]
	v_mfma_f32_16x16x32_bf16 v[68:71], v[180:183], v[224:227], v[68:71]
	v_mfma_f32_16x16x32_bf16 v[64:67], v[188:191], v[224:227], v[64:67]
	v_mfma_f32_16x16x32_bf16 v[116:119], v[184:187], v[200:203], v[116:119]
	v_mfma_f32_16x16x32_bf16 v[112:115], v[192:195], v[200:203], v[112:115]
	v_mfma_f32_16x16x32_bf16 v[100:103], v[184:187], v[208:211], v[100:103]
	v_mfma_f32_16x16x32_bf16 v[96:99], v[192:195], v[208:211], v[96:99]
	v_mfma_f32_16x16x32_bf16 v[84:87], v[184:187], v[220:223], v[84:87]
	v_mfma_f32_16x16x32_bf16 v[80:83], v[192:195], v[220:223], v[80:83]
	v_mfma_f32_16x16x32_bf16 v[68:71], v[184:187], v[228:231], v[68:71]
	v_mfma_f32_16x16x32_bf16 v[64:67], v[192:195], v[228:231], v[64:67]
	s_setprio 1
	s_barrier
; #define PG8_STAGE(bufoff, gbase, voff) do { _Pragma("unroll") for (int _i = 0; _i < 2; ++_i) \
;         __builtin_amdgcn_global_load_lds((const unsigned*)((const char*)(gbase) + (voff)[_i]), (PG8_LAS unsigned*)(lds + (bufoff) + ldsw + _i * 8192), 16, 0, 0); } while (0)
; #define PG8_LDA(dst, b, h) do { _Pragma("unroll") for (int m = 0; m < 4; ++m) _Pragma("unroll") for (int k = 0; k < 2; ++k) dst[m][k] = *(const PG8_LAS bf16x8*)(lds + PG8_SA(b, h) + aoff + m * 2048 + k * 1024); } while (0)
; #define PG8_MMA(ai, bj, At, Bt) do { __builtin_amdgcn_s_setprio(1); _Pragma("unroll") for (int m = 0; m < 4; ++m) _Pragma("unroll") for (int n = 0; n < 2; ++n) _Pragma("unroll") for (int k = 0; k < 2; ++k) \
;         acc[ai][bj][m][n] = __builtin_amdgcn_mfma_f32_16x16x32_bf16(Bt[n][k], At[m][k], acc[ai][bj][m][n], 0, 0, 0); __builtin_amdgcn_s_setprio(0); } while (0)
; #define PG8_WAIT_V(n) asm volatile("s_waitcnt vmcnt(" #n ")" ::: "memory")
; #define PG8_WAIT_L(n) asm volatile("s_waitcnt lgkmcnt(" #n ")" ::: "memory")
; #define PG8_BAR __builtin_amdgcn_s_barrier()
; #define PG8_SCHED __builtin_amdgcn_sched_barrier(0)
; template <class Epi, class Sched, bool ALIGN_EPI = false, bool SP2 = false>
; __device__ __forceinline__ void gemm_phase(PG8_LAS unsigned char* lds, const Gemm g, const Sched& S, const Epi& E) {
;     ...
;             PG8_LDA(At, 1, 1); PG8_STAGE(PG8_SB(1, 0), b3, voffB); PG8_STAGE(PG8_SB(1, 1), b3 + hstep, voffB); PG8_STAGE(PG8_SA(1, 0), a3, voffA);
;             PG8_WAIT_V(8); PG8_WAIT_L(0); PG8_BAR; PG8_MMA(1, 0, At, B0); PG8_MMA(1, 1, At, B1); PG8_BAR; PG8_SCHED;
	s_add_i32 m0, s59, 0xffffff80
	ds_read_b128 v[196:199], v163 offset:49152
	ds_read_b128 v[200:203], v163 offset:50176
	ds_read_b128 v[204:207], v163 offset:51200
	global_load_lds_dwordx4 v[232:233], off offset:128
	s_add_i32 m0, s60, 0xffffff80
	ds_read_b128 v[228:231], v163 offset:56320
	global_load_lds_dwordx4 v[234:235], off offset:128
	s_add_i32 m0, s61, 0xffffff80
	ds_read_b128 v[224:227], v163 offset:55296
	global_load_lds_dwordx4 v[236:237], off offset:128
	s_add_i32 m0, s62, 0xffffff80
	ds_read_b128 v[220:223], v163 offset:54272
	global_load_lds_dwordx4 v[214:215], off offset:128
	s_add_i32 m0, s46, 0xffffff80
	ds_read_b128 v[216:219], v163 offset:53248
	global_load_lds_dwordx4 v[238:239], off offset:128
	s_add_i32 m0, s47, 0xffffff80
	ds_read_b128 v[208:211], v163 offset:52224
	global_load_lds_dwordx4 v[240:241], off offset:128
	s_waitcnt vmcnt(8) lgkmcnt(0)
	s_setprio 0
	s_barrier
	v_mfma_f32_16x16x32_bf16 v[60:63], v[164:167], v[196:199], v[60:63]
	v_mfma_f32_16x16x32_bf16 v[56:59], v[172:175], v[196:199], v[56:59]
	v_mfma_f32_16x16x32_bf16 v[44:47], v[164:167], v[204:207], v[44:47]
	v_mfma_f32_16x16x32_bf16 v[40:43], v[172:175], v[204:207], v[40:43]
	v_mfma_f32_16x16x32_bf16 v[28:31], v[164:167], v[216:219], v[28:31]
	v_mfma_f32_16x16x32_bf16 v[24:27], v[172:175], v[216:219], v[24:27]
	v_mfma_f32_16x16x32_bf16 v[12:15], v[164:167], v[224:227], v[12:15]
	v_mfma_f32_16x16x32_bf16 v[8:11], v[172:175], v[224:227], v[8:11]
	v_mfma_f32_16x16x32_bf16 v[60:63], v[168:171], v[200:203], v[60:63]
	v_mfma_f32_16x16x32_bf16 v[56:59], v[176:179], v[200:203], v[56:59]
	v_mfma_f32_16x16x32_bf16 v[44:47], v[168:171], v[208:211], v[44:47]
	v_mfma_f32_16x16x32_bf16 v[40:43], v[176:179], v[208:211], v[40:43]
	v_mfma_f32_16x16x32_bf16 v[28:31], v[168:171], v[220:223], v[28:31]
	v_mfma_f32_16x16x32_bf16 v[24:27], v[176:179], v[220:223], v[24:27]
	v_mfma_f32_16x16x32_bf16 v[12:15], v[168:171], v[228:231], v[12:15]
	v_mfma_f32_16x16x32_bf16 v[8:11], v[176:179], v[228:231], v[8:11]
	v_mfma_f32_16x16x32_bf16 v[52:55], v[180:183], v[196:199], v[52:55]
	v_mfma_f32_16x16x32_bf16 v[48:51], v[188:191], v[196:199], v[48:51]
	v_mfma_f32_16x16x32_bf16 v[36:39], v[180:183], v[204:207], v[36:39]
	v_mfma_f32_16x16x32_bf16 v[32:35], v[188:191], v[204:207], v[32:35]
	v_mfma_f32_16x16x32_bf16 v[20:23], v[180:183], v[216:219], v[20:23]
	v_mfma_f32_16x16x32_bf16 v[16:19], v[188:191], v[216:219], v[16:19]
	v_mfma_f32_16x16x32_bf16 v[4:7], v[180:183], v[224:227], v[4:7]
	v_mfma_f32_16x16x32_bf16 v[0:3], v[188:191], v[224:227], v[0:3]
	v_mfma_f32_16x16x32_bf16 v[52:55], v[184:187], v[200:203], v[52:55]
	v_mfma_f32_16x16x32_bf16 v[48:51], v[192:195], v[200:203], v[48:51]
	v_mfma_f32_16x16x32_bf16 v[36:39], v[184:187], v[208:211], v[36:39]
	v_mfma_f32_16x16x32_bf16 v[32:35], v[192:195], v[208:211], v[32:35]
	v_mfma_f32_16x16x32_bf16 v[20:23], v[184:187], v[220:223], v[20:23]
	v_mfma_f32_16x16x32_bf16 v[16:19], v[192:195], v[220:223], v[16:19]
	v_mfma_f32_16x16x32_bf16 v[4:7], v[184:187], v[228:231], v[4:7]
	v_mfma_f32_16x16x32_bf16 v[0:3], v[192:195], v[228:231], v[0:3]
	s_setprio 1
	s_barrier
	v_lshl_add_u64 v[154:155], v[154:155], 0, s[28:29]
	s_cmp_ge_i32 s10, s48
	v_lshl_add_u64 v[158:159], v[158:159], 0, s[28:29]
	s_cbranch_scc0 .LBB0_1924
	s_setprio 0

; #define PG8_STAGE(bufoff, gbase, voff) do { _Pragma("unroll") for (int _i = 0; _i < 2; ++_i) \
;         __builtin_amdgcn_global_load_lds((const unsigned*)((const char*)(gbase) + (voff)[_i]), (PG8_LAS unsigned*)(lds + (bufoff) + ldsw + _i * 8192), 16, 0, 0); } while (0)
; #define PG8_LDA(dst, b, h) do { _Pragma("unroll") for (int m = 0; m < 4; ++m) _Pragma("unroll") for (int k = 0; k < 2; ++k) dst[m][k] = *(const PG8_LAS bf16x8*)(lds + PG8_SA(b, h) + aoff + m * 2048 + k * 1024); } while (0)
; #define PG8_LDB(dst, b, h) do { _Pragma("unroll") for (int n = 0; n < 2; ++n) _Pragma("unroll") for (int k = 0; k < 2; ++k) dst[n][k] = *(const PG8_LAS bf16x8*)(lds + PG8_SB(b, h) + boff + n * 2048 + k * 1024); } while (0)
; #define PG8_MMA(ai, bj, At, Bt) do { __builtin_amdgcn_s_setprio(1); _Pragma("unroll") for (int m = 0; m < 4; ++m) _Pragma("unroll") for (int n = 0; n < 2; ++n) _Pragma("unroll") for (int k = 0; k < 2; ++k) \
;         acc[ai][bj][m][n] = __builtin_amdgcn_mfma_f32_16x16x32_bf16(Bt[n][k], At[m][k], acc[ai][bj][m][n], 0, 0, 0); __builtin_amdgcn_s_setprio(0); } while (0)
; #define PG8_WAIT_V(n) asm volatile("s_waitcnt vmcnt(" #n ")" ::: "memory")
; #define PG8_WAIT_L(n) asm volatile("s_waitcnt lgkmcnt(" #n ")" ::: "memory")
; template <class Epi, class Sched, bool ALIGN_EPI = false, bool SP2 = false>
; __device__ __forceinline__ void gemm_phase(PG8_LAS unsigned char* lds, const Gemm g, const Sched& S, const Epi& E) {
;     ...
;             const bool last = (t == nt - 2);
;             const char* a1 = cA + (size_t)(t + 1) * kstep;
;             const char* a2 = last ? nA : cA + (size_t)(t + 2) * kstep; const char* b2 = last ? nB : cB + (size_t)(t + 2) * kstep;
;             const char* a3 = a2 + kstep; const char* b3 = b2 + kstep;
;             if (last && has_next) S.a_ready(nxt);
;             if constexpr (SP2) {
;             PG8_LDB(B0, 0, 0); PG8_LDB(B1, 0, 1); PG8_SCHED; PG8_LDA(At, 0, 0); PG8_STAGE(PG8_SA(1, 1), a1 + hstep, voffA);
;             PG8_WAIT_V(8); PG8_WAIT_L(0); PG8_BAR; PG8_MMA(0, 0, At, B0); PG8_MMA(0, 1, At, B1); PG8_BAR; PG8_SCHED;
;             PG8_LDA(At, 0, 1); PG8_STAGE(PG8_SB(0, 0), b2, voffB); PG8_STAGE(PG8_SB(0, 1), b2 + hstep, voffB); PG8_STAGE(PG8_SA(0, 0), a2, voffA);
;             PG8_WAIT_V(8); PG8_WAIT_L(0); PG8_BAR; PG8_MMA(1, 0, At, B0); PG8_MMA(1, 1, At, B1); PG8_BAR; PG8_SCHED;
.LBB0_1947:
	v_add_u32_e32 v178, s53, v216
	v_add_u32_e32 v194, s54, v216
	ds_read_b128 v[138:141], v178
	ds_read_b128 v[142:145], v178 offset:1024
	ds_read_b128 v[146:149], v178 offset:2048
	ds_read_b128 v[178:181], v178 offset:3072
	ds_read_b128 v[182:185], v194
	ds_read_b128 v[186:189], v194 offset:1024
	ds_read_b128 v[190:193], v194 offset:2048
	ds_read_b128 v[194:197], v194 offset:3072
	s_cmp_eq_u32 s47, s10
	v_lshl_add_u64 v[198:199], v[136:137], 0, s[20:21]
	s_cselect_b64 vcc, -1, 0
	s_add_i32 s10, s10, 2
	v_cndmask_b32_e32 v215, v199, v175, vcc
	v_cndmask_b32_e32 v214, v198, v174, vcc
	v_cndmask_b32_e32 v237, v135, v177, vcc
	v_cndmask_b32_e32 v236, v134, v176, vcc
	v_lshl_add_u64 v[238:239], v[136:137], 0, v[168:169]
	s_add_i32 m0, s34, 0xc000
	ds_read_b128 v[198:201], v218
	ds_read_b128 v[202:205], v218 offset:1024
	ds_read_b128 v[206:209], v218 offset:2048
	ds_read_b128 v[210:213], v218 offset:3072
	ds_read_b128 v[220:223], v218 offset:4096
	ds_read_b128 v[224:227], v218 offset:5120
	ds_read_b128 v[228:231], v218 offset:6144
	ds_read_b128 v[232:235], v218 offset:7168
	global_load_lds_dwordx4 v[238:239], off
	s_add_i32 m0, s34, 0xe000
	v_lshl_add_u64 v[238:239], v[136:137], 0, v[166:167]
	global_load_lds_dwordx4 v[238:239], off
	s_waitcnt vmcnt(8) lgkmcnt(0)
	s_setprio 0
	s_barrier
	v_mfma_f32_16x16x32_bf16 v[130:133], v[138:141], v[198:201], v[130:133]
	v_mfma_f32_16x16x32_bf16 v[126:129], v[146:149], v[198:201], v[126:129]
	v_mfma_f32_16x16x32_bf16 v[114:117], v[138:141], v[206:209], v[114:117]
	v_mfma_f32_16x16x32_bf16 v[110:113], v[146:149], v[206:209], v[110:113]
	v_mfma_f32_16x16x32_bf16 v[98:101], v[138:141], v[220:223], v[98:101]
	v_mfma_f32_16x16x32_bf16 v[94:97], v[146:149], v[220:223], v[94:97]
	v_mfma_f32_16x16x32_bf16 v[82:85], v[138:141], v[228:231], v[82:85]
	v_mfma_f32_16x16x32_bf16 v[78:81], v[146:149], v[228:231], v[78:81]
	v_mfma_f32_16x16x32_bf16 v[130:133], v[142:145], v[202:205], v[130:133]
	v_mfma_f32_16x16x32_bf16 v[126:129], v[178:181], v[202:205], v[126:129]
	v_mfma_f32_16x16x32_bf16 v[114:117], v[142:145], v[210:213], v[114:117]
	v_mfma_f32_16x16x32_bf16 v[110:113], v[178:181], v[210:213], v[110:113]
	v_mfma_f32_16x16x32_bf16 v[98:101], v[142:145], v[224:227], v[98:101]
	v_mfma_f32_16x16x32_bf16 v[94:97], v[178:181], v[224:227], v[94:97]
	v_mfma_f32_16x16x32_bf16 v[82:85], v[142:145], v[232:235], v[82:85]
	v_mfma_f32_16x16x32_bf16 v[78:81], v[178:181], v[232:235], v[78:81]
	v_mfma_f32_16x16x32_bf16 v[122:125], v[182:185], v[198:201], v[122:125]
	v_mfma_f32_16x16x32_bf16 v[118:121], v[190:193], v[198:201], v[118:121]
	v_mfma_f32_16x16x32_bf16 v[106:109], v[182:185], v[206:209], v[106:109]
	v_mfma_f32_16x16x32_bf16 v[102:105], v[190:193], v[206:209], v[102:105]
	v_mfma_f32_16x16x32_bf16 v[90:93], v[182:185], v[220:223], v[90:93]
	v_mfma_f32_16x16x32_bf16 v[86:89], v[190:193], v[220:223], v[86:89]
	v_mfma_f32_16x16x32_bf16 v[74:77], v[182:185], v[228:231], v[74:77]
	v_mfma_f32_16x16x32_bf16 v[70:73], v[190:193], v[228:231], v[70:73]
	v_mfma_f32_16x16x32_bf16 v[122:125], v[186:189], v[202:205], v[122:125]
	v_mfma_f32_16x16x32_bf16 v[118:121], v[194:197], v[202:205], v[118:121]
	v_mfma_f32_16x16x32_bf16 v[106:109], v[186:189], v[210:213], v[106:109]
	v_mfma_f32_16x16x32_bf16 v[102:105], v[194:197], v[210:213], v[102:105]
	v_mfma_f32_16x16x32_bf16 v[90:93], v[186:189], v[224:227], v[90:93]
	v_mfma_f32_16x16x32_bf16 v[86:89], v[194:197], v[224:227], v[86:89]
	v_mfma_f32_16x16x32_bf16 v[74:77], v[186:189], v[232:235], v[74:77]
	v_mfma_f32_16x16x32_bf16 v[70:73], v[194:197], v[232:235], v[70:73]
	s_setprio 1
	s_barrier
	s_add_i32 s11, s53, s29
	v_lshl_add_u64 v[238:239], v[236:237], 0, v[158:159]
	s_mov_b32 m0, s11
	ds_read_b128 v[198:201], v218 offset:16384
	ds_read_b128 v[202:205], v218 offset:17408
	ds_read_b128 v[206:209], v218 offset:18432
	ds_read_b128 v[210:213], v218 offset:19456
	ds_read_b128 v[220:223], v218 offset:20480
	ds_read_b128 v[224:227], v218 offset:21504
	ds_read_b128 v[228:231], v218 offset:22528
	ds_read_b128 v[232:235], v218 offset:23552
	global_load_lds_dwordx4 v[238:239], off
	v_lshl_add_u64 v[240:241], v[236:237], 0, v[162:163]
	s_add_i32 m0, s11, 0x2000
	v_lshl_add_u64 v[236:237], v[236:237], 0, s[12:13]
	s_add_i32 s11, s54, s29
	global_load_lds_dwordx4 v[240:241], off
	v_lshl_add_u64 v[242:243], v[236:237], 0, v[158:159]
	s_mov_b32 m0, s11
	v_lshl_add_u64 v[236:237], v[236:237], 0, v[162:163]
	global_load_lds_dwordx4 v[242:243], off
	s_add_i32 m0, s11, 0x2000
	v_lshl_add_u64 v[244:245], v[214:215], 0, v[154:155]
	global_load_lds_dwordx4 v[236:237], off
	s_mov_b32 m0, s34
	v_lshl_add_u64 v[246:247], v[214:215], 0, v[160:161]
	global_load_lds_dwordx4 v[244:245], off
	s_mov_b32 m0, s35
	s_nop 0
	global_load_lds_dwordx4 v[246:247], off
	s_waitcnt vmcnt(8) lgkmcnt(0)
	s_setprio 0
	s_barrier
; #define PG8_STAGE(bufoff, gbase, voff) do { _Pragma("unroll") for (int _i = 0; _i < 2; ++_i) \
;         __builtin_amdgcn_global_load_lds((const unsigned*)((const char*)(gbase) + (voff)[_i]), (PG8_LAS unsigned*)(lds + (bufoff) + ldsw + _i * 8192), 16, 0, 0); } while (0)
; #define PG8_LDA(dst, b, h) do { _Pragma("unroll") for (int m = 0; m < 4; ++m) _Pragma("unroll") for (int k = 0; k < 2; ++k) dst[m][k] = *(const PG8_LAS bf16x8*)(lds + PG8_SA(b, h) + aoff + m * 2048 + k * 1024); } while (0)
; #define PG8_LDB(dst, b, h) do { _Pragma("unroll") for (int n = 0; n < 2; ++n) _Pragma("unroll") for (int k = 0; k < 2; ++k) dst[n][k] = *(const PG8_LAS bf16x8*)(lds + PG8_SB(b, h) + boff + n * 2048 + k * 1024); } while (0)
; #define PG8_MMA(ai, bj, At, Bt) do { __builtin_amdgcn_s_setprio(1); _Pragma("unroll") for (int m = 0; m < 4; ++m) _Pragma("unroll") for (int n = 0; n < 2; ++n) _Pragma("unroll") for (int k = 0; k < 2; ++k) \
;         acc[ai][bj][m][n] = __builtin_amdgcn_mfma_f32_16x16x32_bf16(Bt[n][k], At[m][k], acc[ai][bj][m][n], 0, 0, 0); __builtin_amdgcn_s_setprio(0); } while (0)
; #define PG8_WAIT_V(n) asm volatile("s_waitcnt vmcnt(" #n ")" ::: "memory")
; #define PG8_WAIT_L(n) asm volatile("s_waitcnt lgkmcnt(" #n ")" ::: "memory")
; #define PG8_BAR __builtin_amdgcn_s_barrier()
; #define PG8_SCHED __builtin_amdgcn_sched_barrier(0)
; template <class Epi, class Sched, bool ALIGN_EPI = false, bool SP2 = false>
; __device__ __forceinline__ void gemm_phase(PG8_LAS unsigned char* lds, const Gemm g, const Sched& S, const Epi& E) {
;     ...
;             PG8_WAIT_V(8); PG8_WAIT_L(0); PG8_BAR; PG8_MMA(1, 0, At, B0); PG8_MMA(1, 1, At, B1); PG8_BAR; PG8_SCHED;
;             PG8_LDB(B0, 1, 0); PG8_LDB(B1, 1, 1); PG8_SCHED; PG8_LDA(At, 1, 0); PG8_STAGE(PG8_SA(0, 1), a2 + hstep, voffA);
	v_mfma_f32_16x16x32_bf16 v[66:69], v[138:141], v[198:201], v[66:69]
	v_mfma_f32_16x16x32_bf16 v[62:65], v[146:149], v[198:201], v[62:65]
	v_mfma_f32_16x16x32_bf16 v[50:53], v[138:141], v[206:209], v[50:53]
	v_mfma_f32_16x16x32_bf16 v[46:49], v[146:149], v[206:209], v[46:49]
	v_mfma_f32_16x16x32_bf16 v[34:37], v[138:141], v[220:223], v[34:37]
	v_mfma_f32_16x16x32_bf16 v[30:33], v[146:149], v[220:223], v[30:33]
	v_mfma_f32_16x16x32_bf16 v[18:21], v[138:141], v[228:231], v[18:21]
	v_mfma_f32_16x16x32_bf16 v[14:17], v[146:149], v[228:231], v[14:17]
	v_mfma_f32_16x16x32_bf16 v[66:69], v[142:145], v[202:205], v[66:69]
	v_mfma_f32_16x16x32_bf16 v[62:65], v[178:181], v[202:205], v[62:65]
	v_mfma_f32_16x16x32_bf16 v[50:53], v[142:145], v[210:213], v[50:53]
	v_mfma_f32_16x16x32_bf16 v[46:49], v[178:181], v[210:213], v[46:49]
	v_mfma_f32_16x16x32_bf16 v[34:37], v[142:145], v[224:227], v[34:37]
	v_mfma_f32_16x16x32_bf16 v[30:33], v[178:181], v[224:227], v[30:33]
	v_mfma_f32_16x16x32_bf16 v[18:21], v[142:145], v[232:235], v[18:21]
	v_mfma_f32_16x16x32_bf16 v[14:17], v[178:181], v[232:235], v[14:17]
	v_mfma_f32_16x16x32_bf16 v[58:61], v[182:185], v[198:201], v[58:61]
	v_mfma_f32_16x16x32_bf16 v[54:57], v[190:193], v[198:201], v[54:57]
	v_mfma_f32_16x16x32_bf16 v[42:45], v[182:185], v[206:209], v[42:45]
	v_mfma_f32_16x16x32_bf16 v[38:41], v[190:193], v[206:209], v[38:41]
	v_mfma_f32_16x16x32_bf16 v[26:29], v[182:185], v[220:223], v[26:29]
	v_mfma_f32_16x16x32_bf16 v[22:25], v[190:193], v[220:223], v[22:25]
	v_mfma_f32_16x16x32_bf16 v[10:13], v[182:185], v[228:231], v[10:13]
	v_mfma_f32_16x16x32_bf16 v[6:9], v[190:193], v[228:231], v[6:9]
	v_mfma_f32_16x16x32_bf16 v[58:61], v[186:189], v[202:205], v[58:61]
	v_mfma_f32_16x16x32_bf16 v[54:57], v[194:197], v[202:205], v[54:57]
	v_mfma_f32_16x16x32_bf16 v[42:45], v[186:189], v[210:213], v[42:45]
	v_mfma_f32_16x16x32_bf16 v[38:41], v[194:197], v[210:213], v[38:41]
	v_mfma_f32_16x16x32_bf16 v[26:29], v[186:189], v[224:227], v[26:29]
	v_mfma_f32_16x16x32_bf16 v[22:25], v[194:197], v[224:227], v[22:25]
	v_mfma_f32_16x16x32_bf16 v[10:13], v[186:189], v[232:235], v[10:13]
	v_mfma_f32_16x16x32_bf16 v[6:9], v[194:197], v[232:235], v[6:9]
	s_setprio 1
	s_barrier
	s_add_i32 s11, 0, 0x18000
	s_add_i32 s31, 0, 0x1c000
	v_add_u32_e32 v178, s11, v216
	v_add_u32_e32 v194, s31, v216
	ds_read_b128 v[138:141], v178
	ds_read_b128 v[142:145], v178 offset:1024
	ds_read_b128 v[146:149], v178 offset:2048
	ds_read_b128 v[178:181], v178 offset:3072
	ds_read_b128 v[182:185], v194
	ds_read_b128 v[186:189], v194 offset:1024
	ds_read_b128 v[190:193], v194 offset:2048
	ds_read_b128 v[194:197], v194 offset:3072
	v_lshl_add_u64 v[214:215], v[214:215], 0, s[12:13]
	s_mov_b32 m0, s36
	v_lshl_add_u64 v[248:249], v[214:215], 0, v[154:155]
	ds_read_b128 v[198:201], v218 offset:32768
	ds_read_b128 v[202:205], v218 offset:33792
	ds_read_b128 v[206:209], v218 offset:34816
	ds_read_b128 v[210:213], v218 offset:35840
	ds_read_b128 v[220:223], v218 offset:36864
	ds_read_b128 v[224:227], v218 offset:37888
	ds_read_b128 v[228:231], v218 offset:38912
	ds_read_b128 v[232:235], v218 offset:39936
	global_load_lds_dwordx4 v[248:249], off
	s_mov_b32 m0, s37
	v_lshl_add_u64 v[214:215], v[214:215], 0, v[160:161]
	global_load_lds_dwordx4 v[214:215], off
	s_waitcnt vmcnt(8) lgkmcnt(0)
	s_setprio 0
	s_barrier
; #define PG8_STAGE(bufoff, gbase, voff) do { _Pragma("unroll") for (int _i = 0; _i < 2; ++_i) \
;         __builtin_amdgcn_global_load_lds((const unsigned*)((const char*)(gbase) + (voff)[_i]), (PG8_LAS unsigned*)(lds + (bufoff) + ldsw + _i * 8192), 16, 0, 0); } while (0)
; #define PG8_LDA(dst, b, h) do { _Pragma("unroll") for (int m = 0; m < 4; ++m) _Pragma("unroll") for (int k = 0; k < 2; ++k) dst[m][k] = *(const PG8_LAS bf16x8*)(lds + PG8_SA(b, h) + aoff + m * 2048 + k * 1024); } while (0)
; #define PG8_MMA(ai, bj, At, Bt) do { __builtin_amdgcn_s_setprio(1); _Pragma("unroll") for (int m = 0; m < 4; ++m) _Pragma("unroll") for (int n = 0; n < 2; ++n) _Pragma("unroll") for (int k = 0; k < 2; ++k) \
;         acc[ai][bj][m][n] = __builtin_amdgcn_mfma_f32_16x16x32_bf16(Bt[n][k], At[m][k], acc[ai][bj][m][n], 0, 0, 0); __builtin_amdgcn_s_setprio(0); } while (0)
; #define PG8_WAIT_V(n) asm volatile("s_waitcnt vmcnt(" #n ")" ::: "memory")
; #define PG8_WAIT_L(n) asm volatile("s_waitcnt lgkmcnt(" #n ")" ::: "memory")
; #define PG8_BAR __builtin_amdgcn_s_barrier()
; #define PG8_SCHED __builtin_amdgcn_sched_barrier(0)
; template <class Epi, class Sched, bool ALIGN_EPI = false, bool SP2 = false>
; __device__ __forceinline__ void gemm_phase(PG8_LAS unsigned char* lds, const Gemm g, const Sched& S, const Epi& E) {
;     ...
;             PG8_WAIT_V(8); PG8_WAIT_L(0); PG8_BAR; PG8_MMA(0, 0, At, B0); PG8_MMA(0, 1, At, B1); PG8_BAR; PG8_SCHED;
;             PG8_LDA(At, 1, 1); PG8_STAGE(PG8_SB(1, 0), b3, voffB); PG8_STAGE(PG8_SB(1, 1), b3 + hstep, voffB); PG8_STAGE(PG8_SA(1, 0), a3, voffA);
;             PG8_WAIT_V(8); PG8_WAIT_L(0); PG8_BAR; PG8_MMA(1, 0, At, B0); PG8_MMA(1, 1, At, B1); PG8_BAR; PG8_SCHED;
	v_mfma_f32_16x16x32_bf16 v[130:133], v[138:141], v[198:201], v[130:133]
	v_mfma_f32_16x16x32_bf16 v[126:129], v[146:149], v[198:201], v[126:129]
	v_mfma_f32_16x16x32_bf16 v[114:117], v[138:141], v[206:209], v[114:117]
	v_mfma_f32_16x16x32_bf16 v[110:113], v[146:149], v[206:209], v[110:113]
	v_mfma_f32_16x16x32_bf16 v[98:101], v[138:141], v[220:223], v[98:101]
	v_mfma_f32_16x16x32_bf16 v[94:97], v[146:149], v[220:223], v[94:97]
	v_mfma_f32_16x16x32_bf16 v[82:85], v[138:141], v[228:231], v[82:85]
	v_mfma_f32_16x16x32_bf16 v[78:81], v[146:149], v[228:231], v[78:81]
	v_mfma_f32_16x16x32_bf16 v[130:133], v[142:145], v[202:205], v[130:133]
	v_mfma_f32_16x16x32_bf16 v[126:129], v[178:181], v[202:205], v[126:129]
	v_mfma_f32_16x16x32_bf16 v[114:117], v[142:145], v[210:213], v[114:117]
	v_mfma_f32_16x16x32_bf16 v[110:113], v[178:181], v[210:213], v[110:113]
	v_mfma_f32_16x16x32_bf16 v[98:101], v[142:145], v[224:227], v[98:101]
	v_mfma_f32_16x16x32_bf16 v[94:97], v[178:181], v[224:227], v[94:97]
	v_mfma_f32_16x16x32_bf16 v[82:85], v[142:145], v[232:235], v[82:85]
	v_mfma_f32_16x16x32_bf16 v[78:81], v[178:181], v[232:235], v[78:81]
	v_mfma_f32_16x16x32_bf16 v[122:125], v[182:185], v[198:201], v[122:125]
	v_mfma_f32_16x16x32_bf16 v[118:121], v[190:193], v[198:201], v[118:121]
	v_mfma_f32_16x16x32_bf16 v[106:109], v[182:185], v[206:209], v[106:109]
	v_mfma_f32_16x16x32_bf16 v[102:105], v[190:193], v[206:209], v[102:105]
	v_mfma_f32_16x16x32_bf16 v[90:93], v[182:185], v[220:223], v[90:93]
	v_mfma_f32_16x16x32_bf16 v[86:89], v[190:193], v[220:223], v[86:89]
	v_mfma_f32_16x16x32_bf16 v[74:77], v[182:185], v[228:231], v[74:77]
	v_mfma_f32_16x16x32_bf16 v[70:73], v[190:193], v[228:231], v[70:73]
	v_mfma_f32_16x16x32_bf16 v[122:125], v[186:189], v[202:205], v[122:125]
	v_mfma_f32_16x16x32_bf16 v[118:121], v[194:197], v[202:205], v[118:121]
	v_mfma_f32_16x16x32_bf16 v[106:109], v[186:189], v[210:213], v[106:109]
	v_mfma_f32_16x16x32_bf16 v[102:105], v[194:197], v[210:213], v[102:105]
	v_mfma_f32_16x16x32_bf16 v[90:93], v[186:189], v[224:227], v[90:93]
	v_mfma_f32_16x16x32_bf16 v[86:89], v[194:197], v[224:227], v[86:89]
	v_mfma_f32_16x16x32_bf16 v[74:77], v[186:189], v[232:235], v[74:77]
	v_mfma_f32_16x16x32_bf16 v[70:73], v[194:197], v[232:235], v[70:73]
	s_setprio 1
	s_barrier
	s_add_i32 s11, s11, s29
	s_add_i32 m0, s11, 0xffffff80
	ds_read_b128 v[198:201], v218 offset:49152
	ds_read_b128 v[202:205], v218 offset:50176
	ds_read_b128 v[206:209], v218 offset:51200
	ds_read_b128 v[210:213], v218 offset:52224
	global_load_lds_dwordx4 v[238:239], off offset:128
	s_add_i32 m0, s11, 0x1f80
	s_add_i32 s11, s31, s29
	global_load_lds_dwordx4 v[240:241], off offset:128
	s_add_i32 m0, s11, 0xffffff80
	ds_read_b128 v[232:235], v218 offset:56320
	global_load_lds_dwordx4 v[242:243], off offset:128
	s_add_i32 m0, s11, 0x1f80
	ds_read_b128 v[228:231], v218 offset:55296
	global_load_lds_dwordx4 v[236:237], off offset:128
	s_add_i32 m0, s41, 0xffffff80
	ds_read_b128 v[224:227], v218 offset:54272
	global_load_lds_dwordx4 v[244:245], off offset:128
	s_add_i32 m0, s44, 0xffffff80
	ds_read_b128 v[220:223], v218 offset:53248
	global_load_lds_dwordx4 v[246:247], off offset:128
	s_waitcnt vmcnt(8) lgkmcnt(0)
	s_setprio 0
	s_barrier
	v_mfma_f32_16x16x32_bf16 v[66:69], v[138:141], v[198:201], v[66:69]
	v_mfma_f32_16x16x32_bf16 v[62:65], v[146:149], v[198:201], v[62:65]
	v_mfma_f32_16x16x32_bf16 v[50:53], v[138:141], v[206:209], v[50:53]
	v_mfma_f32_16x16x32_bf16 v[46:49], v[146:149], v[206:209], v[46:49]
	v_mfma_f32_16x16x32_bf16 v[34:37], v[138:141], v[220:223], v[34:37]
	v_mfma_f32_16x16x32_bf16 v[30:33], v[146:149], v[220:223], v[30:33]
	v_mfma_f32_16x16x32_bf16 v[18:21], v[138:141], v[228:231], v[18:21]
	v_mfma_f32_16x16x32_bf16 v[14:17], v[146:149], v[228:231], v[14:17]
	v_mfma_f32_16x16x32_bf16 v[66:69], v[142:145], v[202:205], v[66:69]
	v_mfma_f32_16x16x32_bf16 v[62:65], v[178:181], v[202:205], v[62:65]
	v_mfma_f32_16x16x32_bf16 v[50:53], v[142:145], v[210:213], v[50:53]
	v_mfma_f32_16x16x32_bf16 v[46:49], v[178:181], v[210:213], v[46:49]
	v_mfma_f32_16x16x32_bf16 v[34:37], v[142:145], v[224:227], v[34:37]
	v_mfma_f32_16x16x32_bf16 v[30:33], v[178:181], v[224:227], v[30:33]
	v_mfma_f32_16x16x32_bf16 v[18:21], v[142:145], v[232:235], v[18:21]
	v_mfma_f32_16x16x32_bf16 v[14:17], v[178:181], v[232:235], v[14:17]
	v_mfma_f32_16x16x32_bf16 v[58:61], v[182:185], v[198:201], v[58:61]
	v_mfma_f32_16x16x32_bf16 v[54:57], v[190:193], v[198:201], v[54:57]
	v_mfma_f32_16x16x32_bf16 v[42:45], v[182:185], v[206:209], v[42:45]
	v_mfma_f32_16x16x32_bf16 v[38:41], v[190:193], v[206:209], v[38:41]
	v_mfma_f32_16x16x32_bf16 v[26:29], v[182:185], v[220:223], v[26:29]
	v_mfma_f32_16x16x32_bf16 v[22:25], v[190:193], v[220:223], v[22:25]
	v_mfma_f32_16x16x32_bf16 v[10:13], v[182:185], v[228:231], v[10:13]
	v_mfma_f32_16x16x32_bf16 v[6:9], v[190:193], v[228:231], v[6:9]
	v_mfma_f32_16x16x32_bf16 v[58:61], v[186:189], v[202:205], v[58:61]
	v_mfma_f32_16x16x32_bf16 v[54:57], v[194:197], v[202:205], v[54:57]
	v_mfma_f32_16x16x32_bf16 v[42:45], v[186:189], v[210:213], v[42:45]
	v_mfma_f32_16x16x32_bf16 v[38:41], v[194:197], v[210:213], v[38:41]
	v_mfma_f32_16x16x32_bf16 v[26:29], v[186:189], v[224:227], v[26:29]
	v_mfma_f32_16x16x32_bf16 v[22:25], v[194:197], v[224:227], v[22:25]
	v_mfma_f32_16x16x32_bf16 v[10:13], v[186:189], v[232:235], v[10:13]
	v_mfma_f32_16x16x32_bf16 v[6:9], v[194:197], v[232:235], v[6:9]
	s_setprio 1
	s_barrier
	v_lshl_add_u64 v[134:135], v[134:135], 0, s[26:27]
	s_cmp_ge_i32 s10, s46
	v_lshl_add_u64 v[136:137], v[136:137], 0, s[26:27]
	s_cbranch_scc0 .LBB0_1947
	s_setprio 0
